# K-loops: s_setprio 1 moved ahead of each pre-MFMA barrier (one instruction less between the release and the first MFMA)
# speedup vs baseline: 1.0031x; 1.0007x over previous
.LBB0_164:
	s_add_i32 s51, s51, 2
	v_add_u32_e32 v146, s33, v179
	v_add_u32_e32 v162, s36, v179
	s_add_u32 s3, s6, s10
	ds_read_b128 v[54:57], v146
	ds_read_b128 v[58:61], v146 offset:1024
	ds_read_b128 v[62:65], v146 offset:2048
	ds_read_b128 v[146:149], v146 offset:3072
	ds_read_b128 v[150:153], v162
	ds_read_b128 v[154:157], v162 offset:1024
	ds_read_b128 v[158:161], v162 offset:2048
	ds_read_b128 v[162:165], v162 offset:3072
	s_addc_u32 s24, s7, s11
	s_add_u32 s3, s3, 0x100
	s_addc_u32 s24, s24, 0
	s_add_u32 s25, s49, s10
	s_addc_u32 s26, s50, s11
	s_cmpk_eq_i32 s10, 0x700
	s_cselect_b32 s77, s75, s26
	s_cselect_b32 s76, s74, s25
	s_cselect_b32 s79, s73, s24
	s_cselect_b32 s78, s72, s3
	v_lshl_add_u64 v[206:207], v[52:53], 0, s[10:11]
	s_add_i32 s3, s20, 0x8000
	v_lshl_add_u64 v[244:245], v[206:207], 0, s[42:43]
	s_mov_b32 m0, s3
	ds_read_b128 v[212:215], v209
	ds_read_b128 v[216:219], v209 offset:1024
	ds_read_b128 v[220:223], v209 offset:2048
	ds_read_b128 v[224:227], v209 offset:3072
	ds_read_b128 v[228:231], v209 offset:4096
	ds_read_b128 v[232:235], v209 offset:5120
	ds_read_b128 v[236:239], v209 offset:6144
	ds_read_b128 v[240:243], v209 offset:7168
	global_load_lds_dwordx4 v[244:245], off
	v_lshl_add_u64 v[244:245], v[50:51], 0, s[10:11]
	s_add_i32 s80, s20, 0xa000
	v_lshl_add_u64 v[246:247], v[244:245], 0, s[42:43]
	s_mov_b32 m0, s80
	s_add_i32 s61, s20, 0xc000
	global_load_lds_dwordx4 v[246:247], off
	v_lshl_add_u64 v[206:207], v[206:207], 0, s[44:45]
	s_mov_b32 m0, s61
	s_add_i32 s71, s20, 0xe000
	global_load_lds_dwordx4 v[206:207], off
	v_lshl_add_u64 v[206:207], v[244:245], 0, s[44:45]
	s_mov_b32 m0, s71
	s_nop 0
	global_load_lds_dwordx4 v[206:207], off
	s_waitcnt vmcnt(8)
	s_waitcnt lgkmcnt(0)
	s_setprio 1
	s_barrier
	v_mfma_f32_16x16x32_bf16 v[142:145], v[54:57], v[212:215], v[142:145]
	v_mfma_f32_16x16x32_bf16 v[138:141], v[62:65], v[212:215], v[138:141]
	v_mfma_f32_16x16x32_bf16 v[126:129], v[54:57], v[220:223], v[126:129]
	v_mfma_f32_16x16x32_bf16 v[122:125], v[62:65], v[220:223], v[122:125]
	v_mfma_f32_16x16x32_bf16 v[110:113], v[54:57], v[228:231], v[110:113]
	v_mfma_f32_16x16x32_bf16 v[106:109], v[62:65], v[228:231], v[106:109]
	v_mfma_f32_16x16x32_bf16 v[94:97], v[54:57], v[236:239], v[94:97]
	v_mfma_f32_16x16x32_bf16 v[90:93], v[62:65], v[236:239], v[90:93]
	v_mfma_f32_16x16x32_bf16 v[142:145], v[58:61], v[216:219], v[142:145]
	v_mfma_f32_16x16x32_bf16 v[138:141], v[146:149], v[216:219], v[138:141]
	v_mfma_f32_16x16x32_bf16 v[126:129], v[58:61], v[224:227], v[126:129]
	v_mfma_f32_16x16x32_bf16 v[122:125], v[146:149], v[224:227], v[122:125]
	v_mfma_f32_16x16x32_bf16 v[110:113], v[58:61], v[232:235], v[110:113]
	v_mfma_f32_16x16x32_bf16 v[106:109], v[146:149], v[232:235], v[106:109]
	v_mfma_f32_16x16x32_bf16 v[94:97], v[58:61], v[240:243], v[94:97]
	v_mfma_f32_16x16x32_bf16 v[90:93], v[146:149], v[240:243], v[90:93]
	v_mfma_f32_16x16x32_bf16 v[134:137], v[150:153], v[212:215], v[134:137]
	v_mfma_f32_16x16x32_bf16 v[130:133], v[158:161], v[212:215], v[130:133]
	v_mfma_f32_16x16x32_bf16 v[118:121], v[150:153], v[220:223], v[118:121]
	v_mfma_f32_16x16x32_bf16 v[114:117], v[158:161], v[220:223], v[114:117]
	v_mfma_f32_16x16x32_bf16 v[102:105], v[150:153], v[228:231], v[102:105]
	v_mfma_f32_16x16x32_bf16 v[98:101], v[158:161], v[228:231], v[98:101]
	v_mfma_f32_16x16x32_bf16 v[86:89], v[150:153], v[236:239], v[86:89]
	v_mfma_f32_16x16x32_bf16 v[82:85], v[158:161], v[236:239], v[82:85]
	v_mfma_f32_16x16x32_bf16 v[134:137], v[154:157], v[216:219], v[134:137]
	v_mfma_f32_16x16x32_bf16 v[130:133], v[162:165], v[216:219], v[130:133]
	v_mfma_f32_16x16x32_bf16 v[118:121], v[154:157], v[224:227], v[118:121]
	v_mfma_f32_16x16x32_bf16 v[114:117], v[162:165], v[224:227], v[114:117]
	v_mfma_f32_16x16x32_bf16 v[102:105], v[154:157], v[232:235], v[102:105]
	v_mfma_f32_16x16x32_bf16 v[98:101], v[162:165], v[232:235], v[98:101]
	v_mfma_f32_16x16x32_bf16 v[86:89], v[154:157], v[240:243], v[86:89]
	v_mfma_f32_16x16x32_bf16 v[82:85], v[162:165], v[240:243], v[82:85]
	s_setprio 0
	s_barrier
	s_add_i32 s24, s33, s19
	v_lshl_add_u64 v[206:207], s[76:77], 0, v[168:169]
	s_mov_b32 m0, s24
	ds_read_b128 v[212:215], v209 offset:16384
	ds_read_b128 v[216:219], v209 offset:17408
	ds_read_b128 v[220:223], v209 offset:18432
	ds_read_b128 v[224:227], v209 offset:19456
	ds_read_b128 v[228:231], v209 offset:20480
	ds_read_b128 v[232:235], v209 offset:21504
	ds_read_b128 v[236:239], v209 offset:22528
	ds_read_b128 v[240:243], v209 offset:23552
	global_load_lds_dwordx4 v[206:207], off
	s_add_i32 m0, s24, 0x2000
	s_add_u32 s24, s76, 0x40000
	v_lshl_add_u64 v[244:245], s[76:77], 0, v[172:173]
	s_addc_u32 s25, s77, 0
	s_add_i32 s26, s36, s19
	global_load_lds_dwordx4 v[244:245], off
	v_lshl_add_u64 v[246:247], s[24:25], 0, v[168:169]
	s_mov_b32 m0, s26
	s_nop 0
	global_load_lds_dwordx4 v[246:247], off
	v_lshl_add_u64 v[246:247], s[24:25], 0, v[172:173]
	s_add_i32 m0, s26, 0x2000
	s_nop 0
	global_load_lds_dwordx4 v[246:247], off
	s_waitcnt vmcnt(4)
	s_waitcnt lgkmcnt(0)
	s_setprio 1
	s_barrier
	v_mfma_f32_16x16x32_bf16 v[78:81], v[54:57], v[212:215], v[78:81]
	v_mfma_f32_16x16x32_bf16 v[74:77], v[62:65], v[212:215], v[74:77]
	v_mfma_f32_16x16x32_bf16 v[46:49], v[54:57], v[220:223], v[46:49]
	v_mfma_f32_16x16x32_bf16 v[42:45], v[62:65], v[220:223], v[42:45]
	v_mfma_f32_16x16x32_bf16 v[30:33], v[54:57], v[228:231], v[30:33]
	v_mfma_f32_16x16x32_bf16 v[26:29], v[62:65], v[228:231], v[26:29]
	v_mfma_f32_16x16x32_bf16 v[14:17], v[54:57], v[236:239], v[14:17]
	v_mfma_f32_16x16x32_bf16 v[10:13], v[62:65], v[236:239], v[10:13]
	v_mfma_f32_16x16x32_bf16 v[78:81], v[58:61], v[216:219], v[78:81]
	v_mfma_f32_16x16x32_bf16 v[74:77], v[146:149], v[216:219], v[74:77]
	v_mfma_f32_16x16x32_bf16 v[46:49], v[58:61], v[224:227], v[46:49]
	v_mfma_f32_16x16x32_bf16 v[42:45], v[146:149], v[224:227], v[42:45]
	v_mfma_f32_16x16x32_bf16 v[30:33], v[58:61], v[232:235], v[30:33]
	v_mfma_f32_16x16x32_bf16 v[26:29], v[146:149], v[232:235], v[26:29]
	v_mfma_f32_16x16x32_bf16 v[14:17], v[58:61], v[240:243], v[14:17]
	v_mfma_f32_16x16x32_bf16 v[10:13], v[146:149], v[240:243], v[10:13]
	v_mfma_f32_16x16x32_bf16 v[38:41], v[150:153], v[220:223], v[38:41]
	v_mfma_f32_16x16x32_bf16 v[34:37], v[158:161], v[220:223], v[34:37]
	v_mfma_f32_16x16x32_bf16 v[22:25], v[150:153], v[228:231], v[22:25]
	v_mfma_f32_16x16x32_bf16 v[18:21], v[158:161], v[228:231], v[18:21]
	v_mfma_f32_16x16x32_bf16 v[6:9], v[150:153], v[236:239], v[6:9]
	v_mfma_f32_16x16x32_bf16 v[2:5], v[158:161], v[236:239], v[2:5]
	v_mfma_f32_16x16x32_bf16 v[54:57], v[150:153], v[212:215], v[70:73]
	v_mfma_f32_16x16x32_bf16 v[58:61], v[158:161], v[212:215], v[66:69]
	v_mfma_f32_16x16x32_bf16 v[38:41], v[154:157], v[224:227], v[38:41]
	v_mfma_f32_16x16x32_bf16 v[34:37], v[162:165], v[224:227], v[34:37]
	v_mfma_f32_16x16x32_bf16 v[22:25], v[154:157], v[232:235], v[22:25]
	v_mfma_f32_16x16x32_bf16 v[18:21], v[162:165], v[232:235], v[18:21]
	v_mfma_f32_16x16x32_bf16 v[6:9], v[154:157], v[240:243], v[6:9]
	v_mfma_f32_16x16x32_bf16 v[2:5], v[162:165], v[240:243], v[2:5]
	v_mfma_f32_16x16x32_bf16 v[54:57], v[154:157], v[216:219], v[54:57]
	v_mfma_f32_16x16x32_bf16 v[58:61], v[162:165], v[216:219], v[58:61]
	s_setprio 0
	s_barrier
	s_add_i32 s26, 0, 0x18000
	s_add_i32 s27, 0, 0x1c000
	v_add_u32_e32 v146, s26, v179
	v_add_u32_e32 v162, s27, v179
	ds_read_b128 v[62:65], v146
	ds_read_b128 v[66:69], v146 offset:1024
	ds_read_b128 v[70:73], v146 offset:2048
	ds_read_b128 v[146:149], v146 offset:3072
	ds_read_b128 v[150:153], v162
	ds_read_b128 v[154:157], v162 offset:1024
	ds_read_b128 v[158:161], v162 offset:2048
	ds_read_b128 v[162:165], v162 offset:3072
	s_mov_b32 m0, s20
	v_lshl_add_u64 v[246:247], s[78:79], 0, v[166:167]
	s_add_u32 s24, s78, 0x40000
	ds_read_b128 v[212:215], v209 offset:32768
	ds_read_b128 v[216:219], v209 offset:33792
	ds_read_b128 v[220:223], v209 offset:34816
	ds_read_b128 v[224:227], v209 offset:35840
	ds_read_b128 v[228:231], v209 offset:36864
	ds_read_b128 v[232:235], v209 offset:37888
	ds_read_b128 v[236:239], v209 offset:38912
	ds_read_b128 v[240:243], v209 offset:39936
	global_load_lds_dwordx4 v[246:247], off
	v_lshl_add_u64 v[246:247], s[78:79], 0, v[170:171]
	s_mov_b32 m0, s21
	s_addc_u32 s25, s79, 0
	global_load_lds_dwordx4 v[246:247], off
	v_lshl_add_u64 v[246:247], s[24:25], 0, v[166:167]
	s_mov_b32 m0, s22
	s_nop 0
	global_load_lds_dwordx4 v[246:247], off
	v_lshl_add_u64 v[246:247], s[24:25], 0, v[170:171]
	s_mov_b32 m0, s23
	s_nop 0
	global_load_lds_dwordx4 v[246:247], off
	s_waitcnt vmcnt(8)
	s_waitcnt lgkmcnt(0)
	s_setprio 1
	s_barrier
	v_mfma_f32_16x16x32_bf16 v[142:145], v[62:65], v[212:215], v[142:145]
	v_mfma_f32_16x16x32_bf16 v[138:141], v[70:73], v[212:215], v[138:141]
	v_mfma_f32_16x16x32_bf16 v[126:129], v[62:65], v[220:223], v[126:129]
	v_mfma_f32_16x16x32_bf16 v[122:125], v[70:73], v[220:223], v[122:125]
	v_mfma_f32_16x16x32_bf16 v[110:113], v[62:65], v[228:231], v[110:113]
	v_mfma_f32_16x16x32_bf16 v[106:109], v[70:73], v[228:231], v[106:109]
	v_mfma_f32_16x16x32_bf16 v[94:97], v[62:65], v[236:239], v[94:97]
	v_mfma_f32_16x16x32_bf16 v[90:93], v[70:73], v[236:239], v[90:93]
	v_mfma_f32_16x16x32_bf16 v[142:145], v[66:69], v[216:219], v[142:145]
	v_mfma_f32_16x16x32_bf16 v[138:141], v[146:149], v[216:219], v[138:141]
	v_mfma_f32_16x16x32_bf16 v[126:129], v[66:69], v[224:227], v[126:129]
	v_mfma_f32_16x16x32_bf16 v[122:125], v[146:149], v[224:227], v[122:125]
	v_mfma_f32_16x16x32_bf16 v[110:113], v[66:69], v[232:235], v[110:113]
	v_mfma_f32_16x16x32_bf16 v[106:109], v[146:149], v[232:235], v[106:109]
	v_mfma_f32_16x16x32_bf16 v[94:97], v[66:69], v[240:243], v[94:97]
	v_mfma_f32_16x16x32_bf16 v[90:93], v[146:149], v[240:243], v[90:93]
	v_mfma_f32_16x16x32_bf16 v[134:137], v[150:153], v[212:215], v[134:137]
	v_mfma_f32_16x16x32_bf16 v[130:133], v[158:161], v[212:215], v[130:133]
	v_mfma_f32_16x16x32_bf16 v[118:121], v[150:153], v[220:223], v[118:121]
	v_mfma_f32_16x16x32_bf16 v[114:117], v[158:161], v[220:223], v[114:117]
	v_mfma_f32_16x16x32_bf16 v[102:105], v[150:153], v[228:231], v[102:105]
	v_mfma_f32_16x16x32_bf16 v[98:101], v[158:161], v[228:231], v[98:101]
	v_mfma_f32_16x16x32_bf16 v[86:89], v[150:153], v[236:239], v[86:89]
	v_mfma_f32_16x16x32_bf16 v[82:85], v[158:161], v[236:239], v[82:85]
	v_mfma_f32_16x16x32_bf16 v[134:137], v[154:157], v[216:219], v[134:137]
	v_mfma_f32_16x16x32_bf16 v[130:133], v[162:165], v[216:219], v[130:133]
	v_mfma_f32_16x16x32_bf16 v[118:121], v[154:157], v[224:227], v[118:121]
	v_mfma_f32_16x16x32_bf16 v[114:117], v[162:165], v[224:227], v[114:117]
	v_mfma_f32_16x16x32_bf16 v[102:105], v[154:157], v[232:235], v[102:105]
	v_mfma_f32_16x16x32_bf16 v[98:101], v[162:165], v[232:235], v[98:101]
	v_mfma_f32_16x16x32_bf16 v[86:89], v[154:157], v[240:243], v[86:89]
	v_mfma_f32_16x16x32_bf16 v[82:85], v[162:165], v[240:243], v[82:85]
	s_setprio 0
	s_barrier
	s_add_i32 s24, s26, s19
	v_lshl_add_u64 v[206:207], v[206:207], 0, s[42:43]
	s_mov_b32 m0, s24
	ds_read_b128 v[212:215], v209 offset:49152
	ds_read_b128 v[216:219], v209 offset:50176
	ds_read_b128 v[220:223], v209 offset:51200
	ds_read_b128 v[224:227], v209 offset:52224
	ds_read_b128 v[228:231], v209 offset:53248
	ds_read_b128 v[232:235], v209 offset:54272
	ds_read_b128 v[236:239], v209 offset:55296
	ds_read_b128 v[240:243], v209 offset:56320
	global_load_lds_dwordx4 v[206:207], off
	s_add_i32 m0, s24, 0x2000
	s_add_u32 s24, s76, 0x40080
	v_lshl_add_u64 v[206:207], v[244:245], 0, s[42:43]
	s_addc_u32 s25, s77, 0
	s_add_i32 s26, s27, s19
	global_load_lds_dwordx4 v[206:207], off
	v_lshl_add_u64 v[206:207], s[24:25], 0, v[168:169]
	s_mov_b32 m0, s26
	s_nop 0
	global_load_lds_dwordx4 v[206:207], off
	v_lshl_add_u64 v[206:207], s[24:25], 0, v[172:173]
	s_add_i32 m0, s26, 0x2000
	s_nop 0
	global_load_lds_dwordx4 v[206:207], off
	s_waitcnt vmcnt(4)
	s_waitcnt lgkmcnt(0)
	s_setprio 1
	s_barrier
	v_mfma_f32_16x16x32_bf16 v[78:81], v[62:65], v[212:215], v[78:81]
	v_mfma_f32_16x16x32_bf16 v[74:77], v[70:73], v[212:215], v[74:77]
	v_mfma_f32_16x16x32_bf16 v[46:49], v[62:65], v[220:223], v[46:49]
	v_mfma_f32_16x16x32_bf16 v[42:45], v[70:73], v[220:223], v[42:45]
	v_mfma_f32_16x16x32_bf16 v[30:33], v[62:65], v[228:231], v[30:33]
	v_mfma_f32_16x16x32_bf16 v[26:29], v[70:73], v[228:231], v[26:29]
	v_mfma_f32_16x16x32_bf16 v[14:17], v[62:65], v[236:239], v[14:17]
	v_mfma_f32_16x16x32_bf16 v[10:13], v[70:73], v[236:239], v[10:13]
	v_mfma_f32_16x16x32_bf16 v[78:81], v[66:69], v[216:219], v[78:81]
	v_mfma_f32_16x16x32_bf16 v[74:77], v[146:149], v[216:219], v[74:77]
	v_mfma_f32_16x16x32_bf16 v[46:49], v[66:69], v[224:227], v[46:49]
	v_mfma_f32_16x16x32_bf16 v[42:45], v[146:149], v[224:227], v[42:45]
	v_mfma_f32_16x16x32_bf16 v[30:33], v[66:69], v[232:235], v[30:33]
	v_mfma_f32_16x16x32_bf16 v[26:29], v[146:149], v[232:235], v[26:29]
	v_mfma_f32_16x16x32_bf16 v[14:17], v[66:69], v[240:243], v[14:17]
	v_mfma_f32_16x16x32_bf16 v[10:13], v[146:149], v[240:243], v[10:13]
	v_mfma_f32_16x16x32_bf16 v[54:57], v[150:153], v[212:215], v[54:57]
	v_mfma_f32_16x16x32_bf16 v[70:73], v[154:157], v[216:219], v[54:57]
	v_mfma_f32_16x16x32_bf16 v[54:57], v[158:161], v[212:215], v[58:61]
	v_mfma_f32_16x16x32_bf16 v[38:41], v[150:153], v[220:223], v[38:41]
	v_mfma_f32_16x16x32_bf16 v[34:37], v[158:161], v[220:223], v[34:37]
	v_mfma_f32_16x16x32_bf16 v[22:25], v[150:153], v[228:231], v[22:25]
	v_mfma_f32_16x16x32_bf16 v[18:21], v[158:161], v[228:231], v[18:21]
	v_mfma_f32_16x16x32_bf16 v[6:9], v[150:153], v[236:239], v[6:9]
	v_mfma_f32_16x16x32_bf16 v[2:5], v[158:161], v[236:239], v[2:5]
	v_mfma_f32_16x16x32_bf16 v[66:69], v[162:165], v[216:219], v[54:57]
	v_mfma_f32_16x16x32_bf16 v[38:41], v[154:157], v[224:227], v[38:41]
	v_mfma_f32_16x16x32_bf16 v[34:37], v[162:165], v[224:227], v[34:37]
	v_mfma_f32_16x16x32_bf16 v[22:25], v[154:157], v[232:235], v[22:25]
	v_mfma_f32_16x16x32_bf16 v[18:21], v[162:165], v[232:235], v[18:21]
	v_mfma_f32_16x16x32_bf16 v[6:9], v[154:157], v[240:243], v[6:9]
	v_mfma_f32_16x16x32_bf16 v[2:5], v[162:165], v[240:243], v[2:5]
	s_setprio 0
	s_barrier
	s_add_u32 s10, s10, 0x100
	s_addc_u32 s11, s11, 0
	s_cmp_ge_u32 s51, s9
	s_cbranch_scc0 .LBB0_164
	s_and_b64 vcc, exec, s[4:5]
	s_cbranch_vccz .LBB0_167
	v_add_u32_e32 v204, 0, v179
	v_add_u32_e32 v62, 0x10000, v204
	v_add_u32_e32 v158, 0x14000, v204
	ds_read_b128 v[50:53], v62
	ds_read_b128 v[54:57], v62 offset:1024
	ds_read_b128 v[58:61], v62 offset:2048
	ds_read_b128 v[62:65], v62 offset:3072
	ds_read_b128 v[146:149], v158
	ds_read_b128 v[150:153], v158 offset:1024
	ds_read_b128 v[154:157], v158 offset:2048
	ds_read_b128 v[158:161], v158 offset:3072
	v_lshl_add_u64 v[206:207], s[6:7], 0, v[166:167]
	s_mov_b32 m0, s3
	v_lshl_add_u64 v[206:207], v[206:207], 0, s[58:59]
	ds_read_b128 v[162:165], v209
	ds_read_b128 v[212:215], v209 offset:1024
	ds_read_b128 v[216:219], v209 offset:2048
	ds_read_b128 v[220:223], v209 offset:3072
	ds_read_b128 v[224:227], v209 offset:4096
	ds_read_b128 v[228:231], v209 offset:5120
	ds_read_b128 v[232:235], v209 offset:6144
	ds_read_b128 v[236:239], v209 offset:7168
	global_load_lds_dwordx4 v[206:207], off
	v_lshl_add_u64 v[206:207], s[6:7], 0, v[170:171]
	s_add_u32 s4, s6, 0x40780
	v_lshl_add_u64 v[206:207], v[206:207], 0, s[58:59]
	s_mov_b32 m0, s80
	s_addc_u32 s5, s7, 0
	global_load_lds_dwordx4 v[206:207], off
	v_lshl_add_u64 v[206:207], s[4:5], 0, v[166:167]
	s_mov_b32 m0, s61
	s_nop 0
	global_load_lds_dwordx4 v[206:207], off
	v_lshl_add_u64 v[206:207], s[4:5], 0, v[170:171]
	s_mov_b32 m0, s71
	s_nop 0
	global_load_lds_dwordx4 v[206:207], off
	s_waitcnt vmcnt(8)
	s_waitcnt lgkmcnt(0)
	s_setprio 1
	s_barrier
	v_mfma_f32_16x16x32_bf16 v[142:145], v[50:53], v[162:165], v[142:145]
	v_mfma_f32_16x16x32_bf16 v[138:141], v[58:61], v[162:165], v[138:141]
	v_mfma_f32_16x16x32_bf16 v[126:129], v[50:53], v[216:219], v[126:129]
	v_mfma_f32_16x16x32_bf16 v[122:125], v[58:61], v[216:219], v[122:125]
	v_mfma_f32_16x16x32_bf16 v[110:113], v[50:53], v[224:227], v[110:113]
	v_mfma_f32_16x16x32_bf16 v[106:109], v[58:61], v[224:227], v[106:109]
	v_mfma_f32_16x16x32_bf16 v[94:97], v[50:53], v[232:235], v[94:97]
	v_mfma_f32_16x16x32_bf16 v[90:93], v[58:61], v[232:235], v[90:93]
	v_mfma_f32_16x16x32_bf16 v[142:145], v[54:57], v[212:215], v[142:145]
	v_mfma_f32_16x16x32_bf16 v[138:141], v[62:65], v[212:215], v[138:141]
	v_mfma_f32_16x16x32_bf16 v[126:129], v[54:57], v[220:223], v[126:129]
	v_mfma_f32_16x16x32_bf16 v[122:125], v[62:65], v[220:223], v[122:125]
	v_mfma_f32_16x16x32_bf16 v[110:113], v[54:57], v[228:231], v[110:113]
	v_mfma_f32_16x16x32_bf16 v[106:109], v[62:65], v[228:231], v[106:109]
	v_mfma_f32_16x16x32_bf16 v[94:97], v[54:57], v[236:239], v[94:97]
	v_mfma_f32_16x16x32_bf16 v[90:93], v[62:65], v[236:239], v[90:93]
	v_mfma_f32_16x16x32_bf16 v[134:137], v[146:149], v[162:165], v[134:137]
	v_mfma_f32_16x16x32_bf16 v[130:133], v[154:157], v[162:165], v[130:133]
	v_mfma_f32_16x16x32_bf16 v[118:121], v[146:149], v[216:219], v[118:121]
	v_mfma_f32_16x16x32_bf16 v[114:117], v[154:157], v[216:219], v[114:117]
	v_mfma_f32_16x16x32_bf16 v[102:105], v[146:149], v[224:227], v[102:105]
	v_mfma_f32_16x16x32_bf16 v[98:101], v[154:157], v[224:227], v[98:101]
	v_mfma_f32_16x16x32_bf16 v[86:89], v[146:149], v[232:235], v[86:89]
	v_mfma_f32_16x16x32_bf16 v[82:85], v[154:157], v[232:235], v[82:85]
	v_mfma_f32_16x16x32_bf16 v[134:137], v[150:153], v[212:215], v[134:137]
	v_mfma_f32_16x16x32_bf16 v[130:133], v[158:161], v[212:215], v[130:133]
	v_mfma_f32_16x16x32_bf16 v[118:121], v[150:153], v[220:223], v[118:121]
	v_mfma_f32_16x16x32_bf16 v[114:117], v[158:161], v[220:223], v[114:117]
	v_mfma_f32_16x16x32_bf16 v[102:105], v[150:153], v[228:231], v[102:105]
	v_mfma_f32_16x16x32_bf16 v[98:101], v[158:161], v[228:231], v[98:101]
	v_mfma_f32_16x16x32_bf16 v[86:89], v[150:153], v[236:239], v[86:89]
	v_mfma_f32_16x16x32_bf16 v[82:85], v[158:161], v[236:239], v[82:85]
	s_setprio 0
	s_barrier
	ds_read_b128 v[162:165], v209 offset:16384
	ds_read_b128 v[212:215], v209 offset:17408
	ds_read_b128 v[216:219], v209 offset:18432
	ds_read_b128 v[220:223], v209 offset:19456
	ds_read_b128 v[224:227], v209 offset:20480
	ds_read_b128 v[228:231], v209 offset:21504
	ds_read_b128 v[232:235], v209 offset:22528
	ds_read_b128 v[236:239], v209 offset:23552
	s_waitcnt vmcnt(0)
	s_waitcnt lgkmcnt(0)
	s_setprio 1
	s_barrier
	v_mfma_f32_16x16x32_bf16 v[78:81], v[50:53], v[162:165], v[78:81]
	v_mfma_f32_16x16x32_bf16 v[74:77], v[58:61], v[162:165], v[74:77]
	v_mfma_f32_16x16x32_bf16 v[46:49], v[50:53], v[216:219], v[46:49]
	v_mfma_f32_16x16x32_bf16 v[42:45], v[58:61], v[216:219], v[42:45]
	v_mfma_f32_16x16x32_bf16 v[30:33], v[50:53], v[224:227], v[30:33]
	v_mfma_f32_16x16x32_bf16 v[26:29], v[58:61], v[224:227], v[26:29]
	v_mfma_f32_16x16x32_bf16 v[14:17], v[50:53], v[232:235], v[14:17]
	v_mfma_f32_16x16x32_bf16 v[10:13], v[58:61], v[232:235], v[10:13]
	v_mfma_f32_16x16x32_bf16 v[78:81], v[54:57], v[212:215], v[78:81]
	v_mfma_f32_16x16x32_bf16 v[74:77], v[62:65], v[212:215], v[74:77]
	v_mfma_f32_16x16x32_bf16 v[46:49], v[54:57], v[220:223], v[46:49]
	v_mfma_f32_16x16x32_bf16 v[42:45], v[62:65], v[220:223], v[42:45]
	v_mfma_f32_16x16x32_bf16 v[30:33], v[54:57], v[228:231], v[30:33]
	v_mfma_f32_16x16x32_bf16 v[26:29], v[62:65], v[228:231], v[26:29]
	v_mfma_f32_16x16x32_bf16 v[14:17], v[54:57], v[236:239], v[14:17]
	v_mfma_f32_16x16x32_bf16 v[10:13], v[62:65], v[236:239], v[10:13]
	v_mfma_f32_16x16x32_bf16 v[38:41], v[146:149], v[216:219], v[38:41]
	v_mfma_f32_16x16x32_bf16 v[34:37], v[154:157], v[216:219], v[34:37]
	v_mfma_f32_16x16x32_bf16 v[22:25], v[146:149], v[224:227], v[22:25]
	v_mfma_f32_16x16x32_bf16 v[18:21], v[154:157], v[224:227], v[18:21]
	v_mfma_f32_16x16x32_bf16 v[6:9], v[146:149], v[232:235], v[6:9]
	v_mfma_f32_16x16x32_bf16 v[2:5], v[154:157], v[232:235], v[2:5]
	v_mfma_f32_16x16x32_bf16 v[50:53], v[146:149], v[162:165], v[70:73]
	v_mfma_f32_16x16x32_bf16 v[54:57], v[154:157], v[162:165], v[66:69]
	v_mfma_f32_16x16x32_bf16 v[38:41], v[150:153], v[220:223], v[38:41]
	v_mfma_f32_16x16x32_bf16 v[34:37], v[158:161], v[220:223], v[34:37]
	v_mfma_f32_16x16x32_bf16 v[22:25], v[150:153], v[228:231], v[22:25]
	v_mfma_f32_16x16x32_bf16 v[18:21], v[158:161], v[228:231], v[18:21]
	v_mfma_f32_16x16x32_bf16 v[6:9], v[150:153], v[236:239], v[6:9]
	v_mfma_f32_16x16x32_bf16 v[2:5], v[158:161], v[236:239], v[2:5]
	v_mfma_f32_16x16x32_bf16 v[50:53], v[150:153], v[212:215], v[50:53]
	v_mfma_f32_16x16x32_bf16 v[54:57], v[158:161], v[212:215], v[54:57]
	s_setprio 0
	s_barrier
	v_add_u32_e32 v70, 0x18000, v204
	v_add_u32_e32 v158, 0x1c000, v204
	ds_read_b128 v[58:61], v70
	ds_read_b128 v[62:65], v70 offset:1024
	ds_read_b128 v[66:69], v70 offset:2048
	ds_read_b128 v[70:73], v70 offset:3072
	ds_read_b128 v[146:149], v158
	ds_read_b128 v[150:153], v158 offset:1024
	ds_read_b128 v[154:157], v158 offset:2048
	ds_read_b128 v[158:161], v158 offset:3072
	ds_read_b128 v[162:165], v209 offset:32768
	ds_read_b128 v[212:215], v209 offset:33792
	ds_read_b128 v[216:219], v209 offset:34816
	ds_read_b128 v[220:223], v209 offset:35840
	ds_read_b128 v[224:227], v209 offset:36864
	ds_read_b128 v[228:231], v209 offset:37888
	ds_read_b128 v[232:235], v209 offset:38912
	ds_read_b128 v[236:239], v209 offset:39936
	s_waitcnt lgkmcnt(0)
	s_setprio 1
	s_barrier
	v_mfma_f32_16x16x32_bf16 v[142:145], v[58:61], v[162:165], v[142:145]
	v_mfma_f32_16x16x32_bf16 v[138:141], v[66:69], v[162:165], v[138:141]
	v_mfma_f32_16x16x32_bf16 v[126:129], v[58:61], v[216:219], v[126:129]
	v_mfma_f32_16x16x32_bf16 v[122:125], v[66:69], v[216:219], v[122:125]
	v_mfma_f32_16x16x32_bf16 v[110:113], v[58:61], v[224:227], v[110:113]
	v_mfma_f32_16x16x32_bf16 v[106:109], v[66:69], v[224:227], v[106:109]
	v_mfma_f32_16x16x32_bf16 v[94:97], v[58:61], v[232:235], v[94:97]
	v_mfma_f32_16x16x32_bf16 v[90:93], v[66:69], v[232:235], v[90:93]
	v_mfma_f32_16x16x32_bf16 v[142:145], v[62:65], v[212:215], v[142:145]
	v_mfma_f32_16x16x32_bf16 v[138:141], v[70:73], v[212:215], v[138:141]
	v_mfma_f32_16x16x32_bf16 v[126:129], v[62:65], v[220:223], v[126:129]
	v_mfma_f32_16x16x32_bf16 v[122:125], v[70:73], v[220:223], v[122:125]
	v_mfma_f32_16x16x32_bf16 v[110:113], v[62:65], v[228:231], v[110:113]
	v_mfma_f32_16x16x32_bf16 v[106:109], v[70:73], v[228:231], v[106:109]
	v_mfma_f32_16x16x32_bf16 v[94:97], v[62:65], v[236:239], v[94:97]
	v_mfma_f32_16x16x32_bf16 v[90:93], v[70:73], v[236:239], v[90:93]
	v_mfma_f32_16x16x32_bf16 v[134:137], v[146:149], v[162:165], v[134:137]
	v_mfma_f32_16x16x32_bf16 v[130:133], v[154:157], v[162:165], v[130:133]
	v_mfma_f32_16x16x32_bf16 v[118:121], v[146:149], v[216:219], v[118:121]
	v_mfma_f32_16x16x32_bf16 v[114:117], v[154:157], v[216:219], v[114:117]
	v_mfma_f32_16x16x32_bf16 v[102:105], v[146:149], v[224:227], v[102:105]
	v_mfma_f32_16x16x32_bf16 v[98:101], v[154:157], v[224:227], v[98:101]
	v_mfma_f32_16x16x32_bf16 v[86:89], v[146:149], v[232:235], v[86:89]
	v_mfma_f32_16x16x32_bf16 v[82:85], v[154:157], v[232:235], v[82:85]
	v_mfma_f32_16x16x32_bf16 v[134:137], v[150:153], v[212:215], v[134:137]
	v_mfma_f32_16x16x32_bf16 v[130:133], v[158:161], v[212:215], v[130:133]
	v_mfma_f32_16x16x32_bf16 v[118:121], v[150:153], v[220:223], v[118:121]
	v_mfma_f32_16x16x32_bf16 v[114:117], v[158:161], v[220:223], v[114:117]
	v_mfma_f32_16x16x32_bf16 v[102:105], v[150:153], v[228:231], v[102:105]
	v_mfma_f32_16x16x32_bf16 v[98:101], v[158:161], v[228:231], v[98:101]
	v_mfma_f32_16x16x32_bf16 v[86:89], v[150:153], v[236:239], v[86:89]
	v_mfma_f32_16x16x32_bf16 v[82:85], v[158:161], v[236:239], v[82:85]
	s_setprio 0
	s_barrier
	ds_read_b128 v[162:165], v209 offset:49152
	ds_read_b128 v[212:215], v209 offset:50176
	ds_read_b128 v[216:219], v209 offset:51200
	ds_read_b128 v[220:223], v209 offset:52224
	ds_read_b128 v[224:227], v209 offset:53248
	ds_read_b128 v[228:231], v209 offset:54272
	ds_read_b128 v[232:235], v209 offset:55296
	ds_read_b128 v[236:239], v209 offset:56320
	s_waitcnt lgkmcnt(0)
	s_setprio 1
	s_barrier
	v_mfma_f32_16x16x32_bf16 v[78:81], v[58:61], v[162:165], v[78:81]
	v_mfma_f32_16x16x32_bf16 v[74:77], v[66:69], v[162:165], v[74:77]
	v_mfma_f32_16x16x32_bf16 v[46:49], v[58:61], v[216:219], v[46:49]
	v_mfma_f32_16x16x32_bf16 v[42:45], v[66:69], v[216:219], v[42:45]
	v_mfma_f32_16x16x32_bf16 v[30:33], v[58:61], v[224:227], v[30:33]
	v_mfma_f32_16x16x32_bf16 v[26:29], v[66:69], v[224:227], v[26:29]
	v_mfma_f32_16x16x32_bf16 v[14:17], v[58:61], v[232:235], v[14:17]
	v_mfma_f32_16x16x32_bf16 v[10:13], v[66:69], v[232:235], v[10:13]
	v_mfma_f32_16x16x32_bf16 v[78:81], v[62:65], v[212:215], v[78:81]
	v_mfma_f32_16x16x32_bf16 v[74:77], v[70:73], v[212:215], v[74:77]
	v_mfma_f32_16x16x32_bf16 v[46:49], v[62:65], v[220:223], v[46:49]
	v_mfma_f32_16x16x32_bf16 v[42:45], v[70:73], v[220:223], v[42:45]
	v_mfma_f32_16x16x32_bf16 v[30:33], v[62:65], v[228:231], v[30:33]
	v_mfma_f32_16x16x32_bf16 v[26:29], v[70:73], v[228:231], v[26:29]
	v_mfma_f32_16x16x32_bf16 v[14:17], v[62:65], v[236:239], v[14:17]
	v_mfma_f32_16x16x32_bf16 v[10:13], v[70:73], v[236:239], v[10:13]
	v_mfma_f32_16x16x32_bf16 v[50:53], v[146:149], v[162:165], v[50:53]
	v_mfma_f32_16x16x32_bf16 v[70:73], v[150:153], v[212:215], v[50:53]
	v_mfma_f32_16x16x32_bf16 v[50:53], v[154:157], v[162:165], v[54:57]
	v_mfma_f32_16x16x32_bf16 v[38:41], v[146:149], v[216:219], v[38:41]
	v_mfma_f32_16x16x32_bf16 v[34:37], v[154:157], v[216:219], v[34:37]
	v_mfma_f32_16x16x32_bf16 v[22:25], v[146:149], v[224:227], v[22:25]
	v_mfma_f32_16x16x32_bf16 v[18:21], v[154:157], v[224:227], v[18:21]
	v_mfma_f32_16x16x32_bf16 v[6:9], v[146:149], v[232:235], v[6:9]
	v_mfma_f32_16x16x32_bf16 v[2:5], v[154:157], v[232:235], v[2:5]
	v_mfma_f32_16x16x32_bf16 v[66:69], v[158:161], v[212:215], v[50:53]
	v_mfma_f32_16x16x32_bf16 v[38:41], v[150:153], v[220:223], v[38:41]
	v_mfma_f32_16x16x32_bf16 v[34:37], v[158:161], v[220:223], v[34:37]
	v_mfma_f32_16x16x32_bf16 v[22:25], v[150:153], v[228:231], v[22:25]
	v_mfma_f32_16x16x32_bf16 v[18:21], v[158:161], v[228:231], v[18:21]
	v_mfma_f32_16x16x32_bf16 v[6:9], v[150:153], v[236:239], v[6:9]
	v_mfma_f32_16x16x32_bf16 v[2:5], v[158:161], v[236:239], v[2:5]
	s_setprio 0
	s_barrier

.LBB0_325:
	ds_read_b128 v[156:159], v151
	ds_read_b128 v[160:163], v151 offset:1024
	ds_read_b128 v[164:167], v151 offset:2048
	ds_read_b128 v[168:171], v151 offset:3072
	ds_read_b128 v[172:175], v152
	ds_read_b128 v[176:179], v152 offset:1024
	ds_read_b128 v[180:183], v152 offset:2048
	ds_read_b128 v[184:187], v152 offset:3072
	v_lshl_add_u64 v[220:221], s[44:45], 0, v[142:143]
	s_mov_b32 m0, s37
	v_lshl_add_u64 v[222:223], v[220:221], 0, s[6:7]
	ds_read_b128 v[188:191], v149
	ds_read_b128 v[192:195], v149 offset:1024
	ds_read_b128 v[196:199], v149 offset:2048
	ds_read_b128 v[200:203], v149 offset:3072
	ds_read_b128 v[204:207], v149 offset:4096
	ds_read_b128 v[208:211], v149 offset:5120
	ds_read_b128 v[212:215], v149 offset:6144
	ds_read_b128 v[216:219], v149 offset:7168
	global_load_lds_dwordx4 v[222:223], off
	v_lshl_add_u64 v[222:223], s[44:45], 0, v[140:141]
	v_lshl_add_u64 v[224:225], v[222:223], 0, s[6:7]
	s_mov_b32 m0, s36
	s_nop 0
	global_load_lds_dwordx4 v[224:225], off
	v_lshl_add_u64 v[224:225], v[220:221], 0, s[8:9]
	s_mov_b32 m0, s33
	s_nop 0
	global_load_lds_dwordx4 v[224:225], off
	v_lshl_add_u64 v[224:225], v[222:223], 0, s[8:9]
	s_mov_b32 m0, s29
	s_nop 0
	global_load_lds_dwordx4 v[224:225], off
	s_waitcnt vmcnt(8)
	s_waitcnt lgkmcnt(0)
	s_setprio 1
	s_barrier
	v_mfma_f32_16x16x32_bf16 v[126:129], v[156:159], v[188:191], v[126:129]
	v_mfma_f32_16x16x32_bf16 v[122:125], v[164:167], v[188:191], v[122:125]
	v_mfma_f32_16x16x32_bf16 v[118:121], v[156:159], v[196:199], v[118:121]
	v_mfma_f32_16x16x32_bf16 v[114:117], v[164:167], v[196:199], v[114:117]
	v_mfma_f32_16x16x32_bf16 v[110:113], v[156:159], v[204:207], v[110:113]
	v_mfma_f32_16x16x32_bf16 v[106:109], v[164:167], v[204:207], v[106:109]
	v_mfma_f32_16x16x32_bf16 v[102:105], v[156:159], v[212:215], v[102:105]
	v_mfma_f32_16x16x32_bf16 v[98:101], v[164:167], v[212:215], v[98:101]
	v_mfma_f32_16x16x32_bf16 v[126:129], v[160:163], v[192:195], v[126:129]
	v_mfma_f32_16x16x32_bf16 v[122:125], v[168:171], v[192:195], v[122:125]
	v_mfma_f32_16x16x32_bf16 v[118:121], v[160:163], v[200:203], v[118:121]
	v_mfma_f32_16x16x32_bf16 v[114:117], v[168:171], v[200:203], v[114:117]
	v_mfma_f32_16x16x32_bf16 v[110:113], v[160:163], v[208:211], v[110:113]
	v_mfma_f32_16x16x32_bf16 v[106:109], v[168:171], v[208:211], v[106:109]
	v_mfma_f32_16x16x32_bf16 v[102:105], v[160:163], v[216:219], v[102:105]
	v_mfma_f32_16x16x32_bf16 v[98:101], v[168:171], v[216:219], v[98:101]
	v_mfma_f32_16x16x32_bf16 v[94:97], v[172:175], v[188:191], v[94:97]
	v_mfma_f32_16x16x32_bf16 v[90:93], v[180:183], v[188:191], v[90:93]
	v_mfma_f32_16x16x32_bf16 v[86:89], v[172:175], v[196:199], v[86:89]
	v_mfma_f32_16x16x32_bf16 v[82:85], v[180:183], v[196:199], v[82:85]
	v_mfma_f32_16x16x32_bf16 v[78:81], v[172:175], v[204:207], v[78:81]
	v_mfma_f32_16x16x32_bf16 v[74:77], v[180:183], v[204:207], v[74:77]
	v_mfma_f32_16x16x32_bf16 v[70:73], v[172:175], v[212:215], v[70:73]
	v_mfma_f32_16x16x32_bf16 v[66:69], v[180:183], v[212:215], v[66:69]
	v_mfma_f32_16x16x32_bf16 v[94:97], v[176:179], v[192:195], v[94:97]
	v_mfma_f32_16x16x32_bf16 v[90:93], v[184:187], v[192:195], v[90:93]
	v_mfma_f32_16x16x32_bf16 v[86:89], v[176:179], v[200:203], v[86:89]
	v_mfma_f32_16x16x32_bf16 v[82:85], v[184:187], v[200:203], v[82:85]
	v_mfma_f32_16x16x32_bf16 v[78:81], v[176:179], v[208:211], v[78:81]
	v_mfma_f32_16x16x32_bf16 v[74:77], v[184:187], v[208:211], v[74:77]
	v_mfma_f32_16x16x32_bf16 v[70:73], v[176:179], v[216:219], v[70:73]
	v_mfma_f32_16x16x32_bf16 v[66:69], v[184:187], v[216:219], v[66:69]
	s_setprio 0
	s_barrier
	v_lshl_add_u64 v[224:225], s[44:45], 0, v[144:145]
	s_mov_b32 m0, s39
	v_lshl_add_u64 v[226:227], v[224:225], 0, s[10:11]
	ds_read_b128 v[188:191], v149 offset:16384
	ds_read_b128 v[192:195], v149 offset:17408
	ds_read_b128 v[196:199], v149 offset:18432
	ds_read_b128 v[200:203], v149 offset:19456
	ds_read_b128 v[204:207], v149 offset:20480
	ds_read_b128 v[208:211], v149 offset:21504
	ds_read_b128 v[212:215], v149 offset:22528
	ds_read_b128 v[216:219], v149 offset:23552
	global_load_lds_dwordx4 v[226:227], off
	v_lshl_add_u64 v[226:227], s[44:45], 0, v[146:147]
	v_lshl_add_u64 v[228:229], v[226:227], 0, s[10:11]
	s_mov_b32 m0, s46
	s_nop 0
	global_load_lds_dwordx4 v[228:229], off
	v_lshl_add_u64 v[228:229], v[224:225], 0, s[12:13]
	s_mov_b32 m0, s47
	s_nop 0
	global_load_lds_dwordx4 v[228:229], off
	v_lshl_add_u64 v[228:229], v[226:227], 0, s[12:13]
	s_mov_b32 m0, s48
	s_nop 0
	global_load_lds_dwordx4 v[228:229], off
	s_waitcnt vmcnt(4)
	s_waitcnt lgkmcnt(0)
	s_setprio 1
	s_barrier
	v_mfma_f32_16x16x32_bf16 v[62:65], v[156:159], v[188:191], v[62:65]
	v_mfma_f32_16x16x32_bf16 v[58:61], v[164:167], v[188:191], v[58:61]
	v_mfma_f32_16x16x32_bf16 v[54:57], v[156:159], v[196:199], v[54:57]
	v_mfma_f32_16x16x32_bf16 v[50:53], v[164:167], v[196:199], v[50:53]
	v_mfma_f32_16x16x32_bf16 v[46:49], v[156:159], v[204:207], v[46:49]
	v_mfma_f32_16x16x32_bf16 v[42:45], v[164:167], v[204:207], v[42:45]
	v_mfma_f32_16x16x32_bf16 v[38:41], v[156:159], v[212:215], v[38:41]
	v_mfma_f32_16x16x32_bf16 v[34:37], v[164:167], v[212:215], v[34:37]
	v_mfma_f32_16x16x32_bf16 v[62:65], v[160:163], v[192:195], v[62:65]
	v_mfma_f32_16x16x32_bf16 v[58:61], v[168:171], v[192:195], v[58:61]
	v_mfma_f32_16x16x32_bf16 v[54:57], v[160:163], v[200:203], v[54:57]
	v_mfma_f32_16x16x32_bf16 v[50:53], v[168:171], v[200:203], v[50:53]
	v_mfma_f32_16x16x32_bf16 v[46:49], v[160:163], v[208:211], v[46:49]
	v_mfma_f32_16x16x32_bf16 v[42:45], v[168:171], v[208:211], v[42:45]
	v_mfma_f32_16x16x32_bf16 v[38:41], v[160:163], v[216:219], v[38:41]
	v_mfma_f32_16x16x32_bf16 v[34:37], v[168:171], v[216:219], v[34:37]
	v_mfma_f32_16x16x32_bf16 v[30:33], v[172:175], v[188:191], v[30:33]
	v_mfma_f32_16x16x32_bf16 v[26:29], v[180:183], v[188:191], v[26:29]
	v_mfma_f32_16x16x32_bf16 v[22:25], v[172:175], v[196:199], v[22:25]
	v_mfma_f32_16x16x32_bf16 v[18:21], v[180:183], v[196:199], v[18:21]
	v_mfma_f32_16x16x32_bf16 v[14:17], v[172:175], v[204:207], v[14:17]
	v_mfma_f32_16x16x32_bf16 v[10:13], v[180:183], v[204:207], v[10:13]
	v_mfma_f32_16x16x32_bf16 v[6:9], v[172:175], v[212:215], v[6:9]
	v_mfma_f32_16x16x32_bf16 v[2:5], v[180:183], v[212:215], v[2:5]
	v_mfma_f32_16x16x32_bf16 v[30:33], v[176:179], v[192:195], v[30:33]
	v_mfma_f32_16x16x32_bf16 v[26:29], v[184:187], v[192:195], v[26:29]
	v_mfma_f32_16x16x32_bf16 v[22:25], v[176:179], v[200:203], v[22:25]
	v_mfma_f32_16x16x32_bf16 v[18:21], v[184:187], v[200:203], v[18:21]
	v_mfma_f32_16x16x32_bf16 v[14:17], v[176:179], v[208:211], v[14:17]
	v_mfma_f32_16x16x32_bf16 v[10:13], v[184:187], v[208:211], v[10:13]
	v_mfma_f32_16x16x32_bf16 v[6:9], v[176:179], v[216:219], v[6:9]
	v_mfma_f32_16x16x32_bf16 v[2:5], v[184:187], v[216:219], v[2:5]
	s_setprio 0
	s_barrier
	ds_read_b128 v[156:159], v153
	ds_read_b128 v[160:163], v153 offset:1024
	ds_read_b128 v[164:167], v153 offset:2048
	ds_read_b128 v[168:171], v153 offset:3072
	ds_read_b128 v[172:175], v154
	ds_read_b128 v[176:179], v154 offset:1024
	ds_read_b128 v[180:183], v154 offset:2048
	ds_read_b128 v[184:187], v154 offset:3072
	s_mov_b32 m0, s21
	v_lshl_add_u64 v[228:229], v[220:221], 0, s[30:31]
	ds_read_b128 v[188:191], v149 offset:32768
	ds_read_b128 v[192:195], v149 offset:33792
	ds_read_b128 v[196:199], v149 offset:34816
	ds_read_b128 v[200:203], v149 offset:35840
	ds_read_b128 v[204:207], v149 offset:36864
	ds_read_b128 v[208:211], v149 offset:37888
	ds_read_b128 v[212:215], v149 offset:38912
	ds_read_b128 v[216:219], v149 offset:39936
	global_load_lds_dwordx4 v[228:229], off
	v_lshl_add_u64 v[228:229], v[222:223], 0, s[30:31]
	s_mov_b32 m0, s22
	v_lshl_add_u64 v[220:221], v[220:221], 0, s[34:35]
	global_load_lds_dwordx4 v[228:229], off
	s_mov_b32 m0, s23
	s_nop 0
	global_load_lds_dwordx4 v[220:221], off
	v_lshl_add_u64 v[220:221], v[222:223], 0, s[34:35]
	s_mov_b32 m0, s28
	s_nop 0
	global_load_lds_dwordx4 v[220:221], off
	s_waitcnt vmcnt(8)
	s_waitcnt lgkmcnt(0)
	s_setprio 1
	s_barrier
	v_mfma_f32_16x16x32_bf16 v[126:129], v[156:159], v[188:191], v[126:129]
	v_mfma_f32_16x16x32_bf16 v[122:125], v[164:167], v[188:191], v[122:125]
	v_mfma_f32_16x16x32_bf16 v[118:121], v[156:159], v[196:199], v[118:121]
	v_mfma_f32_16x16x32_bf16 v[114:117], v[164:167], v[196:199], v[114:117]
	v_mfma_f32_16x16x32_bf16 v[110:113], v[156:159], v[204:207], v[110:113]
	v_mfma_f32_16x16x32_bf16 v[106:109], v[164:167], v[204:207], v[106:109]
	v_mfma_f32_16x16x32_bf16 v[102:105], v[156:159], v[212:215], v[102:105]
	v_mfma_f32_16x16x32_bf16 v[98:101], v[164:167], v[212:215], v[98:101]
	v_mfma_f32_16x16x32_bf16 v[126:129], v[160:163], v[192:195], v[126:129]
	v_mfma_f32_16x16x32_bf16 v[122:125], v[168:171], v[192:195], v[122:125]
	v_mfma_f32_16x16x32_bf16 v[118:121], v[160:163], v[200:203], v[118:121]
	v_mfma_f32_16x16x32_bf16 v[114:117], v[168:171], v[200:203], v[114:117]
	v_mfma_f32_16x16x32_bf16 v[110:113], v[160:163], v[208:211], v[110:113]
	v_mfma_f32_16x16x32_bf16 v[106:109], v[168:171], v[208:211], v[106:109]
	v_mfma_f32_16x16x32_bf16 v[102:105], v[160:163], v[216:219], v[102:105]
	v_mfma_f32_16x16x32_bf16 v[98:101], v[168:171], v[216:219], v[98:101]
	v_mfma_f32_16x16x32_bf16 v[94:97], v[172:175], v[188:191], v[94:97]
	v_mfma_f32_16x16x32_bf16 v[90:93], v[180:183], v[188:191], v[90:93]
	v_mfma_f32_16x16x32_bf16 v[86:89], v[172:175], v[196:199], v[86:89]
	v_mfma_f32_16x16x32_bf16 v[82:85], v[180:183], v[196:199], v[82:85]
	v_mfma_f32_16x16x32_bf16 v[78:81], v[172:175], v[204:207], v[78:81]
	v_mfma_f32_16x16x32_bf16 v[74:77], v[180:183], v[204:207], v[74:77]
	v_mfma_f32_16x16x32_bf16 v[70:73], v[172:175], v[212:215], v[70:73]
	v_mfma_f32_16x16x32_bf16 v[66:69], v[180:183], v[212:215], v[66:69]
	v_mfma_f32_16x16x32_bf16 v[94:97], v[176:179], v[192:195], v[94:97]
	v_mfma_f32_16x16x32_bf16 v[90:93], v[184:187], v[192:195], v[90:93]
	v_mfma_f32_16x16x32_bf16 v[86:89], v[176:179], v[200:203], v[86:89]
	v_mfma_f32_16x16x32_bf16 v[82:85], v[184:187], v[200:203], v[82:85]
	v_mfma_f32_16x16x32_bf16 v[78:81], v[176:179], v[208:211], v[78:81]
	v_mfma_f32_16x16x32_bf16 v[74:77], v[184:187], v[208:211], v[74:77]
	v_mfma_f32_16x16x32_bf16 v[70:73], v[176:179], v[216:219], v[70:73]
	v_mfma_f32_16x16x32_bf16 v[66:69], v[184:187], v[216:219], v[66:69]
	s_setprio 0
	s_barrier
	s_mov_b32 m0, s49
	v_lshl_add_u64 v[220:221], v[224:225], 0, s[40:41]
	ds_read_b128 v[188:191], v149 offset:49152
	ds_read_b128 v[192:195], v149 offset:50176
	ds_read_b128 v[196:199], v149 offset:51200
	ds_read_b128 v[200:203], v149 offset:52224
	ds_read_b128 v[204:207], v149 offset:53248
	ds_read_b128 v[208:211], v149 offset:54272
	ds_read_b128 v[212:215], v149 offset:55296
	ds_read_b128 v[216:219], v149 offset:56320
	global_load_lds_dwordx4 v[220:221], off
	v_lshl_add_u64 v[220:221], v[226:227], 0, s[40:41]
	s_mov_b32 m0, s50
	s_nop 0
	global_load_lds_dwordx4 v[220:221], off
	v_lshl_add_u64 v[220:221], v[224:225], 0, s[42:43]
	s_mov_b32 m0, s51
	s_nop 0
	global_load_lds_dwordx4 v[220:221], off
	v_lshl_add_u64 v[220:221], v[226:227], 0, s[42:43]
	s_mov_b32 m0, s56
	s_nop 0
	global_load_lds_dwordx4 v[220:221], off
	s_waitcnt vmcnt(4)
	s_waitcnt lgkmcnt(0)
	s_setprio 1
	s_barrier
	v_mfma_f32_16x16x32_bf16 v[62:65], v[156:159], v[188:191], v[62:65]
	v_mfma_f32_16x16x32_bf16 v[58:61], v[164:167], v[188:191], v[58:61]
	v_mfma_f32_16x16x32_bf16 v[54:57], v[156:159], v[196:199], v[54:57]
	v_mfma_f32_16x16x32_bf16 v[50:53], v[164:167], v[196:199], v[50:53]
	v_mfma_f32_16x16x32_bf16 v[46:49], v[156:159], v[204:207], v[46:49]
	v_mfma_f32_16x16x32_bf16 v[42:45], v[164:167], v[204:207], v[42:45]
	v_mfma_f32_16x16x32_bf16 v[38:41], v[156:159], v[212:215], v[38:41]
	v_mfma_f32_16x16x32_bf16 v[34:37], v[164:167], v[212:215], v[34:37]
	v_mfma_f32_16x16x32_bf16 v[62:65], v[160:163], v[192:195], v[62:65]
	v_mfma_f32_16x16x32_bf16 v[58:61], v[168:171], v[192:195], v[58:61]
	v_mfma_f32_16x16x32_bf16 v[54:57], v[160:163], v[200:203], v[54:57]
	v_mfma_f32_16x16x32_bf16 v[50:53], v[168:171], v[200:203], v[50:53]
	v_mfma_f32_16x16x32_bf16 v[46:49], v[160:163], v[208:211], v[46:49]
	v_mfma_f32_16x16x32_bf16 v[42:45], v[168:171], v[208:211], v[42:45]
	v_mfma_f32_16x16x32_bf16 v[38:41], v[160:163], v[216:219], v[38:41]
	v_mfma_f32_16x16x32_bf16 v[34:37], v[168:171], v[216:219], v[34:37]
	v_mfma_f32_16x16x32_bf16 v[30:33], v[172:175], v[188:191], v[30:33]
	v_mfma_f32_16x16x32_bf16 v[26:29], v[180:183], v[188:191], v[26:29]
	v_mfma_f32_16x16x32_bf16 v[22:25], v[172:175], v[196:199], v[22:25]
	v_mfma_f32_16x16x32_bf16 v[18:21], v[180:183], v[196:199], v[18:21]
	v_mfma_f32_16x16x32_bf16 v[14:17], v[172:175], v[204:207], v[14:17]
	v_mfma_f32_16x16x32_bf16 v[10:13], v[180:183], v[204:207], v[10:13]
	v_mfma_f32_16x16x32_bf16 v[6:9], v[172:175], v[212:215], v[6:9]
	v_mfma_f32_16x16x32_bf16 v[2:5], v[180:183], v[212:215], v[2:5]
	v_mfma_f32_16x16x32_bf16 v[30:33], v[176:179], v[192:195], v[30:33]
	v_mfma_f32_16x16x32_bf16 v[26:29], v[184:187], v[192:195], v[26:29]
	v_mfma_f32_16x16x32_bf16 v[22:25], v[176:179], v[200:203], v[22:25]
	v_mfma_f32_16x16x32_bf16 v[18:21], v[184:187], v[200:203], v[18:21]
	v_mfma_f32_16x16x32_bf16 v[14:17], v[176:179], v[208:211], v[14:17]
	v_mfma_f32_16x16x32_bf16 v[10:13], v[184:187], v[208:211], v[10:13]
	v_mfma_f32_16x16x32_bf16 v[6:9], v[176:179], v[216:219], v[6:9]
	v_mfma_f32_16x16x32_bf16 v[2:5], v[184:187], v[216:219], v[2:5]
	s_setprio 0
	s_barrier
	s_add_i32 s38, s38, 2
	s_add_u32 s44, s44, 0x100
	s_addc_u32 s45, s45, 0
	s_cmp_lt_u32 s38, 12
	s_cbranch_scc1 .LBB0_325
	v_add_u32_e32 v210, 0, v150
	v_add_u32_e32 v154, 0x10000, v210
	v_add_u32_e32 v170, 0x14000, v210
	ds_read_b128 v[140:143], v154
	ds_read_b128 v[144:147], v154 offset:1024
	ds_read_b128 v[150:153], v154 offset:2048
	ds_read_b128 v[154:157], v154 offset:3072
	ds_read_b128 v[158:161], v170
	ds_read_b128 v[162:165], v170 offset:1024
	ds_read_b128 v[166:169], v170 offset:2048
	ds_read_b128 v[170:173], v170 offset:3072
	s_add_u32 s4, s4, 0x40780
	s_addc_u32 s5, s5, 0
	s_cmpk_gt_u32 s20, 0xff
	s_mov_b64 s[6:7], 0x780
	s_mov_b32 m0, s37
	v_lshl_add_u64 v[138:139], v[138:139], 0, s[6:7]
	ds_read_b128 v[174:177], v149
	ds_read_b128 v[178:181], v149 offset:1024
	ds_read_b128 v[182:185], v149 offset:2048
	ds_read_b128 v[186:189], v149 offset:3072
	ds_read_b128 v[190:193], v149 offset:4096
	ds_read_b128 v[194:197], v149 offset:5120
	ds_read_b128 v[198:201], v149 offset:6144
	ds_read_b128 v[202:205], v149 offset:7168
	global_load_lds_dwordx4 v[138:139], off
	v_lshl_add_u64 v[136:137], v[136:137], 0, s[6:7]
	s_mov_b32 m0, s36
	v_lshl_add_u64 v[134:135], s[4:5], 0, v[134:135]
	global_load_lds_dwordx4 v[136:137], off
	s_mov_b32 m0, s33
	v_lshl_add_u64 v[132:133], s[4:5], 0, v[132:133]
	global_load_lds_dwordx4 v[134:135], off
	s_mov_b32 m0, s29
	s_nop 0
	global_load_lds_dwordx4 v[132:133], off
	s_waitcnt vmcnt(8)
	s_waitcnt lgkmcnt(0)
	s_setprio 1
	s_barrier
	v_mfma_f32_16x16x32_bf16 v[126:129], v[140:143], v[174:177], v[126:129]
	v_mfma_f32_16x16x32_bf16 v[122:125], v[150:153], v[174:177], v[122:125]
	v_mfma_f32_16x16x32_bf16 v[118:121], v[140:143], v[182:185], v[118:121]
	v_mfma_f32_16x16x32_bf16 v[114:117], v[150:153], v[182:185], v[114:117]
	v_mfma_f32_16x16x32_bf16 v[102:105], v[140:143], v[198:201], v[102:105]
	v_mfma_f32_16x16x32_bf16 v[98:101], v[150:153], v[198:201], v[98:101]
	v_mfma_f32_16x16x32_bf16 v[126:129], v[144:147], v[178:181], v[126:129]
	v_mfma_f32_16x16x32_bf16 v[122:125], v[154:157], v[178:181], v[122:125]
	v_mfma_f32_16x16x32_bf16 v[118:121], v[144:147], v[186:189], v[118:121]
	v_mfma_f32_16x16x32_bf16 v[114:117], v[154:157], v[186:189], v[114:117]
	v_mfma_f32_16x16x32_bf16 v[110:113], v[140:143], v[190:193], v[110:113]
	v_mfma_f32_16x16x32_bf16 v[106:109], v[150:153], v[190:193], v[106:109]
	v_mfma_f32_16x16x32_bf16 v[102:105], v[144:147], v[202:205], v[102:105]
	v_mfma_f32_16x16x32_bf16 v[98:101], v[154:157], v[202:205], v[98:101]
	v_mfma_f32_16x16x32_bf16 v[132:135], v[144:147], v[194:197], v[110:113]
	v_mfma_f32_16x16x32_bf16 v[136:139], v[154:157], v[194:197], v[106:109]
	v_mfma_f32_16x16x32_bf16 v[86:89], v[158:161], v[182:185], v[86:89]
	v_mfma_f32_16x16x32_bf16 v[82:85], v[166:169], v[182:185], v[82:85]
	v_mfma_f32_16x16x32_bf16 v[70:73], v[158:161], v[198:201], v[70:73]
	v_mfma_f32_16x16x32_bf16 v[66:69], v[166:169], v[198:201], v[66:69]
	v_mfma_f32_16x16x32_bf16 v[94:97], v[158:161], v[174:177], v[94:97]
	v_mfma_f32_16x16x32_bf16 v[90:93], v[166:169], v[174:177], v[90:93]
	v_mfma_f32_16x16x32_bf16 v[86:89], v[162:165], v[186:189], v[86:89]
	v_mfma_f32_16x16x32_bf16 v[82:85], v[170:173], v[186:189], v[82:85]
	v_mfma_f32_16x16x32_bf16 v[78:81], v[158:161], v[190:193], v[78:81]
	v_mfma_f32_16x16x32_bf16 v[74:77], v[166:169], v[190:193], v[74:77]
	v_mfma_f32_16x16x32_bf16 v[70:73], v[162:165], v[202:205], v[70:73]
	v_mfma_f32_16x16x32_bf16 v[66:69], v[170:173], v[202:205], v[66:69]
	v_mfma_f32_16x16x32_bf16 v[206:209], v[162:165], v[178:181], v[94:97]
	v_mfma_f32_16x16x32_bf16 v[174:177], v[170:173], v[178:181], v[90:93]
	v_mfma_f32_16x16x32_bf16 v[178:181], v[162:165], v[194:197], v[78:81]
	v_mfma_f32_16x16x32_bf16 v[182:185], v[170:173], v[194:197], v[74:77]
	s_setprio 0
	s_barrier
	s_nop 0
	ds_read_b128 v[74:77], v149 offset:16384
	ds_read_b128 v[78:81], v149 offset:17408
	ds_read_b128 v[90:93], v149 offset:18432
	ds_read_b128 v[94:97], v149 offset:19456
	ds_read_b128 v[106:109], v149 offset:20480
	ds_read_b128 v[110:113], v149 offset:21504
	ds_read_b128 v[186:189], v149 offset:22528
	ds_read_b128 v[190:193], v149 offset:23552
	s_waitcnt vmcnt(0)
	s_waitcnt lgkmcnt(0)
	s_setprio 1
	s_barrier
	v_mfma_f32_16x16x32_bf16 v[62:65], v[140:143], v[74:77], v[62:65]
	v_mfma_f32_16x16x32_bf16 v[58:61], v[150:153], v[74:77], v[58:61]
	v_mfma_f32_16x16x32_bf16 v[54:57], v[140:143], v[90:93], v[54:57]
	v_mfma_f32_16x16x32_bf16 v[50:53], v[150:153], v[90:93], v[50:53]
	v_mfma_f32_16x16x32_bf16 v[38:41], v[140:143], v[186:189], v[38:41]
	v_mfma_f32_16x16x32_bf16 v[34:37], v[150:153], v[186:189], v[34:37]
	v_mfma_f32_16x16x32_bf16 v[62:65], v[144:147], v[78:81], v[62:65]
	v_mfma_f32_16x16x32_bf16 v[58:61], v[154:157], v[78:81], v[58:61]
	v_mfma_f32_16x16x32_bf16 v[54:57], v[144:147], v[94:97], v[54:57]
	v_mfma_f32_16x16x32_bf16 v[50:53], v[154:157], v[94:97], v[50:53]
	v_mfma_f32_16x16x32_bf16 v[46:49], v[140:143], v[106:109], v[46:49]
	v_mfma_f32_16x16x32_bf16 v[42:45], v[150:153], v[106:109], v[42:45]
	v_mfma_f32_16x16x32_bf16 v[38:41], v[144:147], v[190:193], v[38:41]
	v_mfma_f32_16x16x32_bf16 v[34:37], v[154:157], v[190:193], v[34:37]
	v_mfma_f32_16x16x32_bf16 v[194:197], v[144:147], v[110:113], v[46:49]
	v_mfma_f32_16x16x32_bf16 v[198:201], v[154:157], v[110:113], v[42:45]
	v_mfma_f32_16x16x32_bf16 v[22:25], v[158:161], v[90:93], v[22:25]
	v_mfma_f32_16x16x32_bf16 v[18:21], v[166:169], v[90:93], v[18:21]
	v_mfma_f32_16x16x32_bf16 v[6:9], v[158:161], v[186:189], v[6:9]
	v_mfma_f32_16x16x32_bf16 v[2:5], v[166:169], v[186:189], v[2:5]
	v_mfma_f32_16x16x32_bf16 v[30:33], v[158:161], v[74:77], v[30:33]
	v_mfma_f32_16x16x32_bf16 v[26:29], v[166:169], v[74:77], v[26:29]
	v_mfma_f32_16x16x32_bf16 v[22:25], v[162:165], v[94:97], v[22:25]
	v_mfma_f32_16x16x32_bf16 v[18:21], v[170:173], v[94:97], v[18:21]
	v_mfma_f32_16x16x32_bf16 v[14:17], v[158:161], v[106:109], v[14:17]
	v_mfma_f32_16x16x32_bf16 v[10:13], v[166:169], v[106:109], v[10:13]
	v_mfma_f32_16x16x32_bf16 v[6:9], v[162:165], v[190:193], v[6:9]
	v_mfma_f32_16x16x32_bf16 v[2:5], v[170:173], v[190:193], v[2:5]
	v_mfma_f32_16x16x32_bf16 v[140:143], v[162:165], v[78:81], v[30:33]
	v_mfma_f32_16x16x32_bf16 v[144:147], v[170:173], v[78:81], v[26:29]
	v_mfma_f32_16x16x32_bf16 v[150:153], v[162:165], v[110:113], v[14:17]
	v_mfma_f32_16x16x32_bf16 v[154:157], v[170:173], v[110:113], v[10:13]
	s_setprio 0
	s_barrier
	v_add_u32_e32 v26, 0x18000, v210
	ds_read_b128 v[10:13], v26
	ds_read_b128 v[14:17], v26 offset:1024
	ds_read_b128 v[158:161], v26 offset:2048
	ds_read_b128 v[162:165], v26 offset:3072
	v_add_u32_e32 v26, 0x1c000, v210
	ds_read_b128 v[166:169], v26
	ds_read_b128 v[170:173], v26 offset:1024
	ds_read_b128 v[186:189], v26 offset:2048
	ds_read_b128 v[190:193], v26 offset:3072
	ds_read_b128 v[26:29], v149 offset:32768
	ds_read_b128 v[30:33], v149 offset:33792
	ds_read_b128 v[42:45], v149 offset:34816
	ds_read_b128 v[46:49], v149 offset:35840
	ds_read_b128 v[202:205], v149 offset:36864
	ds_read_b128 v[210:213], v149 offset:37888
	ds_read_b128 v[214:217], v149 offset:38912
	ds_read_b128 v[218:221], v149 offset:39936
	s_waitcnt lgkmcnt(0)
	s_setprio 1
	s_barrier
	v_mfma_f32_16x16x32_bf16 v[74:77], v[10:13], v[26:29], v[126:129]
	v_mfma_f32_16x16x32_bf16 v[126:129], v[14:17], v[30:33], v[74:77]
	v_mfma_f32_16x16x32_bf16 v[74:77], v[158:161], v[26:29], v[122:125]
	v_mfma_f32_16x16x32_bf16 v[122:125], v[162:165], v[30:33], v[74:77]
	v_mfma_f32_16x16x32_bf16 v[74:77], v[10:13], v[42:45], v[118:121]
	v_mfma_f32_16x16x32_bf16 v[110:113], v[14:17], v[46:49], v[74:77]
	v_mfma_f32_16x16x32_bf16 v[74:77], v[158:161], v[42:45], v[114:117]
	v_mfma_f32_16x16x32_bf16 v[106:109], v[162:165], v[46:49], v[74:77]
	v_mfma_f32_16x16x32_bf16 v[74:77], v[10:13], v[202:205], v[132:135]
	v_mfma_f32_16x16x32_bf16 v[94:97], v[14:17], v[210:213], v[74:77]
	v_mfma_f32_16x16x32_bf16 v[74:77], v[158:161], v[202:205], v[136:139]
	v_mfma_f32_16x16x32_bf16 v[90:93], v[162:165], v[210:213], v[74:77]
	v_mfma_f32_16x16x32_bf16 v[74:77], v[10:13], v[214:217], v[102:105]
	v_mfma_f32_16x16x32_bf16 v[78:81], v[14:17], v[218:221], v[74:77]
	v_mfma_f32_16x16x32_bf16 v[74:77], v[158:161], v[214:217], v[98:101]
	v_mfma_f32_16x16x32_bf16 v[74:77], v[162:165], v[218:221], v[74:77]
	v_mfma_f32_16x16x32_bf16 v[98:101], v[166:169], v[26:29], v[206:209]
	v_mfma_f32_16x16x32_bf16 v[26:29], v[186:189], v[26:29], v[174:177]
	v_mfma_f32_16x16x32_bf16 v[114:117], v[190:193], v[30:33], v[26:29]
	v_mfma_f32_16x16x32_bf16 v[26:29], v[166:169], v[42:45], v[86:89]
	v_mfma_f32_16x16x32_bf16 v[102:105], v[170:173], v[46:49], v[26:29]
	v_mfma_f32_16x16x32_bf16 v[26:29], v[186:189], v[42:45], v[82:85]
	v_mfma_f32_16x16x32_bf16 v[118:121], v[170:173], v[30:33], v[98:101]
	v_mfma_f32_16x16x32_bf16 v[98:101], v[190:193], v[46:49], v[26:29]
	v_mfma_f32_16x16x32_bf16 v[26:29], v[166:169], v[202:205], v[178:181]
	v_mfma_f32_16x16x32_bf16 v[86:89], v[170:173], v[210:213], v[26:29]
	v_mfma_f32_16x16x32_bf16 v[26:29], v[186:189], v[202:205], v[182:185]
	v_mfma_f32_16x16x32_bf16 v[82:85], v[190:193], v[210:213], v[26:29]
	v_mfma_f32_16x16x32_bf16 v[26:29], v[166:169], v[214:217], v[70:73]
	v_mfma_f32_16x16x32_bf16 v[70:73], v[170:173], v[218:221], v[26:29]
	v_mfma_f32_16x16x32_bf16 v[26:29], v[186:189], v[214:217], v[66:69]
	v_mfma_f32_16x16x32_bf16 v[66:69], v[190:193], v[218:221], v[26:29]
	s_setprio 0
	s_barrier
	ds_read_b128 v[132:135], v149 offset:49152
	ds_read_b128 v[136:139], v149 offset:50176
	ds_read_b128 v[174:177], v149 offset:51200
	ds_read_b128 v[178:181], v149 offset:52224
	ds_read_b128 v[182:185], v149 offset:53248
	ds_read_b128 v[202:205], v149 offset:54272
	ds_read_b128 v[206:209], v149 offset:55296
	ds_read_b128 v[210:213], v149 offset:56320
	s_waitcnt lgkmcnt(0)
	s_setprio 1
	s_barrier
	v_mfma_f32_16x16x32_bf16 v[26:29], v[10:13], v[132:135], v[62:65]
	v_mfma_f32_16x16x32_bf16 v[62:65], v[14:17], v[136:139], v[26:29]
	v_mfma_f32_16x16x32_bf16 v[26:29], v[158:161], v[132:135], v[58:61]
	v_mfma_f32_16x16x32_bf16 v[58:61], v[162:165], v[136:139], v[26:29]
	v_mfma_f32_16x16x32_bf16 v[26:29], v[10:13], v[174:177], v[54:57]
	v_mfma_f32_16x16x32_bf16 v[46:49], v[14:17], v[178:181], v[26:29]
	v_mfma_f32_16x16x32_bf16 v[26:29], v[158:161], v[174:177], v[50:53]
	v_mfma_f32_16x16x32_bf16 v[42:45], v[162:165], v[178:181], v[26:29]
	v_mfma_f32_16x16x32_bf16 v[26:29], v[10:13], v[182:185], v[194:197]
	v_mfma_f32_16x16x32_bf16 v[10:13], v[10:13], v[206:209], v[38:41]
	v_mfma_f32_16x16x32_bf16 v[30:33], v[14:17], v[202:205], v[26:29]
	v_mfma_f32_16x16x32_bf16 v[26:29], v[158:161], v[182:185], v[198:201]
	v_mfma_f32_16x16x32_bf16 v[14:17], v[14:17], v[210:213], v[10:13]
	v_mfma_f32_16x16x32_bf16 v[10:13], v[158:161], v[206:209], v[34:37]
	v_mfma_f32_16x16x32_bf16 v[26:29], v[162:165], v[202:205], v[26:29]
	v_mfma_f32_16x16x32_bf16 v[10:13], v[162:165], v[210:213], v[10:13]
	v_mfma_f32_16x16x32_bf16 v[34:37], v[166:169], v[132:135], v[140:143]
	v_mfma_f32_16x16x32_bf16 v[54:57], v[170:173], v[136:139], v[34:37]
	v_mfma_f32_16x16x32_bf16 v[34:37], v[186:189], v[132:135], v[144:147]
	v_mfma_f32_16x16x32_bf16 v[18:21], v[186:189], v[174:177], v[18:21]
	v_mfma_f32_16x16x32_bf16 v[50:53], v[190:193], v[136:139], v[34:37]
	v_mfma_f32_16x16x32_bf16 v[22:25], v[166:169], v[174:177], v[22:25]
	v_mfma_f32_16x16x32_bf16 v[34:37], v[190:193], v[178:181], v[18:21]
	v_mfma_f32_16x16x32_bf16 v[18:21], v[166:169], v[182:185], v[150:153]
	v_mfma_f32_16x16x32_bf16 v[38:41], v[170:173], v[178:181], v[22:25]
	v_mfma_f32_16x16x32_bf16 v[22:25], v[170:173], v[202:205], v[18:21]
	v_mfma_f32_16x16x32_bf16 v[18:21], v[186:189], v[182:185], v[154:157]
	v_mfma_f32_16x16x32_bf16 v[6:9], v[166:169], v[206:209], v[6:9]
	v_mfma_f32_16x16x32_bf16 v[2:5], v[186:189], v[206:209], v[2:5]
	v_mfma_f32_16x16x32_bf16 v[18:21], v[190:193], v[202:205], v[18:21]
	v_mfma_f32_16x16x32_bf16 v[6:9], v[170:173], v[210:213], v[6:9]
	v_mfma_f32_16x16x32_bf16 v[2:5], v[190:193], v[210:213], v[2:5]
	s_setprio 0
	s_barrier
	s_cbranch_scc1 .LBB0_328
	s_barrier

.LBB0_599:
	v_add_u32_e32 v150, s46, v219
	s_waitcnt lgkmcnt(0)
	v_add_u32_e32 v166, s47, v219
	ds_read_b128 v[138:141], v150
	ds_read_b128 v[142:145], v150 offset:1024
	ds_read_b128 v[146:149], v150 offset:2048
	ds_read_b128 v[150:153], v150 offset:3072
	ds_read_b128 v[154:157], v166
	ds_read_b128 v[158:161], v166 offset:1024
	ds_read_b128 v[162:165], v166 offset:2048
	ds_read_b128 v[166:169], v166 offset:3072
	v_lshl_add_u64 v[210:211], v[132:133], 0, s[4:5]
	s_mov_b32 m0, s44
	v_lshl_add_u64 v[212:213], v[210:211], 0, s[16:17]
	ds_read_b128 v[170:173], v217
	ds_read_b128 v[174:177], v217 offset:1024
	ds_read_b128 v[178:181], v217 offset:2048
	ds_read_b128 v[182:185], v217 offset:3072
	ds_read_b128 v[186:189], v217 offset:4096
	ds_read_b128 v[190:193], v217 offset:5120
	ds_read_b128 v[202:205], v217 offset:6144
	ds_read_b128 v[206:209], v217 offset:7168
	global_load_lds_dwordx4 v[212:213], off
	v_lshl_add_u64 v[212:213], v[130:131], 0, s[4:5]
	v_lshl_add_u64 v[214:215], v[212:213], 0, s[16:17]
	s_mov_b32 m0, s43
	s_nop 0
	global_load_lds_dwordx4 v[214:215], off
	v_lshl_add_u64 v[214:215], v[210:211], 0, s[18:19]
	s_mov_b32 m0, s42
	s_nop 0
	global_load_lds_dwordx4 v[214:215], off
	v_lshl_add_u64 v[214:215], v[212:213], 0, s[18:19]
	s_mov_b32 m0, s39
	s_nop 0
	global_load_lds_dwordx4 v[214:215], off
	s_waitcnt vmcnt(8)
	s_waitcnt lgkmcnt(0)
	s_setprio 1
	s_barrier
	v_mfma_f32_16x16x32_bf16 v[126:129], v[138:141], v[170:173], v[126:129]
	v_mfma_f32_16x16x32_bf16 v[122:125], v[146:149], v[170:173], v[122:125]
	v_mfma_f32_16x16x32_bf16 v[118:121], v[138:141], v[178:181], v[118:121]
	v_mfma_f32_16x16x32_bf16 v[114:117], v[146:149], v[178:181], v[114:117]
	v_mfma_f32_16x16x32_bf16 v[110:113], v[138:141], v[186:189], v[110:113]
	v_mfma_f32_16x16x32_bf16 v[106:109], v[146:149], v[186:189], v[106:109]
	v_mfma_f32_16x16x32_bf16 v[102:105], v[138:141], v[202:205], v[102:105]
	v_mfma_f32_16x16x32_bf16 v[98:101], v[146:149], v[202:205], v[98:101]
	v_mfma_f32_16x16x32_bf16 v[126:129], v[142:145], v[174:177], v[126:129]
	v_mfma_f32_16x16x32_bf16 v[122:125], v[150:153], v[174:177], v[122:125]
	v_mfma_f32_16x16x32_bf16 v[118:121], v[142:145], v[182:185], v[118:121]
	v_mfma_f32_16x16x32_bf16 v[114:117], v[150:153], v[182:185], v[114:117]
	v_mfma_f32_16x16x32_bf16 v[110:113], v[142:145], v[190:193], v[110:113]
	v_mfma_f32_16x16x32_bf16 v[106:109], v[150:153], v[190:193], v[106:109]
	v_mfma_f32_16x16x32_bf16 v[102:105], v[142:145], v[206:209], v[102:105]
	v_mfma_f32_16x16x32_bf16 v[98:101], v[150:153], v[206:209], v[98:101]
	v_mfma_f32_16x16x32_bf16 v[94:97], v[154:157], v[170:173], v[94:97]
	v_mfma_f32_16x16x32_bf16 v[90:93], v[162:165], v[170:173], v[90:93]
	v_mfma_f32_16x16x32_bf16 v[86:89], v[154:157], v[178:181], v[86:89]
	v_mfma_f32_16x16x32_bf16 v[82:85], v[162:165], v[178:181], v[82:85]
	v_mfma_f32_16x16x32_bf16 v[78:81], v[154:157], v[186:189], v[78:81]
	v_mfma_f32_16x16x32_bf16 v[74:77], v[162:165], v[186:189], v[74:77]
	v_mfma_f32_16x16x32_bf16 v[70:73], v[154:157], v[202:205], v[70:73]
	v_mfma_f32_16x16x32_bf16 v[66:69], v[162:165], v[202:205], v[66:69]
	v_mfma_f32_16x16x32_bf16 v[94:97], v[158:161], v[174:177], v[94:97]
	v_mfma_f32_16x16x32_bf16 v[90:93], v[166:169], v[174:177], v[90:93]
	v_mfma_f32_16x16x32_bf16 v[86:89], v[158:161], v[182:185], v[86:89]
	v_mfma_f32_16x16x32_bf16 v[82:85], v[166:169], v[182:185], v[82:85]
	v_mfma_f32_16x16x32_bf16 v[78:81], v[158:161], v[190:193], v[78:81]
	v_mfma_f32_16x16x32_bf16 v[74:77], v[166:169], v[190:193], v[74:77]
	v_mfma_f32_16x16x32_bf16 v[70:73], v[158:161], v[206:209], v[70:73]
	v_mfma_f32_16x16x32_bf16 v[66:69], v[166:169], v[206:209], v[66:69]
	s_setprio 0
	s_barrier
	v_lshl_add_u64 v[214:215], v[136:137], 0, s[4:5]
	s_mov_b32 m0, s48
	v_lshl_add_u64 v[220:221], v[214:215], 0, s[22:23]
	ds_read_b128 v[170:173], v217 offset:16384
	ds_read_b128 v[174:177], v217 offset:17408
	ds_read_b128 v[178:181], v217 offset:18432
	ds_read_b128 v[182:185], v217 offset:19456
	ds_read_b128 v[186:189], v217 offset:20480
	ds_read_b128 v[190:193], v217 offset:21504
	ds_read_b128 v[202:205], v217 offset:22528
	ds_read_b128 v[206:209], v217 offset:23552
	global_load_lds_dwordx4 v[220:221], off
	v_lshl_add_u64 v[220:221], v[134:135], 0, s[4:5]
	v_lshl_add_u64 v[222:223], v[220:221], 0, s[22:23]
	s_mov_b32 m0, s49
	s_nop 0
	global_load_lds_dwordx4 v[222:223], off
	v_lshl_add_u64 v[222:223], v[214:215], 0, s[30:31]
	s_mov_b32 m0, s50
	s_nop 0
	global_load_lds_dwordx4 v[222:223], off
	v_lshl_add_u64 v[222:223], v[220:221], 0, s[30:31]
	s_mov_b32 m0, s51
	s_nop 0
	global_load_lds_dwordx4 v[222:223], off
	s_waitcnt vmcnt(4)
	s_waitcnt lgkmcnt(0)
	s_setprio 1
	s_barrier
	v_mfma_f32_16x16x32_bf16 v[62:65], v[138:141], v[170:173], v[62:65]
	v_mfma_f32_16x16x32_bf16 v[58:61], v[146:149], v[170:173], v[58:61]
	v_mfma_f32_16x16x32_bf16 v[54:57], v[138:141], v[178:181], v[54:57]
	v_mfma_f32_16x16x32_bf16 v[50:53], v[146:149], v[178:181], v[50:53]
	v_mfma_f32_16x16x32_bf16 v[46:49], v[138:141], v[186:189], v[46:49]
	v_mfma_f32_16x16x32_bf16 v[42:45], v[146:149], v[186:189], v[42:45]
	v_mfma_f32_16x16x32_bf16 v[38:41], v[138:141], v[202:205], v[38:41]
	v_mfma_f32_16x16x32_bf16 v[34:37], v[146:149], v[202:205], v[34:37]
	v_mfma_f32_16x16x32_bf16 v[62:65], v[142:145], v[174:177], v[62:65]
	v_mfma_f32_16x16x32_bf16 v[58:61], v[150:153], v[174:177], v[58:61]
	v_mfma_f32_16x16x32_bf16 v[54:57], v[142:145], v[182:185], v[54:57]
	v_mfma_f32_16x16x32_bf16 v[50:53], v[150:153], v[182:185], v[50:53]
	v_mfma_f32_16x16x32_bf16 v[46:49], v[142:145], v[190:193], v[46:49]
	v_mfma_f32_16x16x32_bf16 v[42:45], v[150:153], v[190:193], v[42:45]
	v_mfma_f32_16x16x32_bf16 v[38:41], v[142:145], v[206:209], v[38:41]
	v_mfma_f32_16x16x32_bf16 v[34:37], v[150:153], v[206:209], v[34:37]
	v_mfma_f32_16x16x32_bf16 v[30:33], v[154:157], v[170:173], v[30:33]
	v_mfma_f32_16x16x32_bf16 v[26:29], v[162:165], v[170:173], v[26:29]
	v_mfma_f32_16x16x32_bf16 v[22:25], v[154:157], v[178:181], v[22:25]
	v_mfma_f32_16x16x32_bf16 v[18:21], v[162:165], v[178:181], v[18:21]
	v_mfma_f32_16x16x32_bf16 v[14:17], v[154:157], v[186:189], v[14:17]
	v_mfma_f32_16x16x32_bf16 v[10:13], v[162:165], v[186:189], v[10:13]
	v_mfma_f32_16x16x32_bf16 v[6:9], v[154:157], v[202:205], v[6:9]
	v_mfma_f32_16x16x32_bf16 v[2:5], v[162:165], v[202:205], v[2:5]
	v_mfma_f32_16x16x32_bf16 v[30:33], v[158:161], v[174:177], v[30:33]
	v_mfma_f32_16x16x32_bf16 v[26:29], v[166:169], v[174:177], v[26:29]
	v_mfma_f32_16x16x32_bf16 v[22:25], v[158:161], v[182:185], v[22:25]
	v_mfma_f32_16x16x32_bf16 v[18:21], v[166:169], v[182:185], v[18:21]
	v_mfma_f32_16x16x32_bf16 v[14:17], v[158:161], v[190:193], v[14:17]
	v_mfma_f32_16x16x32_bf16 v[10:13], v[166:169], v[190:193], v[10:13]
	v_mfma_f32_16x16x32_bf16 v[6:9], v[158:161], v[206:209], v[6:9]
	v_mfma_f32_16x16x32_bf16 v[2:5], v[166:169], v[206:209], v[2:5]
	s_setprio 0
	s_barrier
	v_add_u32_e32 v150, s56, v219
	v_add_u32_e32 v166, s57, v219
	ds_read_b128 v[138:141], v150
	ds_read_b128 v[142:145], v150 offset:1024
	ds_read_b128 v[146:149], v150 offset:2048
	ds_read_b128 v[150:153], v150 offset:3072
	ds_read_b128 v[154:157], v166
	ds_read_b128 v[158:161], v166 offset:1024
	ds_read_b128 v[162:165], v166 offset:2048
	ds_read_b128 v[166:169], v166 offset:3072
	s_mov_b32 m0, s29
	v_lshl_add_u64 v[222:223], v[210:211], 0, s[22:23]
	ds_read_b128 v[170:173], v217 offset:32768
	ds_read_b128 v[174:177], v217 offset:33792
	ds_read_b128 v[178:181], v217 offset:34816
	ds_read_b128 v[182:185], v217 offset:35840
	ds_read_b128 v[186:189], v217 offset:36864
	ds_read_b128 v[190:193], v217 offset:37888
	ds_read_b128 v[202:205], v217 offset:38912
	ds_read_b128 v[206:209], v217 offset:39936
	global_load_lds_dwordx4 v[222:223], off
	v_lshl_add_u64 v[222:223], v[212:213], 0, s[22:23]
	s_mov_b32 m0, s33
	v_lshl_add_u64 v[210:211], v[210:211], 0, s[30:31]
	global_load_lds_dwordx4 v[222:223], off
	s_mov_b32 m0, s36
	s_nop 0
	global_load_lds_dwordx4 v[210:211], off
	v_lshl_add_u64 v[210:211], v[212:213], 0, s[30:31]
	s_mov_b32 m0, s37
	s_nop 0
	global_load_lds_dwordx4 v[210:211], off
	s_waitcnt vmcnt(8)
	s_waitcnt lgkmcnt(0)
	s_setprio 1
	s_barrier
	v_mfma_f32_16x16x32_bf16 v[126:129], v[138:141], v[170:173], v[126:129]
	v_mfma_f32_16x16x32_bf16 v[122:125], v[146:149], v[170:173], v[122:125]
	v_mfma_f32_16x16x32_bf16 v[118:121], v[138:141], v[178:181], v[118:121]
	v_mfma_f32_16x16x32_bf16 v[114:117], v[146:149], v[178:181], v[114:117]
	v_mfma_f32_16x16x32_bf16 v[110:113], v[138:141], v[186:189], v[110:113]
	v_mfma_f32_16x16x32_bf16 v[106:109], v[146:149], v[186:189], v[106:109]
	v_mfma_f32_16x16x32_bf16 v[102:105], v[138:141], v[202:205], v[102:105]
	v_mfma_f32_16x16x32_bf16 v[98:101], v[146:149], v[202:205], v[98:101]
	v_mfma_f32_16x16x32_bf16 v[126:129], v[142:145], v[174:177], v[126:129]
	v_mfma_f32_16x16x32_bf16 v[122:125], v[150:153], v[174:177], v[122:125]
	v_mfma_f32_16x16x32_bf16 v[118:121], v[142:145], v[182:185], v[118:121]
	v_mfma_f32_16x16x32_bf16 v[114:117], v[150:153], v[182:185], v[114:117]
	v_mfma_f32_16x16x32_bf16 v[110:113], v[142:145], v[190:193], v[110:113]
	v_mfma_f32_16x16x32_bf16 v[106:109], v[150:153], v[190:193], v[106:109]
	v_mfma_f32_16x16x32_bf16 v[102:105], v[142:145], v[206:209], v[102:105]
	v_mfma_f32_16x16x32_bf16 v[98:101], v[150:153], v[206:209], v[98:101]
	v_mfma_f32_16x16x32_bf16 v[94:97], v[154:157], v[170:173], v[94:97]
	v_mfma_f32_16x16x32_bf16 v[90:93], v[162:165], v[170:173], v[90:93]
	v_mfma_f32_16x16x32_bf16 v[86:89], v[154:157], v[178:181], v[86:89]
	v_mfma_f32_16x16x32_bf16 v[82:85], v[162:165], v[178:181], v[82:85]
	v_mfma_f32_16x16x32_bf16 v[78:81], v[154:157], v[186:189], v[78:81]
	v_mfma_f32_16x16x32_bf16 v[74:77], v[162:165], v[186:189], v[74:77]
	v_mfma_f32_16x16x32_bf16 v[70:73], v[154:157], v[202:205], v[70:73]
	v_mfma_f32_16x16x32_bf16 v[66:69], v[162:165], v[202:205], v[66:69]
	v_mfma_f32_16x16x32_bf16 v[94:97], v[158:161], v[174:177], v[94:97]
	v_mfma_f32_16x16x32_bf16 v[90:93], v[166:169], v[174:177], v[90:93]
	v_mfma_f32_16x16x32_bf16 v[86:89], v[158:161], v[182:185], v[86:89]
	v_mfma_f32_16x16x32_bf16 v[82:85], v[166:169], v[182:185], v[82:85]
	v_mfma_f32_16x16x32_bf16 v[78:81], v[158:161], v[190:193], v[78:81]
	v_mfma_f32_16x16x32_bf16 v[74:77], v[166:169], v[190:193], v[74:77]
	v_mfma_f32_16x16x32_bf16 v[70:73], v[158:161], v[206:209], v[70:73]
	v_mfma_f32_16x16x32_bf16 v[66:69], v[166:169], v[206:209], v[66:69]
	s_setprio 0
	s_barrier
	s_mov_b32 m0, s58
	v_lshl_add_u64 v[210:211], v[214:215], 0, s[34:35]
	ds_read_b128 v[170:173], v217 offset:49152
	ds_read_b128 v[174:177], v217 offset:50176
	ds_read_b128 v[178:181], v217 offset:51200
	ds_read_b128 v[182:185], v217 offset:52224
	ds_read_b128 v[186:189], v217 offset:53248
	ds_read_b128 v[190:193], v217 offset:54272
	ds_read_b128 v[202:205], v217 offset:55296
	ds_read_b128 v[206:209], v217 offset:56320
	global_load_lds_dwordx4 v[210:211], off
	v_lshl_add_u64 v[210:211], v[220:221], 0, s[34:35]
	s_mov_b32 m0, s59
	s_nop 0
	global_load_lds_dwordx4 v[210:211], off
	v_lshl_add_u64 v[210:211], v[214:215], 0, s[40:41]
	s_mov_b32 m0, s38
	s_nop 0
	global_load_lds_dwordx4 v[210:211], off
	v_lshl_add_u64 v[210:211], v[220:221], 0, s[40:41]
	s_mov_b32 m0, s60
	s_nop 0
	global_load_lds_dwordx4 v[210:211], off
	s_waitcnt vmcnt(4)
	s_waitcnt lgkmcnt(0)
	s_setprio 1
	s_barrier
	v_mfma_f32_16x16x32_bf16 v[62:65], v[138:141], v[170:173], v[62:65]
	v_mfma_f32_16x16x32_bf16 v[58:61], v[146:149], v[170:173], v[58:61]
	v_mfma_f32_16x16x32_bf16 v[54:57], v[138:141], v[178:181], v[54:57]
	v_mfma_f32_16x16x32_bf16 v[50:53], v[146:149], v[178:181], v[50:53]
	v_mfma_f32_16x16x32_bf16 v[46:49], v[138:141], v[186:189], v[46:49]
	v_mfma_f32_16x16x32_bf16 v[42:45], v[146:149], v[186:189], v[42:45]
	v_mfma_f32_16x16x32_bf16 v[38:41], v[138:141], v[202:205], v[38:41]
	v_mfma_f32_16x16x32_bf16 v[34:37], v[146:149], v[202:205], v[34:37]
	v_mfma_f32_16x16x32_bf16 v[62:65], v[142:145], v[174:177], v[62:65]
	v_mfma_f32_16x16x32_bf16 v[58:61], v[150:153], v[174:177], v[58:61]
	v_mfma_f32_16x16x32_bf16 v[54:57], v[142:145], v[182:185], v[54:57]
	v_mfma_f32_16x16x32_bf16 v[50:53], v[150:153], v[182:185], v[50:53]
	v_mfma_f32_16x16x32_bf16 v[46:49], v[142:145], v[190:193], v[46:49]
	v_mfma_f32_16x16x32_bf16 v[42:45], v[150:153], v[190:193], v[42:45]
	v_mfma_f32_16x16x32_bf16 v[38:41], v[142:145], v[206:209], v[38:41]
	v_mfma_f32_16x16x32_bf16 v[34:37], v[150:153], v[206:209], v[34:37]
	v_mfma_f32_16x16x32_bf16 v[30:33], v[154:157], v[170:173], v[30:33]
	v_mfma_f32_16x16x32_bf16 v[26:29], v[162:165], v[170:173], v[26:29]
	v_mfma_f32_16x16x32_bf16 v[22:25], v[154:157], v[178:181], v[22:25]
	v_mfma_f32_16x16x32_bf16 v[18:21], v[162:165], v[178:181], v[18:21]
	v_mfma_f32_16x16x32_bf16 v[14:17], v[154:157], v[186:189], v[14:17]
	v_mfma_f32_16x16x32_bf16 v[10:13], v[162:165], v[186:189], v[10:13]
	v_mfma_f32_16x16x32_bf16 v[6:9], v[154:157], v[202:205], v[6:9]
	v_mfma_f32_16x16x32_bf16 v[2:5], v[162:165], v[202:205], v[2:5]
	v_mfma_f32_16x16x32_bf16 v[30:33], v[158:161], v[174:177], v[30:33]
	v_mfma_f32_16x16x32_bf16 v[26:29], v[166:169], v[174:177], v[26:29]
	v_mfma_f32_16x16x32_bf16 v[22:25], v[158:161], v[182:185], v[22:25]
	v_mfma_f32_16x16x32_bf16 v[18:21], v[166:169], v[182:185], v[18:21]
	v_mfma_f32_16x16x32_bf16 v[14:17], v[158:161], v[190:193], v[14:17]
	v_mfma_f32_16x16x32_bf16 v[10:13], v[166:169], v[190:193], v[10:13]
	v_mfma_f32_16x16x32_bf16 v[6:9], v[158:161], v[206:209], v[6:9]
	v_mfma_f32_16x16x32_bf16 v[2:5], v[166:169], v[206:209], v[2:5]
	s_setprio 0
	s_barrier
	s_add_i32 s45, s45, 2
	s_add_u32 s4, s4, 0x100
	s_addc_u32 s5, s5, 0
	s_cmp_gt_u32 s45, 27
	s_cbranch_scc0 .LBB0_599
	v_add_u32_e32 v142, 0x10000, v218
	v_add_u32_e32 v158, 0x14000, v218
	ds_read_b128 v[130:133], v142
	ds_read_b128 v[134:137], v142 offset:1024
	ds_read_b128 v[138:141], v142 offset:2048
	ds_read_b128 v[142:145], v142 offset:3072
	ds_read_b128 v[146:149], v158
	ds_read_b128 v[150:153], v158 offset:1024
	ds_read_b128 v[154:157], v158 offset:2048
	ds_read_b128 v[158:161], v158 offset:3072
	s_mov_b64 s[4:5], 0xf80
	s_mov_b32 m0, s44
	v_lshl_add_u64 v[200:201], v[200:201], 0, s[4:5]
	v_lshl_add_u64 v[198:199], v[198:199], 0, s[4:5]
	s_add_u32 s4, s14, 0x80f80
	ds_read_b128 v[162:165], v217
	ds_read_b128 v[166:169], v217 offset:1024
	ds_read_b128 v[170:173], v217 offset:2048
	ds_read_b128 v[174:177], v217 offset:3072
	ds_read_b128 v[178:181], v217 offset:4096
	ds_read_b128 v[182:185], v217 offset:5120
	ds_read_b128 v[186:189], v217 offset:6144
	ds_read_b128 v[190:193], v217 offset:7168
	global_load_lds_dwordx4 v[200:201], off
	s_mov_b32 m0, s43
	s_addc_u32 s5, s15, 0
	global_load_lds_dwordx4 v[198:199], off
	v_lshl_add_u64 v[194:195], s[4:5], 0, v[194:195]
	s_mov_b32 m0, s42
	s_nop 0
	global_load_lds_dwordx4 v[194:195], off
	v_lshl_add_u64 v[194:195], s[4:5], 0, v[196:197]
	s_mov_b32 m0, s39
	s_nop 0
	global_load_lds_dwordx4 v[194:195], off
	s_waitcnt vmcnt(8)
	s_waitcnt lgkmcnt(0)
	s_setprio 1
	s_barrier
	v_mfma_f32_16x16x32_bf16 v[126:129], v[130:133], v[162:165], v[126:129]
	v_mfma_f32_16x16x32_bf16 v[122:125], v[138:141], v[162:165], v[122:125]
	v_mfma_f32_16x16x32_bf16 v[118:121], v[130:133], v[170:173], v[118:121]
	v_mfma_f32_16x16x32_bf16 v[114:117], v[138:141], v[170:173], v[114:117]
	v_mfma_f32_16x16x32_bf16 v[102:105], v[130:133], v[186:189], v[102:105]
	v_mfma_f32_16x16x32_bf16 v[98:101], v[138:141], v[186:189], v[98:101]
	v_mfma_f32_16x16x32_bf16 v[126:129], v[134:137], v[166:169], v[126:129]
	v_mfma_f32_16x16x32_bf16 v[122:125], v[142:145], v[166:169], v[122:125]
	v_mfma_f32_16x16x32_bf16 v[118:121], v[134:137], v[174:177], v[118:121]
	v_mfma_f32_16x16x32_bf16 v[114:117], v[142:145], v[174:177], v[114:117]
	v_mfma_f32_16x16x32_bf16 v[110:113], v[130:133], v[178:181], v[110:113]
	v_mfma_f32_16x16x32_bf16 v[106:109], v[138:141], v[178:181], v[106:109]
	v_mfma_f32_16x16x32_bf16 v[102:105], v[134:137], v[190:193], v[102:105]
	v_mfma_f32_16x16x32_bf16 v[98:101], v[142:145], v[190:193], v[98:101]
	v_mfma_f32_16x16x32_bf16 v[194:197], v[134:137], v[182:185], v[110:113]
	v_mfma_f32_16x16x32_bf16 v[198:201], v[142:145], v[182:185], v[106:109]
	v_mfma_f32_16x16x32_bf16 v[86:89], v[146:149], v[170:173], v[86:89]
	v_mfma_f32_16x16x32_bf16 v[82:85], v[154:157], v[170:173], v[82:85]
	v_mfma_f32_16x16x32_bf16 v[70:73], v[146:149], v[186:189], v[70:73]
	v_mfma_f32_16x16x32_bf16 v[66:69], v[154:157], v[186:189], v[66:69]
	v_mfma_f32_16x16x32_bf16 v[94:97], v[146:149], v[162:165], v[94:97]
	v_mfma_f32_16x16x32_bf16 v[90:93], v[154:157], v[162:165], v[90:93]
	v_mfma_f32_16x16x32_bf16 v[86:89], v[150:153], v[174:177], v[86:89]
	v_mfma_f32_16x16x32_bf16 v[82:85], v[158:161], v[174:177], v[82:85]
	v_mfma_f32_16x16x32_bf16 v[78:81], v[146:149], v[178:181], v[78:81]
	v_mfma_f32_16x16x32_bf16 v[74:77], v[154:157], v[178:181], v[74:77]
	v_mfma_f32_16x16x32_bf16 v[70:73], v[150:153], v[190:193], v[70:73]
	v_mfma_f32_16x16x32_bf16 v[66:69], v[158:161], v[190:193], v[66:69]
	v_mfma_f32_16x16x32_bf16 v[202:205], v[150:153], v[166:169], v[94:97]
	v_mfma_f32_16x16x32_bf16 v[162:165], v[158:161], v[166:169], v[90:93]
	v_mfma_f32_16x16x32_bf16 v[166:169], v[150:153], v[182:185], v[78:81]
	v_mfma_f32_16x16x32_bf16 v[170:173], v[158:161], v[182:185], v[74:77]
	s_setprio 0
	s_barrier
	s_nop 0
	ds_read_b128 v[74:77], v217 offset:16384
	ds_read_b128 v[78:81], v217 offset:17408
	ds_read_b128 v[90:93], v217 offset:18432
	ds_read_b128 v[94:97], v217 offset:19456
	ds_read_b128 v[106:109], v217 offset:20480
	ds_read_b128 v[110:113], v217 offset:21504
	ds_read_b128 v[174:177], v217 offset:22528
	ds_read_b128 v[178:181], v217 offset:23552
	s_waitcnt vmcnt(0)
	s_waitcnt lgkmcnt(0)
	s_setprio 1
	s_barrier
	v_mfma_f32_16x16x32_bf16 v[62:65], v[130:133], v[74:77], v[62:65]
	v_mfma_f32_16x16x32_bf16 v[58:61], v[138:141], v[74:77], v[58:61]
	v_mfma_f32_16x16x32_bf16 v[54:57], v[130:133], v[90:93], v[54:57]
	v_mfma_f32_16x16x32_bf16 v[50:53], v[138:141], v[90:93], v[50:53]
	v_mfma_f32_16x16x32_bf16 v[38:41], v[130:133], v[174:177], v[38:41]
	v_mfma_f32_16x16x32_bf16 v[34:37], v[138:141], v[174:177], v[34:37]
	v_mfma_f32_16x16x32_bf16 v[62:65], v[134:137], v[78:81], v[62:65]
	v_mfma_f32_16x16x32_bf16 v[58:61], v[142:145], v[78:81], v[58:61]
	v_mfma_f32_16x16x32_bf16 v[54:57], v[134:137], v[94:97], v[54:57]
	v_mfma_f32_16x16x32_bf16 v[50:53], v[142:145], v[94:97], v[50:53]
	v_mfma_f32_16x16x32_bf16 v[46:49], v[130:133], v[106:109], v[46:49]
	v_mfma_f32_16x16x32_bf16 v[42:45], v[138:141], v[106:109], v[42:45]
	v_mfma_f32_16x16x32_bf16 v[38:41], v[134:137], v[178:181], v[38:41]
	v_mfma_f32_16x16x32_bf16 v[34:37], v[142:145], v[178:181], v[34:37]
	v_mfma_f32_16x16x32_bf16 v[182:185], v[134:137], v[110:113], v[46:49]
	v_mfma_f32_16x16x32_bf16 v[186:189], v[142:145], v[110:113], v[42:45]
	v_mfma_f32_16x16x32_bf16 v[22:25], v[146:149], v[90:93], v[22:25]
	v_mfma_f32_16x16x32_bf16 v[18:21], v[154:157], v[90:93], v[18:21]
	v_mfma_f32_16x16x32_bf16 v[6:9], v[146:149], v[174:177], v[6:9]
	v_mfma_f32_16x16x32_bf16 v[2:5], v[154:157], v[174:177], v[2:5]
	v_mfma_f32_16x16x32_bf16 v[30:33], v[146:149], v[74:77], v[30:33]
	v_mfma_f32_16x16x32_bf16 v[26:29], v[154:157], v[74:77], v[26:29]
	v_mfma_f32_16x16x32_bf16 v[22:25], v[150:153], v[94:97], v[22:25]
	v_mfma_f32_16x16x32_bf16 v[18:21], v[158:161], v[94:97], v[18:21]
	v_mfma_f32_16x16x32_bf16 v[14:17], v[146:149], v[106:109], v[14:17]
	v_mfma_f32_16x16x32_bf16 v[10:13], v[154:157], v[106:109], v[10:13]
	v_mfma_f32_16x16x32_bf16 v[6:9], v[150:153], v[178:181], v[6:9]
	v_mfma_f32_16x16x32_bf16 v[2:5], v[158:161], v[178:181], v[2:5]
	v_mfma_f32_16x16x32_bf16 v[130:133], v[150:153], v[78:81], v[30:33]
	v_mfma_f32_16x16x32_bf16 v[134:137], v[158:161], v[78:81], v[26:29]
	v_mfma_f32_16x16x32_bf16 v[138:141], v[150:153], v[110:113], v[14:17]
	v_mfma_f32_16x16x32_bf16 v[142:145], v[158:161], v[110:113], v[10:13]
	s_setprio 0
	s_barrier
	v_add_u32_e32 v26, 0x18000, v218
	ds_read_b128 v[10:13], v26
	ds_read_b128 v[14:17], v26 offset:1024
	ds_read_b128 v[146:149], v26 offset:2048
	ds_read_b128 v[150:153], v26 offset:3072
	v_add_u32_e32 v26, 0x1c000, v218
	ds_read_b128 v[154:157], v26
	ds_read_b128 v[158:161], v26 offset:1024
	ds_read_b128 v[174:177], v26 offset:2048
	ds_read_b128 v[178:181], v26 offset:3072
	ds_read_b128 v[26:29], v217 offset:32768
	ds_read_b128 v[30:33], v217 offset:33792
	ds_read_b128 v[42:45], v217 offset:34816
	ds_read_b128 v[46:49], v217 offset:35840
	ds_read_b128 v[190:193], v217 offset:36864
	ds_read_b128 v[206:209], v217 offset:37888
	ds_read_b128 v[210:213], v217 offset:38912
	ds_read_b128 v[218:221], v217 offset:39936
	s_waitcnt lgkmcnt(0)
	s_setprio 1
	s_barrier
	v_mfma_f32_16x16x32_bf16 v[74:77], v[10:13], v[26:29], v[126:129]
	v_mfma_f32_16x16x32_bf16 v[126:129], v[14:17], v[30:33], v[74:77]
	v_mfma_f32_16x16x32_bf16 v[74:77], v[146:149], v[26:29], v[122:125]
	v_mfma_f32_16x16x32_bf16 v[122:125], v[150:153], v[30:33], v[74:77]
	v_mfma_f32_16x16x32_bf16 v[74:77], v[10:13], v[42:45], v[118:121]
	v_mfma_f32_16x16x32_bf16 v[110:113], v[14:17], v[46:49], v[74:77]
	v_mfma_f32_16x16x32_bf16 v[74:77], v[146:149], v[42:45], v[114:117]
	v_mfma_f32_16x16x32_bf16 v[106:109], v[150:153], v[46:49], v[74:77]
	v_mfma_f32_16x16x32_bf16 v[74:77], v[10:13], v[190:193], v[194:197]
	v_mfma_f32_16x16x32_bf16 v[94:97], v[14:17], v[206:209], v[74:77]
	v_mfma_f32_16x16x32_bf16 v[74:77], v[146:149], v[190:193], v[198:201]
	v_mfma_f32_16x16x32_bf16 v[90:93], v[150:153], v[206:209], v[74:77]
	v_mfma_f32_16x16x32_bf16 v[74:77], v[10:13], v[210:213], v[102:105]
	v_mfma_f32_16x16x32_bf16 v[78:81], v[14:17], v[218:221], v[74:77]
	v_mfma_f32_16x16x32_bf16 v[74:77], v[146:149], v[210:213], v[98:101]
	v_mfma_f32_16x16x32_bf16 v[74:77], v[150:153], v[218:221], v[74:77]
	v_mfma_f32_16x16x32_bf16 v[98:101], v[154:157], v[26:29], v[202:205]
	v_mfma_f32_16x16x32_bf16 v[26:29], v[174:177], v[26:29], v[162:165]
	v_mfma_f32_16x16x32_bf16 v[114:117], v[178:181], v[30:33], v[26:29]
	v_mfma_f32_16x16x32_bf16 v[26:29], v[154:157], v[42:45], v[86:89]
	v_mfma_f32_16x16x32_bf16 v[102:105], v[158:161], v[46:49], v[26:29]
	v_mfma_f32_16x16x32_bf16 v[26:29], v[174:177], v[42:45], v[82:85]
	v_mfma_f32_16x16x32_bf16 v[118:121], v[158:161], v[30:33], v[98:101]
	v_mfma_f32_16x16x32_bf16 v[98:101], v[178:181], v[46:49], v[26:29]
	v_mfma_f32_16x16x32_bf16 v[26:29], v[154:157], v[190:193], v[166:169]
	v_mfma_f32_16x16x32_bf16 v[86:89], v[158:161], v[206:209], v[26:29]
	v_mfma_f32_16x16x32_bf16 v[26:29], v[174:177], v[190:193], v[170:173]
	v_mfma_f32_16x16x32_bf16 v[82:85], v[178:181], v[206:209], v[26:29]
	v_mfma_f32_16x16x32_bf16 v[26:29], v[154:157], v[210:213], v[70:73]
	v_mfma_f32_16x16x32_bf16 v[70:73], v[158:161], v[218:221], v[26:29]
	v_mfma_f32_16x16x32_bf16 v[26:29], v[174:177], v[210:213], v[66:69]
	v_mfma_f32_16x16x32_bf16 v[66:69], v[178:181], v[218:221], v[26:29]
	s_setprio 0
	s_barrier
	ds_read_b128 v[162:165], v217 offset:49152
	ds_read_b128 v[166:169], v217 offset:50176
	ds_read_b128 v[170:173], v217 offset:51200
	ds_read_b128 v[190:193], v217 offset:52224
	ds_read_b128 v[194:197], v217 offset:53248
	ds_read_b128 v[198:201], v217 offset:54272
	ds_read_b128 v[202:205], v217 offset:55296
	ds_read_b128 v[206:209], v217 offset:56320
	s_waitcnt lgkmcnt(0)
	s_setprio 1
	s_barrier
	v_mfma_f32_16x16x32_bf16 v[26:29], v[10:13], v[162:165], v[62:65]
	v_mfma_f32_16x16x32_bf16 v[62:65], v[14:17], v[166:169], v[26:29]
	v_mfma_f32_16x16x32_bf16 v[26:29], v[146:149], v[162:165], v[58:61]
	v_mfma_f32_16x16x32_bf16 v[58:61], v[150:153], v[166:169], v[26:29]
	v_mfma_f32_16x16x32_bf16 v[26:29], v[10:13], v[170:173], v[54:57]
	v_mfma_f32_16x16x32_bf16 v[46:49], v[14:17], v[190:193], v[26:29]
	v_mfma_f32_16x16x32_bf16 v[26:29], v[146:149], v[170:173], v[50:53]
	v_mfma_f32_16x16x32_bf16 v[42:45], v[150:153], v[190:193], v[26:29]
	v_mfma_f32_16x16x32_bf16 v[26:29], v[10:13], v[194:197], v[182:185]
	v_mfma_f32_16x16x32_bf16 v[10:13], v[10:13], v[202:205], v[38:41]
	v_mfma_f32_16x16x32_bf16 v[30:33], v[14:17], v[198:201], v[26:29]
	v_mfma_f32_16x16x32_bf16 v[26:29], v[146:149], v[194:197], v[186:189]
	v_mfma_f32_16x16x32_bf16 v[14:17], v[14:17], v[206:209], v[10:13]
	v_mfma_f32_16x16x32_bf16 v[10:13], v[146:149], v[202:205], v[34:37]
	v_mfma_f32_16x16x32_bf16 v[26:29], v[150:153], v[198:201], v[26:29]
	v_mfma_f32_16x16x32_bf16 v[10:13], v[150:153], v[206:209], v[10:13]
	v_mfma_f32_16x16x32_bf16 v[34:37], v[154:157], v[162:165], v[130:133]
	v_mfma_f32_16x16x32_bf16 v[54:57], v[158:161], v[166:169], v[34:37]
	v_mfma_f32_16x16x32_bf16 v[34:37], v[174:177], v[162:165], v[134:137]
	v_mfma_f32_16x16x32_bf16 v[18:21], v[174:177], v[170:173], v[18:21]
	v_mfma_f32_16x16x32_bf16 v[50:53], v[178:181], v[166:169], v[34:37]
	v_mfma_f32_16x16x32_bf16 v[22:25], v[154:157], v[170:173], v[22:25]
	v_mfma_f32_16x16x32_bf16 v[34:37], v[178:181], v[190:193], v[18:21]
	v_mfma_f32_16x16x32_bf16 v[18:21], v[154:157], v[194:197], v[138:141]
	v_mfma_f32_16x16x32_bf16 v[38:41], v[158:161], v[190:193], v[22:25]
	v_mfma_f32_16x16x32_bf16 v[22:25], v[158:161], v[198:201], v[18:21]
	v_mfma_f32_16x16x32_bf16 v[18:21], v[174:177], v[194:197], v[142:145]
	v_mfma_f32_16x16x32_bf16 v[6:9], v[154:157], v[202:205], v[6:9]
	v_mfma_f32_16x16x32_bf16 v[2:5], v[174:177], v[202:205], v[2:5]
	v_mfma_f32_16x16x32_bf16 v[18:21], v[178:181], v[198:201], v[18:21]
	v_mfma_f32_16x16x32_bf16 v[6:9], v[158:161], v[206:209], v[6:9]
	v_mfma_f32_16x16x32_bf16 v[2:5], v[178:181], v[206:209], v[2:5]
	s_setprio 0
	s_barrier

.LBB0_641:
	ds_read_b128 v[150:153], v145
	ds_read_b128 v[154:157], v145 offset:1024
	ds_read_b128 v[158:161], v145 offset:2048
	s_waitcnt lgkmcnt(0)
	ds_read_b128 v[162:165], v145 offset:3072
	ds_read_b128 v[166:169], v146
	ds_read_b128 v[170:173], v146 offset:1024
	ds_read_b128 v[174:177], v146 offset:2048
	ds_read_b128 v[178:181], v146 offset:3072
	v_lshl_add_u64 v[214:215], v[136:137], 0, s[4:5]
	s_mov_b32 m0, s40
	v_lshl_add_u64 v[216:217], v[214:215], 0, s[6:7]
	ds_read_b128 v[182:185], v143
	ds_read_b128 v[186:189], v143 offset:1024
	ds_read_b128 v[190:193], v143 offset:2048
	ds_read_b128 v[194:197], v143 offset:3072
	ds_read_b128 v[198:201], v143 offset:4096
	ds_read_b128 v[202:205], v143 offset:5120
	ds_read_b128 v[206:209], v143 offset:6144
	ds_read_b128 v[210:213], v143 offset:7168
	global_load_lds_dwordx4 v[216:217], off
	v_lshl_add_u64 v[216:217], v[134:135], 0, s[4:5]
	v_lshl_add_u64 v[218:219], v[216:217], 0, s[6:7]
	s_mov_b32 m0, s39
	s_nop 0
	global_load_lds_dwordx4 v[218:219], off
	v_lshl_add_u64 v[218:219], v[214:215], 0, s[12:13]
	s_mov_b32 m0, s38
	s_nop 0
	global_load_lds_dwordx4 v[218:219], off
	v_lshl_add_u64 v[218:219], v[216:217], 0, s[12:13]
	s_mov_b32 m0, s37
	s_nop 0
	global_load_lds_dwordx4 v[218:219], off
	s_waitcnt vmcnt(8)
	s_waitcnt lgkmcnt(0)
	s_setprio 1
	s_barrier
	v_mfma_f32_16x16x32_bf16 v[126:129], v[150:153], v[182:185], v[126:129]
	v_mfma_f32_16x16x32_bf16 v[122:125], v[158:161], v[182:185], v[122:125]
	v_mfma_f32_16x16x32_bf16 v[118:121], v[150:153], v[190:193], v[118:121]
	v_mfma_f32_16x16x32_bf16 v[114:117], v[158:161], v[190:193], v[114:117]
	v_mfma_f32_16x16x32_bf16 v[110:113], v[150:153], v[198:201], v[110:113]
	v_mfma_f32_16x16x32_bf16 v[106:109], v[158:161], v[198:201], v[106:109]
	v_mfma_f32_16x16x32_bf16 v[102:105], v[150:153], v[206:209], v[102:105]
	v_mfma_f32_16x16x32_bf16 v[98:101], v[158:161], v[206:209], v[98:101]
	v_mfma_f32_16x16x32_bf16 v[126:129], v[154:157], v[186:189], v[126:129]
	v_mfma_f32_16x16x32_bf16 v[122:125], v[162:165], v[186:189], v[122:125]
	v_mfma_f32_16x16x32_bf16 v[118:121], v[154:157], v[194:197], v[118:121]
	v_mfma_f32_16x16x32_bf16 v[114:117], v[162:165], v[194:197], v[114:117]
	v_mfma_f32_16x16x32_bf16 v[110:113], v[154:157], v[202:205], v[110:113]
	v_mfma_f32_16x16x32_bf16 v[106:109], v[162:165], v[202:205], v[106:109]
	v_mfma_f32_16x16x32_bf16 v[102:105], v[154:157], v[210:213], v[102:105]
	v_mfma_f32_16x16x32_bf16 v[98:101], v[162:165], v[210:213], v[98:101]
	v_mfma_f32_16x16x32_bf16 v[94:97], v[166:169], v[182:185], v[94:97]
	v_mfma_f32_16x16x32_bf16 v[90:93], v[174:177], v[182:185], v[90:93]
	v_mfma_f32_16x16x32_bf16 v[86:89], v[166:169], v[190:193], v[86:89]
	v_mfma_f32_16x16x32_bf16 v[82:85], v[174:177], v[190:193], v[82:85]
	v_mfma_f32_16x16x32_bf16 v[78:81], v[166:169], v[198:201], v[78:81]
	v_mfma_f32_16x16x32_bf16 v[74:77], v[174:177], v[198:201], v[74:77]
	v_mfma_f32_16x16x32_bf16 v[70:73], v[166:169], v[206:209], v[70:73]
	v_mfma_f32_16x16x32_bf16 v[66:69], v[174:177], v[206:209], v[66:69]
	v_mfma_f32_16x16x32_bf16 v[94:97], v[170:173], v[186:189], v[94:97]
	v_mfma_f32_16x16x32_bf16 v[90:93], v[178:181], v[186:189], v[90:93]
	v_mfma_f32_16x16x32_bf16 v[86:89], v[170:173], v[194:197], v[86:89]
	v_mfma_f32_16x16x32_bf16 v[82:85], v[178:181], v[194:197], v[82:85]
	v_mfma_f32_16x16x32_bf16 v[78:81], v[170:173], v[202:205], v[78:81]
	v_mfma_f32_16x16x32_bf16 v[74:77], v[178:181], v[202:205], v[74:77]
	v_mfma_f32_16x16x32_bf16 v[70:73], v[170:173], v[210:213], v[70:73]
	v_mfma_f32_16x16x32_bf16 v[66:69], v[178:181], v[210:213], v[66:69]
	s_setprio 0
	s_barrier
	v_lshl_add_u64 v[218:219], v[140:141], 0, s[4:5]
	s_mov_b32 m0, s42
	v_lshl_add_u64 v[220:221], v[218:219], 0, s[14:15]
	ds_read_b128 v[182:185], v143 offset:16384
	ds_read_b128 v[186:189], v143 offset:17408
	ds_read_b128 v[190:193], v143 offset:18432
	ds_read_b128 v[194:197], v143 offset:19456
	ds_read_b128 v[198:201], v143 offset:20480
	ds_read_b128 v[202:205], v143 offset:21504
	ds_read_b128 v[206:209], v143 offset:22528
	ds_read_b128 v[210:213], v143 offset:23552
	global_load_lds_dwordx4 v[220:221], off
	v_lshl_add_u64 v[220:221], v[138:139], 0, s[4:5]
	v_lshl_add_u64 v[222:223], v[220:221], 0, s[14:15]
	s_mov_b32 m0, s43
	s_nop 0
	global_load_lds_dwordx4 v[222:223], off
	v_lshl_add_u64 v[222:223], v[218:219], 0, s[16:17]
	s_mov_b32 m0, s44
	s_nop 0
	global_load_lds_dwordx4 v[222:223], off
	v_lshl_add_u64 v[222:223], v[220:221], 0, s[16:17]
	s_mov_b32 m0, s45
	s_nop 0
	global_load_lds_dwordx4 v[222:223], off
	s_waitcnt vmcnt(4)
	s_waitcnt lgkmcnt(0)
	s_setprio 1
	s_barrier
	v_mfma_f32_16x16x32_bf16 v[62:65], v[150:153], v[182:185], v[62:65]
	v_mfma_f32_16x16x32_bf16 v[58:61], v[158:161], v[182:185], v[58:61]
	v_mfma_f32_16x16x32_bf16 v[54:57], v[150:153], v[190:193], v[54:57]
	v_mfma_f32_16x16x32_bf16 v[50:53], v[158:161], v[190:193], v[50:53]
	v_mfma_f32_16x16x32_bf16 v[46:49], v[150:153], v[198:201], v[46:49]
	v_mfma_f32_16x16x32_bf16 v[42:45], v[158:161], v[198:201], v[42:45]
	v_mfma_f32_16x16x32_bf16 v[38:41], v[150:153], v[206:209], v[38:41]
	v_mfma_f32_16x16x32_bf16 v[34:37], v[158:161], v[206:209], v[34:37]
	v_mfma_f32_16x16x32_bf16 v[62:65], v[154:157], v[186:189], v[62:65]
	v_mfma_f32_16x16x32_bf16 v[58:61], v[162:165], v[186:189], v[58:61]
	v_mfma_f32_16x16x32_bf16 v[54:57], v[154:157], v[194:197], v[54:57]
	v_mfma_f32_16x16x32_bf16 v[50:53], v[162:165], v[194:197], v[50:53]
	v_mfma_f32_16x16x32_bf16 v[46:49], v[154:157], v[202:205], v[46:49]
	v_mfma_f32_16x16x32_bf16 v[42:45], v[162:165], v[202:205], v[42:45]
	v_mfma_f32_16x16x32_bf16 v[38:41], v[154:157], v[210:213], v[38:41]
	v_mfma_f32_16x16x32_bf16 v[34:37], v[162:165], v[210:213], v[34:37]
	v_mfma_f32_16x16x32_bf16 v[30:33], v[166:169], v[182:185], v[30:33]
	v_mfma_f32_16x16x32_bf16 v[26:29], v[174:177], v[182:185], v[26:29]
	v_mfma_f32_16x16x32_bf16 v[22:25], v[166:169], v[190:193], v[22:25]
	v_mfma_f32_16x16x32_bf16 v[18:21], v[174:177], v[190:193], v[18:21]
	v_mfma_f32_16x16x32_bf16 v[14:17], v[166:169], v[198:201], v[14:17]
	v_mfma_f32_16x16x32_bf16 v[10:13], v[174:177], v[198:201], v[10:13]
	v_mfma_f32_16x16x32_bf16 v[6:9], v[166:169], v[206:209], v[6:9]
	v_mfma_f32_16x16x32_bf16 v[2:5], v[174:177], v[206:209], v[2:5]
	v_mfma_f32_16x16x32_bf16 v[30:33], v[170:173], v[186:189], v[30:33]
	v_mfma_f32_16x16x32_bf16 v[26:29], v[178:181], v[186:189], v[26:29]
	v_mfma_f32_16x16x32_bf16 v[22:25], v[170:173], v[194:197], v[22:25]
	v_mfma_f32_16x16x32_bf16 v[18:21], v[178:181], v[194:197], v[18:21]
	v_mfma_f32_16x16x32_bf16 v[14:17], v[170:173], v[202:205], v[14:17]
	v_mfma_f32_16x16x32_bf16 v[10:13], v[178:181], v[202:205], v[10:13]
	v_mfma_f32_16x16x32_bf16 v[6:9], v[170:173], v[210:213], v[6:9]
	v_mfma_f32_16x16x32_bf16 v[2:5], v[178:181], v[210:213], v[2:5]
	s_setprio 0
	s_barrier
	ds_read_b128 v[150:153], v147
	ds_read_b128 v[154:157], v147 offset:1024
	ds_read_b128 v[158:161], v147 offset:2048
	ds_read_b128 v[162:165], v147 offset:3072
	ds_read_b128 v[166:169], v148
	ds_read_b128 v[170:173], v148 offset:1024
	ds_read_b128 v[174:177], v148 offset:2048
	ds_read_b128 v[178:181], v148 offset:3072
	s_mov_b32 m0, s28
	v_lshl_add_u64 v[222:223], v[214:215], 0, s[18:19]
	ds_read_b128 v[182:185], v143 offset:32768
	ds_read_b128 v[186:189], v143 offset:33792
	ds_read_b128 v[190:193], v143 offset:34816
	ds_read_b128 v[194:197], v143 offset:35840
	ds_read_b128 v[198:201], v143 offset:36864
	ds_read_b128 v[202:205], v143 offset:37888
	ds_read_b128 v[206:209], v143 offset:38912
	ds_read_b128 v[210:213], v143 offset:39936
	global_load_lds_dwordx4 v[222:223], off
	v_lshl_add_u64 v[222:223], v[216:217], 0, s[18:19]
	s_mov_b32 m0, s29
	v_lshl_add_u64 v[214:215], v[214:215], 0, s[22:23]
	global_load_lds_dwordx4 v[222:223], off
	s_mov_b32 m0, s33
	s_nop 0
	global_load_lds_dwordx4 v[214:215], off
	v_lshl_add_u64 v[214:215], v[216:217], 0, s[22:23]
	s_mov_b32 m0, s36
	s_nop 0
	global_load_lds_dwordx4 v[214:215], off
	s_waitcnt vmcnt(8)
	s_waitcnt lgkmcnt(0)
	s_setprio 1
	s_barrier
	v_mfma_f32_16x16x32_bf16 v[126:129], v[150:153], v[182:185], v[126:129]
	v_mfma_f32_16x16x32_bf16 v[122:125], v[158:161], v[182:185], v[122:125]
	v_mfma_f32_16x16x32_bf16 v[118:121], v[150:153], v[190:193], v[118:121]
	v_mfma_f32_16x16x32_bf16 v[114:117], v[158:161], v[190:193], v[114:117]
	v_mfma_f32_16x16x32_bf16 v[110:113], v[150:153], v[198:201], v[110:113]
	v_mfma_f32_16x16x32_bf16 v[106:109], v[158:161], v[198:201], v[106:109]
	v_mfma_f32_16x16x32_bf16 v[102:105], v[150:153], v[206:209], v[102:105]
	v_mfma_f32_16x16x32_bf16 v[98:101], v[158:161], v[206:209], v[98:101]
	v_mfma_f32_16x16x32_bf16 v[126:129], v[154:157], v[186:189], v[126:129]
	v_mfma_f32_16x16x32_bf16 v[122:125], v[162:165], v[186:189], v[122:125]
	v_mfma_f32_16x16x32_bf16 v[118:121], v[154:157], v[194:197], v[118:121]
	v_mfma_f32_16x16x32_bf16 v[114:117], v[162:165], v[194:197], v[114:117]
	v_mfma_f32_16x16x32_bf16 v[110:113], v[154:157], v[202:205], v[110:113]
	v_mfma_f32_16x16x32_bf16 v[106:109], v[162:165], v[202:205], v[106:109]
	v_mfma_f32_16x16x32_bf16 v[102:105], v[154:157], v[210:213], v[102:105]
	v_mfma_f32_16x16x32_bf16 v[98:101], v[162:165], v[210:213], v[98:101]
	v_mfma_f32_16x16x32_bf16 v[94:97], v[166:169], v[182:185], v[94:97]
	v_mfma_f32_16x16x32_bf16 v[90:93], v[174:177], v[182:185], v[90:93]
	v_mfma_f32_16x16x32_bf16 v[86:89], v[166:169], v[190:193], v[86:89]
	v_mfma_f32_16x16x32_bf16 v[82:85], v[174:177], v[190:193], v[82:85]
	v_mfma_f32_16x16x32_bf16 v[78:81], v[166:169], v[198:201], v[78:81]
	v_mfma_f32_16x16x32_bf16 v[74:77], v[174:177], v[198:201], v[74:77]
	v_mfma_f32_16x16x32_bf16 v[70:73], v[166:169], v[206:209], v[70:73]
	v_mfma_f32_16x16x32_bf16 v[66:69], v[174:177], v[206:209], v[66:69]
	v_mfma_f32_16x16x32_bf16 v[94:97], v[170:173], v[186:189], v[94:97]
	v_mfma_f32_16x16x32_bf16 v[90:93], v[178:181], v[186:189], v[90:93]
	v_mfma_f32_16x16x32_bf16 v[86:89], v[170:173], v[194:197], v[86:89]
	v_mfma_f32_16x16x32_bf16 v[82:85], v[178:181], v[194:197], v[82:85]
	v_mfma_f32_16x16x32_bf16 v[78:81], v[170:173], v[202:205], v[78:81]
	v_mfma_f32_16x16x32_bf16 v[74:77], v[178:181], v[202:205], v[74:77]
	v_mfma_f32_16x16x32_bf16 v[70:73], v[170:173], v[210:213], v[70:73]
	v_mfma_f32_16x16x32_bf16 v[66:69], v[178:181], v[210:213], v[66:69]
	s_setprio 0
	s_barrier
	s_mov_b32 m0, s46
	v_lshl_add_u64 v[214:215], v[218:219], 0, s[30:31]
	ds_read_b128 v[182:185], v143 offset:49152
	ds_read_b128 v[186:189], v143 offset:50176
	ds_read_b128 v[190:193], v143 offset:51200
	ds_read_b128 v[194:197], v143 offset:52224
	ds_read_b128 v[198:201], v143 offset:53248
	ds_read_b128 v[202:205], v143 offset:54272
	ds_read_b128 v[206:209], v143 offset:55296
	ds_read_b128 v[210:213], v143 offset:56320
	global_load_lds_dwordx4 v[214:215], off
	v_lshl_add_u64 v[214:215], v[220:221], 0, s[30:31]
	s_mov_b32 m0, s47
	s_nop 0
	global_load_lds_dwordx4 v[214:215], off
	v_lshl_add_u64 v[214:215], v[218:219], 0, s[34:35]
	s_mov_b32 m0, s48
	s_nop 0
	global_load_lds_dwordx4 v[214:215], off
	v_lshl_add_u64 v[214:215], v[220:221], 0, s[34:35]
	s_mov_b32 m0, s49
	s_nop 0
	global_load_lds_dwordx4 v[214:215], off
	s_waitcnt vmcnt(4)
	s_waitcnt lgkmcnt(0)
	s_setprio 1
	s_barrier
	v_mfma_f32_16x16x32_bf16 v[62:65], v[150:153], v[182:185], v[62:65]
	v_mfma_f32_16x16x32_bf16 v[58:61], v[158:161], v[182:185], v[58:61]
	v_mfma_f32_16x16x32_bf16 v[54:57], v[150:153], v[190:193], v[54:57]
	v_mfma_f32_16x16x32_bf16 v[50:53], v[158:161], v[190:193], v[50:53]
	v_mfma_f32_16x16x32_bf16 v[46:49], v[150:153], v[198:201], v[46:49]
	v_mfma_f32_16x16x32_bf16 v[42:45], v[158:161], v[198:201], v[42:45]
	v_mfma_f32_16x16x32_bf16 v[38:41], v[150:153], v[206:209], v[38:41]
	v_mfma_f32_16x16x32_bf16 v[34:37], v[158:161], v[206:209], v[34:37]
	v_mfma_f32_16x16x32_bf16 v[62:65], v[154:157], v[186:189], v[62:65]
	v_mfma_f32_16x16x32_bf16 v[58:61], v[162:165], v[186:189], v[58:61]
	v_mfma_f32_16x16x32_bf16 v[54:57], v[154:157], v[194:197], v[54:57]
	v_mfma_f32_16x16x32_bf16 v[50:53], v[162:165], v[194:197], v[50:53]
	v_mfma_f32_16x16x32_bf16 v[46:49], v[154:157], v[202:205], v[46:49]
	v_mfma_f32_16x16x32_bf16 v[42:45], v[162:165], v[202:205], v[42:45]
	v_mfma_f32_16x16x32_bf16 v[38:41], v[154:157], v[210:213], v[38:41]
	v_mfma_f32_16x16x32_bf16 v[34:37], v[162:165], v[210:213], v[34:37]
	v_mfma_f32_16x16x32_bf16 v[30:33], v[166:169], v[182:185], v[30:33]
	v_mfma_f32_16x16x32_bf16 v[26:29], v[174:177], v[182:185], v[26:29]
	v_mfma_f32_16x16x32_bf16 v[22:25], v[166:169], v[190:193], v[22:25]
	v_mfma_f32_16x16x32_bf16 v[18:21], v[174:177], v[190:193], v[18:21]
	v_mfma_f32_16x16x32_bf16 v[14:17], v[166:169], v[198:201], v[14:17]
	v_mfma_f32_16x16x32_bf16 v[10:13], v[174:177], v[198:201], v[10:13]
	v_mfma_f32_16x16x32_bf16 v[6:9], v[166:169], v[206:209], v[6:9]
	v_mfma_f32_16x16x32_bf16 v[2:5], v[174:177], v[206:209], v[2:5]
	v_mfma_f32_16x16x32_bf16 v[30:33], v[170:173], v[186:189], v[30:33]
	v_mfma_f32_16x16x32_bf16 v[26:29], v[178:181], v[186:189], v[26:29]
	v_mfma_f32_16x16x32_bf16 v[22:25], v[170:173], v[194:197], v[22:25]
	v_mfma_f32_16x16x32_bf16 v[18:21], v[178:181], v[194:197], v[18:21]
	v_mfma_f32_16x16x32_bf16 v[14:17], v[170:173], v[202:205], v[14:17]
	v_mfma_f32_16x16x32_bf16 v[10:13], v[178:181], v[202:205], v[10:13]
	v_mfma_f32_16x16x32_bf16 v[6:9], v[170:173], v[210:213], v[6:9]
	v_mfma_f32_16x16x32_bf16 v[2:5], v[178:181], v[210:213], v[2:5]
	s_setprio 0
	s_barrier
	s_add_i32 s41, s41, 2
	s_add_u32 s4, s4, 0x100
	s_addc_u32 s5, s5, 0
	s_cmp_gt_u32 s41, 3
	s_cbranch_scc0 .LBB0_641
	v_add_u32_e32 v212, 0, v144
	v_add_u32_e32 v148, 0x10000, v212
	v_add_u32_e32 v164, 0x14000, v212
	ds_read_b128 v[134:137], v148
	ds_read_b128 v[138:141], v148 offset:1024
	ds_read_b128 v[144:147], v148 offset:2048
	ds_read_b128 v[148:151], v148 offset:3072
	ds_read_b128 v[152:155], v164
	ds_read_b128 v[156:159], v164 offset:1024
	ds_read_b128 v[160:163], v164 offset:2048
	ds_read_b128 v[164:167], v164 offset:3072
	s_add_u32 s4, s8, 0x3200380
	s_addc_u32 s5, s9, 0
	s_add_u32 s6, s8, 0x3220380
	s_addc_u32 s7, s9, 0
	s_cmpk_lt_u32 s21, 0x100
	s_mov_b32 m0, s40
	v_lshl_add_u64 v[200:201], s[4:5], 0, v[130:131]
	ds_read_b128 v[168:171], v143
	ds_read_b128 v[172:175], v143 offset:1024
	ds_read_b128 v[176:179], v143 offset:2048
	ds_read_b128 v[180:183], v143 offset:3072
	ds_read_b128 v[184:187], v143 offset:4096
	ds_read_b128 v[188:191], v143 offset:5120
	ds_read_b128 v[192:195], v143 offset:6144
	ds_read_b128 v[196:199], v143 offset:7168
	global_load_lds_dwordx4 v[200:201], off
	v_lshl_add_u64 v[200:201], s[4:5], 0, v[132:133]
	s_mov_b32 m0, s39
	v_lshl_add_u64 v[130:131], s[6:7], 0, v[130:131]
	global_load_lds_dwordx4 v[200:201], off
	s_mov_b32 m0, s38
	s_nop 0
	global_load_lds_dwordx4 v[130:131], off
	v_lshl_add_u64 v[130:131], s[6:7], 0, v[132:133]
	s_mov_b32 m0, s37
	s_nop 0
	global_load_lds_dwordx4 v[130:131], off
	s_waitcnt vmcnt(8)
	s_waitcnt lgkmcnt(0)
	s_setprio 1
	s_barrier
	v_mfma_f32_16x16x32_bf16 v[126:129], v[134:137], v[168:171], v[126:129]
	v_mfma_f32_16x16x32_bf16 v[118:121], v[134:137], v[176:179], v[118:121]
	v_mfma_f32_16x16x32_bf16 v[110:113], v[134:137], v[184:187], v[110:113]
	v_mfma_f32_16x16x32_bf16 v[102:105], v[134:137], v[192:195], v[102:105]
	v_mfma_f32_16x16x32_bf16 v[126:129], v[138:141], v[172:175], v[126:129]
	v_mfma_f32_16x16x32_bf16 v[122:125], v[144:147], v[168:171], v[122:125]
	v_mfma_f32_16x16x32_bf16 v[118:121], v[138:141], v[180:183], v[118:121]
	v_mfma_f32_16x16x32_bf16 v[114:117], v[144:147], v[176:179], v[114:117]
	v_mfma_f32_16x16x32_bf16 v[110:113], v[138:141], v[188:191], v[110:113]
	v_mfma_f32_16x16x32_bf16 v[106:109], v[144:147], v[184:187], v[106:109]
	v_mfma_f32_16x16x32_bf16 v[102:105], v[138:141], v[196:199], v[102:105]
	v_mfma_f32_16x16x32_bf16 v[98:101], v[144:147], v[192:195], v[98:101]
	v_mfma_f32_16x16x32_bf16 v[130:133], v[148:151], v[172:175], v[122:125]
	v_mfma_f32_16x16x32_bf16 v[200:203], v[148:151], v[180:183], v[114:117]
	v_mfma_f32_16x16x32_bf16 v[204:207], v[148:151], v[188:191], v[106:109]
	v_mfma_f32_16x16x32_bf16 v[208:211], v[148:151], v[196:199], v[98:101]
	v_mfma_f32_16x16x32_bf16 v[94:97], v[152:155], v[168:171], v[94:97]
	v_mfma_f32_16x16x32_bf16 v[86:89], v[152:155], v[176:179], v[86:89]
	v_mfma_f32_16x16x32_bf16 v[78:81], v[152:155], v[184:187], v[78:81]
	v_mfma_f32_16x16x32_bf16 v[70:73], v[152:155], v[192:195], v[70:73]
	v_mfma_f32_16x16x32_bf16 v[66:69], v[160:163], v[192:195], v[66:69]
	v_mfma_f32_16x16x32_bf16 v[94:97], v[156:159], v[172:175], v[94:97]
	v_mfma_f32_16x16x32_bf16 v[90:93], v[160:163], v[168:171], v[90:93]
	v_mfma_f32_16x16x32_bf16 v[86:89], v[156:159], v[180:183], v[86:89]
	v_mfma_f32_16x16x32_bf16 v[82:85], v[160:163], v[176:179], v[82:85]
	v_mfma_f32_16x16x32_bf16 v[78:81], v[156:159], v[188:191], v[78:81]
	v_mfma_f32_16x16x32_bf16 v[74:77], v[160:163], v[184:187], v[74:77]
	v_mfma_f32_16x16x32_bf16 v[70:73], v[156:159], v[196:199], v[70:73]
	v_mfma_f32_16x16x32_bf16 v[66:69], v[164:167], v[196:199], v[66:69]
	v_mfma_f32_16x16x32_bf16 v[168:171], v[164:167], v[172:175], v[90:93]
	v_mfma_f32_16x16x32_bf16 v[172:175], v[164:167], v[180:183], v[82:85]
	v_mfma_f32_16x16x32_bf16 v[176:179], v[164:167], v[188:191], v[74:77]
	s_setprio 0
	s_barrier
	s_nop 0
	ds_read_b128 v[74:77], v143 offset:16384
	ds_read_b128 v[82:85], v143 offset:17408
	ds_read_b128 v[90:93], v143 offset:18432
	ds_read_b128 v[98:101], v143 offset:19456
	ds_read_b128 v[106:109], v143 offset:20480
	ds_read_b128 v[114:117], v143 offset:21504
	ds_read_b128 v[122:125], v143 offset:22528
	ds_read_b128 v[180:183], v143 offset:23552
	s_waitcnt vmcnt(0)
	s_waitcnt lgkmcnt(0)
	s_setprio 1
	s_barrier
	v_mfma_f32_16x16x32_bf16 v[54:57], v[134:137], v[90:93], v[54:57]
	v_mfma_f32_16x16x32_bf16 v[46:49], v[134:137], v[106:109], v[46:49]
	v_mfma_f32_16x16x32_bf16 v[38:41], v[134:137], v[122:125], v[38:41]
	v_mfma_f32_16x16x32_bf16 v[62:65], v[134:137], v[74:77], v[62:65]
	v_mfma_f32_16x16x32_bf16 v[58:61], v[144:147], v[74:77], v[58:61]
	v_mfma_f32_16x16x32_bf16 v[54:57], v[138:141], v[98:101], v[54:57]
	v_mfma_f32_16x16x32_bf16 v[50:53], v[144:147], v[90:93], v[50:53]
	v_mfma_f32_16x16x32_bf16 v[46:49], v[138:141], v[114:117], v[46:49]
	v_mfma_f32_16x16x32_bf16 v[42:45], v[144:147], v[106:109], v[42:45]
	v_mfma_f32_16x16x32_bf16 v[38:41], v[138:141], v[180:183], v[38:41]
	v_mfma_f32_16x16x32_bf16 v[34:37], v[144:147], v[122:125], v[34:37]
	v_mfma_f32_16x16x32_bf16 v[184:187], v[138:141], v[82:85], v[62:65]
	v_mfma_f32_16x16x32_bf16 v[188:191], v[148:151], v[82:85], v[58:61]
	v_mfma_f32_16x16x32_bf16 v[192:195], v[148:151], v[98:101], v[50:53]
	v_mfma_f32_16x16x32_bf16 v[196:199], v[148:151], v[114:117], v[42:45]
	v_mfma_f32_16x16x32_bf16 v[134:137], v[148:151], v[180:183], v[34:37]
	v_mfma_f32_16x16x32_bf16 v[30:33], v[152:155], v[74:77], v[30:33]
	v_mfma_f32_16x16x32_bf16 v[22:25], v[152:155], v[90:93], v[22:25]
	v_mfma_f32_16x16x32_bf16 v[14:17], v[152:155], v[106:109], v[14:17]
	v_mfma_f32_16x16x32_bf16 v[6:9], v[152:155], v[122:125], v[6:9]
	v_mfma_f32_16x16x32_bf16 v[30:33], v[156:159], v[82:85], v[30:33]
	v_mfma_f32_16x16x32_bf16 v[26:29], v[160:163], v[74:77], v[26:29]
	v_mfma_f32_16x16x32_bf16 v[22:25], v[156:159], v[98:101], v[22:25]
	v_mfma_f32_16x16x32_bf16 v[18:21], v[160:163], v[90:93], v[18:21]
	v_mfma_f32_16x16x32_bf16 v[14:17], v[156:159], v[114:117], v[14:17]
	v_mfma_f32_16x16x32_bf16 v[10:13], v[160:163], v[106:109], v[10:13]
	v_mfma_f32_16x16x32_bf16 v[6:9], v[156:159], v[180:183], v[6:9]
	v_mfma_f32_16x16x32_bf16 v[2:5], v[160:163], v[122:125], v[2:5]
	v_mfma_f32_16x16x32_bf16 v[138:141], v[164:167], v[82:85], v[26:29]
	v_mfma_f32_16x16x32_bf16 v[144:147], v[164:167], v[98:101], v[18:21]
	v_mfma_f32_16x16x32_bf16 v[148:151], v[164:167], v[114:117], v[10:13]
	v_mfma_f32_16x16x32_bf16 v[152:155], v[164:167], v[180:183], v[2:5]
	s_setprio 0
	s_barrier
	v_add_u32_e32 v18, 0x18000, v212
	s_nop 0
	ds_read_b128 v[2:5], v18
	ds_read_b128 v[10:13], v18 offset:1024
	ds_read_b128 v[156:159], v18 offset:2048
	ds_read_b128 v[160:163], v18 offset:3072
	v_add_u32_e32 v18, 0x1c000, v212
	ds_read_b128 v[164:167], v18
	ds_read_b128 v[180:183], v18 offset:1024
	ds_read_b128 v[212:215], v18 offset:2048
	ds_read_b128 v[216:219], v18 offset:3072
	ds_read_b128 v[18:21], v143 offset:32768
	ds_read_b128 v[26:29], v143 offset:33792
	ds_read_b128 v[34:37], v143 offset:34816
	ds_read_b128 v[42:45], v143 offset:35840
	ds_read_b128 v[50:53], v143 offset:36864
	ds_read_b128 v[62:65], v143 offset:37888
	ds_read_b128 v[220:223], v143 offset:38912
	ds_read_b128 v[224:227], v143 offset:39936
	s_waitcnt lgkmcnt(0)
	s_setprio 1
	s_barrier
	v_mfma_f32_16x16x32_bf16 v[58:61], v[2:5], v[18:21], v[126:129]
	v_mfma_f32_16x16x32_bf16 v[122:125], v[10:13], v[26:29], v[58:61]
	v_mfma_f32_16x16x32_bf16 v[58:61], v[156:159], v[18:21], v[130:133]
	v_mfma_f32_16x16x32_bf16 v[114:117], v[160:163], v[26:29], v[58:61]
	v_mfma_f32_16x16x32_bf16 v[58:61], v[2:5], v[34:37], v[118:121]
	v_mfma_f32_16x16x32_bf16 v[106:109], v[10:13], v[42:45], v[58:61]
	v_mfma_f32_16x16x32_bf16 v[58:61], v[156:159], v[34:37], v[200:203]
	v_mfma_f32_16x16x32_bf16 v[98:101], v[160:163], v[42:45], v[58:61]
	v_mfma_f32_16x16x32_bf16 v[58:61], v[2:5], v[50:53], v[110:113]
	v_mfma_f32_16x16x32_bf16 v[90:93], v[10:13], v[62:65], v[58:61]
	v_mfma_f32_16x16x32_bf16 v[58:61], v[156:159], v[50:53], v[204:207]
	v_mfma_f32_16x16x32_bf16 v[82:85], v[160:163], v[62:65], v[58:61]
	v_mfma_f32_16x16x32_bf16 v[58:61], v[2:5], v[220:223], v[102:105]
	v_mfma_f32_16x16x32_bf16 v[74:77], v[10:13], v[224:227], v[58:61]
	v_mfma_f32_16x16x32_bf16 v[58:61], v[156:159], v[220:223], v[208:211]
	v_mfma_f32_16x16x32_bf16 v[58:61], v[160:163], v[224:227], v[58:61]
	v_mfma_f32_16x16x32_bf16 v[94:97], v[164:167], v[18:21], v[94:97]
	v_mfma_f32_16x16x32_bf16 v[18:21], v[212:215], v[18:21], v[168:171]
	v_mfma_f32_16x16x32_bf16 v[118:121], v[216:219], v[26:29], v[18:21]
	v_mfma_f32_16x16x32_bf16 v[18:21], v[164:167], v[34:37], v[86:89]
	v_mfma_f32_16x16x32_bf16 v[110:113], v[180:183], v[42:45], v[18:21]
	v_mfma_f32_16x16x32_bf16 v[18:21], v[212:215], v[34:37], v[172:175]
	v_mfma_f32_16x16x32_bf16 v[102:105], v[216:219], v[42:45], v[18:21]
	v_mfma_f32_16x16x32_bf16 v[18:21], v[164:167], v[50:53], v[78:81]
	v_mfma_f32_16x16x32_bf16 v[126:129], v[180:183], v[26:29], v[94:97]
	v_mfma_f32_16x16x32_bf16 v[94:97], v[180:183], v[62:65], v[18:21]
	v_mfma_f32_16x16x32_bf16 v[18:21], v[212:215], v[50:53], v[176:179]
	v_mfma_f32_16x16x32_bf16 v[86:89], v[216:219], v[62:65], v[18:21]
	v_mfma_f32_16x16x32_bf16 v[18:21], v[164:167], v[220:223], v[70:73]
	v_mfma_f32_16x16x32_bf16 v[78:81], v[180:183], v[224:227], v[18:21]
	v_mfma_f32_16x16x32_bf16 v[18:21], v[212:215], v[220:223], v[66:69]
	v_mfma_f32_16x16x32_bf16 v[62:65], v[216:219], v[224:227], v[18:21]
	s_setprio 0
	s_barrier
	ds_read_b128 v[130:133], v143 offset:49152
	ds_read_b128 v[168:171], v143 offset:50176
	ds_read_b128 v[172:175], v143 offset:51200
	ds_read_b128 v[176:179], v143 offset:52224
	ds_read_b128 v[200:203], v143 offset:53248
	ds_read_b128 v[204:207], v143 offset:54272
	ds_read_b128 v[208:211], v143 offset:55296
	ds_read_b128 v[220:223], v143 offset:56320
	s_waitcnt lgkmcnt(0)
	s_setprio 1
	s_barrier
	v_mfma_f32_16x16x32_bf16 v[18:21], v[2:5], v[130:133], v[184:187]
	v_mfma_f32_16x16x32_bf16 v[66:69], v[10:13], v[168:171], v[18:21]
	v_mfma_f32_16x16x32_bf16 v[18:21], v[156:159], v[130:133], v[188:191]
	v_mfma_f32_16x16x32_bf16 v[50:53], v[160:163], v[168:171], v[18:21]
	v_mfma_f32_16x16x32_bf16 v[18:21], v[2:5], v[172:175], v[54:57]
	v_mfma_f32_16x16x32_bf16 v[42:45], v[10:13], v[176:179], v[18:21]
	v_mfma_f32_16x16x32_bf16 v[18:21], v[156:159], v[172:175], v[192:195]
	v_mfma_f32_16x16x32_bf16 v[34:37], v[160:163], v[176:179], v[18:21]
	v_mfma_f32_16x16x32_bf16 v[18:21], v[2:5], v[200:203], v[46:49]
	v_mfma_f32_16x16x32_bf16 v[2:5], v[2:5], v[208:211], v[38:41]
	v_mfma_f32_16x16x32_bf16 v[26:29], v[10:13], v[204:207], v[18:21]
	v_mfma_f32_16x16x32_bf16 v[18:21], v[156:159], v[200:203], v[196:199]
	v_mfma_f32_16x16x32_bf16 v[10:13], v[10:13], v[220:223], v[2:5]
	v_mfma_f32_16x16x32_bf16 v[2:5], v[156:159], v[208:211], v[134:137]
	v_mfma_f32_16x16x32_bf16 v[18:21], v[160:163], v[204:207], v[18:21]
	v_mfma_f32_16x16x32_bf16 v[2:5], v[160:163], v[220:223], v[2:5]
	v_mfma_f32_16x16x32_bf16 v[30:33], v[164:167], v[130:133], v[30:33]
	v_mfma_f32_16x16x32_bf16 v[70:73], v[180:183], v[168:171], v[30:33]
	v_mfma_f32_16x16x32_bf16 v[30:33], v[212:215], v[130:133], v[138:141]
	v_mfma_f32_16x16x32_bf16 v[22:25], v[164:167], v[172:175], v[22:25]
	v_mfma_f32_16x16x32_bf16 v[14:17], v[164:167], v[200:203], v[14:17]
	v_mfma_f32_16x16x32_bf16 v[54:57], v[216:219], v[168:171], v[30:33]
	v_mfma_f32_16x16x32_bf16 v[46:49], v[180:183], v[176:179], v[22:25]
	v_mfma_f32_16x16x32_bf16 v[22:25], v[212:215], v[172:175], v[144:147]
	v_mfma_f32_16x16x32_bf16 v[30:33], v[180:183], v[204:207], v[14:17]
	v_mfma_f32_16x16x32_bf16 v[14:17], v[212:215], v[200:203], v[148:151]
	v_mfma_f32_16x16x32_bf16 v[6:9], v[164:167], v[208:211], v[6:9]
	v_mfma_f32_16x16x32_bf16 v[38:41], v[216:219], v[176:179], v[22:25]
	v_mfma_f32_16x16x32_bf16 v[22:25], v[216:219], v[204:207], v[14:17]
	v_mfma_f32_16x16x32_bf16 v[14:17], v[180:183], v[220:223], v[6:9]
	v_mfma_f32_16x16x32_bf16 v[6:9], v[212:215], v[208:211], v[152:155]
	v_mfma_f32_16x16x32_bf16 v[6:9], v[216:219], v[220:223], v[6:9]
	s_setprio 0
	s_barrier
	s_cbranch_scc0 .LBB0_644
	s_barrier

.LBB0_707:
	v_add_u32_e32 v11, s38, v152
	s_add_i32 s24, s24, 2
	ds_read_b128 v[156:159], v11
	ds_read_b128 v[160:163], v11 offset:1024
	ds_read_b128 v[164:167], v11 offset:2048
	ds_read_b128 v[172:175], v11 offset:3072
	v_add_u32_e32 v11, s39, v152
	s_add_u32 s25, s14, s60
	ds_read_b128 v[176:179], v11
	ds_read_b128 v[180:183], v11 offset:1024
	ds_read_b128 v[184:187], v11 offset:2048
	ds_read_b128 v[188:191], v11 offset:3072
	s_addc_u32 s26, s15, s61
	s_add_u32 s25, s25, 0x100
	s_addc_u32 s26, s26, 0
	s_add_u32 s27, s45, s60
	s_addc_u32 s49, s47, s61
	s_cmpk_eq_i32 s60, 0x700
	s_cselect_b32 s63, s59, s49
	s_cselect_b32 s62, s58, s27
	s_cselect_b32 s65, s57, s26
	s_cselect_b32 s64, s56, s25
	v_lshl_add_u64 v[168:169], v[150:151], 0, s[60:61]
	s_add_i32 s49, s29, 0x8000
	v_lshl_add_u64 v[224:225], v[168:169], 0, s[22:23]
	s_mov_b32 m0, s49
	ds_read_b128 v[192:195], v155
	ds_read_b128 v[196:199], v155 offset:1024
	ds_read_b128 v[200:203], v155 offset:2048
	ds_read_b128 v[204:207], v155 offset:3072
	ds_read_b128 v[208:211], v155 offset:4096
	ds_read_b128 v[212:215], v155 offset:5120
	ds_read_b128 v[216:219], v155 offset:6144
	ds_read_b128 v[220:223], v155 offset:7168
	global_load_lds_dwordx4 v[224:225], off
	v_lshl_add_u64 v[224:225], v[12:13], 0, s[60:61]
	s_add_i32 s27, s29, 0xa000
	v_lshl_add_u64 v[226:227], v[224:225], 0, s[22:23]
	s_mov_b32 m0, s27
	s_add_i32 s25, s29, 0xc000
	global_load_lds_dwordx4 v[226:227], off
	v_lshl_add_u64 v[168:169], v[168:169], 0, s[30:31]
	s_mov_b32 m0, s25
	s_add_i32 s26, s29, 0xe000
	global_load_lds_dwordx4 v[168:169], off
	v_lshl_add_u64 v[168:169], v[224:225], 0, s[30:31]
	s_mov_b32 m0, s26
	s_nop 0
	global_load_lds_dwordx4 v[168:169], off
	s_waitcnt vmcnt(8)
	s_waitcnt lgkmcnt(0)
	s_setprio 1
	s_barrier
	v_mfma_f32_16x16x32_bf16 v[126:129], v[156:159], v[192:195], v[126:129]
	v_mfma_f32_16x16x32_bf16 v[122:125], v[164:167], v[192:195], v[122:125]
	v_mfma_f32_16x16x32_bf16 v[110:113], v[156:159], v[200:203], v[110:113]
	v_mfma_f32_16x16x32_bf16 v[106:109], v[164:167], v[200:203], v[106:109]
	v_mfma_f32_16x16x32_bf16 v[94:97], v[156:159], v[208:211], v[94:97]
	v_mfma_f32_16x16x32_bf16 v[90:93], v[164:167], v[208:211], v[90:93]
	v_mfma_f32_16x16x32_bf16 v[78:81], v[156:159], v[216:219], v[78:81]
	v_mfma_f32_16x16x32_bf16 v[74:77], v[164:167], v[216:219], v[74:77]
	v_mfma_f32_16x16x32_bf16 v[126:129], v[160:163], v[196:199], v[126:129]
	v_mfma_f32_16x16x32_bf16 v[122:125], v[172:175], v[196:199], v[122:125]
	v_mfma_f32_16x16x32_bf16 v[110:113], v[160:163], v[204:207], v[110:113]
	v_mfma_f32_16x16x32_bf16 v[106:109], v[172:175], v[204:207], v[106:109]
	v_mfma_f32_16x16x32_bf16 v[94:97], v[160:163], v[212:215], v[94:97]
	v_mfma_f32_16x16x32_bf16 v[90:93], v[172:175], v[212:215], v[90:93]
	v_mfma_f32_16x16x32_bf16 v[78:81], v[160:163], v[220:223], v[78:81]
	v_mfma_f32_16x16x32_bf16 v[74:77], v[172:175], v[220:223], v[74:77]
	v_mfma_f32_16x16x32_bf16 v[62:65], v[176:179], v[192:195], v[62:65]
	v_mfma_f32_16x16x32_bf16 v[58:61], v[184:187], v[192:195], v[58:61]
	v_mfma_f32_16x16x32_bf16 v[46:49], v[176:179], v[200:203], v[46:49]
	v_mfma_f32_16x16x32_bf16 v[42:45], v[184:187], v[200:203], v[42:45]
	v_mfma_f32_16x16x32_bf16 v[30:33], v[176:179], v[208:211], v[30:33]
	v_mfma_f32_16x16x32_bf16 v[26:29], v[184:187], v[208:211], v[26:29]
	v_mfma_f32_16x16x32_bf16 v[14:17], v[176:179], v[216:219], v[14:17]
	v_mfma_f32_16x16x32_bf16 v[130:133], v[184:187], v[216:219], v[130:133]
	v_mfma_f32_16x16x32_bf16 v[62:65], v[180:183], v[196:199], v[62:65]
	v_mfma_f32_16x16x32_bf16 v[58:61], v[188:191], v[196:199], v[58:61]
	v_mfma_f32_16x16x32_bf16 v[46:49], v[180:183], v[204:207], v[46:49]
	v_mfma_f32_16x16x32_bf16 v[42:45], v[188:191], v[204:207], v[42:45]
	v_mfma_f32_16x16x32_bf16 v[30:33], v[180:183], v[212:215], v[30:33]
	v_mfma_f32_16x16x32_bf16 v[26:29], v[188:191], v[212:215], v[26:29]
	v_mfma_f32_16x16x32_bf16 v[14:17], v[180:183], v[220:223], v[14:17]
	v_mfma_f32_16x16x32_bf16 v[130:133], v[188:191], v[220:223], v[130:133]
	s_setprio 0
	s_barrier
	s_add_i32 s51, s38, s11
	v_lshl_add_u64 v[168:169], s[62:63], 0, v[136:137]
	s_mov_b32 m0, s51
	ds_read_b128 v[192:195], v155 offset:16384
	ds_read_b128 v[196:199], v155 offset:17408
	ds_read_b128 v[200:203], v155 offset:18432
	ds_read_b128 v[204:207], v155 offset:19456
	ds_read_b128 v[208:211], v155 offset:20480
	ds_read_b128 v[212:215], v155 offset:21504
	ds_read_b128 v[216:219], v155 offset:22528
	ds_read_b128 v[220:223], v155 offset:23552
	global_load_lds_dwordx4 v[168:169], off
	s_add_i32 m0, s51, 0x2000
	s_add_u32 s66, s62, 0x40000
	v_lshl_add_u64 v[224:225], s[62:63], 0, v[140:141]
	s_addc_u32 s67, s63, 0
	s_add_i32 s51, s39, s11
	global_load_lds_dwordx4 v[224:225], off
	v_lshl_add_u64 v[226:227], s[66:67], 0, v[136:137]
	s_mov_b32 m0, s51
	s_nop 0
	global_load_lds_dwordx4 v[226:227], off
	v_lshl_add_u64 v[226:227], s[66:67], 0, v[140:141]
	s_add_i32 m0, s51, 0x2000
	s_nop 0
	global_load_lds_dwordx4 v[226:227], off
	s_waitcnt vmcnt(4)
	s_waitcnt lgkmcnt(0)
	s_setprio 1
	s_barrier
	v_mfma_f32_16x16x32_bf16 v[118:121], v[156:159], v[192:195], v[118:121]
	v_mfma_f32_16x16x32_bf16 v[114:117], v[164:167], v[192:195], v[114:117]
	v_mfma_f32_16x16x32_bf16 v[102:105], v[156:159], v[200:203], v[102:105]
	v_mfma_f32_16x16x32_bf16 v[98:101], v[164:167], v[200:203], v[98:101]
	v_mfma_f32_16x16x32_bf16 v[86:89], v[156:159], v[208:211], v[86:89]
	v_mfma_f32_16x16x32_bf16 v[82:85], v[164:167], v[208:211], v[82:85]
	v_mfma_f32_16x16x32_bf16 v[70:73], v[156:159], v[216:219], v[70:73]
	v_mfma_f32_16x16x32_bf16 v[66:69], v[164:167], v[216:219], v[66:69]
	v_mfma_f32_16x16x32_bf16 v[118:121], v[160:163], v[196:199], v[118:121]
	v_mfma_f32_16x16x32_bf16 v[114:117], v[172:175], v[196:199], v[114:117]
	v_mfma_f32_16x16x32_bf16 v[102:105], v[160:163], v[204:207], v[102:105]
	v_mfma_f32_16x16x32_bf16 v[98:101], v[172:175], v[204:207], v[98:101]
	v_mfma_f32_16x16x32_bf16 v[86:89], v[160:163], v[212:215], v[86:89]
	v_mfma_f32_16x16x32_bf16 v[82:85], v[172:175], v[212:215], v[82:85]
	v_mfma_f32_16x16x32_bf16 v[70:73], v[160:163], v[220:223], v[70:73]
	v_mfma_f32_16x16x32_bf16 v[66:69], v[172:175], v[220:223], v[66:69]
	v_mfma_f32_16x16x32_bf16 v[54:57], v[176:179], v[192:195], v[54:57]
	v_mfma_f32_16x16x32_bf16 v[50:53], v[184:187], v[192:195], v[50:53]
	v_mfma_f32_16x16x32_bf16 v[38:41], v[176:179], v[200:203], v[38:41]
	v_mfma_f32_16x16x32_bf16 v[34:37], v[184:187], v[200:203], v[34:37]
	v_mfma_f32_16x16x32_bf16 v[22:25], v[176:179], v[208:211], v[22:25]
	v_mfma_f32_16x16x32_bf16 v[18:21], v[184:187], v[208:211], v[18:21]
	v_mfma_f32_16x16x32_bf16 v[6:9], v[176:179], v[216:219], v[6:9]
	v_mfma_f32_16x16x32_bf16 v[2:5], v[184:187], v[216:219], v[2:5]
	v_mfma_f32_16x16x32_bf16 v[54:57], v[180:183], v[196:199], v[54:57]
	v_mfma_f32_16x16x32_bf16 v[50:53], v[188:191], v[196:199], v[50:53]
	v_mfma_f32_16x16x32_bf16 v[38:41], v[180:183], v[204:207], v[38:41]
	v_mfma_f32_16x16x32_bf16 v[34:37], v[188:191], v[204:207], v[34:37]
	v_mfma_f32_16x16x32_bf16 v[22:25], v[180:183], v[212:215], v[22:25]
	v_mfma_f32_16x16x32_bf16 v[18:21], v[188:191], v[212:215], v[18:21]
	v_mfma_f32_16x16x32_bf16 v[6:9], v[180:183], v[220:223], v[6:9]
	v_mfma_f32_16x16x32_bf16 v[2:5], v[188:191], v[220:223], v[2:5]
	s_setprio 0
	s_barrier
	s_add_i32 s51, 0, 0x18000
	v_add_u32_e32 v11, s51, v152
	s_add_i32 s66, 0, 0x1c000
	ds_read_b128 v[156:159], v11
	ds_read_b128 v[160:163], v11 offset:1024
	ds_read_b128 v[164:167], v11 offset:2048
	ds_read_b128 v[172:175], v11 offset:3072
	v_add_u32_e32 v11, s66, v152
	ds_read_b128 v[176:179], v11
	ds_read_b128 v[180:183], v11 offset:1024
	ds_read_b128 v[184:187], v11 offset:2048
	ds_read_b128 v[188:191], v11 offset:3072
	s_mov_b32 m0, s29
	v_lshl_add_u64 v[226:227], s[64:65], 0, v[134:135]
	ds_read_b128 v[192:195], v155 offset:32768
	ds_read_b128 v[196:199], v155 offset:33792
	ds_read_b128 v[200:203], v155 offset:34816
	ds_read_b128 v[204:207], v155 offset:35840
	ds_read_b128 v[208:211], v155 offset:36864
	ds_read_b128 v[212:215], v155 offset:37888
	ds_read_b128 v[216:219], v155 offset:38912
	ds_read_b128 v[220:223], v155 offset:39936
	global_load_lds_dwordx4 v[226:227], off
	v_lshl_add_u64 v[226:227], s[64:65], 0, v[138:139]
	s_add_u32 s64, s64, 0x40000
	s_mov_b32 m0, s33
	s_addc_u32 s65, s65, 0
	global_load_lds_dwordx4 v[226:227], off
	v_lshl_add_u64 v[226:227], s[64:65], 0, v[134:135]
	s_mov_b32 m0, s36
	s_nop 0
	global_load_lds_dwordx4 v[226:227], off
	v_lshl_add_u64 v[226:227], s[64:65], 0, v[138:139]
	s_mov_b32 m0, s37
	s_nop 0
	global_load_lds_dwordx4 v[226:227], off
	s_waitcnt vmcnt(8)
	s_waitcnt lgkmcnt(0)
	s_setprio 1
	s_barrier
	v_mfma_f32_16x16x32_bf16 v[126:129], v[156:159], v[192:195], v[126:129]
	v_mfma_f32_16x16x32_bf16 v[122:125], v[164:167], v[192:195], v[122:125]
	v_mfma_f32_16x16x32_bf16 v[110:113], v[156:159], v[200:203], v[110:113]
	v_mfma_f32_16x16x32_bf16 v[106:109], v[164:167], v[200:203], v[106:109]
	v_mfma_f32_16x16x32_bf16 v[94:97], v[156:159], v[208:211], v[94:97]
	v_mfma_f32_16x16x32_bf16 v[90:93], v[164:167], v[208:211], v[90:93]
	v_mfma_f32_16x16x32_bf16 v[78:81], v[156:159], v[216:219], v[78:81]
	v_mfma_f32_16x16x32_bf16 v[74:77], v[164:167], v[216:219], v[74:77]
	v_mfma_f32_16x16x32_bf16 v[126:129], v[160:163], v[196:199], v[126:129]
	v_mfma_f32_16x16x32_bf16 v[122:125], v[172:175], v[196:199], v[122:125]
	v_mfma_f32_16x16x32_bf16 v[110:113], v[160:163], v[204:207], v[110:113]
	v_mfma_f32_16x16x32_bf16 v[106:109], v[172:175], v[204:207], v[106:109]
	v_mfma_f32_16x16x32_bf16 v[94:97], v[160:163], v[212:215], v[94:97]
	v_mfma_f32_16x16x32_bf16 v[90:93], v[172:175], v[212:215], v[90:93]
	v_mfma_f32_16x16x32_bf16 v[78:81], v[160:163], v[220:223], v[78:81]
	v_mfma_f32_16x16x32_bf16 v[74:77], v[172:175], v[220:223], v[74:77]
	v_mfma_f32_16x16x32_bf16 v[62:65], v[176:179], v[192:195], v[62:65]
	v_mfma_f32_16x16x32_bf16 v[58:61], v[184:187], v[192:195], v[58:61]
	v_mfma_f32_16x16x32_bf16 v[46:49], v[176:179], v[200:203], v[46:49]
	v_mfma_f32_16x16x32_bf16 v[42:45], v[184:187], v[200:203], v[42:45]
	v_mfma_f32_16x16x32_bf16 v[30:33], v[176:179], v[208:211], v[30:33]
	v_mfma_f32_16x16x32_bf16 v[26:29], v[184:187], v[208:211], v[26:29]
	v_mfma_f32_16x16x32_bf16 v[14:17], v[176:179], v[216:219], v[14:17]
	v_mfma_f32_16x16x32_bf16 v[130:133], v[184:187], v[216:219], v[130:133]
	v_mfma_f32_16x16x32_bf16 v[62:65], v[180:183], v[196:199], v[62:65]
	v_mfma_f32_16x16x32_bf16 v[58:61], v[188:191], v[196:199], v[58:61]
	v_mfma_f32_16x16x32_bf16 v[46:49], v[180:183], v[204:207], v[46:49]
	v_mfma_f32_16x16x32_bf16 v[42:45], v[188:191], v[204:207], v[42:45]
	v_mfma_f32_16x16x32_bf16 v[30:33], v[180:183], v[212:215], v[30:33]
	v_mfma_f32_16x16x32_bf16 v[26:29], v[188:191], v[212:215], v[26:29]
	v_mfma_f32_16x16x32_bf16 v[14:17], v[180:183], v[220:223], v[14:17]
	v_mfma_f32_16x16x32_bf16 v[130:133], v[188:191], v[220:223], v[130:133]
	s_setprio 0
	s_barrier
	s_add_i32 s51, s51, s11
	v_lshl_add_u64 v[168:169], v[168:169], 0, s[22:23]
	s_mov_b32 m0, s51
	ds_read_b128 v[192:195], v155 offset:49152
	ds_read_b128 v[196:199], v155 offset:50176
	ds_read_b128 v[200:203], v155 offset:51200
	ds_read_b128 v[204:207], v155 offset:52224
	ds_read_b128 v[208:211], v155 offset:53248
	ds_read_b128 v[212:215], v155 offset:54272
	ds_read_b128 v[216:219], v155 offset:55296
	ds_read_b128 v[220:223], v155 offset:56320
	global_load_lds_dwordx4 v[168:169], off
	s_add_i32 m0, s51, 0x2000
	s_add_u32 s62, s62, 0x40080
	v_lshl_add_u64 v[168:169], v[224:225], 0, s[22:23]
	s_addc_u32 s63, s63, 0
	s_add_i32 s51, s66, s11
	global_load_lds_dwordx4 v[168:169], off
	v_lshl_add_u64 v[168:169], s[62:63], 0, v[136:137]
	s_mov_b32 m0, s51
	s_nop 0
	global_load_lds_dwordx4 v[168:169], off
	v_lshl_add_u64 v[168:169], s[62:63], 0, v[140:141]
	s_add_i32 m0, s51, 0x2000
	s_nop 0
	global_load_lds_dwordx4 v[168:169], off
	s_waitcnt vmcnt(4)
	s_waitcnt lgkmcnt(0)
	s_setprio 1
	s_barrier
	v_mfma_f32_16x16x32_bf16 v[118:121], v[156:159], v[192:195], v[118:121]
	v_mfma_f32_16x16x32_bf16 v[114:117], v[164:167], v[192:195], v[114:117]
	v_mfma_f32_16x16x32_bf16 v[102:105], v[156:159], v[200:203], v[102:105]
	v_mfma_f32_16x16x32_bf16 v[98:101], v[164:167], v[200:203], v[98:101]
	v_mfma_f32_16x16x32_bf16 v[86:89], v[156:159], v[208:211], v[86:89]
	v_mfma_f32_16x16x32_bf16 v[82:85], v[164:167], v[208:211], v[82:85]
	v_mfma_f32_16x16x32_bf16 v[70:73], v[156:159], v[216:219], v[70:73]
	v_mfma_f32_16x16x32_bf16 v[66:69], v[164:167], v[216:219], v[66:69]
	v_mfma_f32_16x16x32_bf16 v[118:121], v[160:163], v[196:199], v[118:121]
	v_mfma_f32_16x16x32_bf16 v[114:117], v[172:175], v[196:199], v[114:117]
	v_mfma_f32_16x16x32_bf16 v[102:105], v[160:163], v[204:207], v[102:105]
	v_mfma_f32_16x16x32_bf16 v[98:101], v[172:175], v[204:207], v[98:101]
	v_mfma_f32_16x16x32_bf16 v[86:89], v[160:163], v[212:215], v[86:89]
	v_mfma_f32_16x16x32_bf16 v[82:85], v[172:175], v[212:215], v[82:85]
	v_mfma_f32_16x16x32_bf16 v[70:73], v[160:163], v[220:223], v[70:73]
	v_mfma_f32_16x16x32_bf16 v[66:69], v[172:175], v[220:223], v[66:69]
	v_mfma_f32_16x16x32_bf16 v[54:57], v[176:179], v[192:195], v[54:57]
	v_mfma_f32_16x16x32_bf16 v[50:53], v[184:187], v[192:195], v[50:53]
	v_mfma_f32_16x16x32_bf16 v[38:41], v[176:179], v[200:203], v[38:41]
	v_mfma_f32_16x16x32_bf16 v[34:37], v[184:187], v[200:203], v[34:37]
	v_mfma_f32_16x16x32_bf16 v[22:25], v[176:179], v[208:211], v[22:25]
	v_mfma_f32_16x16x32_bf16 v[18:21], v[184:187], v[208:211], v[18:21]
	v_mfma_f32_16x16x32_bf16 v[6:9], v[176:179], v[216:219], v[6:9]
	v_mfma_f32_16x16x32_bf16 v[2:5], v[184:187], v[216:219], v[2:5]
	v_mfma_f32_16x16x32_bf16 v[54:57], v[180:183], v[196:199], v[54:57]
	v_mfma_f32_16x16x32_bf16 v[50:53], v[188:191], v[196:199], v[50:53]
	v_mfma_f32_16x16x32_bf16 v[38:41], v[180:183], v[204:207], v[38:41]
	v_mfma_f32_16x16x32_bf16 v[34:37], v[188:191], v[204:207], v[34:37]
	v_mfma_f32_16x16x32_bf16 v[22:25], v[180:183], v[212:215], v[22:25]
	v_mfma_f32_16x16x32_bf16 v[18:21], v[188:191], v[212:215], v[18:21]
	v_mfma_f32_16x16x32_bf16 v[6:9], v[180:183], v[220:223], v[6:9]
	v_mfma_f32_16x16x32_bf16 v[2:5], v[188:191], v[220:223], v[2:5]
	s_setprio 0
	s_barrier
	s_add_u32 s60, s60, 0x100
	s_addc_u32 s61, s61, 0
	s_cmp_ge_u32 s24, s3
	s_cbranch_scc0 .LBB0_707
	s_and_b64 vcc, exec, s[4:5]
	s_cbranch_vccz .LBB0_711
	v_add_u32_e32 v11, 0, v152
	v_add_u32_e32 v12, 0x10000, v11
	ds_read_b128 v[156:159], v12
	ds_read_b128 v[160:163], v12 offset:1024
	ds_read_b128 v[164:167], v12 offset:2048
	ds_read_b128 v[172:175], v12 offset:3072
	v_add_u32_e32 v12, 0x14000, v11
	ds_read_b128 v[176:179], v12
	ds_read_b128 v[180:183], v12 offset:1024
	ds_read_b128 v[184:187], v12 offset:2048
	ds_read_b128 v[188:191], v12 offset:3072
	v_lshl_add_u64 v[12:13], s[14:15], 0, v[134:135]
	s_mov_b32 m0, s49
	v_lshl_add_u64 v[12:13], v[12:13], 0, s[42:43]
	ds_read_b128 v[192:195], v155
	ds_read_b128 v[196:199], v155 offset:1024
	ds_read_b128 v[200:203], v155 offset:2048
	ds_read_b128 v[204:207], v155 offset:3072
	ds_read_b128 v[208:211], v155 offset:4096
	ds_read_b128 v[212:215], v155 offset:5120
	ds_read_b128 v[216:219], v155 offset:6144
	ds_read_b128 v[220:223], v155 offset:7168
	global_load_lds_dwordx4 v[12:13], off
	v_lshl_add_u64 v[12:13], s[14:15], 0, v[138:139]
	s_add_u32 s60, s14, 0x40780
	v_lshl_add_u64 v[12:13], v[12:13], 0, s[42:43]
	s_mov_b32 m0, s27
	s_addc_u32 s61, s15, 0
	global_load_lds_dwordx4 v[12:13], off
	v_lshl_add_u64 v[12:13], s[60:61], 0, v[134:135]
	s_mov_b32 m0, s25
	s_nop 0
	global_load_lds_dwordx4 v[12:13], off
	v_lshl_add_u64 v[12:13], s[60:61], 0, v[138:139]
	s_mov_b32 m0, s26
	s_nop 0
	global_load_lds_dwordx4 v[12:13], off
	s_waitcnt vmcnt(8)
	s_waitcnt lgkmcnt(0)
	s_setprio 1
	s_barrier
	v_mfma_f32_16x16x32_bf16 v[126:129], v[156:159], v[192:195], v[126:129]
	v_mfma_f32_16x16x32_bf16 v[122:125], v[164:167], v[192:195], v[122:125]
	v_mfma_f32_16x16x32_bf16 v[110:113], v[156:159], v[200:203], v[110:113]
	v_mfma_f32_16x16x32_bf16 v[106:109], v[164:167], v[200:203], v[106:109]
	v_mfma_f32_16x16x32_bf16 v[94:97], v[156:159], v[208:211], v[94:97]
	v_mfma_f32_16x16x32_bf16 v[90:93], v[164:167], v[208:211], v[90:93]
	v_mfma_f32_16x16x32_bf16 v[78:81], v[156:159], v[216:219], v[78:81]
	v_mfma_f32_16x16x32_bf16 v[74:77], v[164:167], v[216:219], v[74:77]
	v_mfma_f32_16x16x32_bf16 v[126:129], v[160:163], v[196:199], v[126:129]
	v_mfma_f32_16x16x32_bf16 v[122:125], v[172:175], v[196:199], v[122:125]
	v_mfma_f32_16x16x32_bf16 v[110:113], v[160:163], v[204:207], v[110:113]
	v_mfma_f32_16x16x32_bf16 v[106:109], v[172:175], v[204:207], v[106:109]
	v_mfma_f32_16x16x32_bf16 v[94:97], v[160:163], v[212:215], v[94:97]
	v_mfma_f32_16x16x32_bf16 v[90:93], v[172:175], v[212:215], v[90:93]
	v_mfma_f32_16x16x32_bf16 v[78:81], v[160:163], v[220:223], v[78:81]
	v_mfma_f32_16x16x32_bf16 v[74:77], v[172:175], v[220:223], v[74:77]
	v_mfma_f32_16x16x32_bf16 v[62:65], v[176:179], v[192:195], v[62:65]
	v_mfma_f32_16x16x32_bf16 v[58:61], v[184:187], v[192:195], v[58:61]
	v_mfma_f32_16x16x32_bf16 v[46:49], v[176:179], v[200:203], v[46:49]
	v_mfma_f32_16x16x32_bf16 v[42:45], v[184:187], v[200:203], v[42:45]
	v_mfma_f32_16x16x32_bf16 v[30:33], v[176:179], v[208:211], v[30:33]
	v_mfma_f32_16x16x32_bf16 v[26:29], v[184:187], v[208:211], v[26:29]
	v_mfma_f32_16x16x32_bf16 v[12:15], v[176:179], v[216:219], v[14:17]
	v_mfma_f32_16x16x32_bf16 v[130:133], v[184:187], v[216:219], v[130:133]
	v_mfma_f32_16x16x32_bf16 v[62:65], v[180:183], v[196:199], v[62:65]
	v_mfma_f32_16x16x32_bf16 v[58:61], v[188:191], v[196:199], v[58:61]
	v_mfma_f32_16x16x32_bf16 v[46:49], v[180:183], v[204:207], v[46:49]
	v_mfma_f32_16x16x32_bf16 v[42:45], v[188:191], v[204:207], v[42:45]
	v_mfma_f32_16x16x32_bf16 v[30:33], v[180:183], v[212:215], v[30:33]
	v_mfma_f32_16x16x32_bf16 v[26:29], v[188:191], v[212:215], v[26:29]
	v_mfma_f32_16x16x32_bf16 v[12:15], v[180:183], v[220:223], v[12:15]
	v_mfma_f32_16x16x32_bf16 v[130:133], v[188:191], v[220:223], v[130:133]
	s_setprio 0
	s_barrier
	ds_read_b128 v[192:195], v155 offset:16384
	ds_read_b128 v[196:199], v155 offset:17408
	ds_read_b128 v[200:203], v155 offset:18432
	ds_read_b128 v[204:207], v155 offset:19456
	ds_read_b128 v[208:211], v155 offset:20480
	ds_read_b128 v[212:215], v155 offset:21504
	ds_read_b128 v[216:219], v155 offset:22528
	ds_read_b128 v[220:223], v155 offset:23552
	s_waitcnt vmcnt(0)
	s_waitcnt lgkmcnt(0)
	s_setprio 1
	s_barrier
	v_mfma_f32_16x16x32_bf16 v[118:121], v[156:159], v[192:195], v[118:121]
	v_mfma_f32_16x16x32_bf16 v[114:117], v[164:167], v[192:195], v[114:117]
	v_mfma_f32_16x16x32_bf16 v[102:105], v[156:159], v[200:203], v[102:105]
	v_mfma_f32_16x16x32_bf16 v[98:101], v[164:167], v[200:203], v[98:101]
	v_mfma_f32_16x16x32_bf16 v[86:89], v[156:159], v[208:211], v[86:89]
	v_mfma_f32_16x16x32_bf16 v[82:85], v[164:167], v[208:211], v[82:85]
	v_mfma_f32_16x16x32_bf16 v[70:73], v[156:159], v[216:219], v[70:73]
	v_mfma_f32_16x16x32_bf16 v[66:69], v[164:167], v[216:219], v[66:69]
	v_mfma_f32_16x16x32_bf16 v[118:121], v[160:163], v[196:199], v[118:121]
	v_mfma_f32_16x16x32_bf16 v[114:117], v[172:175], v[196:199], v[114:117]
	v_mfma_f32_16x16x32_bf16 v[102:105], v[160:163], v[204:207], v[102:105]
	v_mfma_f32_16x16x32_bf16 v[98:101], v[172:175], v[204:207], v[98:101]
	v_mfma_f32_16x16x32_bf16 v[86:89], v[160:163], v[212:215], v[86:89]
	v_mfma_f32_16x16x32_bf16 v[82:85], v[172:175], v[212:215], v[82:85]
	v_mfma_f32_16x16x32_bf16 v[70:73], v[160:163], v[220:223], v[70:73]
	v_mfma_f32_16x16x32_bf16 v[66:69], v[172:175], v[220:223], v[66:69]
	v_mfma_f32_16x16x32_bf16 v[54:57], v[176:179], v[192:195], v[54:57]
	v_mfma_f32_16x16x32_bf16 v[50:53], v[184:187], v[192:195], v[50:53]
	v_mfma_f32_16x16x32_bf16 v[38:41], v[176:179], v[200:203], v[38:41]
	v_mfma_f32_16x16x32_bf16 v[34:37], v[184:187], v[200:203], v[34:37]
	v_mfma_f32_16x16x32_bf16 v[22:25], v[176:179], v[208:211], v[22:25]
	v_mfma_f32_16x16x32_bf16 v[16:19], v[184:187], v[208:211], v[18:21]
	v_mfma_f32_16x16x32_bf16 v[6:9], v[176:179], v[216:219], v[6:9]
	v_mfma_f32_16x16x32_bf16 v[2:5], v[184:187], v[216:219], v[2:5]
	v_mfma_f32_16x16x32_bf16 v[54:57], v[180:183], v[196:199], v[54:57]
	v_mfma_f32_16x16x32_bf16 v[50:53], v[188:191], v[196:199], v[50:53]
	v_mfma_f32_16x16x32_bf16 v[38:41], v[180:183], v[204:207], v[38:41]
	v_mfma_f32_16x16x32_bf16 v[34:37], v[188:191], v[204:207], v[34:37]
	v_mfma_f32_16x16x32_bf16 v[22:25], v[180:183], v[212:215], v[22:25]
	v_mfma_f32_16x16x32_bf16 v[18:21], v[188:191], v[212:215], v[16:19]
	v_mfma_f32_16x16x32_bf16 v[6:9], v[180:183], v[220:223], v[6:9]
	v_mfma_f32_16x16x32_bf16 v[2:5], v[188:191], v[220:223], v[2:5]
	s_setprio 0
	s_barrier
	v_add_u32_e32 v16, 0x18000, v11
	v_add_u32_e32 v11, 0x1c000, v11
	ds_read_b128 v[156:159], v16
	ds_read_b128 v[160:163], v16 offset:1024
	ds_read_b128 v[164:167], v16 offset:2048
	ds_read_b128 v[172:175], v16 offset:3072
	ds_read_b128 v[176:179], v11
	ds_read_b128 v[180:183], v11 offset:1024
	ds_read_b128 v[184:187], v11 offset:2048
	ds_read_b128 v[188:191], v11 offset:3072
	ds_read_b128 v[192:195], v155 offset:32768
	ds_read_b128 v[196:199], v155 offset:33792
	ds_read_b128 v[200:203], v155 offset:34816
	ds_read_b128 v[204:207], v155 offset:35840
	ds_read_b128 v[208:211], v155 offset:36864
	ds_read_b128 v[212:215], v155 offset:37888
	ds_read_b128 v[216:219], v155 offset:38912
	ds_read_b128 v[220:223], v155 offset:39936
	s_waitcnt lgkmcnt(0)
	s_setprio 1
	s_barrier
	v_mfma_f32_16x16x32_bf16 v[126:129], v[156:159], v[192:195], v[126:129]
	v_mfma_f32_16x16x32_bf16 v[122:125], v[164:167], v[192:195], v[122:125]
	v_mfma_f32_16x16x32_bf16 v[110:113], v[156:159], v[200:203], v[110:113]
	v_mfma_f32_16x16x32_bf16 v[106:109], v[164:167], v[200:203], v[106:109]
	v_mfma_f32_16x16x32_bf16 v[94:97], v[156:159], v[208:211], v[94:97]
	v_mfma_f32_16x16x32_bf16 v[90:93], v[164:167], v[208:211], v[90:93]
	v_mfma_f32_16x16x32_bf16 v[78:81], v[156:159], v[216:219], v[78:81]
	v_mfma_f32_16x16x32_bf16 v[74:77], v[164:167], v[216:219], v[74:77]
	v_mfma_f32_16x16x32_bf16 v[126:129], v[160:163], v[196:199], v[126:129]
	v_mfma_f32_16x16x32_bf16 v[122:125], v[172:175], v[196:199], v[122:125]
	v_mfma_f32_16x16x32_bf16 v[110:113], v[160:163], v[204:207], v[110:113]
	v_mfma_f32_16x16x32_bf16 v[106:109], v[172:175], v[204:207], v[106:109]
	v_mfma_f32_16x16x32_bf16 v[94:97], v[160:163], v[212:215], v[94:97]
	v_mfma_f32_16x16x32_bf16 v[90:93], v[172:175], v[212:215], v[90:93]
	v_mfma_f32_16x16x32_bf16 v[78:81], v[160:163], v[220:223], v[78:81]
	v_mfma_f32_16x16x32_bf16 v[74:77], v[172:175], v[220:223], v[74:77]
	v_mfma_f32_16x16x32_bf16 v[62:65], v[176:179], v[192:195], v[62:65]
	v_mfma_f32_16x16x32_bf16 v[58:61], v[184:187], v[192:195], v[58:61]
	v_mfma_f32_16x16x32_bf16 v[46:49], v[176:179], v[200:203], v[46:49]
	v_mfma_f32_16x16x32_bf16 v[42:45], v[184:187], v[200:203], v[42:45]
	v_mfma_f32_16x16x32_bf16 v[30:33], v[176:179], v[208:211], v[30:33]
	v_mfma_f32_16x16x32_bf16 v[26:29], v[184:187], v[208:211], v[26:29]
	v_mfma_f32_16x16x32_bf16 v[12:15], v[176:179], v[216:219], v[12:15]
	v_mfma_f32_16x16x32_bf16 v[130:133], v[184:187], v[216:219], v[130:133]
	v_mfma_f32_16x16x32_bf16 v[62:65], v[180:183], v[196:199], v[62:65]
	v_mfma_f32_16x16x32_bf16 v[58:61], v[188:191], v[196:199], v[58:61]
	v_mfma_f32_16x16x32_bf16 v[46:49], v[180:183], v[204:207], v[46:49]
	v_mfma_f32_16x16x32_bf16 v[42:45], v[188:191], v[204:207], v[42:45]
	v_mfma_f32_16x16x32_bf16 v[30:33], v[180:183], v[212:215], v[30:33]
	v_mfma_f32_16x16x32_bf16 v[26:29], v[188:191], v[212:215], v[26:29]
	v_mfma_f32_16x16x32_bf16 v[14:17], v[180:183], v[220:223], v[12:15]
	v_mfma_f32_16x16x32_bf16 v[130:133], v[188:191], v[220:223], v[130:133]
	s_setprio 0
	s_barrier
	ds_read_b128 v[192:195], v155 offset:49152
	ds_read_b128 v[196:199], v155 offset:50176
	ds_read_b128 v[200:203], v155 offset:51200
	ds_read_b128 v[204:207], v155 offset:52224
	ds_read_b128 v[208:211], v155 offset:53248
	ds_read_b128 v[212:215], v155 offset:54272
	ds_read_b128 v[216:219], v155 offset:55296
	ds_read_b128 v[220:223], v155 offset:56320
	s_waitcnt lgkmcnt(0)
	s_setprio 1
	s_barrier
	v_mfma_f32_16x16x32_bf16 v[118:121], v[156:159], v[192:195], v[118:121]
	v_mfma_f32_16x16x32_bf16 v[114:117], v[164:167], v[192:195], v[114:117]
	v_mfma_f32_16x16x32_bf16 v[102:105], v[156:159], v[200:203], v[102:105]
	v_mfma_f32_16x16x32_bf16 v[98:101], v[164:167], v[200:203], v[98:101]
	v_mfma_f32_16x16x32_bf16 v[86:89], v[156:159], v[208:211], v[86:89]
	v_mfma_f32_16x16x32_bf16 v[82:85], v[164:167], v[208:211], v[82:85]
	v_mfma_f32_16x16x32_bf16 v[70:73], v[156:159], v[216:219], v[70:73]
	v_mfma_f32_16x16x32_bf16 v[66:69], v[164:167], v[216:219], v[66:69]
	v_mfma_f32_16x16x32_bf16 v[118:121], v[160:163], v[196:199], v[118:121]
	v_mfma_f32_16x16x32_bf16 v[114:117], v[172:175], v[196:199], v[114:117]
	v_mfma_f32_16x16x32_bf16 v[102:105], v[160:163], v[204:207], v[102:105]
	v_mfma_f32_16x16x32_bf16 v[98:101], v[172:175], v[204:207], v[98:101]
	v_mfma_f32_16x16x32_bf16 v[86:89], v[160:163], v[212:215], v[86:89]
	v_mfma_f32_16x16x32_bf16 v[82:85], v[172:175], v[212:215], v[82:85]
	v_mfma_f32_16x16x32_bf16 v[70:73], v[160:163], v[220:223], v[70:73]
	v_mfma_f32_16x16x32_bf16 v[66:69], v[172:175], v[220:223], v[66:69]
	v_mfma_f32_16x16x32_bf16 v[54:57], v[176:179], v[192:195], v[54:57]
	v_mfma_f32_16x16x32_bf16 v[50:53], v[184:187], v[192:195], v[50:53]
	v_mfma_f32_16x16x32_bf16 v[38:41], v[176:179], v[200:203], v[38:41]
	v_mfma_f32_16x16x32_bf16 v[34:37], v[184:187], v[200:203], v[34:37]
	v_mfma_f32_16x16x32_bf16 v[22:25], v[176:179], v[208:211], v[22:25]
	v_mfma_f32_16x16x32_bf16 v[18:21], v[184:187], v[208:211], v[18:21]
	v_mfma_f32_16x16x32_bf16 v[6:9], v[176:179], v[216:219], v[6:9]
	v_mfma_f32_16x16x32_bf16 v[2:5], v[184:187], v[216:219], v[2:5]
	v_mfma_f32_16x16x32_bf16 v[54:57], v[180:183], v[196:199], v[54:57]
	v_mfma_f32_16x16x32_bf16 v[50:53], v[188:191], v[196:199], v[50:53]
	v_mfma_f32_16x16x32_bf16 v[38:41], v[180:183], v[204:207], v[38:41]
	v_mfma_f32_16x16x32_bf16 v[34:37], v[188:191], v[204:207], v[34:37]
	v_mfma_f32_16x16x32_bf16 v[22:25], v[180:183], v[212:215], v[22:25]
	v_mfma_f32_16x16x32_bf16 v[18:21], v[188:191], v[212:215], v[18:21]
	v_mfma_f32_16x16x32_bf16 v[6:9], v[180:183], v[220:223], v[6:9]
	v_mfma_f32_16x16x32_bf16 v[2:5], v[188:191], v[220:223], v[2:5]
	s_setprio 0
	s_barrier
	s_andn2_b64 vcc, exec, s[40:41]
	s_cbranch_vccz .LBB0_712

.LBB0_853:
	s_add_i32 s78, s78, 2
	s_add_u32 s0, s70, s8
	s_addc_u32 s1, s71, s9
	s_add_u32 s0, s0, 0x100
	s_addc_u32 s1, s1, 0
	s_add_u32 s3, s50, s8
	s_addc_u32 s10, s65, s9
	s_add_i32 s24, 0, 0x10000
	v_add_u32_e32 v2, s24, v226
	s_add_i32 s26, 0, 0x14000
	s_waitcnt lgkmcnt(0)
	ds_read_b128 v[134:137], v2
	ds_read_b128 v[138:141], v2 offset:1024
	ds_read_b128 v[142:145], v2 offset:2048
	ds_read_b128 v[146:149], v2 offset:3072
	v_add_u32_e32 v2, s26, v226
	ds_read_b128 v[150:153], v2
	ds_read_b128 v[154:157], v2 offset:1024
	ds_read_b128 v[158:161], v2 offset:2048
	ds_read_b128 v[162:165], v2 offset:3072
	s_cmpk_eq_i32 s8, 0x700
	s_cselect_b32 s11, s69, s10
	s_cselect_b32 s10, s68, s3
	s_cselect_b32 s77, s67, s1
	s_cselect_b32 s76, s66, s0
	v_lshl_add_u64 v[4:5], v[222:223], 0, s[8:9]
	s_add_i32 s0, s88, 0x8000
	v_lshl_add_u64 v[224:225], v[4:5], 0, s[44:45]
	s_mov_b32 m0, s0
	s_waitcnt lgkmcnt(0)
	ds_read_b128 v[166:169], v227
	ds_read_b128 v[170:173], v227 offset:1024
	ds_read_b128 v[174:177], v227 offset:2048
	ds_read_b128 v[178:181], v227 offset:3072
	ds_read_b128 v[182:185], v227 offset:4096
	ds_read_b128 v[186:189], v227 offset:5120
	ds_read_b128 v[190:193], v227 offset:6144
	ds_read_b128 v[194:197], v227 offset:7168
	global_load_lds_dwordx4 v[224:225], off
	v_lshl_add_u64 v[224:225], v[220:221], 0, s[8:9]
	s_add_i32 s79, s88, 0xa000
	v_lshl_add_u64 v[246:247], v[224:225], 0, s[44:45]
	s_mov_b32 m0, s79
	s_add_i32 s22, s88, 0xc000
	global_load_lds_dwordx4 v[246:247], off
	v_lshl_add_u64 v[4:5], v[4:5], 0, s[46:47]
	s_mov_b32 m0, s22
	s_add_i32 s23, s88, 0xe000
	global_load_lds_dwordx4 v[4:5], off
	v_lshl_add_u64 v[4:5], v[224:225], 0, s[46:47]
	s_mov_b32 m0, s23
	s_nop 0
	global_load_lds_dwordx4 v[4:5], off
	s_waitcnt vmcnt(8)
	s_waitcnt lgkmcnt(0)
	s_setprio 1
	s_barrier
	v_mfma_f32_16x16x32_bf16 v[82:85], v[134:137], v[166:169], v[82:85]
	v_mfma_f32_16x16x32_bf16 v[10:13], v[142:145], v[166:169], v[10:13]
	v_mfma_f32_16x16x32_bf16 v[130:133], v[134:137], v[174:177], v[130:133]
	v_mfma_f32_16x16x32_bf16 v[66:69], v[142:145], v[174:177], v[66:69]
	v_mfma_f32_16x16x32_bf16 v[126:129], v[134:137], v[182:185], v[126:129]
	v_mfma_f32_16x16x32_bf16 v[62:65], v[142:145], v[182:185], v[62:65]
	v_mfma_f32_16x16x32_bf16 v[122:125], v[134:137], v[190:193], v[122:125]
	v_mfma_f32_16x16x32_bf16 v[58:61], v[142:145], v[190:193], v[58:61]
	v_mfma_f32_16x16x32_bf16 v[82:85], v[138:141], v[170:173], v[82:85]
	v_mfma_f32_16x16x32_bf16 v[10:13], v[146:149], v[170:173], v[10:13]
	v_mfma_f32_16x16x32_bf16 v[130:133], v[138:141], v[178:181], v[130:133]
	v_mfma_f32_16x16x32_bf16 v[66:69], v[146:149], v[178:181], v[66:69]
	v_mfma_f32_16x16x32_bf16 v[126:129], v[138:141], v[186:189], v[126:129]
	v_mfma_f32_16x16x32_bf16 v[62:65], v[146:149], v[186:189], v[62:65]
	v_mfma_f32_16x16x32_bf16 v[122:125], v[138:141], v[194:197], v[122:125]
	v_mfma_f32_16x16x32_bf16 v[58:61], v[146:149], v[194:197], v[58:61]
	v_mfma_f32_16x16x32_bf16 v[70:73], v[150:153], v[166:169], v[70:73]
	v_mfma_f32_16x16x32_bf16 v[4:7], v[158:161], v[166:169], v[6:9]
	v_mfma_f32_16x16x32_bf16 v[118:121], v[150:153], v[174:177], v[118:121]
	v_mfma_f32_16x16x32_bf16 v[54:57], v[158:161], v[174:177], v[54:57]
	v_mfma_f32_16x16x32_bf16 v[114:117], v[150:153], v[182:185], v[114:117]
	v_mfma_f32_16x16x32_bf16 v[50:53], v[158:161], v[182:185], v[50:53]
	v_mfma_f32_16x16x32_bf16 v[110:113], v[150:153], v[190:193], v[110:113]
	v_mfma_f32_16x16x32_bf16 v[46:49], v[158:161], v[190:193], v[46:49]
	v_mfma_f32_16x16x32_bf16 v[70:73], v[154:157], v[170:173], v[70:73]
	v_mfma_f32_16x16x32_bf16 v[4:7], v[162:165], v[170:173], v[4:7]
	v_mfma_f32_16x16x32_bf16 v[118:121], v[154:157], v[178:181], v[118:121]
	v_mfma_f32_16x16x32_bf16 v[54:57], v[162:165], v[178:181], v[54:57]
	v_mfma_f32_16x16x32_bf16 v[114:117], v[154:157], v[186:189], v[114:117]
	v_mfma_f32_16x16x32_bf16 v[50:53], v[162:165], v[186:189], v[50:53]
	v_mfma_f32_16x16x32_bf16 v[110:113], v[154:157], v[194:197], v[110:113]
	v_mfma_f32_16x16x32_bf16 v[46:49], v[162:165], v[194:197], v[46:49]
	s_setprio 0
	s_barrier
	s_add_i32 s1, s24, s87
	v_lshl_add_u64 v[224:225], s[10:11], 0, v[200:201]
	s_mov_b32 m0, s1
	ds_read_b128 v[166:169], v227 offset:16384
	ds_read_b128 v[170:173], v227 offset:17408
	ds_read_b128 v[174:177], v227 offset:18432
	ds_read_b128 v[178:181], v227 offset:19456
	ds_read_b128 v[182:185], v227 offset:20480
	ds_read_b128 v[186:189], v227 offset:21504
	ds_read_b128 v[190:193], v227 offset:22528
	ds_read_b128 v[194:197], v227 offset:23552
	global_load_lds_dwordx4 v[224:225], off
	s_add_i32 m0, s1, 0x2000
	s_add_u32 s24, s10, 0x40000
	v_lshl_add_u64 v[246:247], s[10:11], 0, v[204:205]
	s_addc_u32 s25, s11, 0
	s_add_i32 s1, s26, s87
	global_load_lds_dwordx4 v[246:247], off
	v_lshl_add_u64 v[8:9], s[24:25], 0, v[200:201]
	s_mov_b32 m0, s1
	s_nop 0
	global_load_lds_dwordx4 v[8:9], off
	v_lshl_add_u64 v[8:9], s[24:25], 0, v[204:205]
	s_add_i32 m0, s1, 0x2000
	s_nop 0
	global_load_lds_dwordx4 v[8:9], off
	s_waitcnt vmcnt(4)
	s_waitcnt lgkmcnt(0)
	s_setprio 1
	s_barrier
	v_mfma_f32_16x16x32_bf16 v[102:105], v[134:137], v[166:169], v[102:105]
	v_mfma_f32_16x16x32_bf16 v[30:33], v[142:145], v[166:169], v[30:33]
	v_mfma_f32_16x16x32_bf16 v[106:109], v[134:137], v[174:177], v[106:109]
	v_mfma_f32_16x16x32_bf16 v[42:45], v[142:145], v[174:177], v[42:45]
	v_mfma_f32_16x16x32_bf16 v[98:101], v[134:137], v[182:185], v[98:101]
	v_mfma_f32_16x16x32_bf16 v[38:41], v[142:145], v[182:185], v[38:41]
	v_mfma_f32_16x16x32_bf16 v[94:97], v[134:137], v[190:193], v[94:97]
	v_mfma_f32_16x16x32_bf16 v[34:37], v[142:145], v[190:193], v[34:37]
	v_mfma_f32_16x16x32_bf16 v[102:105], v[138:141], v[170:173], v[102:105]
	v_mfma_f32_16x16x32_bf16 v[30:33], v[146:149], v[170:173], v[30:33]
	v_mfma_f32_16x16x32_bf16 v[106:109], v[138:141], v[178:181], v[106:109]
	v_mfma_f32_16x16x32_bf16 v[42:45], v[146:149], v[178:181], v[42:45]
	v_mfma_f32_16x16x32_bf16 v[98:101], v[138:141], v[186:189], v[98:101]
	v_mfma_f32_16x16x32_bf16 v[38:41], v[146:149], v[186:189], v[38:41]
	v_mfma_f32_16x16x32_bf16 v[94:97], v[138:141], v[194:197], v[94:97]
	v_mfma_f32_16x16x32_bf16 v[34:37], v[146:149], v[194:197], v[34:37]
	v_mfma_f32_16x16x32_bf16 v[74:77], v[150:153], v[166:169], v[74:77]
	v_mfma_f32_16x16x32_bf16 v[14:17], v[158:161], v[166:169], v[14:17]
	v_mfma_f32_16x16x32_bf16 v[90:93], v[150:153], v[174:177], v[90:93]
	v_mfma_f32_16x16x32_bf16 v[26:29], v[158:161], v[174:177], v[26:29]
	v_mfma_f32_16x16x32_bf16 v[86:89], v[150:153], v[182:185], v[86:89]
	v_mfma_f32_16x16x32_bf16 v[22:25], v[158:161], v[182:185], v[22:25]
	v_mfma_f32_16x16x32_bf16 v[78:81], v[150:153], v[190:193], v[78:81]
	v_mfma_f32_16x16x32_bf16 v[18:21], v[158:161], v[190:193], v[18:21]
	v_mfma_f32_16x16x32_bf16 v[74:77], v[154:157], v[170:173], v[74:77]
	v_mfma_f32_16x16x32_bf16 v[14:17], v[162:165], v[170:173], v[14:17]
	v_mfma_f32_16x16x32_bf16 v[90:93], v[154:157], v[178:181], v[90:93]
	v_mfma_f32_16x16x32_bf16 v[26:29], v[162:165], v[178:181], v[26:29]
	v_mfma_f32_16x16x32_bf16 v[86:89], v[154:157], v[186:189], v[86:89]
	v_mfma_f32_16x16x32_bf16 v[22:25], v[162:165], v[186:189], v[22:25]
	v_mfma_f32_16x16x32_bf16 v[78:81], v[154:157], v[194:197], v[78:81]
	v_mfma_f32_16x16x32_bf16 v[18:21], v[162:165], v[194:197], v[18:21]
	s_setprio 0
	s_barrier
	s_add_i32 s1, 0, 0x18000
	v_add_u32_e32 v2, s1, v226
	s_add_i32 s3, 0, 0x1c000
	ds_read_b128 v[134:137], v2
	ds_read_b128 v[138:141], v2 offset:1024
	ds_read_b128 v[142:145], v2 offset:2048
	ds_read_b128 v[146:149], v2 offset:3072
	v_add_u32_e32 v2, s3, v226
	ds_read_b128 v[150:153], v2
	ds_read_b128 v[154:157], v2 offset:1024
	ds_read_b128 v[158:161], v2 offset:2048
	ds_read_b128 v[162:165], v2 offset:3072
	s_mov_b32 m0, s88
	v_lshl_add_u64 v[8:9], s[76:77], 0, v[198:199]
	s_add_u32 s24, s76, 0x40000
	ds_read_b128 v[166:169], v227 offset:32768
	ds_read_b128 v[170:173], v227 offset:33792
	ds_read_b128 v[174:177], v227 offset:34816
	ds_read_b128 v[178:181], v227 offset:35840
	ds_read_b128 v[182:185], v227 offset:36864
	ds_read_b128 v[186:189], v227 offset:37888
	ds_read_b128 v[190:193], v227 offset:38912
	ds_read_b128 v[194:197], v227 offset:39936
	global_load_lds_dwordx4 v[8:9], off
	v_lshl_add_u64 v[8:9], s[76:77], 0, v[202:203]
	s_mov_b32 m0, s28
	s_addc_u32 s25, s77, 0
	global_load_lds_dwordx4 v[8:9], off
	v_lshl_add_u64 v[8:9], s[24:25], 0, v[198:199]
	s_mov_b32 m0, s29
	s_nop 0
	global_load_lds_dwordx4 v[8:9], off
	v_lshl_add_u64 v[8:9], s[24:25], 0, v[202:203]
	s_mov_b32 m0, s18
	s_nop 0
	global_load_lds_dwordx4 v[8:9], off
	s_waitcnt vmcnt(8)
	s_waitcnt lgkmcnt(0)
	s_setprio 1
	s_barrier
	v_mfma_f32_16x16x32_bf16 v[82:85], v[134:137], v[166:169], v[82:85]
	v_mfma_f32_16x16x32_bf16 v[8:11], v[142:145], v[166:169], v[10:13]
	v_mfma_f32_16x16x32_bf16 v[130:133], v[134:137], v[174:177], v[130:133]
	v_mfma_f32_16x16x32_bf16 v[66:69], v[142:145], v[174:177], v[66:69]
	v_mfma_f32_16x16x32_bf16 v[126:129], v[134:137], v[182:185], v[126:129]
	v_mfma_f32_16x16x32_bf16 v[62:65], v[142:145], v[182:185], v[62:65]
	v_mfma_f32_16x16x32_bf16 v[122:125], v[134:137], v[190:193], v[122:125]
	v_mfma_f32_16x16x32_bf16 v[58:61], v[142:145], v[190:193], v[58:61]
	v_mfma_f32_16x16x32_bf16 v[82:85], v[138:141], v[170:173], v[82:85]
	v_mfma_f32_16x16x32_bf16 v[10:13], v[146:149], v[170:173], v[8:11]
	v_mfma_f32_16x16x32_bf16 v[130:133], v[138:141], v[178:181], v[130:133]
	v_mfma_f32_16x16x32_bf16 v[66:69], v[146:149], v[178:181], v[66:69]
	v_mfma_f32_16x16x32_bf16 v[126:129], v[138:141], v[186:189], v[126:129]
	v_mfma_f32_16x16x32_bf16 v[62:65], v[146:149], v[186:189], v[62:65]
	v_mfma_f32_16x16x32_bf16 v[122:125], v[138:141], v[194:197], v[122:125]
	v_mfma_f32_16x16x32_bf16 v[58:61], v[146:149], v[194:197], v[58:61]
	v_mfma_f32_16x16x32_bf16 v[70:73], v[150:153], v[166:169], v[70:73]
	v_mfma_f32_16x16x32_bf16 v[4:7], v[158:161], v[166:169], v[4:7]
	v_mfma_f32_16x16x32_bf16 v[118:121], v[150:153], v[174:177], v[118:121]
	v_mfma_f32_16x16x32_bf16 v[54:57], v[158:161], v[174:177], v[54:57]
	v_mfma_f32_16x16x32_bf16 v[114:117], v[150:153], v[182:185], v[114:117]
	v_mfma_f32_16x16x32_bf16 v[50:53], v[158:161], v[182:185], v[50:53]
	v_mfma_f32_16x16x32_bf16 v[110:113], v[150:153], v[190:193], v[110:113]
	v_mfma_f32_16x16x32_bf16 v[46:49], v[158:161], v[190:193], v[46:49]
	v_mfma_f32_16x16x32_bf16 v[70:73], v[154:157], v[170:173], v[70:73]
	v_mfma_f32_16x16x32_bf16 v[6:9], v[162:165], v[170:173], v[4:7]
	v_mfma_f32_16x16x32_bf16 v[118:121], v[154:157], v[178:181], v[118:121]
	v_mfma_f32_16x16x32_bf16 v[54:57], v[162:165], v[178:181], v[54:57]
	v_mfma_f32_16x16x32_bf16 v[114:117], v[154:157], v[186:189], v[114:117]
	v_mfma_f32_16x16x32_bf16 v[50:53], v[162:165], v[186:189], v[50:53]
	v_mfma_f32_16x16x32_bf16 v[110:113], v[154:157], v[194:197], v[110:113]
	v_mfma_f32_16x16x32_bf16 v[46:49], v[162:165], v[194:197], v[46:49]
	s_setprio 0
	s_barrier
	s_add_i32 s1, s1, s87
	v_lshl_add_u64 v[4:5], v[224:225], 0, s[44:45]
	s_mov_b32 m0, s1
	ds_read_b128 v[166:169], v227 offset:49152
	ds_read_b128 v[170:173], v227 offset:50176
	ds_read_b128 v[174:177], v227 offset:51200
	ds_read_b128 v[178:181], v227 offset:52224
	ds_read_b128 v[182:185], v227 offset:53248
	ds_read_b128 v[186:189], v227 offset:54272
	ds_read_b128 v[190:193], v227 offset:55296
	ds_read_b128 v[194:197], v227 offset:56320
	global_load_lds_dwordx4 v[4:5], off
	s_add_i32 m0, s1, 0x2000
	s_add_u32 s10, s10, 0x40080
	v_lshl_add_u64 v[4:5], v[246:247], 0, s[44:45]
	s_addc_u32 s11, s11, 0
	s_add_i32 s1, s3, s87
	global_load_lds_dwordx4 v[4:5], off
	v_lshl_add_u64 v[4:5], s[10:11], 0, v[200:201]
	s_mov_b32 m0, s1
	s_nop 0
	global_load_lds_dwordx4 v[4:5], off
	v_lshl_add_u64 v[4:5], s[10:11], 0, v[204:205]
	s_add_i32 m0, s1, 0x2000
	s_nop 0
	global_load_lds_dwordx4 v[4:5], off
	s_waitcnt vmcnt(4)
	s_waitcnt lgkmcnt(0)
	s_setprio 1
	s_barrier
	v_mfma_f32_16x16x32_bf16 v[102:105], v[134:137], v[166:169], v[102:105]
	v_mfma_f32_16x16x32_bf16 v[30:33], v[142:145], v[166:169], v[30:33]
	v_mfma_f32_16x16x32_bf16 v[106:109], v[134:137], v[174:177], v[106:109]
	v_mfma_f32_16x16x32_bf16 v[42:45], v[142:145], v[174:177], v[42:45]
	v_mfma_f32_16x16x32_bf16 v[98:101], v[134:137], v[182:185], v[98:101]
	v_mfma_f32_16x16x32_bf16 v[38:41], v[142:145], v[182:185], v[38:41]
	v_mfma_f32_16x16x32_bf16 v[94:97], v[134:137], v[190:193], v[94:97]
	v_mfma_f32_16x16x32_bf16 v[34:37], v[142:145], v[190:193], v[34:37]
	v_mfma_f32_16x16x32_bf16 v[102:105], v[138:141], v[170:173], v[102:105]
	v_mfma_f32_16x16x32_bf16 v[30:33], v[146:149], v[170:173], v[30:33]
	v_mfma_f32_16x16x32_bf16 v[106:109], v[138:141], v[178:181], v[106:109]
	v_mfma_f32_16x16x32_bf16 v[42:45], v[146:149], v[178:181], v[42:45]
	v_mfma_f32_16x16x32_bf16 v[98:101], v[138:141], v[186:189], v[98:101]
	v_mfma_f32_16x16x32_bf16 v[38:41], v[146:149], v[186:189], v[38:41]
	v_mfma_f32_16x16x32_bf16 v[94:97], v[138:141], v[194:197], v[94:97]
	v_mfma_f32_16x16x32_bf16 v[34:37], v[146:149], v[194:197], v[34:37]
	v_mfma_f32_16x16x32_bf16 v[74:77], v[150:153], v[166:169], v[74:77]
	v_mfma_f32_16x16x32_bf16 v[14:17], v[158:161], v[166:169], v[14:17]
	v_mfma_f32_16x16x32_bf16 v[90:93], v[150:153], v[174:177], v[90:93]
	v_mfma_f32_16x16x32_bf16 v[26:29], v[158:161], v[174:177], v[26:29]
	v_mfma_f32_16x16x32_bf16 v[86:89], v[150:153], v[182:185], v[86:89]
	v_mfma_f32_16x16x32_bf16 v[22:25], v[158:161], v[182:185], v[22:25]
	v_mfma_f32_16x16x32_bf16 v[78:81], v[150:153], v[190:193], v[78:81]
	v_mfma_f32_16x16x32_bf16 v[18:21], v[158:161], v[190:193], v[18:21]
	v_mfma_f32_16x16x32_bf16 v[74:77], v[154:157], v[170:173], v[74:77]
	v_mfma_f32_16x16x32_bf16 v[14:17], v[162:165], v[170:173], v[14:17]
	v_mfma_f32_16x16x32_bf16 v[90:93], v[154:157], v[178:181], v[90:93]
	v_mfma_f32_16x16x32_bf16 v[26:29], v[162:165], v[178:181], v[26:29]
	v_mfma_f32_16x16x32_bf16 v[86:89], v[154:157], v[186:189], v[86:89]
	v_mfma_f32_16x16x32_bf16 v[22:25], v[162:165], v[186:189], v[22:25]
	v_mfma_f32_16x16x32_bf16 v[78:81], v[154:157], v[194:197], v[78:81]
	v_mfma_f32_16x16x32_bf16 v[18:21], v[162:165], v[194:197], v[18:21]
	s_setprio 0
	s_barrier
	s_add_u32 s8, s8, 0x100
	s_addc_u32 s9, s9, 0
	s_cmp_ge_u32 s78, s17
	s_cbranch_scc0 .LBB0_853
	s_and_b64 vcc, exec, s[72:73]
	s_cbranch_vccz .LBB0_856
	v_add_u32_e32 v2, 0, v226
	v_add_u32_e32 v4, 0x10000, v2
	ds_read_b128 v[134:137], v4
	ds_read_b128 v[138:141], v4 offset:1024
	ds_read_b128 v[142:145], v4 offset:2048
	ds_read_b128 v[146:149], v4 offset:3072
	v_add_u32_e32 v4, 0x14000, v2
	ds_read_b128 v[150:153], v4
	ds_read_b128 v[154:157], v4 offset:1024
	ds_read_b128 v[158:161], v4 offset:2048
	ds_read_b128 v[162:165], v4 offset:3072
	s_mov_b32 m0, s0
	v_lshl_add_u64 v[4:5], s[70:71], 0, v[198:199]
	s_mov_b64 s[0:1], 0x780
	v_lshl_add_u64 v[4:5], v[4:5], 0, s[0:1]
	ds_read_b128 v[166:169], v227
	ds_read_b128 v[170:173], v227 offset:1024
	ds_read_b128 v[174:177], v227 offset:2048
	ds_read_b128 v[178:181], v227 offset:3072
	ds_read_b128 v[182:185], v227 offset:4096
	ds_read_b128 v[186:189], v227 offset:5120
	ds_read_b128 v[190:193], v227 offset:6144
	ds_read_b128 v[194:197], v227 offset:7168
	global_load_lds_dwordx4 v[4:5], off
	v_lshl_add_u64 v[4:5], s[70:71], 0, v[202:203]
	v_lshl_add_u64 v[4:5], v[4:5], 0, s[0:1]
	s_add_u32 s0, s70, 0x40780
	s_mov_b32 m0, s79
	s_addc_u32 s1, s71, 0
	global_load_lds_dwordx4 v[4:5], off
	v_lshl_add_u64 v[4:5], s[0:1], 0, v[198:199]
	s_mov_b32 m0, s22
	s_nop 0
	global_load_lds_dwordx4 v[4:5], off
	v_lshl_add_u64 v[4:5], s[0:1], 0, v[202:203]
	s_mov_b32 m0, s23
	s_nop 0
	global_load_lds_dwordx4 v[4:5], off
	s_waitcnt vmcnt(8)
	s_waitcnt lgkmcnt(0)
	s_setprio 1
	s_barrier
	v_mfma_f32_16x16x32_bf16 v[82:85], v[134:137], v[166:169], v[82:85]
	v_mfma_f32_16x16x32_bf16 v[10:13], v[142:145], v[166:169], v[10:13]
	v_mfma_f32_16x16x32_bf16 v[130:133], v[134:137], v[174:177], v[130:133]
	v_mfma_f32_16x16x32_bf16 v[66:69], v[142:145], v[174:177], v[66:69]
	v_mfma_f32_16x16x32_bf16 v[126:129], v[134:137], v[182:185], v[126:129]
	v_mfma_f32_16x16x32_bf16 v[62:65], v[142:145], v[182:185], v[62:65]
	v_mfma_f32_16x16x32_bf16 v[122:125], v[134:137], v[190:193], v[122:125]
	v_mfma_f32_16x16x32_bf16 v[58:61], v[142:145], v[190:193], v[58:61]
	v_mfma_f32_16x16x32_bf16 v[82:85], v[138:141], v[170:173], v[82:85]
	v_mfma_f32_16x16x32_bf16 v[10:13], v[146:149], v[170:173], v[10:13]
	v_mfma_f32_16x16x32_bf16 v[130:133], v[138:141], v[178:181], v[130:133]
	v_mfma_f32_16x16x32_bf16 v[66:69], v[146:149], v[178:181], v[66:69]
	v_mfma_f32_16x16x32_bf16 v[126:129], v[138:141], v[186:189], v[126:129]
	v_mfma_f32_16x16x32_bf16 v[62:65], v[146:149], v[186:189], v[62:65]
	v_mfma_f32_16x16x32_bf16 v[122:125], v[138:141], v[194:197], v[122:125]
	v_mfma_f32_16x16x32_bf16 v[58:61], v[146:149], v[194:197], v[58:61]
	v_mfma_f32_16x16x32_bf16 v[70:73], v[150:153], v[166:169], v[70:73]
	v_mfma_f32_16x16x32_bf16 v[4:7], v[158:161], v[166:169], v[6:9]
	v_mfma_f32_16x16x32_bf16 v[118:121], v[150:153], v[174:177], v[118:121]
	v_mfma_f32_16x16x32_bf16 v[54:57], v[158:161], v[174:177], v[54:57]
	v_mfma_f32_16x16x32_bf16 v[114:117], v[150:153], v[182:185], v[114:117]
	v_mfma_f32_16x16x32_bf16 v[50:53], v[158:161], v[182:185], v[50:53]
	v_mfma_f32_16x16x32_bf16 v[110:113], v[150:153], v[190:193], v[110:113]
	v_mfma_f32_16x16x32_bf16 v[46:49], v[158:161], v[190:193], v[46:49]
	v_mfma_f32_16x16x32_bf16 v[70:73], v[154:157], v[170:173], v[70:73]
	v_mfma_f32_16x16x32_bf16 v[4:7], v[162:165], v[170:173], v[4:7]
	v_mfma_f32_16x16x32_bf16 v[118:121], v[154:157], v[178:181], v[118:121]
	v_mfma_f32_16x16x32_bf16 v[54:57], v[162:165], v[178:181], v[54:57]
	v_mfma_f32_16x16x32_bf16 v[114:117], v[154:157], v[186:189], v[114:117]
	v_mfma_f32_16x16x32_bf16 v[50:53], v[162:165], v[186:189], v[50:53]
	v_mfma_f32_16x16x32_bf16 v[110:113], v[154:157], v[194:197], v[110:113]
	v_mfma_f32_16x16x32_bf16 v[46:49], v[162:165], v[194:197], v[46:49]
	s_setprio 0
	s_barrier
	ds_read_b128 v[166:169], v227 offset:16384
	ds_read_b128 v[170:173], v227 offset:17408
	ds_read_b128 v[174:177], v227 offset:18432
	ds_read_b128 v[178:181], v227 offset:19456
	ds_read_b128 v[182:185], v227 offset:20480
	ds_read_b128 v[186:189], v227 offset:21504
	ds_read_b128 v[190:193], v227 offset:22528
	ds_read_b128 v[194:197], v227 offset:23552
	s_waitcnt vmcnt(0)
	s_waitcnt lgkmcnt(0)
	s_setprio 1
	s_barrier
	v_mfma_f32_16x16x32_bf16 v[102:105], v[134:137], v[166:169], v[102:105]
	v_mfma_f32_16x16x32_bf16 v[30:33], v[142:145], v[166:169], v[30:33]
	v_mfma_f32_16x16x32_bf16 v[106:109], v[134:137], v[174:177], v[106:109]
	v_mfma_f32_16x16x32_bf16 v[42:45], v[142:145], v[174:177], v[42:45]
	v_mfma_f32_16x16x32_bf16 v[98:101], v[134:137], v[182:185], v[98:101]
	v_mfma_f32_16x16x32_bf16 v[38:41], v[142:145], v[182:185], v[38:41]
	v_mfma_f32_16x16x32_bf16 v[94:97], v[134:137], v[190:193], v[94:97]
	v_mfma_f32_16x16x32_bf16 v[34:37], v[142:145], v[190:193], v[34:37]
	v_mfma_f32_16x16x32_bf16 v[102:105], v[138:141], v[170:173], v[102:105]
	v_mfma_f32_16x16x32_bf16 v[30:33], v[146:149], v[170:173], v[30:33]
	v_mfma_f32_16x16x32_bf16 v[106:109], v[138:141], v[178:181], v[106:109]
	v_mfma_f32_16x16x32_bf16 v[42:45], v[146:149], v[178:181], v[42:45]
	v_mfma_f32_16x16x32_bf16 v[98:101], v[138:141], v[186:189], v[98:101]
	v_mfma_f32_16x16x32_bf16 v[38:41], v[146:149], v[186:189], v[38:41]
	v_mfma_f32_16x16x32_bf16 v[94:97], v[138:141], v[194:197], v[94:97]
	v_mfma_f32_16x16x32_bf16 v[34:37], v[146:149], v[194:197], v[34:37]
	v_mfma_f32_16x16x32_bf16 v[74:77], v[150:153], v[166:169], v[74:77]
	v_mfma_f32_16x16x32_bf16 v[14:17], v[158:161], v[166:169], v[14:17]
	v_mfma_f32_16x16x32_bf16 v[90:93], v[150:153], v[174:177], v[90:93]
	v_mfma_f32_16x16x32_bf16 v[26:29], v[158:161], v[174:177], v[26:29]
	v_mfma_f32_16x16x32_bf16 v[86:89], v[150:153], v[182:185], v[86:89]
	v_mfma_f32_16x16x32_bf16 v[22:25], v[158:161], v[182:185], v[22:25]
	v_mfma_f32_16x16x32_bf16 v[78:81], v[150:153], v[190:193], v[78:81]
	v_mfma_f32_16x16x32_bf16 v[18:21], v[158:161], v[190:193], v[18:21]
	v_mfma_f32_16x16x32_bf16 v[74:77], v[154:157], v[170:173], v[74:77]
	v_mfma_f32_16x16x32_bf16 v[14:17], v[162:165], v[170:173], v[14:17]
	v_mfma_f32_16x16x32_bf16 v[90:93], v[154:157], v[178:181], v[90:93]
	v_mfma_f32_16x16x32_bf16 v[26:29], v[162:165], v[178:181], v[26:29]
	v_mfma_f32_16x16x32_bf16 v[86:89], v[154:157], v[186:189], v[86:89]
	v_mfma_f32_16x16x32_bf16 v[22:25], v[162:165], v[186:189], v[22:25]
	v_mfma_f32_16x16x32_bf16 v[78:81], v[154:157], v[194:197], v[78:81]
	v_mfma_f32_16x16x32_bf16 v[18:21], v[162:165], v[194:197], v[18:21]
	s_setprio 0
	s_barrier
	v_add_u32_e32 v8, 0x18000, v2
	v_add_u32_e32 v2, 0x1c000, v2
	ds_read_b128 v[134:137], v8
	ds_read_b128 v[138:141], v8 offset:1024
	ds_read_b128 v[142:145], v8 offset:2048
	ds_read_b128 v[146:149], v8 offset:3072
	ds_read_b128 v[150:153], v2
	ds_read_b128 v[154:157], v2 offset:1024
	ds_read_b128 v[158:161], v2 offset:2048
	ds_read_b128 v[162:165], v2 offset:3072
	ds_read_b128 v[166:169], v227 offset:32768
	ds_read_b128 v[170:173], v227 offset:33792
	ds_read_b128 v[174:177], v227 offset:34816
	ds_read_b128 v[178:181], v227 offset:35840
	ds_read_b128 v[182:185], v227 offset:36864
	ds_read_b128 v[186:189], v227 offset:37888
	ds_read_b128 v[190:193], v227 offset:38912
	ds_read_b128 v[194:197], v227 offset:39936
	s_waitcnt lgkmcnt(0)
	s_setprio 1
	s_barrier
	v_mfma_f32_16x16x32_bf16 v[82:85], v[134:137], v[166:169], v[82:85]
	v_mfma_f32_16x16x32_bf16 v[8:11], v[142:145], v[166:169], v[10:13]
	v_mfma_f32_16x16x32_bf16 v[130:133], v[134:137], v[174:177], v[130:133]
	v_mfma_f32_16x16x32_bf16 v[66:69], v[142:145], v[174:177], v[66:69]
	v_mfma_f32_16x16x32_bf16 v[126:129], v[134:137], v[182:185], v[126:129]
	v_mfma_f32_16x16x32_bf16 v[62:65], v[142:145], v[182:185], v[62:65]
	v_mfma_f32_16x16x32_bf16 v[122:125], v[134:137], v[190:193], v[122:125]
	v_mfma_f32_16x16x32_bf16 v[58:61], v[142:145], v[190:193], v[58:61]
	v_mfma_f32_16x16x32_bf16 v[82:85], v[138:141], v[170:173], v[82:85]
	v_mfma_f32_16x16x32_bf16 v[10:13], v[146:149], v[170:173], v[8:11]
	v_mfma_f32_16x16x32_bf16 v[130:133], v[138:141], v[178:181], v[130:133]
	v_mfma_f32_16x16x32_bf16 v[66:69], v[146:149], v[178:181], v[66:69]
	v_mfma_f32_16x16x32_bf16 v[126:129], v[138:141], v[186:189], v[126:129]
	v_mfma_f32_16x16x32_bf16 v[62:65], v[146:149], v[186:189], v[62:65]
	v_mfma_f32_16x16x32_bf16 v[122:125], v[138:141], v[194:197], v[122:125]
	v_mfma_f32_16x16x32_bf16 v[58:61], v[146:149], v[194:197], v[58:61]
	v_mfma_f32_16x16x32_bf16 v[70:73], v[150:153], v[166:169], v[70:73]
	v_mfma_f32_16x16x32_bf16 v[4:7], v[158:161], v[166:169], v[4:7]
	v_mfma_f32_16x16x32_bf16 v[118:121], v[150:153], v[174:177], v[118:121]
	v_mfma_f32_16x16x32_bf16 v[54:57], v[158:161], v[174:177], v[54:57]
	v_mfma_f32_16x16x32_bf16 v[114:117], v[150:153], v[182:185], v[114:117]
	v_mfma_f32_16x16x32_bf16 v[50:53], v[158:161], v[182:185], v[50:53]
	v_mfma_f32_16x16x32_bf16 v[110:113], v[150:153], v[190:193], v[110:113]
	v_mfma_f32_16x16x32_bf16 v[46:49], v[158:161], v[190:193], v[46:49]
	v_mfma_f32_16x16x32_bf16 v[70:73], v[154:157], v[170:173], v[70:73]
	v_mfma_f32_16x16x32_bf16 v[6:9], v[162:165], v[170:173], v[4:7]
	v_mfma_f32_16x16x32_bf16 v[118:121], v[154:157], v[178:181], v[118:121]
	v_mfma_f32_16x16x32_bf16 v[54:57], v[162:165], v[178:181], v[54:57]
	v_mfma_f32_16x16x32_bf16 v[114:117], v[154:157], v[186:189], v[114:117]
	v_mfma_f32_16x16x32_bf16 v[50:53], v[162:165], v[186:189], v[50:53]
	v_mfma_f32_16x16x32_bf16 v[110:113], v[154:157], v[194:197], v[110:113]
	v_mfma_f32_16x16x32_bf16 v[46:49], v[162:165], v[194:197], v[46:49]
	s_setprio 0
	s_barrier
	ds_read_b128 v[166:169], v227 offset:49152
	ds_read_b128 v[170:173], v227 offset:50176
	ds_read_b128 v[174:177], v227 offset:51200
	ds_read_b128 v[178:181], v227 offset:52224
	ds_read_b128 v[182:185], v227 offset:53248
	ds_read_b128 v[186:189], v227 offset:54272
	ds_read_b128 v[190:193], v227 offset:55296
	ds_read_b128 v[194:197], v227 offset:56320
	s_waitcnt lgkmcnt(0)
	s_setprio 1
	s_barrier
	v_mfma_f32_16x16x32_bf16 v[102:105], v[134:137], v[166:169], v[102:105]
	v_mfma_f32_16x16x32_bf16 v[30:33], v[142:145], v[166:169], v[30:33]
	v_mfma_f32_16x16x32_bf16 v[106:109], v[134:137], v[174:177], v[106:109]
	v_mfma_f32_16x16x32_bf16 v[42:45], v[142:145], v[174:177], v[42:45]
	v_mfma_f32_16x16x32_bf16 v[98:101], v[134:137], v[182:185], v[98:101]
	v_mfma_f32_16x16x32_bf16 v[38:41], v[142:145], v[182:185], v[38:41]
	v_mfma_f32_16x16x32_bf16 v[94:97], v[134:137], v[190:193], v[94:97]
	v_mfma_f32_16x16x32_bf16 v[34:37], v[142:145], v[190:193], v[34:37]
	v_mfma_f32_16x16x32_bf16 v[102:105], v[138:141], v[170:173], v[102:105]
	v_mfma_f32_16x16x32_bf16 v[30:33], v[146:149], v[170:173], v[30:33]
	v_mfma_f32_16x16x32_bf16 v[106:109], v[138:141], v[178:181], v[106:109]
	v_mfma_f32_16x16x32_bf16 v[42:45], v[146:149], v[178:181], v[42:45]
	v_mfma_f32_16x16x32_bf16 v[98:101], v[138:141], v[186:189], v[98:101]
	v_mfma_f32_16x16x32_bf16 v[38:41], v[146:149], v[186:189], v[38:41]
	v_mfma_f32_16x16x32_bf16 v[94:97], v[138:141], v[194:197], v[94:97]
	v_mfma_f32_16x16x32_bf16 v[34:37], v[146:149], v[194:197], v[34:37]
	v_mfma_f32_16x16x32_bf16 v[74:77], v[150:153], v[166:169], v[74:77]
	v_mfma_f32_16x16x32_bf16 v[14:17], v[158:161], v[166:169], v[14:17]
	v_mfma_f32_16x16x32_bf16 v[90:93], v[150:153], v[174:177], v[90:93]
	v_mfma_f32_16x16x32_bf16 v[26:29], v[158:161], v[174:177], v[26:29]
	v_mfma_f32_16x16x32_bf16 v[86:89], v[150:153], v[182:185], v[86:89]
	v_mfma_f32_16x16x32_bf16 v[22:25], v[158:161], v[182:185], v[22:25]
	v_mfma_f32_16x16x32_bf16 v[78:81], v[150:153], v[190:193], v[78:81]
	v_mfma_f32_16x16x32_bf16 v[18:21], v[158:161], v[190:193], v[18:21]
	v_mfma_f32_16x16x32_bf16 v[74:77], v[154:157], v[170:173], v[74:77]
	v_mfma_f32_16x16x32_bf16 v[14:17], v[162:165], v[170:173], v[14:17]
	v_mfma_f32_16x16x32_bf16 v[90:93], v[154:157], v[178:181], v[90:93]
	v_mfma_f32_16x16x32_bf16 v[26:29], v[162:165], v[178:181], v[26:29]
	v_mfma_f32_16x16x32_bf16 v[86:89], v[154:157], v[186:189], v[86:89]
	v_mfma_f32_16x16x32_bf16 v[22:25], v[162:165], v[186:189], v[22:25]
	v_mfma_f32_16x16x32_bf16 v[78:81], v[154:157], v[194:197], v[78:81]
	v_mfma_f32_16x16x32_bf16 v[18:21], v[162:165], v[194:197], v[18:21]
	s_setprio 0
	s_barrier

.LBB0_1036:
	v_add_u32_e32 v11, s38, v152
	s_add_i32 s1, s1, 2
	ds_read_b128 v[156:159], v11
	ds_read_b128 v[160:163], v11 offset:1024
	ds_read_b128 v[164:167], v11 offset:2048
	ds_read_b128 v[168:171], v11 offset:3072
	v_add_u32_e32 v11, s39, v152
	s_add_u32 s3, s14, s58
	ds_read_b128 v[172:175], v11
	ds_read_b128 v[176:179], v11 offset:1024
	ds_read_b128 v[184:187], v11 offset:2048
	ds_read_b128 v[188:191], v11 offset:3072
	s_addc_u32 s22, s15, s59
	s_add_u32 s3, s3, 0x100
	s_addc_u32 s22, s22, 0
	s_add_u32 s23, s53, s58
	s_addc_u32 s24, s64, s59
	s_cmpk_eq_i32 s58, 0x1500
	s_cselect_b32 s61, s57, s24
	s_cselect_b32 s60, s56, s23
	s_cselect_b32 s63, s55, s22
	s_cselect_b32 s62, s54, s3
	v_lshl_add_u64 v[180:181], v[150:151], 0, s[58:59]
	s_add_i32 s24, s31, 0x8000
	v_lshl_add_u64 v[216:217], v[180:181], 0, s[42:43]
	s_mov_b32 m0, s24
	ds_read_b128 v[192:195], v154
	ds_read_b128 v[196:199], v154 offset:1024
	ds_read_b128 v[200:203], v154 offset:2048
	ds_read_b128 v[204:207], v154 offset:3072
	ds_read_b128 v[208:211], v154 offset:4096
	ds_read_b128 v[212:215], v154 offset:5120
	ds_read_b128 v[220:223], v154 offset:6144
	ds_read_b128 v[224:227], v154 offset:7168
	global_load_lds_dwordx4 v[216:217], off
	v_lshl_add_u64 v[216:217], v[12:13], 0, s[58:59]
	s_add_i32 s23, s31, 0xa000
	v_lshl_add_u64 v[228:229], v[216:217], 0, s[42:43]
	s_mov_b32 m0, s23
	s_add_i32 s3, s31, 0xc000
	global_load_lds_dwordx4 v[228:229], off
	v_lshl_add_u64 v[180:181], v[180:181], 0, s[44:45]
	s_mov_b32 m0, s3
	s_add_i32 s22, s31, 0xe000
	global_load_lds_dwordx4 v[180:181], off
	v_lshl_add_u64 v[180:181], v[216:217], 0, s[44:45]
	s_mov_b32 m0, s22
	s_nop 0
	global_load_lds_dwordx4 v[180:181], off
	s_waitcnt vmcnt(8)
	s_waitcnt lgkmcnt(0)
	s_setprio 1
	s_barrier
	v_mfma_f32_16x16x32_bf16 v[126:129], v[156:159], v[192:195], v[126:129]
	v_mfma_f32_16x16x32_bf16 v[122:125], v[164:167], v[192:195], v[122:125]
	v_mfma_f32_16x16x32_bf16 v[106:109], v[156:159], v[200:203], v[106:109]
	v_mfma_f32_16x16x32_bf16 v[110:113], v[164:167], v[200:203], v[110:113]
	v_mfma_f32_16x16x32_bf16 v[90:93], v[156:159], v[208:211], v[90:93]
	v_mfma_f32_16x16x32_bf16 v[94:97], v[164:167], v[208:211], v[94:97]
	v_mfma_f32_16x16x32_bf16 v[74:77], v[156:159], v[220:223], v[74:77]
	v_mfma_f32_16x16x32_bf16 v[78:81], v[164:167], v[220:223], v[78:81]
	v_mfma_f32_16x16x32_bf16 v[126:129], v[160:163], v[196:199], v[126:129]
	v_mfma_f32_16x16x32_bf16 v[122:125], v[168:171], v[196:199], v[122:125]
	v_mfma_f32_16x16x32_bf16 v[106:109], v[160:163], v[204:207], v[106:109]
	v_mfma_f32_16x16x32_bf16 v[110:113], v[168:171], v[204:207], v[110:113]
	v_mfma_f32_16x16x32_bf16 v[90:93], v[160:163], v[212:215], v[90:93]
	v_mfma_f32_16x16x32_bf16 v[94:97], v[168:171], v[212:215], v[94:97]
	v_mfma_f32_16x16x32_bf16 v[74:77], v[160:163], v[224:227], v[74:77]
	v_mfma_f32_16x16x32_bf16 v[78:81], v[168:171], v[224:227], v[78:81]
	v_mfma_f32_16x16x32_bf16 v[58:61], v[172:175], v[192:195], v[58:61]
	v_mfma_f32_16x16x32_bf16 v[62:65], v[184:187], v[192:195], v[62:65]
	v_mfma_f32_16x16x32_bf16 v[42:45], v[172:175], v[200:203], v[42:45]
	v_mfma_f32_16x16x32_bf16 v[46:49], v[184:187], v[200:203], v[46:49]
	v_mfma_f32_16x16x32_bf16 v[26:29], v[172:175], v[208:211], v[26:29]
	v_mfma_f32_16x16x32_bf16 v[30:33], v[184:187], v[208:211], v[30:33]
	v_mfma_f32_16x16x32_bf16 v[130:133], v[172:175], v[220:223], v[130:133]
	v_mfma_f32_16x16x32_bf16 v[14:17], v[184:187], v[220:223], v[14:17]
	v_mfma_f32_16x16x32_bf16 v[58:61], v[176:179], v[196:199], v[58:61]
	v_mfma_f32_16x16x32_bf16 v[62:65], v[188:191], v[196:199], v[62:65]
	v_mfma_f32_16x16x32_bf16 v[42:45], v[176:179], v[204:207], v[42:45]
	v_mfma_f32_16x16x32_bf16 v[46:49], v[188:191], v[204:207], v[46:49]
	v_mfma_f32_16x16x32_bf16 v[26:29], v[176:179], v[212:215], v[26:29]
	v_mfma_f32_16x16x32_bf16 v[30:33], v[188:191], v[212:215], v[30:33]
	v_mfma_f32_16x16x32_bf16 v[130:133], v[176:179], v[224:227], v[130:133]
	v_mfma_f32_16x16x32_bf16 v[14:17], v[188:191], v[224:227], v[14:17]
	s_setprio 0
	s_barrier
	s_add_i32 s25, s38, s30
	v_lshl_add_u64 v[180:181], s[60:61], 0, v[136:137]
	s_mov_b32 m0, s25
	ds_read_b128 v[192:195], v154 offset:16384
	ds_read_b128 v[196:199], v154 offset:17408
	ds_read_b128 v[200:203], v154 offset:18432
	ds_read_b128 v[204:207], v154 offset:19456
	ds_read_b128 v[208:211], v154 offset:20480
	ds_read_b128 v[212:215], v154 offset:21504
	ds_read_b128 v[220:223], v154 offset:22528
	ds_read_b128 v[224:227], v154 offset:23552
	global_load_lds_dwordx4 v[180:181], off
	s_add_i32 m0, s25, 0x2000
	s_add_u32 s26, s60, 0xb0000
	v_lshl_add_u64 v[216:217], s[60:61], 0, v[140:141]
	s_addc_u32 s27, s61, 0
	s_add_i32 s25, s39, s30
	global_load_lds_dwordx4 v[216:217], off
	v_lshl_add_u64 v[228:229], s[26:27], 0, v[136:137]
	s_mov_b32 m0, s25
	s_nop 0
	global_load_lds_dwordx4 v[228:229], off
	v_lshl_add_u64 v[228:229], s[26:27], 0, v[140:141]
	s_add_i32 m0, s25, 0x2000
	s_nop 0
	global_load_lds_dwordx4 v[228:229], off
	s_waitcnt vmcnt(4)
	s_waitcnt lgkmcnt(0)
	s_setprio 1
	s_barrier
	v_mfma_f32_16x16x32_bf16 v[114:117], v[156:159], v[192:195], v[114:117]
	v_mfma_f32_16x16x32_bf16 v[118:121], v[164:167], v[192:195], v[118:121]
	v_mfma_f32_16x16x32_bf16 v[98:101], v[156:159], v[200:203], v[98:101]
	v_mfma_f32_16x16x32_bf16 v[102:105], v[164:167], v[200:203], v[102:105]
	v_mfma_f32_16x16x32_bf16 v[82:85], v[156:159], v[208:211], v[82:85]
	v_mfma_f32_16x16x32_bf16 v[86:89], v[164:167], v[208:211], v[86:89]
	v_mfma_f32_16x16x32_bf16 v[66:69], v[156:159], v[220:223], v[66:69]
	v_mfma_f32_16x16x32_bf16 v[70:73], v[164:167], v[220:223], v[70:73]
	v_mfma_f32_16x16x32_bf16 v[114:117], v[160:163], v[196:199], v[114:117]
	v_mfma_f32_16x16x32_bf16 v[118:121], v[168:171], v[196:199], v[118:121]
	v_mfma_f32_16x16x32_bf16 v[98:101], v[160:163], v[204:207], v[98:101]
	v_mfma_f32_16x16x32_bf16 v[102:105], v[168:171], v[204:207], v[102:105]
	v_mfma_f32_16x16x32_bf16 v[82:85], v[160:163], v[212:215], v[82:85]
	v_mfma_f32_16x16x32_bf16 v[86:89], v[168:171], v[212:215], v[86:89]
	v_mfma_f32_16x16x32_bf16 v[66:69], v[160:163], v[224:227], v[66:69]
	v_mfma_f32_16x16x32_bf16 v[70:73], v[168:171], v[224:227], v[70:73]
	v_mfma_f32_16x16x32_bf16 v[50:53], v[172:175], v[192:195], v[50:53]
	v_mfma_f32_16x16x32_bf16 v[54:57], v[184:187], v[192:195], v[54:57]
	v_mfma_f32_16x16x32_bf16 v[34:37], v[172:175], v[200:203], v[34:37]
	v_mfma_f32_16x16x32_bf16 v[38:41], v[184:187], v[200:203], v[38:41]
	v_mfma_f32_16x16x32_bf16 v[18:21], v[172:175], v[208:211], v[18:21]
	v_mfma_f32_16x16x32_bf16 v[22:25], v[184:187], v[208:211], v[22:25]
	v_mfma_f32_16x16x32_bf16 v[6:9], v[172:175], v[220:223], v[6:9]
	v_mfma_f32_16x16x32_bf16 v[2:5], v[184:187], v[220:223], v[2:5]
	v_mfma_f32_16x16x32_bf16 v[50:53], v[176:179], v[196:199], v[50:53]
	v_mfma_f32_16x16x32_bf16 v[54:57], v[188:191], v[196:199], v[54:57]
	v_mfma_f32_16x16x32_bf16 v[34:37], v[176:179], v[204:207], v[34:37]
	v_mfma_f32_16x16x32_bf16 v[38:41], v[188:191], v[204:207], v[38:41]
	v_mfma_f32_16x16x32_bf16 v[18:21], v[176:179], v[212:215], v[18:21]
	v_mfma_f32_16x16x32_bf16 v[22:25], v[188:191], v[212:215], v[22:25]
	v_mfma_f32_16x16x32_bf16 v[6:9], v[176:179], v[224:227], v[6:9]
	v_mfma_f32_16x16x32_bf16 v[2:5], v[188:191], v[224:227], v[2:5]
	s_setprio 0
	s_barrier
	s_add_i32 s25, 0, 0x18000
	v_add_u32_e32 v11, s25, v152
	s_add_i32 s65, 0, 0x1c000
	ds_read_b128 v[156:159], v11
	ds_read_b128 v[160:163], v11 offset:1024
	ds_read_b128 v[164:167], v11 offset:2048
	ds_read_b128 v[168:171], v11 offset:3072
	v_add_u32_e32 v11, s65, v152
	ds_read_b128 v[172:175], v11
	ds_read_b128 v[176:179], v11 offset:1024
	ds_read_b128 v[184:187], v11 offset:2048
	ds_read_b128 v[188:191], v11 offset:3072
	s_mov_b32 m0, s31
	v_lshl_add_u64 v[228:229], s[62:63], 0, v[134:135]
	s_add_u32 s26, s62, 0xb0000
	ds_read_b128 v[192:195], v154 offset:32768
	ds_read_b128 v[196:199], v154 offset:33792
	ds_read_b128 v[200:203], v154 offset:34816
	ds_read_b128 v[204:207], v154 offset:35840
	ds_read_b128 v[208:211], v154 offset:36864
	ds_read_b128 v[212:215], v154 offset:37888
	ds_read_b128 v[220:223], v154 offset:38912
	ds_read_b128 v[224:227], v154 offset:39936
	global_load_lds_dwordx4 v[228:229], off
	v_lshl_add_u64 v[228:229], s[62:63], 0, v[138:139]
	s_mov_b32 m0, s33
	s_addc_u32 s27, s63, 0
	global_load_lds_dwordx4 v[228:229], off
	v_lshl_add_u64 v[228:229], s[26:27], 0, v[134:135]
	s_mov_b32 m0, s36
	s_nop 0
	global_load_lds_dwordx4 v[228:229], off
	v_lshl_add_u64 v[228:229], s[26:27], 0, v[138:139]
	s_mov_b32 m0, s37
	s_nop 0
	global_load_lds_dwordx4 v[228:229], off
	s_waitcnt vmcnt(8)
	s_waitcnt lgkmcnt(0)
	s_setprio 1
	s_barrier
	v_mfma_f32_16x16x32_bf16 v[126:129], v[156:159], v[192:195], v[126:129]
	v_mfma_f32_16x16x32_bf16 v[122:125], v[164:167], v[192:195], v[122:125]
	v_mfma_f32_16x16x32_bf16 v[106:109], v[156:159], v[200:203], v[106:109]
	v_mfma_f32_16x16x32_bf16 v[110:113], v[164:167], v[200:203], v[110:113]
	v_mfma_f32_16x16x32_bf16 v[90:93], v[156:159], v[208:211], v[90:93]
	v_mfma_f32_16x16x32_bf16 v[94:97], v[164:167], v[208:211], v[94:97]
	v_mfma_f32_16x16x32_bf16 v[74:77], v[156:159], v[220:223], v[74:77]
	v_mfma_f32_16x16x32_bf16 v[78:81], v[164:167], v[220:223], v[78:81]
	v_mfma_f32_16x16x32_bf16 v[126:129], v[160:163], v[196:199], v[126:129]
	v_mfma_f32_16x16x32_bf16 v[122:125], v[168:171], v[196:199], v[122:125]
	v_mfma_f32_16x16x32_bf16 v[106:109], v[160:163], v[204:207], v[106:109]
	v_mfma_f32_16x16x32_bf16 v[110:113], v[168:171], v[204:207], v[110:113]
	v_mfma_f32_16x16x32_bf16 v[90:93], v[160:163], v[212:215], v[90:93]
	v_mfma_f32_16x16x32_bf16 v[94:97], v[168:171], v[212:215], v[94:97]
	v_mfma_f32_16x16x32_bf16 v[74:77], v[160:163], v[224:227], v[74:77]
	v_mfma_f32_16x16x32_bf16 v[78:81], v[168:171], v[224:227], v[78:81]
	v_mfma_f32_16x16x32_bf16 v[58:61], v[172:175], v[192:195], v[58:61]
	v_mfma_f32_16x16x32_bf16 v[62:65], v[184:187], v[192:195], v[62:65]
	v_mfma_f32_16x16x32_bf16 v[42:45], v[172:175], v[200:203], v[42:45]
	v_mfma_f32_16x16x32_bf16 v[46:49], v[184:187], v[200:203], v[46:49]
	v_mfma_f32_16x16x32_bf16 v[26:29], v[172:175], v[208:211], v[26:29]
	v_mfma_f32_16x16x32_bf16 v[30:33], v[184:187], v[208:211], v[30:33]
	v_mfma_f32_16x16x32_bf16 v[130:133], v[172:175], v[220:223], v[130:133]
	v_mfma_f32_16x16x32_bf16 v[14:17], v[184:187], v[220:223], v[14:17]
	v_mfma_f32_16x16x32_bf16 v[58:61], v[176:179], v[196:199], v[58:61]
	v_mfma_f32_16x16x32_bf16 v[62:65], v[188:191], v[196:199], v[62:65]
	v_mfma_f32_16x16x32_bf16 v[42:45], v[176:179], v[204:207], v[42:45]
	v_mfma_f32_16x16x32_bf16 v[46:49], v[188:191], v[204:207], v[46:49]
	v_mfma_f32_16x16x32_bf16 v[26:29], v[176:179], v[212:215], v[26:29]
	v_mfma_f32_16x16x32_bf16 v[30:33], v[188:191], v[212:215], v[30:33]
	v_mfma_f32_16x16x32_bf16 v[130:133], v[176:179], v[224:227], v[130:133]
	v_mfma_f32_16x16x32_bf16 v[14:17], v[188:191], v[224:227], v[14:17]
	s_setprio 0
	s_barrier
	s_add_i32 s25, s25, s30
	v_lshl_add_u64 v[180:181], v[180:181], 0, s[42:43]
	s_mov_b32 m0, s25
	ds_read_b128 v[192:195], v154 offset:49152
	ds_read_b128 v[196:199], v154 offset:50176
	ds_read_b128 v[200:203], v154 offset:51200
	ds_read_b128 v[204:207], v154 offset:52224
	ds_read_b128 v[208:211], v154 offset:53248
	ds_read_b128 v[212:215], v154 offset:54272
	ds_read_b128 v[220:223], v154 offset:55296
	ds_read_b128 v[224:227], v154 offset:56320
	global_load_lds_dwordx4 v[180:181], off
	s_add_i32 m0, s25, 0x2000
	s_add_u32 s26, s60, 0xb0080
	v_lshl_add_u64 v[180:181], v[216:217], 0, s[42:43]
	s_addc_u32 s27, s61, 0
	s_add_i32 s25, s65, s30
	global_load_lds_dwordx4 v[180:181], off
	v_lshl_add_u64 v[180:181], s[26:27], 0, v[136:137]
	s_mov_b32 m0, s25
	s_nop 0
	global_load_lds_dwordx4 v[180:181], off
	v_lshl_add_u64 v[180:181], s[26:27], 0, v[140:141]
	s_add_i32 m0, s25, 0x2000
	s_nop 0
	global_load_lds_dwordx4 v[180:181], off
	s_waitcnt vmcnt(4)
	s_waitcnt lgkmcnt(0)
	s_setprio 1
	s_barrier
	v_mfma_f32_16x16x32_bf16 v[114:117], v[156:159], v[192:195], v[114:117]
	v_mfma_f32_16x16x32_bf16 v[118:121], v[164:167], v[192:195], v[118:121]
	v_mfma_f32_16x16x32_bf16 v[98:101], v[156:159], v[200:203], v[98:101]
	v_mfma_f32_16x16x32_bf16 v[102:105], v[164:167], v[200:203], v[102:105]
	v_mfma_f32_16x16x32_bf16 v[82:85], v[156:159], v[208:211], v[82:85]
	v_mfma_f32_16x16x32_bf16 v[86:89], v[164:167], v[208:211], v[86:89]
	v_mfma_f32_16x16x32_bf16 v[66:69], v[156:159], v[220:223], v[66:69]
	v_mfma_f32_16x16x32_bf16 v[70:73], v[164:167], v[220:223], v[70:73]
	v_mfma_f32_16x16x32_bf16 v[114:117], v[160:163], v[196:199], v[114:117]
	v_mfma_f32_16x16x32_bf16 v[118:121], v[168:171], v[196:199], v[118:121]
	v_mfma_f32_16x16x32_bf16 v[98:101], v[160:163], v[204:207], v[98:101]
	v_mfma_f32_16x16x32_bf16 v[102:105], v[168:171], v[204:207], v[102:105]
	v_mfma_f32_16x16x32_bf16 v[82:85], v[160:163], v[212:215], v[82:85]
	v_mfma_f32_16x16x32_bf16 v[86:89], v[168:171], v[212:215], v[86:89]
	v_mfma_f32_16x16x32_bf16 v[66:69], v[160:163], v[224:227], v[66:69]
	v_mfma_f32_16x16x32_bf16 v[70:73], v[168:171], v[224:227], v[70:73]
	v_mfma_f32_16x16x32_bf16 v[50:53], v[172:175], v[192:195], v[50:53]
	v_mfma_f32_16x16x32_bf16 v[54:57], v[184:187], v[192:195], v[54:57]
	v_mfma_f32_16x16x32_bf16 v[34:37], v[172:175], v[200:203], v[34:37]
	v_mfma_f32_16x16x32_bf16 v[38:41], v[184:187], v[200:203], v[38:41]
	v_mfma_f32_16x16x32_bf16 v[18:21], v[172:175], v[208:211], v[18:21]
	v_mfma_f32_16x16x32_bf16 v[22:25], v[184:187], v[208:211], v[22:25]
	v_mfma_f32_16x16x32_bf16 v[6:9], v[172:175], v[220:223], v[6:9]
	v_mfma_f32_16x16x32_bf16 v[2:5], v[184:187], v[220:223], v[2:5]
	v_mfma_f32_16x16x32_bf16 v[50:53], v[176:179], v[196:199], v[50:53]
	v_mfma_f32_16x16x32_bf16 v[54:57], v[188:191], v[196:199], v[54:57]
	v_mfma_f32_16x16x32_bf16 v[34:37], v[176:179], v[204:207], v[34:37]
	v_mfma_f32_16x16x32_bf16 v[38:41], v[188:191], v[204:207], v[38:41]
	v_mfma_f32_16x16x32_bf16 v[18:21], v[176:179], v[212:215], v[18:21]
	v_mfma_f32_16x16x32_bf16 v[22:25], v[188:191], v[212:215], v[22:25]
	v_mfma_f32_16x16x32_bf16 v[6:9], v[176:179], v[224:227], v[6:9]
	v_mfma_f32_16x16x32_bf16 v[2:5], v[188:191], v[224:227], v[2:5]
	s_setprio 0
	s_barrier
	s_add_u32 s58, s58, 0x100
	s_addc_u32 s59, s59, 0
	s_cmp_ge_u32 s1, s0
	s_cbranch_scc0 .LBB0_1036
	s_and_b64 vcc, exec, s[4:5]
	s_cbranch_vccz .LBB0_1040
	v_add_u32_e32 v11, 0, v152
	v_add_u32_e32 v12, 0x10000, v11
	ds_read_b128 v[156:159], v12
	ds_read_b128 v[160:163], v12 offset:1024
	ds_read_b128 v[164:167], v12 offset:2048
	ds_read_b128 v[168:171], v12 offset:3072
	v_add_u32_e32 v12, 0x14000, v11
	ds_read_b128 v[172:175], v12
	ds_read_b128 v[176:179], v12 offset:1024
	ds_read_b128 v[184:187], v12 offset:2048
	ds_read_b128 v[188:191], v12 offset:3072
	s_add_u32 s0, s14, 0x1580
	s_addc_u32 s1, s15, 0
	s_mov_b32 m0, s24
	v_lshl_add_u64 v[12:13], s[0:1], 0, v[134:135]
	ds_read_b128 v[192:195], v154
	ds_read_b128 v[196:199], v154 offset:1024
	ds_read_b128 v[200:203], v154 offset:2048
	ds_read_b128 v[204:207], v154 offset:3072
	ds_read_b128 v[208:211], v154 offset:4096
	ds_read_b128 v[212:215], v154 offset:5120
	ds_read_b128 v[220:223], v154 offset:6144
	ds_read_b128 v[224:227], v154 offset:7168
	global_load_lds_dwordx4 v[12:13], off
	v_lshl_add_u64 v[12:13], s[0:1], 0, v[138:139]
	s_add_u32 s0, s14, 0xb1580
	s_mov_b32 m0, s23
	s_addc_u32 s1, s15, 0
	global_load_lds_dwordx4 v[12:13], off
	v_lshl_add_u64 v[12:13], s[0:1], 0, v[134:135]
	s_mov_b32 m0, s3
	s_nop 0
	global_load_lds_dwordx4 v[12:13], off
	v_lshl_add_u64 v[12:13], s[0:1], 0, v[138:139]
	s_mov_b32 m0, s22
	s_nop 0
	global_load_lds_dwordx4 v[12:13], off
	s_waitcnt vmcnt(8)
	s_waitcnt lgkmcnt(0)
	s_setprio 1
	s_barrier
	v_mfma_f32_16x16x32_bf16 v[126:129], v[156:159], v[192:195], v[126:129]
	v_mfma_f32_16x16x32_bf16 v[122:125], v[164:167], v[192:195], v[122:125]
	v_mfma_f32_16x16x32_bf16 v[106:109], v[156:159], v[200:203], v[106:109]
	v_mfma_f32_16x16x32_bf16 v[110:113], v[164:167], v[200:203], v[110:113]
	v_mfma_f32_16x16x32_bf16 v[90:93], v[156:159], v[208:211], v[90:93]
	v_mfma_f32_16x16x32_bf16 v[94:97], v[164:167], v[208:211], v[94:97]
	v_mfma_f32_16x16x32_bf16 v[74:77], v[156:159], v[220:223], v[74:77]
	v_mfma_f32_16x16x32_bf16 v[78:81], v[164:167], v[220:223], v[78:81]
	v_mfma_f32_16x16x32_bf16 v[126:129], v[160:163], v[196:199], v[126:129]
	v_mfma_f32_16x16x32_bf16 v[122:125], v[168:171], v[196:199], v[122:125]
	v_mfma_f32_16x16x32_bf16 v[106:109], v[160:163], v[204:207], v[106:109]
	v_mfma_f32_16x16x32_bf16 v[110:113], v[168:171], v[204:207], v[110:113]
	v_mfma_f32_16x16x32_bf16 v[90:93], v[160:163], v[212:215], v[90:93]
	v_mfma_f32_16x16x32_bf16 v[94:97], v[168:171], v[212:215], v[94:97]
	v_mfma_f32_16x16x32_bf16 v[74:77], v[160:163], v[224:227], v[74:77]
	v_mfma_f32_16x16x32_bf16 v[78:81], v[168:171], v[224:227], v[78:81]
	v_mfma_f32_16x16x32_bf16 v[58:61], v[172:175], v[192:195], v[58:61]
	v_mfma_f32_16x16x32_bf16 v[62:65], v[184:187], v[192:195], v[62:65]
	v_mfma_f32_16x16x32_bf16 v[42:45], v[172:175], v[200:203], v[42:45]
	v_mfma_f32_16x16x32_bf16 v[46:49], v[184:187], v[200:203], v[46:49]
	v_mfma_f32_16x16x32_bf16 v[26:29], v[172:175], v[208:211], v[26:29]
	v_mfma_f32_16x16x32_bf16 v[30:33], v[184:187], v[208:211], v[30:33]
	v_mfma_f32_16x16x32_bf16 v[130:133], v[172:175], v[220:223], v[130:133]
	v_mfma_f32_16x16x32_bf16 v[12:15], v[184:187], v[220:223], v[14:17]
	v_mfma_f32_16x16x32_bf16 v[58:61], v[176:179], v[196:199], v[58:61]
	v_mfma_f32_16x16x32_bf16 v[62:65], v[188:191], v[196:199], v[62:65]
	v_mfma_f32_16x16x32_bf16 v[42:45], v[176:179], v[204:207], v[42:45]
	v_mfma_f32_16x16x32_bf16 v[46:49], v[188:191], v[204:207], v[46:49]
	v_mfma_f32_16x16x32_bf16 v[26:29], v[176:179], v[212:215], v[26:29]
	v_mfma_f32_16x16x32_bf16 v[30:33], v[188:191], v[212:215], v[30:33]
	v_mfma_f32_16x16x32_bf16 v[130:133], v[176:179], v[224:227], v[130:133]
	v_mfma_f32_16x16x32_bf16 v[12:15], v[188:191], v[224:227], v[12:15]
	s_setprio 0
	s_barrier
	ds_read_b128 v[192:195], v154 offset:16384
	ds_read_b128 v[196:199], v154 offset:17408
	ds_read_b128 v[200:203], v154 offset:18432
	ds_read_b128 v[204:207], v154 offset:19456
	ds_read_b128 v[208:211], v154 offset:20480
	ds_read_b128 v[212:215], v154 offset:21504
	ds_read_b128 v[220:223], v154 offset:22528
	ds_read_b128 v[224:227], v154 offset:23552
	s_waitcnt vmcnt(0)
	s_waitcnt lgkmcnt(0)
	s_setprio 1
	s_barrier
	v_mfma_f32_16x16x32_bf16 v[114:117], v[156:159], v[192:195], v[114:117]
	v_mfma_f32_16x16x32_bf16 v[118:121], v[164:167], v[192:195], v[118:121]
	v_mfma_f32_16x16x32_bf16 v[98:101], v[156:159], v[200:203], v[98:101]
	v_mfma_f32_16x16x32_bf16 v[102:105], v[164:167], v[200:203], v[102:105]
	v_mfma_f32_16x16x32_bf16 v[82:85], v[156:159], v[208:211], v[82:85]
	v_mfma_f32_16x16x32_bf16 v[86:89], v[164:167], v[208:211], v[86:89]
	v_mfma_f32_16x16x32_bf16 v[66:69], v[156:159], v[220:223], v[66:69]
	v_mfma_f32_16x16x32_bf16 v[70:73], v[164:167], v[220:223], v[70:73]
	v_mfma_f32_16x16x32_bf16 v[114:117], v[160:163], v[196:199], v[114:117]
	v_mfma_f32_16x16x32_bf16 v[118:121], v[168:171], v[196:199], v[118:121]
	v_mfma_f32_16x16x32_bf16 v[98:101], v[160:163], v[204:207], v[98:101]
	v_mfma_f32_16x16x32_bf16 v[102:105], v[168:171], v[204:207], v[102:105]
	v_mfma_f32_16x16x32_bf16 v[82:85], v[160:163], v[212:215], v[82:85]
	v_mfma_f32_16x16x32_bf16 v[86:89], v[168:171], v[212:215], v[86:89]
	v_mfma_f32_16x16x32_bf16 v[66:69], v[160:163], v[224:227], v[66:69]
	v_mfma_f32_16x16x32_bf16 v[70:73], v[168:171], v[224:227], v[70:73]
	v_mfma_f32_16x16x32_bf16 v[50:53], v[172:175], v[192:195], v[50:53]
	v_mfma_f32_16x16x32_bf16 v[54:57], v[184:187], v[192:195], v[54:57]
	v_mfma_f32_16x16x32_bf16 v[34:37], v[172:175], v[200:203], v[34:37]
	v_mfma_f32_16x16x32_bf16 v[38:41], v[184:187], v[200:203], v[38:41]
	v_mfma_f32_16x16x32_bf16 v[16:19], v[172:175], v[208:211], v[18:21]
	v_mfma_f32_16x16x32_bf16 v[22:25], v[184:187], v[208:211], v[22:25]
	v_mfma_f32_16x16x32_bf16 v[6:9], v[172:175], v[220:223], v[6:9]
	v_mfma_f32_16x16x32_bf16 v[2:5], v[184:187], v[220:223], v[2:5]
	v_mfma_f32_16x16x32_bf16 v[50:53], v[176:179], v[196:199], v[50:53]
	v_mfma_f32_16x16x32_bf16 v[54:57], v[188:191], v[196:199], v[54:57]
	v_mfma_f32_16x16x32_bf16 v[34:37], v[176:179], v[204:207], v[34:37]
	v_mfma_f32_16x16x32_bf16 v[38:41], v[188:191], v[204:207], v[38:41]
	v_mfma_f32_16x16x32_bf16 v[18:21], v[176:179], v[212:215], v[16:19]
	v_mfma_f32_16x16x32_bf16 v[22:25], v[188:191], v[212:215], v[22:25]
	v_mfma_f32_16x16x32_bf16 v[6:9], v[176:179], v[224:227], v[6:9]
	v_mfma_f32_16x16x32_bf16 v[2:5], v[188:191], v[224:227], v[2:5]
	s_setprio 0
	s_barrier
	v_add_u32_e32 v16, 0x18000, v11
	v_add_u32_e32 v11, 0x1c000, v11
	ds_read_b128 v[156:159], v16
	ds_read_b128 v[160:163], v16 offset:1024
	ds_read_b128 v[164:167], v16 offset:2048
	ds_read_b128 v[168:171], v16 offset:3072
	ds_read_b128 v[172:175], v11
	ds_read_b128 v[176:179], v11 offset:1024
	ds_read_b128 v[184:187], v11 offset:2048
	ds_read_b128 v[188:191], v11 offset:3072
	ds_read_b128 v[192:195], v154 offset:32768
	ds_read_b128 v[196:199], v154 offset:33792
	ds_read_b128 v[200:203], v154 offset:34816
	ds_read_b128 v[204:207], v154 offset:35840
	ds_read_b128 v[208:211], v154 offset:36864
	ds_read_b128 v[212:215], v154 offset:37888
	ds_read_b128 v[220:223], v154 offset:38912
	ds_read_b128 v[224:227], v154 offset:39936
	s_waitcnt lgkmcnt(0)
	s_setprio 1
	s_barrier
	v_mfma_f32_16x16x32_bf16 v[126:129], v[156:159], v[192:195], v[126:129]
	v_mfma_f32_16x16x32_bf16 v[122:125], v[164:167], v[192:195], v[122:125]
	v_mfma_f32_16x16x32_bf16 v[106:109], v[156:159], v[200:203], v[106:109]
	v_mfma_f32_16x16x32_bf16 v[110:113], v[164:167], v[200:203], v[110:113]
	v_mfma_f32_16x16x32_bf16 v[90:93], v[156:159], v[208:211], v[90:93]
	v_mfma_f32_16x16x32_bf16 v[94:97], v[164:167], v[208:211], v[94:97]
	v_mfma_f32_16x16x32_bf16 v[74:77], v[156:159], v[220:223], v[74:77]
	v_mfma_f32_16x16x32_bf16 v[78:81], v[164:167], v[220:223], v[78:81]
	v_mfma_f32_16x16x32_bf16 v[126:129], v[160:163], v[196:199], v[126:129]
	v_mfma_f32_16x16x32_bf16 v[122:125], v[168:171], v[196:199], v[122:125]
	v_mfma_f32_16x16x32_bf16 v[106:109], v[160:163], v[204:207], v[106:109]
	v_mfma_f32_16x16x32_bf16 v[110:113], v[168:171], v[204:207], v[110:113]
	v_mfma_f32_16x16x32_bf16 v[90:93], v[160:163], v[212:215], v[90:93]
	v_mfma_f32_16x16x32_bf16 v[94:97], v[168:171], v[212:215], v[94:97]
	v_mfma_f32_16x16x32_bf16 v[74:77], v[160:163], v[224:227], v[74:77]
	v_mfma_f32_16x16x32_bf16 v[78:81], v[168:171], v[224:227], v[78:81]
	v_mfma_f32_16x16x32_bf16 v[58:61], v[172:175], v[192:195], v[58:61]
	v_mfma_f32_16x16x32_bf16 v[62:65], v[184:187], v[192:195], v[62:65]
	v_mfma_f32_16x16x32_bf16 v[42:45], v[172:175], v[200:203], v[42:45]
	v_mfma_f32_16x16x32_bf16 v[46:49], v[184:187], v[200:203], v[46:49]
	v_mfma_f32_16x16x32_bf16 v[26:29], v[172:175], v[208:211], v[26:29]
	v_mfma_f32_16x16x32_bf16 v[30:33], v[184:187], v[208:211], v[30:33]
	v_mfma_f32_16x16x32_bf16 v[130:133], v[172:175], v[220:223], v[130:133]
	v_mfma_f32_16x16x32_bf16 v[12:15], v[184:187], v[220:223], v[12:15]
	v_mfma_f32_16x16x32_bf16 v[58:61], v[176:179], v[196:199], v[58:61]
	v_mfma_f32_16x16x32_bf16 v[62:65], v[188:191], v[196:199], v[62:65]
	v_mfma_f32_16x16x32_bf16 v[42:45], v[176:179], v[204:207], v[42:45]
	v_mfma_f32_16x16x32_bf16 v[46:49], v[188:191], v[204:207], v[46:49]
	v_mfma_f32_16x16x32_bf16 v[26:29], v[176:179], v[212:215], v[26:29]
	v_mfma_f32_16x16x32_bf16 v[30:33], v[188:191], v[212:215], v[30:33]
	v_mfma_f32_16x16x32_bf16 v[130:133], v[176:179], v[224:227], v[130:133]
	v_mfma_f32_16x16x32_bf16 v[14:17], v[188:191], v[224:227], v[12:15]
	s_setprio 0
	s_barrier
	ds_read_b128 v[192:195], v154 offset:49152
	ds_read_b128 v[196:199], v154 offset:50176
	ds_read_b128 v[200:203], v154 offset:51200
	ds_read_b128 v[204:207], v154 offset:52224
	ds_read_b128 v[208:211], v154 offset:53248
	ds_read_b128 v[212:215], v154 offset:54272
	ds_read_b128 v[220:223], v154 offset:55296
	ds_read_b128 v[224:227], v154 offset:56320
	s_waitcnt lgkmcnt(0)
	s_setprio 1
	s_barrier
	v_mfma_f32_16x16x32_bf16 v[114:117], v[156:159], v[192:195], v[114:117]
	v_mfma_f32_16x16x32_bf16 v[118:121], v[164:167], v[192:195], v[118:121]
	v_mfma_f32_16x16x32_bf16 v[98:101], v[156:159], v[200:203], v[98:101]
	v_mfma_f32_16x16x32_bf16 v[102:105], v[164:167], v[200:203], v[102:105]
	v_mfma_f32_16x16x32_bf16 v[82:85], v[156:159], v[208:211], v[82:85]
	v_mfma_f32_16x16x32_bf16 v[86:89], v[164:167], v[208:211], v[86:89]
	v_mfma_f32_16x16x32_bf16 v[66:69], v[156:159], v[220:223], v[66:69]
	v_mfma_f32_16x16x32_bf16 v[70:73], v[164:167], v[220:223], v[70:73]
	v_mfma_f32_16x16x32_bf16 v[114:117], v[160:163], v[196:199], v[114:117]
	v_mfma_f32_16x16x32_bf16 v[118:121], v[168:171], v[196:199], v[118:121]
	v_mfma_f32_16x16x32_bf16 v[98:101], v[160:163], v[204:207], v[98:101]
	v_mfma_f32_16x16x32_bf16 v[102:105], v[168:171], v[204:207], v[102:105]
	v_mfma_f32_16x16x32_bf16 v[82:85], v[160:163], v[212:215], v[82:85]
	v_mfma_f32_16x16x32_bf16 v[86:89], v[168:171], v[212:215], v[86:89]
	v_mfma_f32_16x16x32_bf16 v[66:69], v[160:163], v[224:227], v[66:69]
	v_mfma_f32_16x16x32_bf16 v[70:73], v[168:171], v[224:227], v[70:73]
	v_mfma_f32_16x16x32_bf16 v[50:53], v[172:175], v[192:195], v[50:53]
	v_mfma_f32_16x16x32_bf16 v[54:57], v[184:187], v[192:195], v[54:57]
	v_mfma_f32_16x16x32_bf16 v[34:37], v[172:175], v[200:203], v[34:37]
	v_mfma_f32_16x16x32_bf16 v[38:41], v[184:187], v[200:203], v[38:41]
	v_mfma_f32_16x16x32_bf16 v[18:21], v[172:175], v[208:211], v[18:21]
	v_mfma_f32_16x16x32_bf16 v[22:25], v[184:187], v[208:211], v[22:25]
	v_mfma_f32_16x16x32_bf16 v[6:9], v[172:175], v[220:223], v[6:9]
	v_mfma_f32_16x16x32_bf16 v[2:5], v[184:187], v[220:223], v[2:5]
	v_mfma_f32_16x16x32_bf16 v[50:53], v[176:179], v[196:199], v[50:53]
	v_mfma_f32_16x16x32_bf16 v[54:57], v[188:191], v[196:199], v[54:57]
	v_mfma_f32_16x16x32_bf16 v[34:37], v[176:179], v[204:207], v[34:37]
	v_mfma_f32_16x16x32_bf16 v[38:41], v[188:191], v[204:207], v[38:41]
	v_mfma_f32_16x16x32_bf16 v[18:21], v[176:179], v[212:215], v[18:21]
	v_mfma_f32_16x16x32_bf16 v[22:25], v[188:191], v[212:215], v[22:25]
	v_mfma_f32_16x16x32_bf16 v[6:9], v[176:179], v[224:227], v[6:9]
	v_mfma_f32_16x16x32_bf16 v[2:5], v[188:191], v[224:227], v[2:5]
	s_setprio 0
	s_barrier
	s_andn2_b64 vcc, exec, s[48:49]
	s_cbranch_vccz .LBB0_1041

.LBB0_1134:
	s_add_i32 s51, s51, 2
	s_add_u32 s0, s10, s86
	ds_read_b128 v[134:137], v243
	ds_read_b128 v[138:141], v243 offset:1024
	ds_read_b128 v[142:145], v243 offset:2048
	ds_read_b128 v[146:149], v243 offset:3072
	ds_read_b128 v[150:153], v244
	ds_read_b128 v[154:157], v244 offset:1024
	ds_read_b128 v[158:161], v244 offset:2048
	ds_read_b128 v[162:165], v244 offset:3072
	s_addc_u32 s1, s11, s87
	s_add_u32 s0, s0, 0x100
	s_addc_u32 s1, s1, 0
	s_add_u32 s3, s14, s86
	s_addc_u32 s22, s50, s87
	s_cmpk_eq_i32 s86, 0x700
	s_cselect_b32 s89, s83, s22
	s_cselect_b32 s88, s82, s3
	s_cselect_b32 s91, s85, s1
	s_cselect_b32 s90, s84, s0
	v_lshl_add_u64 v[214:215], v[132:133], 0, s[86:87]
	s_add_i32 s0, s21, 0x8000
	v_lshl_add_u64 v[216:217], v[214:215], 0, s[44:45]
	s_mov_b32 m0, s0
	ds_read_b128 v[166:169], v245
	ds_read_b128 v[170:173], v245 offset:1024
	ds_read_b128 v[174:177], v245 offset:2048
	ds_read_b128 v[178:181], v245 offset:3072
	ds_read_b128 v[182:185], v245 offset:4096
	ds_read_b128 v[186:189], v245 offset:5120
	ds_read_b128 v[190:193], v245 offset:6144
	ds_read_b128 v[210:213], v245 offset:7168
	global_load_lds_dwordx4 v[216:217], off
	v_lshl_add_u64 v[216:217], v[130:131], 0, s[86:87]
	s_add_i32 s67, s21, 0xa000
	v_lshl_add_u64 v[218:219], v[216:217], 0, s[44:45]
	s_mov_b32 m0, s67
	s_add_i32 s22, s21, 0xc000
	global_load_lds_dwordx4 v[218:219], off
	v_lshl_add_u64 v[214:215], v[214:215], 0, s[46:47]
	s_mov_b32 m0, s22
	s_add_i32 s23, s21, 0xe000
	global_load_lds_dwordx4 v[214:215], off
	v_lshl_add_u64 v[214:215], v[216:217], 0, s[46:47]
	s_mov_b32 m0, s23
	s_nop 0
	global_load_lds_dwordx4 v[214:215], off
	s_waitcnt vmcnt(8)
	s_waitcnt lgkmcnt(0)
	s_setprio 1
	s_barrier
	v_mfma_f32_16x16x32_bf16 v[118:121], v[134:137], v[166:169], v[118:121]
	v_mfma_f32_16x16x32_bf16 v[114:117], v[142:145], v[166:169], v[114:117]
	v_mfma_f32_16x16x32_bf16 v[62:65], v[134:137], v[174:177], v[62:65]
	v_mfma_f32_16x16x32_bf16 v[58:61], v[142:145], v[174:177], v[58:61]
	v_mfma_f32_16x16x32_bf16 v[54:57], v[134:137], v[182:185], v[54:57]
	v_mfma_f32_16x16x32_bf16 v[50:53], v[142:145], v[182:185], v[50:53]
	v_mfma_f32_16x16x32_bf16 v[126:129], v[134:137], v[190:193], v[126:129]
	v_mfma_f32_16x16x32_bf16 v[102:105], v[142:145], v[190:193], v[102:105]
	v_mfma_f32_16x16x32_bf16 v[118:121], v[138:141], v[170:173], v[118:121]
	v_mfma_f32_16x16x32_bf16 v[114:117], v[146:149], v[170:173], v[114:117]
	v_mfma_f32_16x16x32_bf16 v[62:65], v[138:141], v[178:181], v[62:65]
	v_mfma_f32_16x16x32_bf16 v[58:61], v[146:149], v[178:181], v[58:61]
	v_mfma_f32_16x16x32_bf16 v[54:57], v[138:141], v[186:189], v[54:57]
	v_mfma_f32_16x16x32_bf16 v[50:53], v[146:149], v[186:189], v[50:53]
	v_mfma_f32_16x16x32_bf16 v[126:129], v[138:141], v[210:213], v[126:129]
	v_mfma_f32_16x16x32_bf16 v[102:105], v[146:149], v[210:213], v[102:105]
	v_mfma_f32_16x16x32_bf16 v[110:113], v[150:153], v[166:169], v[110:113]
	v_mfma_f32_16x16x32_bf16 v[106:109], v[158:161], v[166:169], v[106:109]
	v_mfma_f32_16x16x32_bf16 v[46:49], v[150:153], v[174:177], v[46:49]
	v_mfma_f32_16x16x32_bf16 v[42:45], v[158:161], v[174:177], v[42:45]
	v_mfma_f32_16x16x32_bf16 v[38:41], v[150:153], v[182:185], v[38:41]
	v_mfma_f32_16x16x32_bf16 v[34:37], v[158:161], v[182:185], v[34:37]
	v_mfma_f32_16x16x32_bf16 v[122:125], v[150:153], v[190:193], v[122:125]
	v_mfma_f32_16x16x32_bf16 v[98:101], v[158:161], v[190:193], v[98:101]
	v_mfma_f32_16x16x32_bf16 v[110:113], v[154:157], v[170:173], v[110:113]
	v_mfma_f32_16x16x32_bf16 v[106:109], v[162:165], v[170:173], v[106:109]
	v_mfma_f32_16x16x32_bf16 v[46:49], v[154:157], v[178:181], v[46:49]
	v_mfma_f32_16x16x32_bf16 v[42:45], v[162:165], v[178:181], v[42:45]
	v_mfma_f32_16x16x32_bf16 v[38:41], v[154:157], v[186:189], v[38:41]
	v_mfma_f32_16x16x32_bf16 v[34:37], v[162:165], v[186:189], v[34:37]
	v_mfma_f32_16x16x32_bf16 v[122:125], v[154:157], v[210:213], v[122:125]
	v_mfma_f32_16x16x32_bf16 v[98:101], v[162:165], v[210:213], v[98:101]
	s_setprio 0
	s_barrier
	s_add_i32 s1, s36, s20
	v_lshl_add_u64 v[214:215], s[88:89], 0, v[196:197]
	s_mov_b32 m0, s1
	ds_read_b128 v[166:169], v245 offset:16384
	ds_read_b128 v[170:173], v245 offset:17408
	ds_read_b128 v[174:177], v245 offset:18432
	ds_read_b128 v[178:181], v245 offset:19456
	ds_read_b128 v[182:185], v245 offset:20480
	ds_read_b128 v[186:189], v245 offset:21504
	ds_read_b128 v[190:193], v245 offset:22528
	ds_read_b128 v[210:213], v245 offset:23552
	global_load_lds_dwordx4 v[214:215], off
	s_add_i32 m0, s1, 0x2000
	s_add_u32 s24, s88, 0x40000
	v_lshl_add_u64 v[216:217], s[88:89], 0, v[200:201]
	s_addc_u32 s25, s89, 0
	s_add_i32 s1, s37, s20
	global_load_lds_dwordx4 v[216:217], off
	v_lshl_add_u64 v[218:219], s[24:25], 0, v[196:197]
	s_mov_b32 m0, s1
	s_nop 0
	global_load_lds_dwordx4 v[218:219], off
	v_lshl_add_u64 v[218:219], s[24:25], 0, v[200:201]
	s_add_i32 m0, s1, 0x2000
	s_nop 0
	global_load_lds_dwordx4 v[218:219], off
	s_waitcnt vmcnt(4)
	s_waitcnt lgkmcnt(0)
	s_setprio 1
	s_barrier
	v_mfma_f32_16x16x32_bf16 v[94:97], v[134:137], v[166:169], v[94:97]
	v_mfma_f32_16x16x32_bf16 v[90:93], v[142:145], v[166:169], v[90:93]
	v_mfma_f32_16x16x32_bf16 v[30:33], v[134:137], v[174:177], v[30:33]
	v_mfma_f32_16x16x32_bf16 v[26:29], v[142:145], v[174:177], v[26:29]
	v_mfma_f32_16x16x32_bf16 v[22:25], v[134:137], v[182:185], v[22:25]
	v_mfma_f32_16x16x32_bf16 v[18:21], v[142:145], v[182:185], v[18:21]
	v_mfma_f32_16x16x32_bf16 v[82:85], v[134:137], v[190:193], v[82:85]
	v_mfma_f32_16x16x32_bf16 v[74:77], v[142:145], v[190:193], v[74:77]
	v_mfma_f32_16x16x32_bf16 v[94:97], v[138:141], v[170:173], v[94:97]
	v_mfma_f32_16x16x32_bf16 v[90:93], v[146:149], v[170:173], v[90:93]
	v_mfma_f32_16x16x32_bf16 v[30:33], v[138:141], v[178:181], v[30:33]
	v_mfma_f32_16x16x32_bf16 v[26:29], v[146:149], v[178:181], v[26:29]
	v_mfma_f32_16x16x32_bf16 v[22:25], v[138:141], v[186:189], v[22:25]
	v_mfma_f32_16x16x32_bf16 v[18:21], v[146:149], v[186:189], v[18:21]
	v_mfma_f32_16x16x32_bf16 v[82:85], v[138:141], v[210:213], v[82:85]
	v_mfma_f32_16x16x32_bf16 v[74:77], v[146:149], v[210:213], v[74:77]
	v_mfma_f32_16x16x32_bf16 v[86:89], v[150:153], v[166:169], v[86:89]
	v_mfma_f32_16x16x32_bf16 v[78:81], v[158:161], v[166:169], v[78:81]
	v_mfma_f32_16x16x32_bf16 v[14:17], v[150:153], v[174:177], v[14:17]
	v_mfma_f32_16x16x32_bf16 v[10:13], v[158:161], v[174:177], v[10:13]
	v_mfma_f32_16x16x32_bf16 v[6:9], v[150:153], v[182:185], v[6:9]
	v_mfma_f32_16x16x32_bf16 v[2:5], v[158:161], v[182:185], v[2:5]
	v_mfma_f32_16x16x32_bf16 v[70:73], v[150:153], v[190:193], v[70:73]
	v_mfma_f32_16x16x32_bf16 v[66:69], v[158:161], v[190:193], v[66:69]
	v_mfma_f32_16x16x32_bf16 v[86:89], v[154:157], v[170:173], v[86:89]
	v_mfma_f32_16x16x32_bf16 v[78:81], v[162:165], v[170:173], v[78:81]
	v_mfma_f32_16x16x32_bf16 v[14:17], v[154:157], v[178:181], v[14:17]
	v_mfma_f32_16x16x32_bf16 v[10:13], v[162:165], v[178:181], v[10:13]
	v_mfma_f32_16x16x32_bf16 v[6:9], v[154:157], v[186:189], v[6:9]
	v_mfma_f32_16x16x32_bf16 v[2:5], v[162:165], v[186:189], v[2:5]
	v_mfma_f32_16x16x32_bf16 v[70:73], v[154:157], v[210:213], v[70:73]
	v_mfma_f32_16x16x32_bf16 v[66:69], v[162:165], v[210:213], v[66:69]
	s_setprio 0
	s_barrier
	s_add_i32 s1, 0, 0x18000
	s_add_i32 s3, 0, 0x1c000
	v_add_u32_e32 v146, s1, v233
	v_add_u32_e32 v162, s3, v233
	ds_read_b128 v[134:137], v146
	ds_read_b128 v[138:141], v146 offset:1024
	ds_read_b128 v[142:145], v146 offset:2048
	ds_read_b128 v[146:149], v146 offset:3072
	ds_read_b128 v[150:153], v162
	ds_read_b128 v[154:157], v162 offset:1024
	ds_read_b128 v[158:161], v162 offset:2048
	ds_read_b128 v[162:165], v162 offset:3072
	s_mov_b32 m0, s21
	v_lshl_add_u64 v[218:219], s[90:91], 0, v[194:195]
	s_add_u32 s24, s90, 0x40000
	ds_read_b128 v[166:169], v245 offset:32768
	ds_read_b128 v[170:173], v245 offset:33792
	ds_read_b128 v[174:177], v245 offset:34816
	ds_read_b128 v[178:181], v245 offset:35840
	ds_read_b128 v[182:185], v245 offset:36864
	ds_read_b128 v[186:189], v245 offset:37888
	ds_read_b128 v[190:193], v245 offset:38912
	ds_read_b128 v[210:213], v245 offset:39936
	global_load_lds_dwordx4 v[218:219], off
	v_lshl_add_u64 v[218:219], s[90:91], 0, v[198:199]
	s_mov_b32 m0, s28
	s_addc_u32 s25, s91, 0
	global_load_lds_dwordx4 v[218:219], off
	v_lshl_add_u64 v[218:219], s[24:25], 0, v[194:195]
	s_mov_b32 m0, s29
	s_nop 0
	global_load_lds_dwordx4 v[218:219], off
	v_lshl_add_u64 v[218:219], s[24:25], 0, v[198:199]
	s_mov_b32 m0, s30
	s_nop 0
	global_load_lds_dwordx4 v[218:219], off
	s_waitcnt vmcnt(8)
	s_waitcnt lgkmcnt(0)
	s_setprio 1
	s_barrier
	v_mfma_f32_16x16x32_bf16 v[118:121], v[134:137], v[166:169], v[118:121]
	v_mfma_f32_16x16x32_bf16 v[114:117], v[142:145], v[166:169], v[114:117]
	v_mfma_f32_16x16x32_bf16 v[62:65], v[134:137], v[174:177], v[62:65]
	v_mfma_f32_16x16x32_bf16 v[58:61], v[142:145], v[174:177], v[58:61]
	v_mfma_f32_16x16x32_bf16 v[54:57], v[134:137], v[182:185], v[54:57]
	v_mfma_f32_16x16x32_bf16 v[50:53], v[142:145], v[182:185], v[50:53]
	v_mfma_f32_16x16x32_bf16 v[126:129], v[134:137], v[190:193], v[126:129]
	v_mfma_f32_16x16x32_bf16 v[102:105], v[142:145], v[190:193], v[102:105]
	v_mfma_f32_16x16x32_bf16 v[118:121], v[138:141], v[170:173], v[118:121]
	v_mfma_f32_16x16x32_bf16 v[114:117], v[146:149], v[170:173], v[114:117]
	v_mfma_f32_16x16x32_bf16 v[62:65], v[138:141], v[178:181], v[62:65]
	v_mfma_f32_16x16x32_bf16 v[58:61], v[146:149], v[178:181], v[58:61]
	v_mfma_f32_16x16x32_bf16 v[54:57], v[138:141], v[186:189], v[54:57]
	v_mfma_f32_16x16x32_bf16 v[50:53], v[146:149], v[186:189], v[50:53]
	v_mfma_f32_16x16x32_bf16 v[126:129], v[138:141], v[210:213], v[126:129]
	v_mfma_f32_16x16x32_bf16 v[102:105], v[146:149], v[210:213], v[102:105]
	v_mfma_f32_16x16x32_bf16 v[110:113], v[150:153], v[166:169], v[110:113]
	v_mfma_f32_16x16x32_bf16 v[106:109], v[158:161], v[166:169], v[106:109]
	v_mfma_f32_16x16x32_bf16 v[46:49], v[150:153], v[174:177], v[46:49]
	v_mfma_f32_16x16x32_bf16 v[42:45], v[158:161], v[174:177], v[42:45]
	v_mfma_f32_16x16x32_bf16 v[38:41], v[150:153], v[182:185], v[38:41]
	v_mfma_f32_16x16x32_bf16 v[34:37], v[158:161], v[182:185], v[34:37]
	v_mfma_f32_16x16x32_bf16 v[122:125], v[150:153], v[190:193], v[122:125]
	v_mfma_f32_16x16x32_bf16 v[98:101], v[158:161], v[190:193], v[98:101]
	v_mfma_f32_16x16x32_bf16 v[110:113], v[154:157], v[170:173], v[110:113]
	v_mfma_f32_16x16x32_bf16 v[106:109], v[162:165], v[170:173], v[106:109]
	v_mfma_f32_16x16x32_bf16 v[46:49], v[154:157], v[178:181], v[46:49]
	v_mfma_f32_16x16x32_bf16 v[42:45], v[162:165], v[178:181], v[42:45]
	v_mfma_f32_16x16x32_bf16 v[38:41], v[154:157], v[186:189], v[38:41]
	v_mfma_f32_16x16x32_bf16 v[34:37], v[162:165], v[186:189], v[34:37]
	v_mfma_f32_16x16x32_bf16 v[122:125], v[154:157], v[210:213], v[122:125]
	v_mfma_f32_16x16x32_bf16 v[98:101], v[162:165], v[210:213], v[98:101]
	s_setprio 0
	s_barrier
	s_add_i32 s1, s1, s20
	v_lshl_add_u64 v[214:215], v[214:215], 0, s[44:45]
	s_mov_b32 m0, s1
	ds_read_b128 v[166:169], v245 offset:49152
	ds_read_b128 v[170:173], v245 offset:50176
	ds_read_b128 v[174:177], v245 offset:51200
	ds_read_b128 v[178:181], v245 offset:52224
	ds_read_b128 v[182:185], v245 offset:53248
	ds_read_b128 v[186:189], v245 offset:54272
	ds_read_b128 v[190:193], v245 offset:55296
	ds_read_b128 v[210:213], v245 offset:56320
	global_load_lds_dwordx4 v[214:215], off
	s_add_i32 m0, s1, 0x2000
	s_add_u32 s24, s88, 0x40080
	v_lshl_add_u64 v[214:215], v[216:217], 0, s[44:45]
	s_addc_u32 s25, s89, 0
	s_add_i32 s1, s3, s20
	global_load_lds_dwordx4 v[214:215], off
	v_lshl_add_u64 v[214:215], s[24:25], 0, v[196:197]
	s_mov_b32 m0, s1
	s_nop 0
	global_load_lds_dwordx4 v[214:215], off
	v_lshl_add_u64 v[214:215], s[24:25], 0, v[200:201]
	s_add_i32 m0, s1, 0x2000
	s_nop 0
	global_load_lds_dwordx4 v[214:215], off
	s_waitcnt vmcnt(4)
	s_waitcnt lgkmcnt(0)
	s_setprio 1
	s_barrier
	v_mfma_f32_16x16x32_bf16 v[94:97], v[134:137], v[166:169], v[94:97]
	v_mfma_f32_16x16x32_bf16 v[90:93], v[142:145], v[166:169], v[90:93]
	v_mfma_f32_16x16x32_bf16 v[30:33], v[134:137], v[174:177], v[30:33]
	v_mfma_f32_16x16x32_bf16 v[26:29], v[142:145], v[174:177], v[26:29]
	v_mfma_f32_16x16x32_bf16 v[22:25], v[134:137], v[182:185], v[22:25]
	v_mfma_f32_16x16x32_bf16 v[18:21], v[142:145], v[182:185], v[18:21]
	v_mfma_f32_16x16x32_bf16 v[82:85], v[134:137], v[190:193], v[82:85]
	v_mfma_f32_16x16x32_bf16 v[74:77], v[142:145], v[190:193], v[74:77]
	v_mfma_f32_16x16x32_bf16 v[94:97], v[138:141], v[170:173], v[94:97]
	v_mfma_f32_16x16x32_bf16 v[90:93], v[146:149], v[170:173], v[90:93]
	v_mfma_f32_16x16x32_bf16 v[30:33], v[138:141], v[178:181], v[30:33]
	v_mfma_f32_16x16x32_bf16 v[26:29], v[146:149], v[178:181], v[26:29]
	v_mfma_f32_16x16x32_bf16 v[22:25], v[138:141], v[186:189], v[22:25]
	v_mfma_f32_16x16x32_bf16 v[18:21], v[146:149], v[186:189], v[18:21]
	v_mfma_f32_16x16x32_bf16 v[82:85], v[138:141], v[210:213], v[82:85]
	v_mfma_f32_16x16x32_bf16 v[74:77], v[146:149], v[210:213], v[74:77]
	v_mfma_f32_16x16x32_bf16 v[86:89], v[150:153], v[166:169], v[86:89]
	v_mfma_f32_16x16x32_bf16 v[78:81], v[158:161], v[166:169], v[78:81]
	v_mfma_f32_16x16x32_bf16 v[14:17], v[150:153], v[174:177], v[14:17]
	v_mfma_f32_16x16x32_bf16 v[10:13], v[158:161], v[174:177], v[10:13]
	v_mfma_f32_16x16x32_bf16 v[6:9], v[150:153], v[182:185], v[6:9]
	v_mfma_f32_16x16x32_bf16 v[2:5], v[158:161], v[182:185], v[2:5]
	v_mfma_f32_16x16x32_bf16 v[70:73], v[150:153], v[190:193], v[70:73]
	v_mfma_f32_16x16x32_bf16 v[66:69], v[158:161], v[190:193], v[66:69]
	v_mfma_f32_16x16x32_bf16 v[86:89], v[154:157], v[170:173], v[86:89]
	v_mfma_f32_16x16x32_bf16 v[78:81], v[162:165], v[170:173], v[78:81]
	v_mfma_f32_16x16x32_bf16 v[14:17], v[154:157], v[178:181], v[14:17]
	v_mfma_f32_16x16x32_bf16 v[10:13], v[162:165], v[178:181], v[10:13]
	v_mfma_f32_16x16x32_bf16 v[6:9], v[154:157], v[186:189], v[6:9]
	v_mfma_f32_16x16x32_bf16 v[2:5], v[162:165], v[186:189], v[2:5]
	v_mfma_f32_16x16x32_bf16 v[70:73], v[154:157], v[210:213], v[70:73]
	v_mfma_f32_16x16x32_bf16 v[66:69], v[162:165], v[210:213], v[66:69]
	s_setprio 0
	s_barrier
	s_add_u32 s86, s86, 0x100
	s_addc_u32 s87, s87, 0
	s_cmp_ge_u32 s51, s13
	s_cbranch_scc0 .LBB0_1134
	s_and_b64 vcc, exec, s[80:81]
	s_cbranch_vccz .LBB0_1137
	v_add_u32_e32 v202, 0, v233
	v_add_u32_e32 v142, 0x10000, v202
	v_add_u32_e32 v158, 0x14000, v202
	ds_read_b128 v[130:133], v142
	ds_read_b128 v[134:137], v142 offset:1024
	ds_read_b128 v[138:141], v142 offset:2048
	ds_read_b128 v[142:145], v142 offset:3072
	ds_read_b128 v[146:149], v158
	ds_read_b128 v[150:153], v158 offset:1024
	ds_read_b128 v[154:157], v158 offset:2048
	ds_read_b128 v[158:161], v158 offset:3072
	v_lshl_add_u64 v[210:211], s[10:11], 0, v[194:195]
	s_mov_b32 m0, s0
	v_lshl_add_u64 v[210:211], v[210:211], 0, s[26:27]
	ds_read_b128 v[162:165], v245
	ds_read_b128 v[166:169], v245 offset:1024
	ds_read_b128 v[170:173], v245 offset:2048
	ds_read_b128 v[174:177], v245 offset:3072
	ds_read_b128 v[178:181], v245 offset:4096
	ds_read_b128 v[182:185], v245 offset:5120
	ds_read_b128 v[186:189], v245 offset:6144
	ds_read_b128 v[190:193], v245 offset:7168
	global_load_lds_dwordx4 v[210:211], off
	v_lshl_add_u64 v[210:211], s[10:11], 0, v[198:199]
	s_add_u32 s0, s10, 0x40780
	v_lshl_add_u64 v[210:211], v[210:211], 0, s[26:27]
	s_mov_b32 m0, s67
	s_addc_u32 s1, s11, 0
	global_load_lds_dwordx4 v[210:211], off
	v_lshl_add_u64 v[210:211], s[0:1], 0, v[194:195]
	s_mov_b32 m0, s22
	s_nop 0
	global_load_lds_dwordx4 v[210:211], off
	v_lshl_add_u64 v[210:211], s[0:1], 0, v[198:199]
	s_mov_b32 m0, s23
	s_nop 0
	global_load_lds_dwordx4 v[210:211], off
	s_waitcnt vmcnt(8)
	s_waitcnt lgkmcnt(0)
	s_setprio 1
	s_barrier
	v_mfma_f32_16x16x32_bf16 v[118:121], v[130:133], v[162:165], v[118:121]
	v_mfma_f32_16x16x32_bf16 v[114:117], v[138:141], v[162:165], v[114:117]
	v_mfma_f32_16x16x32_bf16 v[62:65], v[130:133], v[170:173], v[62:65]
	v_mfma_f32_16x16x32_bf16 v[58:61], v[138:141], v[170:173], v[58:61]
	v_mfma_f32_16x16x32_bf16 v[54:57], v[130:133], v[178:181], v[54:57]
	v_mfma_f32_16x16x32_bf16 v[50:53], v[138:141], v[178:181], v[50:53]
	v_mfma_f32_16x16x32_bf16 v[126:129], v[130:133], v[186:189], v[126:129]
	v_mfma_f32_16x16x32_bf16 v[102:105], v[138:141], v[186:189], v[102:105]
	v_mfma_f32_16x16x32_bf16 v[118:121], v[134:137], v[166:169], v[118:121]
	v_mfma_f32_16x16x32_bf16 v[114:117], v[142:145], v[166:169], v[114:117]
	v_mfma_f32_16x16x32_bf16 v[62:65], v[134:137], v[174:177], v[62:65]
	v_mfma_f32_16x16x32_bf16 v[58:61], v[142:145], v[174:177], v[58:61]
	v_mfma_f32_16x16x32_bf16 v[54:57], v[134:137], v[182:185], v[54:57]
	v_mfma_f32_16x16x32_bf16 v[50:53], v[142:145], v[182:185], v[50:53]
	v_mfma_f32_16x16x32_bf16 v[126:129], v[134:137], v[190:193], v[126:129]
	v_mfma_f32_16x16x32_bf16 v[102:105], v[142:145], v[190:193], v[102:105]
	v_mfma_f32_16x16x32_bf16 v[110:113], v[146:149], v[162:165], v[110:113]
	v_mfma_f32_16x16x32_bf16 v[106:109], v[154:157], v[162:165], v[106:109]
	v_mfma_f32_16x16x32_bf16 v[46:49], v[146:149], v[170:173], v[46:49]
	v_mfma_f32_16x16x32_bf16 v[42:45], v[154:157], v[170:173], v[42:45]
	v_mfma_f32_16x16x32_bf16 v[38:41], v[146:149], v[178:181], v[38:41]
	v_mfma_f32_16x16x32_bf16 v[34:37], v[154:157], v[178:181], v[34:37]
	v_mfma_f32_16x16x32_bf16 v[122:125], v[146:149], v[186:189], v[122:125]
	v_mfma_f32_16x16x32_bf16 v[98:101], v[154:157], v[186:189], v[98:101]
	v_mfma_f32_16x16x32_bf16 v[110:113], v[150:153], v[166:169], v[110:113]
	v_mfma_f32_16x16x32_bf16 v[106:109], v[158:161], v[166:169], v[106:109]
	v_mfma_f32_16x16x32_bf16 v[46:49], v[150:153], v[174:177], v[46:49]
	v_mfma_f32_16x16x32_bf16 v[42:45], v[158:161], v[174:177], v[42:45]
	v_mfma_f32_16x16x32_bf16 v[38:41], v[150:153], v[182:185], v[38:41]
	v_mfma_f32_16x16x32_bf16 v[34:37], v[158:161], v[182:185], v[34:37]
	v_mfma_f32_16x16x32_bf16 v[122:125], v[150:153], v[190:193], v[122:125]
	v_mfma_f32_16x16x32_bf16 v[98:101], v[158:161], v[190:193], v[98:101]
	s_setprio 0
	s_barrier
	ds_read_b128 v[162:165], v245 offset:16384
	ds_read_b128 v[166:169], v245 offset:17408
	ds_read_b128 v[170:173], v245 offset:18432
	ds_read_b128 v[174:177], v245 offset:19456
	ds_read_b128 v[178:181], v245 offset:20480
	ds_read_b128 v[182:185], v245 offset:21504
	ds_read_b128 v[186:189], v245 offset:22528
	ds_read_b128 v[190:193], v245 offset:23552
	s_waitcnt vmcnt(0)
	s_waitcnt lgkmcnt(0)
	s_setprio 1
	s_barrier
	v_mfma_f32_16x16x32_bf16 v[94:97], v[130:133], v[162:165], v[94:97]
	v_mfma_f32_16x16x32_bf16 v[90:93], v[138:141], v[162:165], v[90:93]
	v_mfma_f32_16x16x32_bf16 v[30:33], v[130:133], v[170:173], v[30:33]
	v_mfma_f32_16x16x32_bf16 v[26:29], v[138:141], v[170:173], v[26:29]
	v_mfma_f32_16x16x32_bf16 v[22:25], v[130:133], v[178:181], v[22:25]
	v_mfma_f32_16x16x32_bf16 v[18:21], v[138:141], v[178:181], v[18:21]
	v_mfma_f32_16x16x32_bf16 v[82:85], v[130:133], v[186:189], v[82:85]
	v_mfma_f32_16x16x32_bf16 v[74:77], v[138:141], v[186:189], v[74:77]
	v_mfma_f32_16x16x32_bf16 v[94:97], v[134:137], v[166:169], v[94:97]
	v_mfma_f32_16x16x32_bf16 v[90:93], v[142:145], v[166:169], v[90:93]
	v_mfma_f32_16x16x32_bf16 v[30:33], v[134:137], v[174:177], v[30:33]
	v_mfma_f32_16x16x32_bf16 v[26:29], v[142:145], v[174:177], v[26:29]
	v_mfma_f32_16x16x32_bf16 v[22:25], v[134:137], v[182:185], v[22:25]
	v_mfma_f32_16x16x32_bf16 v[18:21], v[142:145], v[182:185], v[18:21]
	v_mfma_f32_16x16x32_bf16 v[82:85], v[134:137], v[190:193], v[82:85]
	v_mfma_f32_16x16x32_bf16 v[74:77], v[142:145], v[190:193], v[74:77]
	v_mfma_f32_16x16x32_bf16 v[86:89], v[146:149], v[162:165], v[86:89]
	v_mfma_f32_16x16x32_bf16 v[78:81], v[154:157], v[162:165], v[78:81]
	v_mfma_f32_16x16x32_bf16 v[14:17], v[146:149], v[170:173], v[14:17]
	v_mfma_f32_16x16x32_bf16 v[10:13], v[154:157], v[170:173], v[10:13]
	v_mfma_f32_16x16x32_bf16 v[6:9], v[146:149], v[178:181], v[6:9]
	v_mfma_f32_16x16x32_bf16 v[2:5], v[154:157], v[178:181], v[2:5]
	v_mfma_f32_16x16x32_bf16 v[70:73], v[146:149], v[186:189], v[70:73]
	v_mfma_f32_16x16x32_bf16 v[66:69], v[154:157], v[186:189], v[66:69]
	v_mfma_f32_16x16x32_bf16 v[86:89], v[150:153], v[166:169], v[86:89]
	v_mfma_f32_16x16x32_bf16 v[78:81], v[158:161], v[166:169], v[78:81]
	v_mfma_f32_16x16x32_bf16 v[14:17], v[150:153], v[174:177], v[14:17]
	v_mfma_f32_16x16x32_bf16 v[10:13], v[158:161], v[174:177], v[10:13]
	v_mfma_f32_16x16x32_bf16 v[6:9], v[150:153], v[182:185], v[6:9]
	v_mfma_f32_16x16x32_bf16 v[2:5], v[158:161], v[182:185], v[2:5]
	v_mfma_f32_16x16x32_bf16 v[70:73], v[150:153], v[190:193], v[70:73]
	v_mfma_f32_16x16x32_bf16 v[66:69], v[158:161], v[190:193], v[66:69]
	s_setprio 0
	s_barrier
	v_add_u32_e32 v142, 0x18000, v202
	v_add_u32_e32 v158, 0x1c000, v202
	ds_read_b128 v[130:133], v142
	ds_read_b128 v[134:137], v142 offset:1024
	ds_read_b128 v[138:141], v142 offset:2048
	ds_read_b128 v[142:145], v142 offset:3072
	ds_read_b128 v[146:149], v158
	ds_read_b128 v[150:153], v158 offset:1024
	ds_read_b128 v[154:157], v158 offset:2048
	ds_read_b128 v[158:161], v158 offset:3072
	ds_read_b128 v[162:165], v245 offset:32768
	ds_read_b128 v[166:169], v245 offset:33792
	ds_read_b128 v[170:173], v245 offset:34816
	ds_read_b128 v[174:177], v245 offset:35840
	ds_read_b128 v[178:181], v245 offset:36864
	ds_read_b128 v[182:185], v245 offset:37888
	ds_read_b128 v[186:189], v245 offset:38912
	ds_read_b128 v[190:193], v245 offset:39936
	s_waitcnt lgkmcnt(0)
	s_setprio 1
	s_barrier
	v_mfma_f32_16x16x32_bf16 v[118:121], v[130:133], v[162:165], v[118:121]
	v_mfma_f32_16x16x32_bf16 v[114:117], v[138:141], v[162:165], v[114:117]
	v_mfma_f32_16x16x32_bf16 v[62:65], v[130:133], v[170:173], v[62:65]
	v_mfma_f32_16x16x32_bf16 v[58:61], v[138:141], v[170:173], v[58:61]
	v_mfma_f32_16x16x32_bf16 v[54:57], v[130:133], v[178:181], v[54:57]
	v_mfma_f32_16x16x32_bf16 v[50:53], v[138:141], v[178:181], v[50:53]
	v_mfma_f32_16x16x32_bf16 v[126:129], v[130:133], v[186:189], v[126:129]
	v_mfma_f32_16x16x32_bf16 v[102:105], v[138:141], v[186:189], v[102:105]
	v_mfma_f32_16x16x32_bf16 v[118:121], v[134:137], v[166:169], v[118:121]
	v_mfma_f32_16x16x32_bf16 v[114:117], v[142:145], v[166:169], v[114:117]
	v_mfma_f32_16x16x32_bf16 v[62:65], v[134:137], v[174:177], v[62:65]
	v_mfma_f32_16x16x32_bf16 v[58:61], v[142:145], v[174:177], v[58:61]
	v_mfma_f32_16x16x32_bf16 v[54:57], v[134:137], v[182:185], v[54:57]
	v_mfma_f32_16x16x32_bf16 v[50:53], v[142:145], v[182:185], v[50:53]
	v_mfma_f32_16x16x32_bf16 v[126:129], v[134:137], v[190:193], v[126:129]
	v_mfma_f32_16x16x32_bf16 v[102:105], v[142:145], v[190:193], v[102:105]
	v_mfma_f32_16x16x32_bf16 v[110:113], v[146:149], v[162:165], v[110:113]
	v_mfma_f32_16x16x32_bf16 v[106:109], v[154:157], v[162:165], v[106:109]
	v_mfma_f32_16x16x32_bf16 v[46:49], v[146:149], v[170:173], v[46:49]
	v_mfma_f32_16x16x32_bf16 v[42:45], v[154:157], v[170:173], v[42:45]
	v_mfma_f32_16x16x32_bf16 v[38:41], v[146:149], v[178:181], v[38:41]
	v_mfma_f32_16x16x32_bf16 v[34:37], v[154:157], v[178:181], v[34:37]
	v_mfma_f32_16x16x32_bf16 v[122:125], v[146:149], v[186:189], v[122:125]
	v_mfma_f32_16x16x32_bf16 v[98:101], v[154:157], v[186:189], v[98:101]
	v_mfma_f32_16x16x32_bf16 v[110:113], v[150:153], v[166:169], v[110:113]
	v_mfma_f32_16x16x32_bf16 v[106:109], v[158:161], v[166:169], v[106:109]
	v_mfma_f32_16x16x32_bf16 v[46:49], v[150:153], v[174:177], v[46:49]
	v_mfma_f32_16x16x32_bf16 v[42:45], v[158:161], v[174:177], v[42:45]
	v_mfma_f32_16x16x32_bf16 v[38:41], v[150:153], v[182:185], v[38:41]
	v_mfma_f32_16x16x32_bf16 v[34:37], v[158:161], v[182:185], v[34:37]
	v_mfma_f32_16x16x32_bf16 v[122:125], v[150:153], v[190:193], v[122:125]
	v_mfma_f32_16x16x32_bf16 v[98:101], v[158:161], v[190:193], v[98:101]
	s_setprio 0
	s_barrier
	ds_read_b128 v[162:165], v245 offset:49152
	ds_read_b128 v[166:169], v245 offset:50176
	ds_read_b128 v[170:173], v245 offset:51200
	ds_read_b128 v[174:177], v245 offset:52224
	ds_read_b128 v[178:181], v245 offset:53248
	ds_read_b128 v[182:185], v245 offset:54272
	ds_read_b128 v[186:189], v245 offset:55296
	ds_read_b128 v[190:193], v245 offset:56320
	s_waitcnt lgkmcnt(0)
	s_setprio 1
	s_barrier
	v_mfma_f32_16x16x32_bf16 v[94:97], v[130:133], v[162:165], v[94:97]
	v_mfma_f32_16x16x32_bf16 v[90:93], v[138:141], v[162:165], v[90:93]
	v_mfma_f32_16x16x32_bf16 v[30:33], v[130:133], v[170:173], v[30:33]
	v_mfma_f32_16x16x32_bf16 v[26:29], v[138:141], v[170:173], v[26:29]
	v_mfma_f32_16x16x32_bf16 v[22:25], v[130:133], v[178:181], v[22:25]
	v_mfma_f32_16x16x32_bf16 v[18:21], v[138:141], v[178:181], v[18:21]
	v_mfma_f32_16x16x32_bf16 v[82:85], v[130:133], v[186:189], v[82:85]
	v_mfma_f32_16x16x32_bf16 v[74:77], v[138:141], v[186:189], v[74:77]
	v_mfma_f32_16x16x32_bf16 v[94:97], v[134:137], v[166:169], v[94:97]
	v_mfma_f32_16x16x32_bf16 v[90:93], v[142:145], v[166:169], v[90:93]
	v_mfma_f32_16x16x32_bf16 v[30:33], v[134:137], v[174:177], v[30:33]
	v_mfma_f32_16x16x32_bf16 v[26:29], v[142:145], v[174:177], v[26:29]
	v_mfma_f32_16x16x32_bf16 v[22:25], v[134:137], v[182:185], v[22:25]
	v_mfma_f32_16x16x32_bf16 v[18:21], v[142:145], v[182:185], v[18:21]
	v_mfma_f32_16x16x32_bf16 v[82:85], v[134:137], v[190:193], v[82:85]
	v_mfma_f32_16x16x32_bf16 v[74:77], v[142:145], v[190:193], v[74:77]
	v_mfma_f32_16x16x32_bf16 v[86:89], v[146:149], v[162:165], v[86:89]
	v_mfma_f32_16x16x32_bf16 v[78:81], v[154:157], v[162:165], v[78:81]
	v_mfma_f32_16x16x32_bf16 v[14:17], v[146:149], v[170:173], v[14:17]
	v_mfma_f32_16x16x32_bf16 v[10:13], v[154:157], v[170:173], v[10:13]
	v_mfma_f32_16x16x32_bf16 v[6:9], v[146:149], v[178:181], v[6:9]
	v_mfma_f32_16x16x32_bf16 v[2:5], v[154:157], v[178:181], v[2:5]
	v_mfma_f32_16x16x32_bf16 v[70:73], v[146:149], v[186:189], v[70:73]
	v_mfma_f32_16x16x32_bf16 v[66:69], v[154:157], v[186:189], v[66:69]
	v_mfma_f32_16x16x32_bf16 v[86:89], v[150:153], v[166:169], v[86:89]
	v_mfma_f32_16x16x32_bf16 v[78:81], v[158:161], v[166:169], v[78:81]
	v_mfma_f32_16x16x32_bf16 v[14:17], v[150:153], v[174:177], v[14:17]
	v_mfma_f32_16x16x32_bf16 v[10:13], v[158:161], v[174:177], v[10:13]
	v_mfma_f32_16x16x32_bf16 v[6:9], v[150:153], v[182:185], v[6:9]
	v_mfma_f32_16x16x32_bf16 v[2:5], v[158:161], v[182:185], v[2:5]
	v_mfma_f32_16x16x32_bf16 v[70:73], v[150:153], v[190:193], v[70:73]
	v_mfma_f32_16x16x32_bf16 v[66:69], v[158:161], v[190:193], v[66:69]
	s_setprio 0
	s_barrier

.LBB0_1261:
	v_add_u32_e32 v11, s38, v152
	s_add_i32 s1, s1, 2
	ds_read_b128 v[156:159], v11
	ds_read_b128 v[160:163], v11 offset:1024
	ds_read_b128 v[164:167], v11 offset:2048
	ds_read_b128 v[168:171], v11 offset:3072
	v_add_u32_e32 v11, s39, v152
	s_add_u32 s3, s14, s62
	ds_read_b128 v[172:175], v11
	ds_read_b128 v[176:179], v11 offset:1024
	ds_read_b128 v[184:187], v11 offset:2048
	ds_read_b128 v[188:191], v11 offset:3072
	s_addc_u32 s22, s15, s63
	s_add_u32 s3, s3, 0x100
	s_addc_u32 s22, s22, 0
	s_add_u32 s23, s53, s62
	s_addc_u32 s24, s55, s63
	s_cmpk_eq_i32 s62, 0x700
	s_cselect_b32 s65, s61, s24
	s_cselect_b32 s64, s60, s23
	s_cselect_b32 s67, s59, s22
	s_cselect_b32 s66, s58, s3
	v_lshl_add_u64 v[180:181], v[150:151], 0, s[62:63]
	s_add_i32 s24, s31, 0x8000
	v_lshl_add_u64 v[216:217], v[180:181], 0, s[42:43]
	s_mov_b32 m0, s24
	ds_read_b128 v[192:195], v154
	ds_read_b128 v[196:199], v154 offset:1024
	ds_read_b128 v[200:203], v154 offset:2048
	ds_read_b128 v[204:207], v154 offset:3072
	ds_read_b128 v[208:211], v154 offset:4096
	ds_read_b128 v[212:215], v154 offset:5120
	ds_read_b128 v[220:223], v154 offset:6144
	ds_read_b128 v[224:227], v154 offset:7168
	global_load_lds_dwordx4 v[216:217], off
	v_lshl_add_u64 v[216:217], v[12:13], 0, s[62:63]
	s_add_i32 s23, s31, 0xa000
	v_lshl_add_u64 v[228:229], v[216:217], 0, s[42:43]
	s_mov_b32 m0, s23
	s_add_i32 s3, s31, 0xc000
	global_load_lds_dwordx4 v[228:229], off
	v_lshl_add_u64 v[180:181], v[180:181], 0, s[44:45]
	s_mov_b32 m0, s3
	s_add_i32 s22, s31, 0xe000
	global_load_lds_dwordx4 v[180:181], off
	v_lshl_add_u64 v[180:181], v[216:217], 0, s[44:45]
	s_mov_b32 m0, s22
	s_nop 0
	global_load_lds_dwordx4 v[180:181], off
	s_waitcnt vmcnt(8)
	s_waitcnt lgkmcnt(0)
	s_setprio 1
	s_barrier
	v_mfma_f32_16x16x32_bf16 v[126:129], v[156:159], v[192:195], v[126:129]
	v_mfma_f32_16x16x32_bf16 v[122:125], v[164:167], v[192:195], v[122:125]
	v_mfma_f32_16x16x32_bf16 v[106:109], v[156:159], v[200:203], v[106:109]
	v_mfma_f32_16x16x32_bf16 v[110:113], v[164:167], v[200:203], v[110:113]
	v_mfma_f32_16x16x32_bf16 v[90:93], v[156:159], v[208:211], v[90:93]
	v_mfma_f32_16x16x32_bf16 v[94:97], v[164:167], v[208:211], v[94:97]
	v_mfma_f32_16x16x32_bf16 v[74:77], v[156:159], v[220:223], v[74:77]
	v_mfma_f32_16x16x32_bf16 v[78:81], v[164:167], v[220:223], v[78:81]
	v_mfma_f32_16x16x32_bf16 v[126:129], v[160:163], v[196:199], v[126:129]
	v_mfma_f32_16x16x32_bf16 v[122:125], v[168:171], v[196:199], v[122:125]
	v_mfma_f32_16x16x32_bf16 v[106:109], v[160:163], v[204:207], v[106:109]
	v_mfma_f32_16x16x32_bf16 v[110:113], v[168:171], v[204:207], v[110:113]
	v_mfma_f32_16x16x32_bf16 v[90:93], v[160:163], v[212:215], v[90:93]
	v_mfma_f32_16x16x32_bf16 v[94:97], v[168:171], v[212:215], v[94:97]
	v_mfma_f32_16x16x32_bf16 v[74:77], v[160:163], v[224:227], v[74:77]
	v_mfma_f32_16x16x32_bf16 v[78:81], v[168:171], v[224:227], v[78:81]
	v_mfma_f32_16x16x32_bf16 v[58:61], v[172:175], v[192:195], v[58:61]
	v_mfma_f32_16x16x32_bf16 v[62:65], v[184:187], v[192:195], v[62:65]
	v_mfma_f32_16x16x32_bf16 v[42:45], v[172:175], v[200:203], v[42:45]
	v_mfma_f32_16x16x32_bf16 v[46:49], v[184:187], v[200:203], v[46:49]
	v_mfma_f32_16x16x32_bf16 v[26:29], v[172:175], v[208:211], v[26:29]
	v_mfma_f32_16x16x32_bf16 v[30:33], v[184:187], v[208:211], v[30:33]
	v_mfma_f32_16x16x32_bf16 v[130:133], v[172:175], v[220:223], v[130:133]
	v_mfma_f32_16x16x32_bf16 v[14:17], v[184:187], v[220:223], v[14:17]
	v_mfma_f32_16x16x32_bf16 v[58:61], v[176:179], v[196:199], v[58:61]
	v_mfma_f32_16x16x32_bf16 v[62:65], v[188:191], v[196:199], v[62:65]
	v_mfma_f32_16x16x32_bf16 v[42:45], v[176:179], v[204:207], v[42:45]
	v_mfma_f32_16x16x32_bf16 v[46:49], v[188:191], v[204:207], v[46:49]
	v_mfma_f32_16x16x32_bf16 v[26:29], v[176:179], v[212:215], v[26:29]
	v_mfma_f32_16x16x32_bf16 v[30:33], v[188:191], v[212:215], v[30:33]
	v_mfma_f32_16x16x32_bf16 v[130:133], v[176:179], v[224:227], v[130:133]
	v_mfma_f32_16x16x32_bf16 v[14:17], v[188:191], v[224:227], v[14:17]
	s_setprio 0
	s_barrier
	s_add_i32 s25, s38, s11
	v_lshl_add_u64 v[180:181], s[64:65], 0, v[136:137]
	s_mov_b32 m0, s25
	ds_read_b128 v[192:195], v154 offset:16384
	ds_read_b128 v[196:199], v154 offset:17408
	ds_read_b128 v[200:203], v154 offset:18432
	ds_read_b128 v[204:207], v154 offset:19456
	ds_read_b128 v[208:211], v154 offset:20480
	ds_read_b128 v[212:215], v154 offset:21504
	ds_read_b128 v[220:223], v154 offset:22528
	ds_read_b128 v[224:227], v154 offset:23552
	global_load_lds_dwordx4 v[180:181], off
	s_add_i32 m0, s25, 0x2000
	s_add_u32 s26, s64, 0x40000
	v_lshl_add_u64 v[216:217], s[64:65], 0, v[140:141]
	s_addc_u32 s27, s65, 0
	s_add_i32 s25, s39, s11
	global_load_lds_dwordx4 v[216:217], off
	v_lshl_add_u64 v[228:229], s[26:27], 0, v[136:137]
	s_mov_b32 m0, s25
	s_nop 0
	global_load_lds_dwordx4 v[228:229], off
	v_lshl_add_u64 v[228:229], s[26:27], 0, v[140:141]
	s_add_i32 m0, s25, 0x2000
	s_nop 0
	global_load_lds_dwordx4 v[228:229], off
	s_waitcnt vmcnt(4)
	s_waitcnt lgkmcnt(0)
	s_setprio 1
	s_barrier
	v_mfma_f32_16x16x32_bf16 v[114:117], v[156:159], v[192:195], v[114:117]
	v_mfma_f32_16x16x32_bf16 v[118:121], v[164:167], v[192:195], v[118:121]
	v_mfma_f32_16x16x32_bf16 v[98:101], v[156:159], v[200:203], v[98:101]
	v_mfma_f32_16x16x32_bf16 v[102:105], v[164:167], v[200:203], v[102:105]
	v_mfma_f32_16x16x32_bf16 v[82:85], v[156:159], v[208:211], v[82:85]
	v_mfma_f32_16x16x32_bf16 v[86:89], v[164:167], v[208:211], v[86:89]
	v_mfma_f32_16x16x32_bf16 v[66:69], v[156:159], v[220:223], v[66:69]
	v_mfma_f32_16x16x32_bf16 v[70:73], v[164:167], v[220:223], v[70:73]
	v_mfma_f32_16x16x32_bf16 v[114:117], v[160:163], v[196:199], v[114:117]
	v_mfma_f32_16x16x32_bf16 v[118:121], v[168:171], v[196:199], v[118:121]
	v_mfma_f32_16x16x32_bf16 v[98:101], v[160:163], v[204:207], v[98:101]
	v_mfma_f32_16x16x32_bf16 v[102:105], v[168:171], v[204:207], v[102:105]
	v_mfma_f32_16x16x32_bf16 v[82:85], v[160:163], v[212:215], v[82:85]
	v_mfma_f32_16x16x32_bf16 v[86:89], v[168:171], v[212:215], v[86:89]
	v_mfma_f32_16x16x32_bf16 v[66:69], v[160:163], v[224:227], v[66:69]
	v_mfma_f32_16x16x32_bf16 v[70:73], v[168:171], v[224:227], v[70:73]
	v_mfma_f32_16x16x32_bf16 v[50:53], v[172:175], v[192:195], v[50:53]
	v_mfma_f32_16x16x32_bf16 v[54:57], v[184:187], v[192:195], v[54:57]
	v_mfma_f32_16x16x32_bf16 v[34:37], v[172:175], v[200:203], v[34:37]
	v_mfma_f32_16x16x32_bf16 v[38:41], v[184:187], v[200:203], v[38:41]
	v_mfma_f32_16x16x32_bf16 v[18:21], v[172:175], v[208:211], v[18:21]
	v_mfma_f32_16x16x32_bf16 v[22:25], v[184:187], v[208:211], v[22:25]
	v_mfma_f32_16x16x32_bf16 v[6:9], v[172:175], v[220:223], v[6:9]
	v_mfma_f32_16x16x32_bf16 v[2:5], v[184:187], v[220:223], v[2:5]
	v_mfma_f32_16x16x32_bf16 v[50:53], v[176:179], v[196:199], v[50:53]
	v_mfma_f32_16x16x32_bf16 v[54:57], v[188:191], v[196:199], v[54:57]
	v_mfma_f32_16x16x32_bf16 v[34:37], v[176:179], v[204:207], v[34:37]
	v_mfma_f32_16x16x32_bf16 v[38:41], v[188:191], v[204:207], v[38:41]
	v_mfma_f32_16x16x32_bf16 v[18:21], v[176:179], v[212:215], v[18:21]
	v_mfma_f32_16x16x32_bf16 v[22:25], v[188:191], v[212:215], v[22:25]
	v_mfma_f32_16x16x32_bf16 v[6:9], v[176:179], v[224:227], v[6:9]
	v_mfma_f32_16x16x32_bf16 v[2:5], v[188:191], v[224:227], v[2:5]
	s_setprio 0
	s_barrier
	s_add_i32 s25, 0, 0x18000
	v_add_u32_e32 v11, s25, v152
	s_add_i32 s57, 0, 0x1c000
	ds_read_b128 v[156:159], v11
	ds_read_b128 v[160:163], v11 offset:1024
	ds_read_b128 v[164:167], v11 offset:2048
	ds_read_b128 v[168:171], v11 offset:3072
	v_add_u32_e32 v11, s57, v152
	ds_read_b128 v[172:175], v11
	ds_read_b128 v[176:179], v11 offset:1024
	ds_read_b128 v[184:187], v11 offset:2048
	ds_read_b128 v[188:191], v11 offset:3072
	s_mov_b32 m0, s31
	v_lshl_add_u64 v[228:229], s[66:67], 0, v[134:135]
	s_add_u32 s26, s66, 0x40000
	ds_read_b128 v[192:195], v154 offset:32768
	ds_read_b128 v[196:199], v154 offset:33792
	ds_read_b128 v[200:203], v154 offset:34816
	ds_read_b128 v[204:207], v154 offset:35840
	ds_read_b128 v[208:211], v154 offset:36864
	ds_read_b128 v[212:215], v154 offset:37888
	ds_read_b128 v[220:223], v154 offset:38912
	ds_read_b128 v[224:227], v154 offset:39936
	global_load_lds_dwordx4 v[228:229], off
	v_lshl_add_u64 v[228:229], s[66:67], 0, v[138:139]
	s_mov_b32 m0, s33
	s_addc_u32 s27, s67, 0
	global_load_lds_dwordx4 v[228:229], off
	v_lshl_add_u64 v[228:229], s[26:27], 0, v[134:135]
	s_mov_b32 m0, s36
	s_nop 0
	global_load_lds_dwordx4 v[228:229], off
	v_lshl_add_u64 v[228:229], s[26:27], 0, v[138:139]
	s_mov_b32 m0, s37
	s_nop 0
	global_load_lds_dwordx4 v[228:229], off
	s_waitcnt vmcnt(8)
	s_waitcnt lgkmcnt(0)
	s_setprio 1
	s_barrier
	v_mfma_f32_16x16x32_bf16 v[126:129], v[156:159], v[192:195], v[126:129]
	v_mfma_f32_16x16x32_bf16 v[122:125], v[164:167], v[192:195], v[122:125]
	v_mfma_f32_16x16x32_bf16 v[106:109], v[156:159], v[200:203], v[106:109]
	v_mfma_f32_16x16x32_bf16 v[110:113], v[164:167], v[200:203], v[110:113]
	v_mfma_f32_16x16x32_bf16 v[90:93], v[156:159], v[208:211], v[90:93]
	v_mfma_f32_16x16x32_bf16 v[94:97], v[164:167], v[208:211], v[94:97]
	v_mfma_f32_16x16x32_bf16 v[74:77], v[156:159], v[220:223], v[74:77]
	v_mfma_f32_16x16x32_bf16 v[78:81], v[164:167], v[220:223], v[78:81]
	v_mfma_f32_16x16x32_bf16 v[126:129], v[160:163], v[196:199], v[126:129]
	v_mfma_f32_16x16x32_bf16 v[122:125], v[168:171], v[196:199], v[122:125]
	v_mfma_f32_16x16x32_bf16 v[106:109], v[160:163], v[204:207], v[106:109]
	v_mfma_f32_16x16x32_bf16 v[110:113], v[168:171], v[204:207], v[110:113]
	v_mfma_f32_16x16x32_bf16 v[90:93], v[160:163], v[212:215], v[90:93]
	v_mfma_f32_16x16x32_bf16 v[94:97], v[168:171], v[212:215], v[94:97]
	v_mfma_f32_16x16x32_bf16 v[74:77], v[160:163], v[224:227], v[74:77]
	v_mfma_f32_16x16x32_bf16 v[78:81], v[168:171], v[224:227], v[78:81]
	v_mfma_f32_16x16x32_bf16 v[58:61], v[172:175], v[192:195], v[58:61]
	v_mfma_f32_16x16x32_bf16 v[62:65], v[184:187], v[192:195], v[62:65]
	v_mfma_f32_16x16x32_bf16 v[42:45], v[172:175], v[200:203], v[42:45]
	v_mfma_f32_16x16x32_bf16 v[46:49], v[184:187], v[200:203], v[46:49]
	v_mfma_f32_16x16x32_bf16 v[26:29], v[172:175], v[208:211], v[26:29]
	v_mfma_f32_16x16x32_bf16 v[30:33], v[184:187], v[208:211], v[30:33]
	v_mfma_f32_16x16x32_bf16 v[130:133], v[172:175], v[220:223], v[130:133]
	v_mfma_f32_16x16x32_bf16 v[14:17], v[184:187], v[220:223], v[14:17]
	v_mfma_f32_16x16x32_bf16 v[58:61], v[176:179], v[196:199], v[58:61]
	v_mfma_f32_16x16x32_bf16 v[62:65], v[188:191], v[196:199], v[62:65]
	v_mfma_f32_16x16x32_bf16 v[42:45], v[176:179], v[204:207], v[42:45]
	v_mfma_f32_16x16x32_bf16 v[46:49], v[188:191], v[204:207], v[46:49]
	v_mfma_f32_16x16x32_bf16 v[26:29], v[176:179], v[212:215], v[26:29]
	v_mfma_f32_16x16x32_bf16 v[30:33], v[188:191], v[212:215], v[30:33]
	v_mfma_f32_16x16x32_bf16 v[130:133], v[176:179], v[224:227], v[130:133]
	v_mfma_f32_16x16x32_bf16 v[14:17], v[188:191], v[224:227], v[14:17]
	s_setprio 0
	s_barrier
	s_add_i32 s25, s25, s11
	v_lshl_add_u64 v[180:181], v[180:181], 0, s[42:43]
	s_mov_b32 m0, s25
	ds_read_b128 v[192:195], v154 offset:49152
	ds_read_b128 v[196:199], v154 offset:50176
	ds_read_b128 v[200:203], v154 offset:51200
	ds_read_b128 v[204:207], v154 offset:52224
	ds_read_b128 v[208:211], v154 offset:53248
	ds_read_b128 v[212:215], v154 offset:54272
	ds_read_b128 v[220:223], v154 offset:55296
	ds_read_b128 v[224:227], v154 offset:56320
	global_load_lds_dwordx4 v[180:181], off
	s_add_i32 m0, s25, 0x2000
	s_add_u32 s26, s64, 0x40080
	v_lshl_add_u64 v[180:181], v[216:217], 0, s[42:43]
	s_addc_u32 s27, s65, 0
	s_add_i32 s25, s57, s11
	global_load_lds_dwordx4 v[180:181], off
	v_lshl_add_u64 v[180:181], s[26:27], 0, v[136:137]
	s_mov_b32 m0, s25
	s_nop 0
	global_load_lds_dwordx4 v[180:181], off
	v_lshl_add_u64 v[180:181], s[26:27], 0, v[140:141]
	s_add_i32 m0, s25, 0x2000
	s_nop 0
	global_load_lds_dwordx4 v[180:181], off
	s_waitcnt vmcnt(4)
	s_waitcnt lgkmcnt(0)
	s_setprio 1
	s_barrier
	v_mfma_f32_16x16x32_bf16 v[114:117], v[156:159], v[192:195], v[114:117]
	v_mfma_f32_16x16x32_bf16 v[118:121], v[164:167], v[192:195], v[118:121]
	v_mfma_f32_16x16x32_bf16 v[98:101], v[156:159], v[200:203], v[98:101]
	v_mfma_f32_16x16x32_bf16 v[102:105], v[164:167], v[200:203], v[102:105]
	v_mfma_f32_16x16x32_bf16 v[82:85], v[156:159], v[208:211], v[82:85]
	v_mfma_f32_16x16x32_bf16 v[86:89], v[164:167], v[208:211], v[86:89]
	v_mfma_f32_16x16x32_bf16 v[66:69], v[156:159], v[220:223], v[66:69]
	v_mfma_f32_16x16x32_bf16 v[70:73], v[164:167], v[220:223], v[70:73]
	v_mfma_f32_16x16x32_bf16 v[114:117], v[160:163], v[196:199], v[114:117]
	v_mfma_f32_16x16x32_bf16 v[118:121], v[168:171], v[196:199], v[118:121]
	v_mfma_f32_16x16x32_bf16 v[98:101], v[160:163], v[204:207], v[98:101]
	v_mfma_f32_16x16x32_bf16 v[102:105], v[168:171], v[204:207], v[102:105]
	v_mfma_f32_16x16x32_bf16 v[82:85], v[160:163], v[212:215], v[82:85]
	v_mfma_f32_16x16x32_bf16 v[86:89], v[168:171], v[212:215], v[86:89]
	v_mfma_f32_16x16x32_bf16 v[66:69], v[160:163], v[224:227], v[66:69]
	v_mfma_f32_16x16x32_bf16 v[70:73], v[168:171], v[224:227], v[70:73]
	v_mfma_f32_16x16x32_bf16 v[50:53], v[172:175], v[192:195], v[50:53]
	v_mfma_f32_16x16x32_bf16 v[54:57], v[184:187], v[192:195], v[54:57]
	v_mfma_f32_16x16x32_bf16 v[34:37], v[172:175], v[200:203], v[34:37]
	v_mfma_f32_16x16x32_bf16 v[38:41], v[184:187], v[200:203], v[38:41]
	v_mfma_f32_16x16x32_bf16 v[18:21], v[172:175], v[208:211], v[18:21]
	v_mfma_f32_16x16x32_bf16 v[22:25], v[184:187], v[208:211], v[22:25]
	v_mfma_f32_16x16x32_bf16 v[6:9], v[172:175], v[220:223], v[6:9]
	v_mfma_f32_16x16x32_bf16 v[2:5], v[184:187], v[220:223], v[2:5]
	v_mfma_f32_16x16x32_bf16 v[50:53], v[176:179], v[196:199], v[50:53]
	v_mfma_f32_16x16x32_bf16 v[54:57], v[188:191], v[196:199], v[54:57]
	v_mfma_f32_16x16x32_bf16 v[34:37], v[176:179], v[204:207], v[34:37]
	v_mfma_f32_16x16x32_bf16 v[38:41], v[188:191], v[204:207], v[38:41]
	v_mfma_f32_16x16x32_bf16 v[18:21], v[176:179], v[212:215], v[18:21]
	v_mfma_f32_16x16x32_bf16 v[22:25], v[188:191], v[212:215], v[22:25]
	v_mfma_f32_16x16x32_bf16 v[6:9], v[176:179], v[224:227], v[6:9]
	v_mfma_f32_16x16x32_bf16 v[2:5], v[188:191], v[224:227], v[2:5]
	s_setprio 0
	s_barrier
	s_add_u32 s62, s62, 0x100
	s_addc_u32 s63, s63, 0
	s_cmp_ge_u32 s1, s0
	s_cbranch_scc0 .LBB0_1261
	s_and_b64 vcc, exec, s[4:5]
	s_cbranch_vccz .LBB0_1265
	v_add_u32_e32 v11, 0, v152
	v_add_u32_e32 v12, 0x10000, v11
	ds_read_b128 v[156:159], v12
	ds_read_b128 v[160:163], v12 offset:1024
	ds_read_b128 v[164:167], v12 offset:2048
	ds_read_b128 v[168:171], v12 offset:3072
	v_add_u32_e32 v12, 0x14000, v11
	ds_read_b128 v[172:175], v12
	ds_read_b128 v[176:179], v12 offset:1024
	ds_read_b128 v[184:187], v12 offset:2048
	ds_read_b128 v[188:191], v12 offset:3072
	v_lshl_add_u64 v[12:13], s[14:15], 0, v[134:135]
	s_mov_b32 m0, s24
	v_lshl_add_u64 v[12:13], v[12:13], 0, s[50:51]
	ds_read_b128 v[192:195], v154
	ds_read_b128 v[196:199], v154 offset:1024
	ds_read_b128 v[200:203], v154 offset:2048
	ds_read_b128 v[204:207], v154 offset:3072
	ds_read_b128 v[208:211], v154 offset:4096
	ds_read_b128 v[212:215], v154 offset:5120
	ds_read_b128 v[220:223], v154 offset:6144
	ds_read_b128 v[224:227], v154 offset:7168
	global_load_lds_dwordx4 v[12:13], off
	v_lshl_add_u64 v[12:13], s[14:15], 0, v[138:139]
	s_add_u32 s0, s14, 0x40780
	v_lshl_add_u64 v[12:13], v[12:13], 0, s[50:51]
	s_mov_b32 m0, s23
	s_addc_u32 s1, s15, 0
	global_load_lds_dwordx4 v[12:13], off
	v_lshl_add_u64 v[12:13], s[0:1], 0, v[134:135]
	s_mov_b32 m0, s3
	s_nop 0
	global_load_lds_dwordx4 v[12:13], off
	v_lshl_add_u64 v[12:13], s[0:1], 0, v[138:139]
	s_mov_b32 m0, s22
	s_nop 0
	global_load_lds_dwordx4 v[12:13], off
	s_waitcnt vmcnt(8)
	s_waitcnt lgkmcnt(0)
	s_setprio 1
	s_barrier
	v_mfma_f32_16x16x32_bf16 v[126:129], v[156:159], v[192:195], v[126:129]
	v_mfma_f32_16x16x32_bf16 v[122:125], v[164:167], v[192:195], v[122:125]
	v_mfma_f32_16x16x32_bf16 v[106:109], v[156:159], v[200:203], v[106:109]
	v_mfma_f32_16x16x32_bf16 v[110:113], v[164:167], v[200:203], v[110:113]
	v_mfma_f32_16x16x32_bf16 v[90:93], v[156:159], v[208:211], v[90:93]
	v_mfma_f32_16x16x32_bf16 v[94:97], v[164:167], v[208:211], v[94:97]
	v_mfma_f32_16x16x32_bf16 v[74:77], v[156:159], v[220:223], v[74:77]
	v_mfma_f32_16x16x32_bf16 v[78:81], v[164:167], v[220:223], v[78:81]
	v_mfma_f32_16x16x32_bf16 v[126:129], v[160:163], v[196:199], v[126:129]
	v_mfma_f32_16x16x32_bf16 v[122:125], v[168:171], v[196:199], v[122:125]
	v_mfma_f32_16x16x32_bf16 v[106:109], v[160:163], v[204:207], v[106:109]
	v_mfma_f32_16x16x32_bf16 v[110:113], v[168:171], v[204:207], v[110:113]
	v_mfma_f32_16x16x32_bf16 v[90:93], v[160:163], v[212:215], v[90:93]
	v_mfma_f32_16x16x32_bf16 v[94:97], v[168:171], v[212:215], v[94:97]
	v_mfma_f32_16x16x32_bf16 v[74:77], v[160:163], v[224:227], v[74:77]
	v_mfma_f32_16x16x32_bf16 v[78:81], v[168:171], v[224:227], v[78:81]
	v_mfma_f32_16x16x32_bf16 v[58:61], v[172:175], v[192:195], v[58:61]
	v_mfma_f32_16x16x32_bf16 v[62:65], v[184:187], v[192:195], v[62:65]
	v_mfma_f32_16x16x32_bf16 v[42:45], v[172:175], v[200:203], v[42:45]
	v_mfma_f32_16x16x32_bf16 v[46:49], v[184:187], v[200:203], v[46:49]
	v_mfma_f32_16x16x32_bf16 v[26:29], v[172:175], v[208:211], v[26:29]
	v_mfma_f32_16x16x32_bf16 v[30:33], v[184:187], v[208:211], v[30:33]
	v_mfma_f32_16x16x32_bf16 v[130:133], v[172:175], v[220:223], v[130:133]
	v_mfma_f32_16x16x32_bf16 v[12:15], v[184:187], v[220:223], v[14:17]
	v_mfma_f32_16x16x32_bf16 v[58:61], v[176:179], v[196:199], v[58:61]
	v_mfma_f32_16x16x32_bf16 v[62:65], v[188:191], v[196:199], v[62:65]
	v_mfma_f32_16x16x32_bf16 v[42:45], v[176:179], v[204:207], v[42:45]
	v_mfma_f32_16x16x32_bf16 v[46:49], v[188:191], v[204:207], v[46:49]
	v_mfma_f32_16x16x32_bf16 v[26:29], v[176:179], v[212:215], v[26:29]
	v_mfma_f32_16x16x32_bf16 v[30:33], v[188:191], v[212:215], v[30:33]
	v_mfma_f32_16x16x32_bf16 v[130:133], v[176:179], v[224:227], v[130:133]
	v_mfma_f32_16x16x32_bf16 v[12:15], v[188:191], v[224:227], v[12:15]
	s_setprio 0
	s_barrier
	ds_read_b128 v[192:195], v154 offset:16384
	ds_read_b128 v[196:199], v154 offset:17408
	ds_read_b128 v[200:203], v154 offset:18432
	ds_read_b128 v[204:207], v154 offset:19456
	ds_read_b128 v[208:211], v154 offset:20480
	ds_read_b128 v[212:215], v154 offset:21504
	ds_read_b128 v[220:223], v154 offset:22528
	ds_read_b128 v[224:227], v154 offset:23552
	s_waitcnt vmcnt(0)
	s_waitcnt lgkmcnt(0)
	s_setprio 1
	s_barrier
	v_mfma_f32_16x16x32_bf16 v[114:117], v[156:159], v[192:195], v[114:117]
	v_mfma_f32_16x16x32_bf16 v[118:121], v[164:167], v[192:195], v[118:121]
	v_mfma_f32_16x16x32_bf16 v[98:101], v[156:159], v[200:203], v[98:101]
	v_mfma_f32_16x16x32_bf16 v[102:105], v[164:167], v[200:203], v[102:105]
	v_mfma_f32_16x16x32_bf16 v[82:85], v[156:159], v[208:211], v[82:85]
	v_mfma_f32_16x16x32_bf16 v[86:89], v[164:167], v[208:211], v[86:89]
	v_mfma_f32_16x16x32_bf16 v[66:69], v[156:159], v[220:223], v[66:69]
	v_mfma_f32_16x16x32_bf16 v[70:73], v[164:167], v[220:223], v[70:73]
	v_mfma_f32_16x16x32_bf16 v[114:117], v[160:163], v[196:199], v[114:117]
	v_mfma_f32_16x16x32_bf16 v[118:121], v[168:171], v[196:199], v[118:121]
	v_mfma_f32_16x16x32_bf16 v[98:101], v[160:163], v[204:207], v[98:101]
	v_mfma_f32_16x16x32_bf16 v[102:105], v[168:171], v[204:207], v[102:105]
	v_mfma_f32_16x16x32_bf16 v[82:85], v[160:163], v[212:215], v[82:85]
	v_mfma_f32_16x16x32_bf16 v[86:89], v[168:171], v[212:215], v[86:89]
	v_mfma_f32_16x16x32_bf16 v[66:69], v[160:163], v[224:227], v[66:69]
	v_mfma_f32_16x16x32_bf16 v[70:73], v[168:171], v[224:227], v[70:73]
	v_mfma_f32_16x16x32_bf16 v[50:53], v[172:175], v[192:195], v[50:53]
	v_mfma_f32_16x16x32_bf16 v[54:57], v[184:187], v[192:195], v[54:57]
	v_mfma_f32_16x16x32_bf16 v[34:37], v[172:175], v[200:203], v[34:37]
	v_mfma_f32_16x16x32_bf16 v[38:41], v[184:187], v[200:203], v[38:41]
	v_mfma_f32_16x16x32_bf16 v[16:19], v[172:175], v[208:211], v[18:21]
	v_mfma_f32_16x16x32_bf16 v[22:25], v[184:187], v[208:211], v[22:25]
	v_mfma_f32_16x16x32_bf16 v[6:9], v[172:175], v[220:223], v[6:9]
	v_mfma_f32_16x16x32_bf16 v[2:5], v[184:187], v[220:223], v[2:5]
	v_mfma_f32_16x16x32_bf16 v[50:53], v[176:179], v[196:199], v[50:53]
	v_mfma_f32_16x16x32_bf16 v[54:57], v[188:191], v[196:199], v[54:57]
	v_mfma_f32_16x16x32_bf16 v[34:37], v[176:179], v[204:207], v[34:37]
	v_mfma_f32_16x16x32_bf16 v[38:41], v[188:191], v[204:207], v[38:41]
	v_mfma_f32_16x16x32_bf16 v[18:21], v[176:179], v[212:215], v[16:19]
	v_mfma_f32_16x16x32_bf16 v[22:25], v[188:191], v[212:215], v[22:25]
	v_mfma_f32_16x16x32_bf16 v[6:9], v[176:179], v[224:227], v[6:9]
	v_mfma_f32_16x16x32_bf16 v[2:5], v[188:191], v[224:227], v[2:5]
	s_setprio 0
	s_barrier
	v_add_u32_e32 v16, 0x18000, v11
	v_add_u32_e32 v11, 0x1c000, v11
	ds_read_b128 v[156:159], v16
	ds_read_b128 v[160:163], v16 offset:1024
	ds_read_b128 v[164:167], v16 offset:2048
	ds_read_b128 v[168:171], v16 offset:3072
	ds_read_b128 v[172:175], v11
	ds_read_b128 v[176:179], v11 offset:1024
	ds_read_b128 v[184:187], v11 offset:2048
	ds_read_b128 v[188:191], v11 offset:3072
	ds_read_b128 v[192:195], v154 offset:32768
	ds_read_b128 v[196:199], v154 offset:33792
	ds_read_b128 v[200:203], v154 offset:34816
	ds_read_b128 v[204:207], v154 offset:35840
	ds_read_b128 v[208:211], v154 offset:36864
	ds_read_b128 v[212:215], v154 offset:37888
	ds_read_b128 v[220:223], v154 offset:38912
	ds_read_b128 v[224:227], v154 offset:39936
	s_waitcnt lgkmcnt(0)
	s_setprio 1
	s_barrier
	v_mfma_f32_16x16x32_bf16 v[126:129], v[156:159], v[192:195], v[126:129]
	v_mfma_f32_16x16x32_bf16 v[122:125], v[164:167], v[192:195], v[122:125]
	v_mfma_f32_16x16x32_bf16 v[106:109], v[156:159], v[200:203], v[106:109]
	v_mfma_f32_16x16x32_bf16 v[110:113], v[164:167], v[200:203], v[110:113]
	v_mfma_f32_16x16x32_bf16 v[90:93], v[156:159], v[208:211], v[90:93]
	v_mfma_f32_16x16x32_bf16 v[94:97], v[164:167], v[208:211], v[94:97]
	v_mfma_f32_16x16x32_bf16 v[74:77], v[156:159], v[220:223], v[74:77]
	v_mfma_f32_16x16x32_bf16 v[78:81], v[164:167], v[220:223], v[78:81]
	v_mfma_f32_16x16x32_bf16 v[126:129], v[160:163], v[196:199], v[126:129]
	v_mfma_f32_16x16x32_bf16 v[122:125], v[168:171], v[196:199], v[122:125]
	v_mfma_f32_16x16x32_bf16 v[106:109], v[160:163], v[204:207], v[106:109]
	v_mfma_f32_16x16x32_bf16 v[110:113], v[168:171], v[204:207], v[110:113]
	v_mfma_f32_16x16x32_bf16 v[90:93], v[160:163], v[212:215], v[90:93]
	v_mfma_f32_16x16x32_bf16 v[94:97], v[168:171], v[212:215], v[94:97]
	v_mfma_f32_16x16x32_bf16 v[74:77], v[160:163], v[224:227], v[74:77]
	v_mfma_f32_16x16x32_bf16 v[78:81], v[168:171], v[224:227], v[78:81]
	v_mfma_f32_16x16x32_bf16 v[58:61], v[172:175], v[192:195], v[58:61]
	v_mfma_f32_16x16x32_bf16 v[62:65], v[184:187], v[192:195], v[62:65]
	v_mfma_f32_16x16x32_bf16 v[42:45], v[172:175], v[200:203], v[42:45]
	v_mfma_f32_16x16x32_bf16 v[46:49], v[184:187], v[200:203], v[46:49]
	v_mfma_f32_16x16x32_bf16 v[26:29], v[172:175], v[208:211], v[26:29]
	v_mfma_f32_16x16x32_bf16 v[30:33], v[184:187], v[208:211], v[30:33]
	v_mfma_f32_16x16x32_bf16 v[130:133], v[172:175], v[220:223], v[130:133]
	v_mfma_f32_16x16x32_bf16 v[12:15], v[184:187], v[220:223], v[12:15]
	v_mfma_f32_16x16x32_bf16 v[58:61], v[176:179], v[196:199], v[58:61]
	v_mfma_f32_16x16x32_bf16 v[62:65], v[188:191], v[196:199], v[62:65]
	v_mfma_f32_16x16x32_bf16 v[42:45], v[176:179], v[204:207], v[42:45]
	v_mfma_f32_16x16x32_bf16 v[46:49], v[188:191], v[204:207], v[46:49]
	v_mfma_f32_16x16x32_bf16 v[26:29], v[176:179], v[212:215], v[26:29]
	v_mfma_f32_16x16x32_bf16 v[30:33], v[188:191], v[212:215], v[30:33]
	v_mfma_f32_16x16x32_bf16 v[130:133], v[176:179], v[224:227], v[130:133]
	v_mfma_f32_16x16x32_bf16 v[14:17], v[188:191], v[224:227], v[12:15]
	s_setprio 0
	s_barrier
	ds_read_b128 v[192:195], v154 offset:49152
	ds_read_b128 v[196:199], v154 offset:50176
	ds_read_b128 v[200:203], v154 offset:51200
	ds_read_b128 v[204:207], v154 offset:52224
	ds_read_b128 v[208:211], v154 offset:53248
	ds_read_b128 v[212:215], v154 offset:54272
	ds_read_b128 v[220:223], v154 offset:55296
	ds_read_b128 v[224:227], v154 offset:56320
	s_waitcnt lgkmcnt(0)
	s_setprio 1
	s_barrier
	v_mfma_f32_16x16x32_bf16 v[114:117], v[156:159], v[192:195], v[114:117]
	v_mfma_f32_16x16x32_bf16 v[118:121], v[164:167], v[192:195], v[118:121]
	v_mfma_f32_16x16x32_bf16 v[98:101], v[156:159], v[200:203], v[98:101]
	v_mfma_f32_16x16x32_bf16 v[102:105], v[164:167], v[200:203], v[102:105]
	v_mfma_f32_16x16x32_bf16 v[82:85], v[156:159], v[208:211], v[82:85]
	v_mfma_f32_16x16x32_bf16 v[86:89], v[164:167], v[208:211], v[86:89]
	v_mfma_f32_16x16x32_bf16 v[66:69], v[156:159], v[220:223], v[66:69]
	v_mfma_f32_16x16x32_bf16 v[70:73], v[164:167], v[220:223], v[70:73]
	v_mfma_f32_16x16x32_bf16 v[114:117], v[160:163], v[196:199], v[114:117]
	v_mfma_f32_16x16x32_bf16 v[118:121], v[168:171], v[196:199], v[118:121]
	v_mfma_f32_16x16x32_bf16 v[98:101], v[160:163], v[204:207], v[98:101]
	v_mfma_f32_16x16x32_bf16 v[102:105], v[168:171], v[204:207], v[102:105]
	v_mfma_f32_16x16x32_bf16 v[82:85], v[160:163], v[212:215], v[82:85]
	v_mfma_f32_16x16x32_bf16 v[86:89], v[168:171], v[212:215], v[86:89]
	v_mfma_f32_16x16x32_bf16 v[66:69], v[160:163], v[224:227], v[66:69]
	v_mfma_f32_16x16x32_bf16 v[70:73], v[168:171], v[224:227], v[70:73]
	v_mfma_f32_16x16x32_bf16 v[50:53], v[172:175], v[192:195], v[50:53]
	v_mfma_f32_16x16x32_bf16 v[54:57], v[184:187], v[192:195], v[54:57]
	v_mfma_f32_16x16x32_bf16 v[34:37], v[172:175], v[200:203], v[34:37]
	v_mfma_f32_16x16x32_bf16 v[38:41], v[184:187], v[200:203], v[38:41]
	v_mfma_f32_16x16x32_bf16 v[18:21], v[172:175], v[208:211], v[18:21]
	v_mfma_f32_16x16x32_bf16 v[22:25], v[184:187], v[208:211], v[22:25]
	v_mfma_f32_16x16x32_bf16 v[6:9], v[172:175], v[220:223], v[6:9]
	v_mfma_f32_16x16x32_bf16 v[2:5], v[184:187], v[220:223], v[2:5]
	v_mfma_f32_16x16x32_bf16 v[50:53], v[176:179], v[196:199], v[50:53]
	v_mfma_f32_16x16x32_bf16 v[54:57], v[188:191], v[196:199], v[54:57]
	v_mfma_f32_16x16x32_bf16 v[34:37], v[176:179], v[204:207], v[34:37]
	v_mfma_f32_16x16x32_bf16 v[38:41], v[188:191], v[204:207], v[38:41]
	v_mfma_f32_16x16x32_bf16 v[18:21], v[176:179], v[212:215], v[18:21]
	v_mfma_f32_16x16x32_bf16 v[22:25], v[188:191], v[212:215], v[22:25]
	v_mfma_f32_16x16x32_bf16 v[6:9], v[176:179], v[224:227], v[6:9]
	v_mfma_f32_16x16x32_bf16 v[2:5], v[188:191], v[224:227], v[2:5]
	s_setprio 0
	s_barrier
	s_andn2_b64 vcc, exec, s[48:49]
	s_cbranch_vccz .LBB0_1266

.LBB0_1400:
	s_add_i32 s74, s74, 2
	s_add_u32 s0, s16, s8
	s_addc_u32 s1, s17, s9
	s_add_u32 s0, s0, 0x100
	s_addc_u32 s1, s1, 0
	s_add_u32 s3, s72, s8
	s_addc_u32 s10, s73, s9
	s_add_i32 s25, 0, 0x10000
	v_add_u32_e32 v2, s25, v226
	s_add_i32 s75, 0, 0x14000
	s_waitcnt lgkmcnt(0)
	ds_read_b128 v[134:137], v2
	ds_read_b128 v[138:141], v2 offset:1024
	ds_read_b128 v[142:145], v2 offset:2048
	ds_read_b128 v[146:149], v2 offset:3072
	v_add_u32_e32 v2, s75, v226
	ds_read_b128 v[150:153], v2
	ds_read_b128 v[154:157], v2 offset:1024
	ds_read_b128 v[158:161], v2 offset:2048
	ds_read_b128 v[162:165], v2 offset:3072
	s_cmpk_eq_i32 s8, 0x700
	s_cselect_b32 s11, s65, s10
	s_cselect_b32 s10, s64, s3
	s_cselect_b32 s71, s63, s1
	s_cselect_b32 s70, s62, s0
	v_lshl_add_u64 v[4:5], v[222:223], 0, s[8:9]
	s_add_i32 s0, s24, 0x8000
	v_lshl_add_u64 v[224:225], v[4:5], 0, s[30:31]
	s_mov_b32 m0, s0
	s_waitcnt lgkmcnt(0)
	ds_read_b128 v[166:169], v227
	ds_read_b128 v[170:173], v227 offset:1024
	ds_read_b128 v[174:177], v227 offset:2048
	ds_read_b128 v[178:181], v227 offset:3072
	ds_read_b128 v[182:185], v227 offset:4096
	ds_read_b128 v[186:189], v227 offset:5120
	ds_read_b128 v[190:193], v227 offset:6144
	ds_read_b128 v[194:197], v227 offset:7168
	global_load_lds_dwordx4 v[224:225], off
	v_lshl_add_u64 v[224:225], v[220:221], 0, s[8:9]
	s_add_i32 s33, s24, 0xa000
	v_lshl_add_u64 v[246:247], v[224:225], 0, s[30:31]
	s_mov_b32 m0, s33
	s_add_i32 s22, s24, 0xc000
	global_load_lds_dwordx4 v[246:247], off
	v_lshl_add_u64 v[4:5], v[4:5], 0, s[44:45]
	s_mov_b32 m0, s22
	s_add_i32 s23, s24, 0xe000
	global_load_lds_dwordx4 v[4:5], off
	v_lshl_add_u64 v[4:5], v[224:225], 0, s[44:45]
	s_mov_b32 m0, s23
	s_nop 0
	global_load_lds_dwordx4 v[4:5], off
	s_waitcnt vmcnt(8)
	s_waitcnt lgkmcnt(0)
	s_setprio 1
	s_barrier
	v_mfma_f32_16x16x32_bf16 v[82:85], v[134:137], v[166:169], v[82:85]
	v_mfma_f32_16x16x32_bf16 v[10:13], v[142:145], v[166:169], v[10:13]
	v_mfma_f32_16x16x32_bf16 v[130:133], v[134:137], v[174:177], v[130:133]
	v_mfma_f32_16x16x32_bf16 v[66:69], v[142:145], v[174:177], v[66:69]
	v_mfma_f32_16x16x32_bf16 v[126:129], v[134:137], v[182:185], v[126:129]
	v_mfma_f32_16x16x32_bf16 v[62:65], v[142:145], v[182:185], v[62:65]
	v_mfma_f32_16x16x32_bf16 v[122:125], v[134:137], v[190:193], v[122:125]
	v_mfma_f32_16x16x32_bf16 v[58:61], v[142:145], v[190:193], v[58:61]
	v_mfma_f32_16x16x32_bf16 v[82:85], v[138:141], v[170:173], v[82:85]
	v_mfma_f32_16x16x32_bf16 v[10:13], v[146:149], v[170:173], v[10:13]
	v_mfma_f32_16x16x32_bf16 v[130:133], v[138:141], v[178:181], v[130:133]
	v_mfma_f32_16x16x32_bf16 v[66:69], v[146:149], v[178:181], v[66:69]
	v_mfma_f32_16x16x32_bf16 v[126:129], v[138:141], v[186:189], v[126:129]
	v_mfma_f32_16x16x32_bf16 v[62:65], v[146:149], v[186:189], v[62:65]
	v_mfma_f32_16x16x32_bf16 v[122:125], v[138:141], v[194:197], v[122:125]
	v_mfma_f32_16x16x32_bf16 v[58:61], v[146:149], v[194:197], v[58:61]
	v_mfma_f32_16x16x32_bf16 v[70:73], v[150:153], v[166:169], v[70:73]
	v_mfma_f32_16x16x32_bf16 v[4:7], v[158:161], v[166:169], v[6:9]
	v_mfma_f32_16x16x32_bf16 v[118:121], v[150:153], v[174:177], v[118:121]
	v_mfma_f32_16x16x32_bf16 v[54:57], v[158:161], v[174:177], v[54:57]
	v_mfma_f32_16x16x32_bf16 v[114:117], v[150:153], v[182:185], v[114:117]
	v_mfma_f32_16x16x32_bf16 v[50:53], v[158:161], v[182:185], v[50:53]
	v_mfma_f32_16x16x32_bf16 v[110:113], v[150:153], v[190:193], v[110:113]
	v_mfma_f32_16x16x32_bf16 v[46:49], v[158:161], v[190:193], v[46:49]
	v_mfma_f32_16x16x32_bf16 v[70:73], v[154:157], v[170:173], v[70:73]
	v_mfma_f32_16x16x32_bf16 v[4:7], v[162:165], v[170:173], v[4:7]
	v_mfma_f32_16x16x32_bf16 v[118:121], v[154:157], v[178:181], v[118:121]
	v_mfma_f32_16x16x32_bf16 v[54:57], v[162:165], v[178:181], v[54:57]
	v_mfma_f32_16x16x32_bf16 v[114:117], v[154:157], v[186:189], v[114:117]
	v_mfma_f32_16x16x32_bf16 v[50:53], v[162:165], v[186:189], v[50:53]
	v_mfma_f32_16x16x32_bf16 v[110:113], v[154:157], v[194:197], v[110:113]
	v_mfma_f32_16x16x32_bf16 v[46:49], v[162:165], v[194:197], v[46:49]
	s_setprio 0
	s_barrier
	s_add_i32 s1, s25, s78
	v_lshl_add_u64 v[224:225], s[10:11], 0, v[200:201]
	s_mov_b32 m0, s1
	ds_read_b128 v[166:169], v227 offset:16384
	ds_read_b128 v[170:173], v227 offset:17408
	ds_read_b128 v[174:177], v227 offset:18432
	ds_read_b128 v[178:181], v227 offset:19456
	ds_read_b128 v[182:185], v227 offset:20480
	ds_read_b128 v[186:189], v227 offset:21504
	ds_read_b128 v[190:193], v227 offset:22528
	ds_read_b128 v[194:197], v227 offset:23552
	global_load_lds_dwordx4 v[224:225], off
	s_add_i32 m0, s1, 0x2000
	s_add_u32 s26, s10, 0x40000
	v_lshl_add_u64 v[246:247], s[10:11], 0, v[204:205]
	s_addc_u32 s27, s11, 0
	s_add_i32 s1, s75, s78
	global_load_lds_dwordx4 v[246:247], off
	v_lshl_add_u64 v[8:9], s[26:27], 0, v[200:201]
	s_mov_b32 m0, s1
	s_nop 0
	global_load_lds_dwordx4 v[8:9], off
	v_lshl_add_u64 v[8:9], s[26:27], 0, v[204:205]
	s_add_i32 m0, s1, 0x2000
	s_nop 0
	global_load_lds_dwordx4 v[8:9], off
	s_waitcnt vmcnt(4)
	s_waitcnt lgkmcnt(0)
	s_setprio 1
	s_barrier
	v_mfma_f32_16x16x32_bf16 v[102:105], v[134:137], v[166:169], v[102:105]
	v_mfma_f32_16x16x32_bf16 v[30:33], v[142:145], v[166:169], v[30:33]
	v_mfma_f32_16x16x32_bf16 v[106:109], v[134:137], v[174:177], v[106:109]
	v_mfma_f32_16x16x32_bf16 v[42:45], v[142:145], v[174:177], v[42:45]
	v_mfma_f32_16x16x32_bf16 v[98:101], v[134:137], v[182:185], v[98:101]
	v_mfma_f32_16x16x32_bf16 v[38:41], v[142:145], v[182:185], v[38:41]
	v_mfma_f32_16x16x32_bf16 v[94:97], v[134:137], v[190:193], v[94:97]
	v_mfma_f32_16x16x32_bf16 v[34:37], v[142:145], v[190:193], v[34:37]
	v_mfma_f32_16x16x32_bf16 v[102:105], v[138:141], v[170:173], v[102:105]
	v_mfma_f32_16x16x32_bf16 v[30:33], v[146:149], v[170:173], v[30:33]
	v_mfma_f32_16x16x32_bf16 v[106:109], v[138:141], v[178:181], v[106:109]
	v_mfma_f32_16x16x32_bf16 v[42:45], v[146:149], v[178:181], v[42:45]
	v_mfma_f32_16x16x32_bf16 v[98:101], v[138:141], v[186:189], v[98:101]
	v_mfma_f32_16x16x32_bf16 v[38:41], v[146:149], v[186:189], v[38:41]
	v_mfma_f32_16x16x32_bf16 v[94:97], v[138:141], v[194:197], v[94:97]
	v_mfma_f32_16x16x32_bf16 v[34:37], v[146:149], v[194:197], v[34:37]
	v_mfma_f32_16x16x32_bf16 v[74:77], v[150:153], v[166:169], v[74:77]
	v_mfma_f32_16x16x32_bf16 v[14:17], v[158:161], v[166:169], v[14:17]
	v_mfma_f32_16x16x32_bf16 v[90:93], v[150:153], v[174:177], v[90:93]
	v_mfma_f32_16x16x32_bf16 v[26:29], v[158:161], v[174:177], v[26:29]
	v_mfma_f32_16x16x32_bf16 v[86:89], v[150:153], v[182:185], v[86:89]
	v_mfma_f32_16x16x32_bf16 v[22:25], v[158:161], v[182:185], v[22:25]
	v_mfma_f32_16x16x32_bf16 v[78:81], v[150:153], v[190:193], v[78:81]
	v_mfma_f32_16x16x32_bf16 v[18:21], v[158:161], v[190:193], v[18:21]
	v_mfma_f32_16x16x32_bf16 v[74:77], v[154:157], v[170:173], v[74:77]
	v_mfma_f32_16x16x32_bf16 v[14:17], v[162:165], v[170:173], v[14:17]
	v_mfma_f32_16x16x32_bf16 v[90:93], v[154:157], v[178:181], v[90:93]
	v_mfma_f32_16x16x32_bf16 v[26:29], v[162:165], v[178:181], v[26:29]
	v_mfma_f32_16x16x32_bf16 v[86:89], v[154:157], v[186:189], v[86:89]
	v_mfma_f32_16x16x32_bf16 v[22:25], v[162:165], v[186:189], v[22:25]
	v_mfma_f32_16x16x32_bf16 v[78:81], v[154:157], v[194:197], v[78:81]
	v_mfma_f32_16x16x32_bf16 v[18:21], v[162:165], v[194:197], v[18:21]
	s_setprio 0
	s_barrier
	s_add_i32 s1, 0, 0x18000
	v_add_u32_e32 v2, s1, v226
	s_add_i32 s3, 0, 0x1c000
	ds_read_b128 v[134:137], v2
	ds_read_b128 v[138:141], v2 offset:1024
	ds_read_b128 v[142:145], v2 offset:2048
	ds_read_b128 v[146:149], v2 offset:3072
	v_add_u32_e32 v2, s3, v226
	ds_read_b128 v[150:153], v2
	ds_read_b128 v[154:157], v2 offset:1024
	ds_read_b128 v[158:161], v2 offset:2048
	ds_read_b128 v[162:165], v2 offset:3072
	s_mov_b32 m0, s24
	v_lshl_add_u64 v[8:9], s[70:71], 0, v[198:199]
	s_add_u32 s26, s70, 0x40000
	ds_read_b128 v[166:169], v227 offset:32768
	ds_read_b128 v[170:173], v227 offset:33792
	ds_read_b128 v[174:177], v227 offset:34816
	ds_read_b128 v[178:181], v227 offset:35840
	ds_read_b128 v[182:185], v227 offset:36864
	ds_read_b128 v[186:189], v227 offset:37888
	ds_read_b128 v[190:193], v227 offset:38912
	ds_read_b128 v[194:197], v227 offset:39936
	global_load_lds_dwordx4 v[8:9], off
	v_lshl_add_u64 v[8:9], s[70:71], 0, v[202:203]
	s_mov_b32 m0, s83
	s_addc_u32 s27, s71, 0
	global_load_lds_dwordx4 v[8:9], off
	v_lshl_add_u64 v[8:9], s[26:27], 0, v[198:199]
	s_mov_b32 m0, s84
	s_nop 0
	global_load_lds_dwordx4 v[8:9], off
	v_lshl_add_u64 v[8:9], s[26:27], 0, v[202:203]
	s_mov_b32 m0, s85
	s_nop 0
	global_load_lds_dwordx4 v[8:9], off
	s_waitcnt vmcnt(8)
	s_waitcnt lgkmcnt(0)
	s_setprio 1
	s_barrier
	v_mfma_f32_16x16x32_bf16 v[82:85], v[134:137], v[166:169], v[82:85]
	v_mfma_f32_16x16x32_bf16 v[8:11], v[142:145], v[166:169], v[10:13]
	v_mfma_f32_16x16x32_bf16 v[130:133], v[134:137], v[174:177], v[130:133]
	v_mfma_f32_16x16x32_bf16 v[66:69], v[142:145], v[174:177], v[66:69]
	v_mfma_f32_16x16x32_bf16 v[126:129], v[134:137], v[182:185], v[126:129]
	v_mfma_f32_16x16x32_bf16 v[62:65], v[142:145], v[182:185], v[62:65]
	v_mfma_f32_16x16x32_bf16 v[122:125], v[134:137], v[190:193], v[122:125]
	v_mfma_f32_16x16x32_bf16 v[58:61], v[142:145], v[190:193], v[58:61]
	v_mfma_f32_16x16x32_bf16 v[82:85], v[138:141], v[170:173], v[82:85]
	v_mfma_f32_16x16x32_bf16 v[10:13], v[146:149], v[170:173], v[8:11]
	v_mfma_f32_16x16x32_bf16 v[130:133], v[138:141], v[178:181], v[130:133]
	v_mfma_f32_16x16x32_bf16 v[66:69], v[146:149], v[178:181], v[66:69]
	v_mfma_f32_16x16x32_bf16 v[126:129], v[138:141], v[186:189], v[126:129]
	v_mfma_f32_16x16x32_bf16 v[62:65], v[146:149], v[186:189], v[62:65]
	v_mfma_f32_16x16x32_bf16 v[122:125], v[138:141], v[194:197], v[122:125]
	v_mfma_f32_16x16x32_bf16 v[58:61], v[146:149], v[194:197], v[58:61]
	v_mfma_f32_16x16x32_bf16 v[70:73], v[150:153], v[166:169], v[70:73]
	v_mfma_f32_16x16x32_bf16 v[4:7], v[158:161], v[166:169], v[4:7]
	v_mfma_f32_16x16x32_bf16 v[118:121], v[150:153], v[174:177], v[118:121]
	v_mfma_f32_16x16x32_bf16 v[54:57], v[158:161], v[174:177], v[54:57]
	v_mfma_f32_16x16x32_bf16 v[114:117], v[150:153], v[182:185], v[114:117]
	v_mfma_f32_16x16x32_bf16 v[50:53], v[158:161], v[182:185], v[50:53]
	v_mfma_f32_16x16x32_bf16 v[110:113], v[150:153], v[190:193], v[110:113]
	v_mfma_f32_16x16x32_bf16 v[46:49], v[158:161], v[190:193], v[46:49]
	v_mfma_f32_16x16x32_bf16 v[70:73], v[154:157], v[170:173], v[70:73]
	v_mfma_f32_16x16x32_bf16 v[6:9], v[162:165], v[170:173], v[4:7]
	v_mfma_f32_16x16x32_bf16 v[118:121], v[154:157], v[178:181], v[118:121]
	v_mfma_f32_16x16x32_bf16 v[54:57], v[162:165], v[178:181], v[54:57]
	v_mfma_f32_16x16x32_bf16 v[114:117], v[154:157], v[186:189], v[114:117]
	v_mfma_f32_16x16x32_bf16 v[50:53], v[162:165], v[186:189], v[50:53]
	v_mfma_f32_16x16x32_bf16 v[110:113], v[154:157], v[194:197], v[110:113]
	v_mfma_f32_16x16x32_bf16 v[46:49], v[162:165], v[194:197], v[46:49]
	s_setprio 0
	s_barrier
	s_add_i32 s1, s1, s78
	v_lshl_add_u64 v[4:5], v[224:225], 0, s[30:31]
	s_mov_b32 m0, s1
	ds_read_b128 v[166:169], v227 offset:49152
	ds_read_b128 v[170:173], v227 offset:50176
	ds_read_b128 v[174:177], v227 offset:51200
	ds_read_b128 v[178:181], v227 offset:52224
	ds_read_b128 v[182:185], v227 offset:53248
	ds_read_b128 v[186:189], v227 offset:54272
	ds_read_b128 v[190:193], v227 offset:55296
	ds_read_b128 v[194:197], v227 offset:56320
	global_load_lds_dwordx4 v[4:5], off
	s_add_i32 m0, s1, 0x2000
	s_add_u32 s10, s10, 0x40080
	v_lshl_add_u64 v[4:5], v[246:247], 0, s[30:31]
	s_addc_u32 s11, s11, 0
	s_add_i32 s1, s3, s78
	global_load_lds_dwordx4 v[4:5], off
	v_lshl_add_u64 v[4:5], s[10:11], 0, v[200:201]
	s_mov_b32 m0, s1
	s_nop 0
	global_load_lds_dwordx4 v[4:5], off
	v_lshl_add_u64 v[4:5], s[10:11], 0, v[204:205]
	s_add_i32 m0, s1, 0x2000
	s_nop 0
	global_load_lds_dwordx4 v[4:5], off
	s_waitcnt vmcnt(4)
	s_waitcnt lgkmcnt(0)
	s_setprio 1
	s_barrier
	v_mfma_f32_16x16x32_bf16 v[102:105], v[134:137], v[166:169], v[102:105]
	v_mfma_f32_16x16x32_bf16 v[30:33], v[142:145], v[166:169], v[30:33]
	v_mfma_f32_16x16x32_bf16 v[106:109], v[134:137], v[174:177], v[106:109]
	v_mfma_f32_16x16x32_bf16 v[42:45], v[142:145], v[174:177], v[42:45]
	v_mfma_f32_16x16x32_bf16 v[98:101], v[134:137], v[182:185], v[98:101]
	v_mfma_f32_16x16x32_bf16 v[38:41], v[142:145], v[182:185], v[38:41]
	v_mfma_f32_16x16x32_bf16 v[94:97], v[134:137], v[190:193], v[94:97]
	v_mfma_f32_16x16x32_bf16 v[34:37], v[142:145], v[190:193], v[34:37]
	v_mfma_f32_16x16x32_bf16 v[102:105], v[138:141], v[170:173], v[102:105]
	v_mfma_f32_16x16x32_bf16 v[30:33], v[146:149], v[170:173], v[30:33]
	v_mfma_f32_16x16x32_bf16 v[106:109], v[138:141], v[178:181], v[106:109]
	v_mfma_f32_16x16x32_bf16 v[42:45], v[146:149], v[178:181], v[42:45]
	v_mfma_f32_16x16x32_bf16 v[98:101], v[138:141], v[186:189], v[98:101]
	v_mfma_f32_16x16x32_bf16 v[38:41], v[146:149], v[186:189], v[38:41]
	v_mfma_f32_16x16x32_bf16 v[94:97], v[138:141], v[194:197], v[94:97]
	v_mfma_f32_16x16x32_bf16 v[34:37], v[146:149], v[194:197], v[34:37]
	v_mfma_f32_16x16x32_bf16 v[74:77], v[150:153], v[166:169], v[74:77]
	v_mfma_f32_16x16x32_bf16 v[14:17], v[158:161], v[166:169], v[14:17]
	v_mfma_f32_16x16x32_bf16 v[90:93], v[150:153], v[174:177], v[90:93]
	v_mfma_f32_16x16x32_bf16 v[26:29], v[158:161], v[174:177], v[26:29]
	v_mfma_f32_16x16x32_bf16 v[86:89], v[150:153], v[182:185], v[86:89]
	v_mfma_f32_16x16x32_bf16 v[22:25], v[158:161], v[182:185], v[22:25]
	v_mfma_f32_16x16x32_bf16 v[78:81], v[150:153], v[190:193], v[78:81]
	v_mfma_f32_16x16x32_bf16 v[18:21], v[158:161], v[190:193], v[18:21]
	v_mfma_f32_16x16x32_bf16 v[74:77], v[154:157], v[170:173], v[74:77]
	v_mfma_f32_16x16x32_bf16 v[14:17], v[162:165], v[170:173], v[14:17]
	v_mfma_f32_16x16x32_bf16 v[90:93], v[154:157], v[178:181], v[90:93]
	v_mfma_f32_16x16x32_bf16 v[26:29], v[162:165], v[178:181], v[26:29]
	v_mfma_f32_16x16x32_bf16 v[86:89], v[154:157], v[186:189], v[86:89]
	v_mfma_f32_16x16x32_bf16 v[22:25], v[162:165], v[186:189], v[22:25]
	v_mfma_f32_16x16x32_bf16 v[78:81], v[154:157], v[194:197], v[78:81]
	v_mfma_f32_16x16x32_bf16 v[18:21], v[162:165], v[194:197], v[18:21]
	s_setprio 0
	s_barrier
	s_add_u32 s8, s8, 0x100
	s_addc_u32 s9, s9, 0
	s_cmp_ge_u32 s74, s96
	s_cbranch_scc0 .LBB0_1400
	s_and_b64 vcc, exec, s[66:67]
	s_cbranch_vccz .LBB0_1403
	v_add_u32_e32 v2, 0, v226
	v_add_u32_e32 v4, 0x10000, v2
	ds_read_b128 v[134:137], v4
	ds_read_b128 v[138:141], v4 offset:1024
	ds_read_b128 v[142:145], v4 offset:2048
	ds_read_b128 v[146:149], v4 offset:3072
	v_add_u32_e32 v4, 0x14000, v2
	ds_read_b128 v[150:153], v4
	ds_read_b128 v[154:157], v4 offset:1024
	ds_read_b128 v[158:161], v4 offset:2048
	ds_read_b128 v[162:165], v4 offset:3072
	v_lshl_add_u64 v[4:5], s[16:17], 0, v[198:199]
	s_mov_b32 m0, s0
	v_lshl_add_u64 v[4:5], v[4:5], 0, s[58:59]
	ds_read_b128 v[166:169], v227
	ds_read_b128 v[170:173], v227 offset:1024
	ds_read_b128 v[174:177], v227 offset:2048
	ds_read_b128 v[178:181], v227 offset:3072
	ds_read_b128 v[182:185], v227 offset:4096
	ds_read_b128 v[186:189], v227 offset:5120
	ds_read_b128 v[190:193], v227 offset:6144
	ds_read_b128 v[194:197], v227 offset:7168
	global_load_lds_dwordx4 v[4:5], off
	v_lshl_add_u64 v[4:5], s[16:17], 0, v[202:203]
	s_add_u32 s0, s16, 0x40780
	v_lshl_add_u64 v[4:5], v[4:5], 0, s[58:59]
	s_mov_b32 m0, s33
	s_addc_u32 s1, s17, 0
	global_load_lds_dwordx4 v[4:5], off
	v_lshl_add_u64 v[4:5], s[0:1], 0, v[198:199]
	s_mov_b32 m0, s22
	s_nop 0
	global_load_lds_dwordx4 v[4:5], off
	v_lshl_add_u64 v[4:5], s[0:1], 0, v[202:203]
	s_mov_b32 m0, s23
	s_nop 0
	global_load_lds_dwordx4 v[4:5], off
	s_waitcnt vmcnt(8)
	s_waitcnt lgkmcnt(0)
	s_setprio 1
	s_barrier
	v_mfma_f32_16x16x32_bf16 v[82:85], v[134:137], v[166:169], v[82:85]
	v_mfma_f32_16x16x32_bf16 v[10:13], v[142:145], v[166:169], v[10:13]
	v_mfma_f32_16x16x32_bf16 v[130:133], v[134:137], v[174:177], v[130:133]
	v_mfma_f32_16x16x32_bf16 v[66:69], v[142:145], v[174:177], v[66:69]
	v_mfma_f32_16x16x32_bf16 v[126:129], v[134:137], v[182:185], v[126:129]
	v_mfma_f32_16x16x32_bf16 v[62:65], v[142:145], v[182:185], v[62:65]
	v_mfma_f32_16x16x32_bf16 v[122:125], v[134:137], v[190:193], v[122:125]
	v_mfma_f32_16x16x32_bf16 v[58:61], v[142:145], v[190:193], v[58:61]
	v_mfma_f32_16x16x32_bf16 v[82:85], v[138:141], v[170:173], v[82:85]
	v_mfma_f32_16x16x32_bf16 v[10:13], v[146:149], v[170:173], v[10:13]
	v_mfma_f32_16x16x32_bf16 v[130:133], v[138:141], v[178:181], v[130:133]
	v_mfma_f32_16x16x32_bf16 v[66:69], v[146:149], v[178:181], v[66:69]
	v_mfma_f32_16x16x32_bf16 v[126:129], v[138:141], v[186:189], v[126:129]
	v_mfma_f32_16x16x32_bf16 v[62:65], v[146:149], v[186:189], v[62:65]
	v_mfma_f32_16x16x32_bf16 v[122:125], v[138:141], v[194:197], v[122:125]
	v_mfma_f32_16x16x32_bf16 v[58:61], v[146:149], v[194:197], v[58:61]
	v_mfma_f32_16x16x32_bf16 v[70:73], v[150:153], v[166:169], v[70:73]
	v_mfma_f32_16x16x32_bf16 v[4:7], v[158:161], v[166:169], v[6:9]
	v_mfma_f32_16x16x32_bf16 v[118:121], v[150:153], v[174:177], v[118:121]
	v_mfma_f32_16x16x32_bf16 v[54:57], v[158:161], v[174:177], v[54:57]
	v_mfma_f32_16x16x32_bf16 v[114:117], v[150:153], v[182:185], v[114:117]
	v_mfma_f32_16x16x32_bf16 v[50:53], v[158:161], v[182:185], v[50:53]
	v_mfma_f32_16x16x32_bf16 v[110:113], v[150:153], v[190:193], v[110:113]
	v_mfma_f32_16x16x32_bf16 v[46:49], v[158:161], v[190:193], v[46:49]
	v_mfma_f32_16x16x32_bf16 v[70:73], v[154:157], v[170:173], v[70:73]
	v_mfma_f32_16x16x32_bf16 v[4:7], v[162:165], v[170:173], v[4:7]
	v_mfma_f32_16x16x32_bf16 v[118:121], v[154:157], v[178:181], v[118:121]
	v_mfma_f32_16x16x32_bf16 v[54:57], v[162:165], v[178:181], v[54:57]
	v_mfma_f32_16x16x32_bf16 v[114:117], v[154:157], v[186:189], v[114:117]
	v_mfma_f32_16x16x32_bf16 v[50:53], v[162:165], v[186:189], v[50:53]
	v_mfma_f32_16x16x32_bf16 v[110:113], v[154:157], v[194:197], v[110:113]
	v_mfma_f32_16x16x32_bf16 v[46:49], v[162:165], v[194:197], v[46:49]
	s_setprio 0
	s_barrier
	ds_read_b128 v[166:169], v227 offset:16384
	ds_read_b128 v[170:173], v227 offset:17408
	ds_read_b128 v[174:177], v227 offset:18432
	ds_read_b128 v[178:181], v227 offset:19456
	ds_read_b128 v[182:185], v227 offset:20480
	ds_read_b128 v[186:189], v227 offset:21504
	ds_read_b128 v[190:193], v227 offset:22528
	ds_read_b128 v[194:197], v227 offset:23552
	s_waitcnt vmcnt(0)
	s_waitcnt lgkmcnt(0)
	s_setprio 1
	s_barrier
	v_mfma_f32_16x16x32_bf16 v[102:105], v[134:137], v[166:169], v[102:105]
	v_mfma_f32_16x16x32_bf16 v[30:33], v[142:145], v[166:169], v[30:33]
	v_mfma_f32_16x16x32_bf16 v[106:109], v[134:137], v[174:177], v[106:109]
	v_mfma_f32_16x16x32_bf16 v[42:45], v[142:145], v[174:177], v[42:45]
	v_mfma_f32_16x16x32_bf16 v[98:101], v[134:137], v[182:185], v[98:101]
	v_mfma_f32_16x16x32_bf16 v[38:41], v[142:145], v[182:185], v[38:41]
	v_mfma_f32_16x16x32_bf16 v[94:97], v[134:137], v[190:193], v[94:97]
	v_mfma_f32_16x16x32_bf16 v[34:37], v[142:145], v[190:193], v[34:37]
	v_mfma_f32_16x16x32_bf16 v[102:105], v[138:141], v[170:173], v[102:105]
	v_mfma_f32_16x16x32_bf16 v[30:33], v[146:149], v[170:173], v[30:33]
	v_mfma_f32_16x16x32_bf16 v[106:109], v[138:141], v[178:181], v[106:109]
	v_mfma_f32_16x16x32_bf16 v[42:45], v[146:149], v[178:181], v[42:45]
	v_mfma_f32_16x16x32_bf16 v[98:101], v[138:141], v[186:189], v[98:101]
	v_mfma_f32_16x16x32_bf16 v[38:41], v[146:149], v[186:189], v[38:41]
	v_mfma_f32_16x16x32_bf16 v[94:97], v[138:141], v[194:197], v[94:97]
	v_mfma_f32_16x16x32_bf16 v[34:37], v[146:149], v[194:197], v[34:37]
	v_mfma_f32_16x16x32_bf16 v[74:77], v[150:153], v[166:169], v[74:77]
	v_mfma_f32_16x16x32_bf16 v[14:17], v[158:161], v[166:169], v[14:17]
	v_mfma_f32_16x16x32_bf16 v[90:93], v[150:153], v[174:177], v[90:93]
	v_mfma_f32_16x16x32_bf16 v[26:29], v[158:161], v[174:177], v[26:29]
	v_mfma_f32_16x16x32_bf16 v[86:89], v[150:153], v[182:185], v[86:89]
	v_mfma_f32_16x16x32_bf16 v[22:25], v[158:161], v[182:185], v[22:25]
	v_mfma_f32_16x16x32_bf16 v[78:81], v[150:153], v[190:193], v[78:81]
	v_mfma_f32_16x16x32_bf16 v[18:21], v[158:161], v[190:193], v[18:21]
	v_mfma_f32_16x16x32_bf16 v[74:77], v[154:157], v[170:173], v[74:77]
	v_mfma_f32_16x16x32_bf16 v[14:17], v[162:165], v[170:173], v[14:17]
	v_mfma_f32_16x16x32_bf16 v[90:93], v[154:157], v[178:181], v[90:93]
	v_mfma_f32_16x16x32_bf16 v[26:29], v[162:165], v[178:181], v[26:29]
	v_mfma_f32_16x16x32_bf16 v[86:89], v[154:157], v[186:189], v[86:89]
	v_mfma_f32_16x16x32_bf16 v[22:25], v[162:165], v[186:189], v[22:25]
	v_mfma_f32_16x16x32_bf16 v[78:81], v[154:157], v[194:197], v[78:81]
	v_mfma_f32_16x16x32_bf16 v[18:21], v[162:165], v[194:197], v[18:21]
	s_setprio 0
	s_barrier
	v_add_u32_e32 v8, 0x18000, v2
	v_add_u32_e32 v2, 0x1c000, v2
	ds_read_b128 v[134:137], v8
	ds_read_b128 v[138:141], v8 offset:1024
	ds_read_b128 v[142:145], v8 offset:2048
	ds_read_b128 v[146:149], v8 offset:3072
	ds_read_b128 v[150:153], v2
	ds_read_b128 v[154:157], v2 offset:1024
	ds_read_b128 v[158:161], v2 offset:2048
	ds_read_b128 v[162:165], v2 offset:3072
	ds_read_b128 v[166:169], v227 offset:32768
	ds_read_b128 v[170:173], v227 offset:33792
	ds_read_b128 v[174:177], v227 offset:34816
	ds_read_b128 v[178:181], v227 offset:35840
	ds_read_b128 v[182:185], v227 offset:36864
	ds_read_b128 v[186:189], v227 offset:37888
	ds_read_b128 v[190:193], v227 offset:38912
	ds_read_b128 v[194:197], v227 offset:39936
	s_waitcnt lgkmcnt(0)
	s_setprio 1
	s_barrier
	v_mfma_f32_16x16x32_bf16 v[82:85], v[134:137], v[166:169], v[82:85]
	v_mfma_f32_16x16x32_bf16 v[8:11], v[142:145], v[166:169], v[10:13]
	v_mfma_f32_16x16x32_bf16 v[130:133], v[134:137], v[174:177], v[130:133]
	v_mfma_f32_16x16x32_bf16 v[66:69], v[142:145], v[174:177], v[66:69]
	v_mfma_f32_16x16x32_bf16 v[126:129], v[134:137], v[182:185], v[126:129]
	v_mfma_f32_16x16x32_bf16 v[62:65], v[142:145], v[182:185], v[62:65]
	v_mfma_f32_16x16x32_bf16 v[122:125], v[134:137], v[190:193], v[122:125]
	v_mfma_f32_16x16x32_bf16 v[58:61], v[142:145], v[190:193], v[58:61]
	v_mfma_f32_16x16x32_bf16 v[82:85], v[138:141], v[170:173], v[82:85]
	v_mfma_f32_16x16x32_bf16 v[10:13], v[146:149], v[170:173], v[8:11]
	v_mfma_f32_16x16x32_bf16 v[130:133], v[138:141], v[178:181], v[130:133]
	v_mfma_f32_16x16x32_bf16 v[66:69], v[146:149], v[178:181], v[66:69]
	v_mfma_f32_16x16x32_bf16 v[126:129], v[138:141], v[186:189], v[126:129]
	v_mfma_f32_16x16x32_bf16 v[62:65], v[146:149], v[186:189], v[62:65]
	v_mfma_f32_16x16x32_bf16 v[122:125], v[138:141], v[194:197], v[122:125]
	v_mfma_f32_16x16x32_bf16 v[58:61], v[146:149], v[194:197], v[58:61]
	v_mfma_f32_16x16x32_bf16 v[70:73], v[150:153], v[166:169], v[70:73]
	v_mfma_f32_16x16x32_bf16 v[4:7], v[158:161], v[166:169], v[4:7]
	v_mfma_f32_16x16x32_bf16 v[118:121], v[150:153], v[174:177], v[118:121]
	v_mfma_f32_16x16x32_bf16 v[54:57], v[158:161], v[174:177], v[54:57]
	v_mfma_f32_16x16x32_bf16 v[114:117], v[150:153], v[182:185], v[114:117]
	v_mfma_f32_16x16x32_bf16 v[50:53], v[158:161], v[182:185], v[50:53]
	v_mfma_f32_16x16x32_bf16 v[110:113], v[150:153], v[190:193], v[110:113]
	v_mfma_f32_16x16x32_bf16 v[46:49], v[158:161], v[190:193], v[46:49]
	v_mfma_f32_16x16x32_bf16 v[70:73], v[154:157], v[170:173], v[70:73]
	v_mfma_f32_16x16x32_bf16 v[6:9], v[162:165], v[170:173], v[4:7]
	v_mfma_f32_16x16x32_bf16 v[118:121], v[154:157], v[178:181], v[118:121]
	v_mfma_f32_16x16x32_bf16 v[54:57], v[162:165], v[178:181], v[54:57]
	v_mfma_f32_16x16x32_bf16 v[114:117], v[154:157], v[186:189], v[114:117]
	v_mfma_f32_16x16x32_bf16 v[50:53], v[162:165], v[186:189], v[50:53]
	v_mfma_f32_16x16x32_bf16 v[110:113], v[154:157], v[194:197], v[110:113]
	v_mfma_f32_16x16x32_bf16 v[46:49], v[162:165], v[194:197], v[46:49]
	s_setprio 0
	s_barrier
	ds_read_b128 v[166:169], v227 offset:49152
	ds_read_b128 v[170:173], v227 offset:50176
	ds_read_b128 v[174:177], v227 offset:51200
	ds_read_b128 v[178:181], v227 offset:52224
	ds_read_b128 v[182:185], v227 offset:53248
	ds_read_b128 v[186:189], v227 offset:54272
	ds_read_b128 v[190:193], v227 offset:55296
	ds_read_b128 v[194:197], v227 offset:56320
	s_waitcnt lgkmcnt(0)
	s_setprio 1
	s_barrier
	v_mfma_f32_16x16x32_bf16 v[102:105], v[134:137], v[166:169], v[102:105]
	v_mfma_f32_16x16x32_bf16 v[30:33], v[142:145], v[166:169], v[30:33]
	v_mfma_f32_16x16x32_bf16 v[106:109], v[134:137], v[174:177], v[106:109]
	v_mfma_f32_16x16x32_bf16 v[42:45], v[142:145], v[174:177], v[42:45]
	v_mfma_f32_16x16x32_bf16 v[98:101], v[134:137], v[182:185], v[98:101]
	v_mfma_f32_16x16x32_bf16 v[38:41], v[142:145], v[182:185], v[38:41]
	v_mfma_f32_16x16x32_bf16 v[94:97], v[134:137], v[190:193], v[94:97]
	v_mfma_f32_16x16x32_bf16 v[34:37], v[142:145], v[190:193], v[34:37]
	v_mfma_f32_16x16x32_bf16 v[102:105], v[138:141], v[170:173], v[102:105]
	v_mfma_f32_16x16x32_bf16 v[30:33], v[146:149], v[170:173], v[30:33]
	v_mfma_f32_16x16x32_bf16 v[106:109], v[138:141], v[178:181], v[106:109]
	v_mfma_f32_16x16x32_bf16 v[42:45], v[146:149], v[178:181], v[42:45]
	v_mfma_f32_16x16x32_bf16 v[98:101], v[138:141], v[186:189], v[98:101]
	v_mfma_f32_16x16x32_bf16 v[38:41], v[146:149], v[186:189], v[38:41]
	v_mfma_f32_16x16x32_bf16 v[94:97], v[138:141], v[194:197], v[94:97]
	v_mfma_f32_16x16x32_bf16 v[34:37], v[146:149], v[194:197], v[34:37]
	v_mfma_f32_16x16x32_bf16 v[74:77], v[150:153], v[166:169], v[74:77]
	v_mfma_f32_16x16x32_bf16 v[14:17], v[158:161], v[166:169], v[14:17]
	v_mfma_f32_16x16x32_bf16 v[90:93], v[150:153], v[174:177], v[90:93]
	v_mfma_f32_16x16x32_bf16 v[26:29], v[158:161], v[174:177], v[26:29]
	v_mfma_f32_16x16x32_bf16 v[86:89], v[150:153], v[182:185], v[86:89]
	v_mfma_f32_16x16x32_bf16 v[22:25], v[158:161], v[182:185], v[22:25]
	v_mfma_f32_16x16x32_bf16 v[78:81], v[150:153], v[190:193], v[78:81]
	v_mfma_f32_16x16x32_bf16 v[18:21], v[158:161], v[190:193], v[18:21]
	v_mfma_f32_16x16x32_bf16 v[74:77], v[154:157], v[170:173], v[74:77]
	v_mfma_f32_16x16x32_bf16 v[14:17], v[162:165], v[170:173], v[14:17]
	v_mfma_f32_16x16x32_bf16 v[90:93], v[154:157], v[178:181], v[90:93]
	v_mfma_f32_16x16x32_bf16 v[26:29], v[162:165], v[178:181], v[26:29]
	v_mfma_f32_16x16x32_bf16 v[86:89], v[154:157], v[186:189], v[86:89]
	v_mfma_f32_16x16x32_bf16 v[22:25], v[162:165], v[186:189], v[22:25]
	v_mfma_f32_16x16x32_bf16 v[78:81], v[154:157], v[194:197], v[78:81]
	v_mfma_f32_16x16x32_bf16 v[18:21], v[162:165], v[194:197], v[18:21]
	s_setprio 0
	s_barrier

.LBB0_1582:
	v_add_u32_e32 v11, s58, v152
	s_add_i32 s24, s24, 2
	ds_read_b128 v[156:159], v11
	ds_read_b128 v[160:163], v11 offset:1024
	ds_read_b128 v[164:167], v11 offset:2048
	ds_read_b128 v[168:171], v11 offset:3072
	v_add_u32_e32 v11, s59, v152
	s_add_u32 s25, s12, s38
	ds_read_b128 v[172:175], v11
	ds_read_b128 v[176:179], v11 offset:1024
	ds_read_b128 v[180:183], v11 offset:2048
	ds_read_b128 v[188:191], v11 offset:3072
	s_addc_u32 s40, s13, s39
	s_add_u32 s25, s25, 0x100
	s_addc_u32 s42, s40, 0
	s_add_u32 s40, s31, s38
	s_addc_u32 s41, s44, s39
	s_cmpk_eq_i32 s38, 0x1500
	s_cselect_b32 s41, s37, s41
	s_cselect_b32 s40, s36, s40
	s_cselect_b32 s43, s35, s42
	s_cselect_b32 s42, s34, s25
	v_lshl_add_u64 v[184:185], v[150:151], 0, s[38:39]
	s_add_i32 s64, s52, 0x8000
	v_lshl_add_u64 v[226:227], v[184:185], 0, s[20:21]
	s_mov_b32 m0, s64
	ds_read_b128 v[192:195], v154
	ds_read_b128 v[196:199], v154 offset:1024
	ds_read_b128 v[200:203], v154 offset:2048
	ds_read_b128 v[206:209], v154 offset:3072
	ds_read_b128 v[210:213], v154 offset:4096
	ds_read_b128 v[214:217], v154 offset:5120
	ds_read_b128 v[218:221], v154 offset:6144
	ds_read_b128 v[222:225], v154 offset:7168
	global_load_lds_dwordx4 v[226:227], off
	v_lshl_add_u64 v[226:227], v[12:13], 0, s[38:39]
	s_add_i32 s63, s52, 0xa000
	v_lshl_add_u64 v[228:229], v[226:227], 0, s[20:21]
	s_mov_b32 m0, s63
	s_add_i32 s25, s52, 0xc000
	global_load_lds_dwordx4 v[228:229], off
	v_lshl_add_u64 v[184:185], v[184:185], 0, s[22:23]
	s_mov_b32 m0, s25
	s_add_i32 s45, s52, 0xe000
	global_load_lds_dwordx4 v[184:185], off
	v_lshl_add_u64 v[184:185], v[226:227], 0, s[22:23]
	s_mov_b32 m0, s45
	s_nop 0
	global_load_lds_dwordx4 v[184:185], off
	s_waitcnt vmcnt(8)
	s_waitcnt lgkmcnt(0)
	s_setprio 1
	s_barrier
	v_mfma_f32_16x16x32_bf16 v[90:93], v[156:159], v[192:195], v[90:93]
	v_mfma_f32_16x16x32_bf16 v[94:97], v[164:167], v[192:195], v[94:97]
	v_mfma_f32_16x16x32_bf16 v[82:85], v[156:159], v[200:203], v[82:85]
	v_mfma_f32_16x16x32_bf16 v[86:89], v[164:167], v[200:203], v[86:89]
	v_mfma_f32_16x16x32_bf16 v[74:77], v[156:159], v[210:213], v[74:77]
	v_mfma_f32_16x16x32_bf16 v[78:81], v[164:167], v[210:213], v[78:81]
	v_mfma_f32_16x16x32_bf16 v[66:69], v[156:159], v[218:221], v[66:69]
	v_mfma_f32_16x16x32_bf16 v[70:73], v[164:167], v[218:221], v[70:73]
	v_mfma_f32_16x16x32_bf16 v[90:93], v[160:163], v[196:199], v[90:93]
	v_mfma_f32_16x16x32_bf16 v[94:97], v[168:171], v[196:199], v[94:97]
	v_mfma_f32_16x16x32_bf16 v[82:85], v[160:163], v[206:209], v[82:85]
	v_mfma_f32_16x16x32_bf16 v[86:89], v[168:171], v[206:209], v[86:89]
	v_mfma_f32_16x16x32_bf16 v[74:77], v[160:163], v[214:217], v[74:77]
	v_mfma_f32_16x16x32_bf16 v[78:81], v[168:171], v[214:217], v[78:81]
	v_mfma_f32_16x16x32_bf16 v[66:69], v[160:163], v[222:225], v[66:69]
	v_mfma_f32_16x16x32_bf16 v[70:73], v[168:171], v[222:225], v[70:73]
	v_mfma_f32_16x16x32_bf16 v[26:29], v[172:175], v[192:195], v[26:29]
	v_mfma_f32_16x16x32_bf16 v[30:33], v[180:183], v[192:195], v[30:33]
	v_mfma_f32_16x16x32_bf16 v[18:21], v[172:175], v[200:203], v[18:21]
	v_mfma_f32_16x16x32_bf16 v[22:25], v[180:183], v[200:203], v[22:25]
	v_mfma_f32_16x16x32_bf16 v[130:133], v[172:175], v[210:213], v[130:133]
	v_mfma_f32_16x16x32_bf16 v[14:17], v[180:183], v[210:213], v[14:17]
	v_mfma_f32_16x16x32_bf16 v[2:5], v[172:175], v[218:221], v[2:5]
	v_mfma_f32_16x16x32_bf16 v[6:9], v[180:183], v[218:221], v[6:9]
	v_mfma_f32_16x16x32_bf16 v[26:29], v[176:179], v[196:199], v[26:29]
	v_mfma_f32_16x16x32_bf16 v[30:33], v[188:191], v[196:199], v[30:33]
	v_mfma_f32_16x16x32_bf16 v[18:21], v[176:179], v[206:209], v[18:21]
	v_mfma_f32_16x16x32_bf16 v[22:25], v[188:191], v[206:209], v[22:25]
	v_mfma_f32_16x16x32_bf16 v[130:133], v[176:179], v[214:217], v[130:133]
	v_mfma_f32_16x16x32_bf16 v[14:17], v[188:191], v[214:217], v[14:17]
	v_mfma_f32_16x16x32_bf16 v[2:5], v[176:179], v[222:225], v[2:5]
	v_mfma_f32_16x16x32_bf16 v[6:9], v[188:191], v[222:225], v[6:9]
	s_setprio 0
	s_barrier
	s_add_i32 s65, s58, s51
	v_lshl_add_u64 v[184:185], s[40:41], 0, v[136:137]
	s_mov_b32 m0, s65
	ds_read_b128 v[192:195], v154 offset:16384
	ds_read_b128 v[196:199], v154 offset:17408
	ds_read_b128 v[200:203], v154 offset:18432
	ds_read_b128 v[206:209], v154 offset:19456
	ds_read_b128 v[210:213], v154 offset:20480
	ds_read_b128 v[214:217], v154 offset:21504
	ds_read_b128 v[218:221], v154 offset:22528
	ds_read_b128 v[222:225], v154 offset:23552
	global_load_lds_dwordx4 v[184:185], off
	s_add_i32 m0, s65, 0x2000
	s_add_u32 s66, s40, 0xb0000
	v_lshl_add_u64 v[226:227], s[40:41], 0, v[140:141]
	s_addc_u32 s67, s41, 0
	s_add_i32 s65, s59, s51
	global_load_lds_dwordx4 v[226:227], off
	v_lshl_add_u64 v[228:229], s[66:67], 0, v[136:137]
	s_mov_b32 m0, s65
	s_nop 0
	global_load_lds_dwordx4 v[228:229], off
	v_lshl_add_u64 v[228:229], s[66:67], 0, v[140:141]
	s_add_i32 m0, s65, 0x2000
	s_nop 0
	global_load_lds_dwordx4 v[228:229], off
	s_waitcnt vmcnt(4)
	s_waitcnt lgkmcnt(0)
	s_setprio 1
	s_barrier
	v_mfma_f32_16x16x32_bf16 v[122:125], v[156:159], v[192:195], v[122:125]
	v_mfma_f32_16x16x32_bf16 v[126:129], v[164:167], v[192:195], v[126:129]
	v_mfma_f32_16x16x32_bf16 v[114:117], v[156:159], v[200:203], v[114:117]
	v_mfma_f32_16x16x32_bf16 v[118:121], v[164:167], v[200:203], v[118:121]
	v_mfma_f32_16x16x32_bf16 v[106:109], v[156:159], v[210:213], v[106:109]
	v_mfma_f32_16x16x32_bf16 v[110:113], v[164:167], v[210:213], v[110:113]
	v_mfma_f32_16x16x32_bf16 v[98:101], v[156:159], v[218:221], v[98:101]
	v_mfma_f32_16x16x32_bf16 v[102:105], v[164:167], v[218:221], v[102:105]
	v_mfma_f32_16x16x32_bf16 v[122:125], v[160:163], v[196:199], v[122:125]
	v_mfma_f32_16x16x32_bf16 v[126:129], v[168:171], v[196:199], v[126:129]
	v_mfma_f32_16x16x32_bf16 v[114:117], v[160:163], v[206:209], v[114:117]
	v_mfma_f32_16x16x32_bf16 v[118:121], v[168:171], v[206:209], v[118:121]
	v_mfma_f32_16x16x32_bf16 v[106:109], v[160:163], v[214:217], v[106:109]
	v_mfma_f32_16x16x32_bf16 v[110:113], v[168:171], v[214:217], v[110:113]
	v_mfma_f32_16x16x32_bf16 v[98:101], v[160:163], v[222:225], v[98:101]
	v_mfma_f32_16x16x32_bf16 v[102:105], v[168:171], v[222:225], v[102:105]
	v_mfma_f32_16x16x32_bf16 v[58:61], v[172:175], v[192:195], v[58:61]
	v_mfma_f32_16x16x32_bf16 v[62:65], v[180:183], v[192:195], v[62:65]
	v_mfma_f32_16x16x32_bf16 v[50:53], v[172:175], v[200:203], v[50:53]
	v_mfma_f32_16x16x32_bf16 v[54:57], v[180:183], v[200:203], v[54:57]
	v_mfma_f32_16x16x32_bf16 v[42:45], v[172:175], v[210:213], v[42:45]
	v_mfma_f32_16x16x32_bf16 v[46:49], v[180:183], v[210:213], v[46:49]
	v_mfma_f32_16x16x32_bf16 v[38:41], v[172:175], v[218:221], v[38:41]
	v_mfma_f32_16x16x32_bf16 v[34:37], v[180:183], v[218:221], v[34:37]
	v_mfma_f32_16x16x32_bf16 v[58:61], v[176:179], v[196:199], v[58:61]
	v_mfma_f32_16x16x32_bf16 v[62:65], v[188:191], v[196:199], v[62:65]
	v_mfma_f32_16x16x32_bf16 v[50:53], v[176:179], v[206:209], v[50:53]
	v_mfma_f32_16x16x32_bf16 v[54:57], v[188:191], v[206:209], v[54:57]
	v_mfma_f32_16x16x32_bf16 v[42:45], v[176:179], v[214:217], v[42:45]
	v_mfma_f32_16x16x32_bf16 v[46:49], v[188:191], v[214:217], v[46:49]
	v_mfma_f32_16x16x32_bf16 v[38:41], v[176:179], v[222:225], v[38:41]
	v_mfma_f32_16x16x32_bf16 v[34:37], v[188:191], v[222:225], v[34:37]
	s_setprio 0
	s_barrier
	s_add_i32 s65, 0, 0x18000
	v_add_u32_e32 v11, s65, v152
	s_add_i32 s66, 0, 0x1c000
	ds_read_b128 v[156:159], v11
	ds_read_b128 v[160:163], v11 offset:1024
	ds_read_b128 v[164:167], v11 offset:2048
	ds_read_b128 v[168:171], v11 offset:3072
	v_add_u32_e32 v11, s66, v152
	ds_read_b128 v[172:175], v11
	ds_read_b128 v[176:179], v11 offset:1024
	ds_read_b128 v[180:183], v11 offset:2048
	ds_read_b128 v[188:191], v11 offset:3072
	s_mov_b32 m0, s52
	v_lshl_add_u64 v[228:229], s[42:43], 0, v[134:135]
	ds_read_b128 v[192:195], v154 offset:32768
	ds_read_b128 v[196:199], v154 offset:33792
	ds_read_b128 v[200:203], v154 offset:34816
	ds_read_b128 v[206:209], v154 offset:35840
	ds_read_b128 v[210:213], v154 offset:36864
	ds_read_b128 v[214:217], v154 offset:37888
	ds_read_b128 v[218:221], v154 offset:38912
	ds_read_b128 v[222:225], v154 offset:39936
	global_load_lds_dwordx4 v[228:229], off
	v_lshl_add_u64 v[228:229], s[42:43], 0, v[138:139]
	s_add_u32 s42, s42, 0xb0000
	s_mov_b32 m0, s53
	s_addc_u32 s43, s43, 0
	global_load_lds_dwordx4 v[228:229], off
	v_lshl_add_u64 v[228:229], s[42:43], 0, v[134:135]
	s_mov_b32 m0, s54
	s_nop 0
	global_load_lds_dwordx4 v[228:229], off
	v_lshl_add_u64 v[228:229], s[42:43], 0, v[138:139]
	s_mov_b32 m0, s55
	s_nop 0
	global_load_lds_dwordx4 v[228:229], off
	s_waitcnt vmcnt(8)
	s_waitcnt lgkmcnt(0)
	s_setprio 1
	s_barrier
	v_mfma_f32_16x16x32_bf16 v[90:93], v[156:159], v[192:195], v[90:93]
	v_mfma_f32_16x16x32_bf16 v[94:97], v[164:167], v[192:195], v[94:97]
	v_mfma_f32_16x16x32_bf16 v[82:85], v[156:159], v[200:203], v[82:85]
	v_mfma_f32_16x16x32_bf16 v[86:89], v[164:167], v[200:203], v[86:89]
	v_mfma_f32_16x16x32_bf16 v[74:77], v[156:159], v[210:213], v[74:77]
	v_mfma_f32_16x16x32_bf16 v[78:81], v[164:167], v[210:213], v[78:81]
	v_mfma_f32_16x16x32_bf16 v[66:69], v[156:159], v[218:221], v[66:69]
	v_mfma_f32_16x16x32_bf16 v[70:73], v[164:167], v[218:221], v[70:73]
	v_mfma_f32_16x16x32_bf16 v[90:93], v[160:163], v[196:199], v[90:93]
	v_mfma_f32_16x16x32_bf16 v[94:97], v[168:171], v[196:199], v[94:97]
	v_mfma_f32_16x16x32_bf16 v[82:85], v[160:163], v[206:209], v[82:85]
	v_mfma_f32_16x16x32_bf16 v[86:89], v[168:171], v[206:209], v[86:89]
	v_mfma_f32_16x16x32_bf16 v[74:77], v[160:163], v[214:217], v[74:77]
	v_mfma_f32_16x16x32_bf16 v[78:81], v[168:171], v[214:217], v[78:81]
	v_mfma_f32_16x16x32_bf16 v[66:69], v[160:163], v[222:225], v[66:69]
	v_mfma_f32_16x16x32_bf16 v[70:73], v[168:171], v[222:225], v[70:73]
	v_mfma_f32_16x16x32_bf16 v[26:29], v[172:175], v[192:195], v[26:29]
	v_mfma_f32_16x16x32_bf16 v[30:33], v[180:183], v[192:195], v[30:33]
	v_mfma_f32_16x16x32_bf16 v[18:21], v[172:175], v[200:203], v[18:21]
	v_mfma_f32_16x16x32_bf16 v[22:25], v[180:183], v[200:203], v[22:25]
	v_mfma_f32_16x16x32_bf16 v[130:133], v[172:175], v[210:213], v[130:133]
	v_mfma_f32_16x16x32_bf16 v[14:17], v[180:183], v[210:213], v[14:17]
	v_mfma_f32_16x16x32_bf16 v[2:5], v[172:175], v[218:221], v[2:5]
	v_mfma_f32_16x16x32_bf16 v[6:9], v[180:183], v[218:221], v[6:9]
	v_mfma_f32_16x16x32_bf16 v[26:29], v[176:179], v[196:199], v[26:29]
	v_mfma_f32_16x16x32_bf16 v[30:33], v[188:191], v[196:199], v[30:33]
	v_mfma_f32_16x16x32_bf16 v[18:21], v[176:179], v[206:209], v[18:21]
	v_mfma_f32_16x16x32_bf16 v[22:25], v[188:191], v[206:209], v[22:25]
	v_mfma_f32_16x16x32_bf16 v[130:133], v[176:179], v[214:217], v[130:133]
	v_mfma_f32_16x16x32_bf16 v[14:17], v[188:191], v[214:217], v[14:17]
	v_mfma_f32_16x16x32_bf16 v[2:5], v[176:179], v[222:225], v[2:5]
	v_mfma_f32_16x16x32_bf16 v[6:9], v[188:191], v[222:225], v[6:9]
	s_setprio 0
	s_barrier
	s_add_i32 s42, s65, s51
	v_lshl_add_u64 v[184:185], v[184:185], 0, s[20:21]
	s_mov_b32 m0, s42
	ds_read_b128 v[192:195], v154 offset:49152
	ds_read_b128 v[196:199], v154 offset:50176
	ds_read_b128 v[200:203], v154 offset:51200
	ds_read_b128 v[206:209], v154 offset:52224
	ds_read_b128 v[210:213], v154 offset:53248
	ds_read_b128 v[214:217], v154 offset:54272
	ds_read_b128 v[218:221], v154 offset:55296
	ds_read_b128 v[222:225], v154 offset:56320
	global_load_lds_dwordx4 v[184:185], off
	s_add_i32 m0, s42, 0x2000
	s_add_u32 s40, s40, 0xb0080
	v_lshl_add_u64 v[184:185], v[226:227], 0, s[20:21]
	s_addc_u32 s41, s41, 0
	s_add_i32 s42, s66, s51
	global_load_lds_dwordx4 v[184:185], off
	v_lshl_add_u64 v[184:185], s[40:41], 0, v[136:137]
	s_mov_b32 m0, s42
	s_nop 0
	global_load_lds_dwordx4 v[184:185], off
	v_lshl_add_u64 v[184:185], s[40:41], 0, v[140:141]
	s_add_i32 m0, s42, 0x2000
	s_nop 0
	global_load_lds_dwordx4 v[184:185], off
	s_waitcnt vmcnt(4)
	s_waitcnt lgkmcnt(0)
	s_setprio 1
	s_barrier
	v_mfma_f32_16x16x32_bf16 v[122:125], v[156:159], v[192:195], v[122:125]
	v_mfma_f32_16x16x32_bf16 v[126:129], v[164:167], v[192:195], v[126:129]
	v_mfma_f32_16x16x32_bf16 v[114:117], v[156:159], v[200:203], v[114:117]
	v_mfma_f32_16x16x32_bf16 v[118:121], v[164:167], v[200:203], v[118:121]
	v_mfma_f32_16x16x32_bf16 v[106:109], v[156:159], v[210:213], v[106:109]
	v_mfma_f32_16x16x32_bf16 v[110:113], v[164:167], v[210:213], v[110:113]
	v_mfma_f32_16x16x32_bf16 v[98:101], v[156:159], v[218:221], v[98:101]
	v_mfma_f32_16x16x32_bf16 v[102:105], v[164:167], v[218:221], v[102:105]
	v_mfma_f32_16x16x32_bf16 v[122:125], v[160:163], v[196:199], v[122:125]
	v_mfma_f32_16x16x32_bf16 v[126:129], v[168:171], v[196:199], v[126:129]
	v_mfma_f32_16x16x32_bf16 v[114:117], v[160:163], v[206:209], v[114:117]
	v_mfma_f32_16x16x32_bf16 v[118:121], v[168:171], v[206:209], v[118:121]
	v_mfma_f32_16x16x32_bf16 v[106:109], v[160:163], v[214:217], v[106:109]
	v_mfma_f32_16x16x32_bf16 v[110:113], v[168:171], v[214:217], v[110:113]
	v_mfma_f32_16x16x32_bf16 v[98:101], v[160:163], v[222:225], v[98:101]
	v_mfma_f32_16x16x32_bf16 v[102:105], v[168:171], v[222:225], v[102:105]
	v_mfma_f32_16x16x32_bf16 v[58:61], v[172:175], v[192:195], v[58:61]
	v_mfma_f32_16x16x32_bf16 v[62:65], v[180:183], v[192:195], v[62:65]
	v_mfma_f32_16x16x32_bf16 v[50:53], v[172:175], v[200:203], v[50:53]
	v_mfma_f32_16x16x32_bf16 v[54:57], v[180:183], v[200:203], v[54:57]
	v_mfma_f32_16x16x32_bf16 v[42:45], v[172:175], v[210:213], v[42:45]
	v_mfma_f32_16x16x32_bf16 v[46:49], v[180:183], v[210:213], v[46:49]
	v_mfma_f32_16x16x32_bf16 v[38:41], v[172:175], v[218:221], v[38:41]
	v_mfma_f32_16x16x32_bf16 v[34:37], v[180:183], v[218:221], v[34:37]
	v_mfma_f32_16x16x32_bf16 v[58:61], v[176:179], v[196:199], v[58:61]
	v_mfma_f32_16x16x32_bf16 v[62:65], v[188:191], v[196:199], v[62:65]
	v_mfma_f32_16x16x32_bf16 v[50:53], v[176:179], v[206:209], v[50:53]
	v_mfma_f32_16x16x32_bf16 v[54:57], v[188:191], v[206:209], v[54:57]
	v_mfma_f32_16x16x32_bf16 v[42:45], v[176:179], v[214:217], v[42:45]
	v_mfma_f32_16x16x32_bf16 v[46:49], v[188:191], v[214:217], v[46:49]
	v_mfma_f32_16x16x32_bf16 v[38:41], v[176:179], v[222:225], v[38:41]
	v_mfma_f32_16x16x32_bf16 v[34:37], v[188:191], v[222:225], v[34:37]
	s_setprio 0
	s_barrier
	s_add_u32 s38, s38, 0x100
	s_addc_u32 s39, s39, 0
	s_cmp_ge_u32 s24, s3
	s_cbranch_scc0 .LBB0_1582
	s_and_b64 vcc, exec, s[0:1]
	s_cbranch_vccz .LBB0_1586
	v_add_u32_e32 v11, 0, v152
	v_add_u32_e32 v12, 0x10000, v11
	ds_read_b128 v[156:159], v12
	ds_read_b128 v[160:163], v12 offset:1024
	ds_read_b128 v[164:167], v12 offset:2048
	ds_read_b128 v[168:171], v12 offset:3072
	v_add_u32_e32 v12, 0x14000, v11
	ds_read_b128 v[172:175], v12
	ds_read_b128 v[176:179], v12 offset:1024
	ds_read_b128 v[180:183], v12 offset:2048
	ds_read_b128 v[188:191], v12 offset:3072
	s_add_u32 s38, s12, 0x1580
	s_addc_u32 s39, s13, 0
	s_mov_b32 m0, s64
	v_lshl_add_u64 v[12:13], s[38:39], 0, v[134:135]
	ds_read_b128 v[192:195], v154
	ds_read_b128 v[196:199], v154 offset:1024
	ds_read_b128 v[200:203], v154 offset:2048
	ds_read_b128 v[206:209], v154 offset:3072
	ds_read_b128 v[210:213], v154 offset:4096
	ds_read_b128 v[214:217], v154 offset:5120
	ds_read_b128 v[218:221], v154 offset:6144
	ds_read_b128 v[222:225], v154 offset:7168
	global_load_lds_dwordx4 v[12:13], off
	v_lshl_add_u64 v[12:13], s[38:39], 0, v[138:139]
	s_add_u32 s38, s12, 0xb1580
	s_mov_b32 m0, s63
	s_addc_u32 s39, s13, 0
	global_load_lds_dwordx4 v[12:13], off
	v_lshl_add_u64 v[12:13], s[38:39], 0, v[134:135]
	s_mov_b32 m0, s25
	s_nop 0
	global_load_lds_dwordx4 v[12:13], off
	v_lshl_add_u64 v[12:13], s[38:39], 0, v[138:139]
	s_mov_b32 m0, s45
	s_nop 0
	global_load_lds_dwordx4 v[12:13], off
	s_waitcnt vmcnt(8)
	s_waitcnt lgkmcnt(0)
	s_setprio 1
	s_barrier
	v_mfma_f32_16x16x32_bf16 v[90:93], v[156:159], v[192:195], v[90:93]
	v_mfma_f32_16x16x32_bf16 v[94:97], v[164:167], v[192:195], v[94:97]
	v_mfma_f32_16x16x32_bf16 v[82:85], v[156:159], v[200:203], v[82:85]
	v_mfma_f32_16x16x32_bf16 v[86:89], v[164:167], v[200:203], v[86:89]
	v_mfma_f32_16x16x32_bf16 v[74:77], v[156:159], v[210:213], v[74:77]
	v_mfma_f32_16x16x32_bf16 v[78:81], v[164:167], v[210:213], v[78:81]
	v_mfma_f32_16x16x32_bf16 v[66:69], v[156:159], v[218:221], v[66:69]
	v_mfma_f32_16x16x32_bf16 v[70:73], v[164:167], v[218:221], v[70:73]
	v_mfma_f32_16x16x32_bf16 v[90:93], v[160:163], v[196:199], v[90:93]
	v_mfma_f32_16x16x32_bf16 v[94:97], v[168:171], v[196:199], v[94:97]
	v_mfma_f32_16x16x32_bf16 v[82:85], v[160:163], v[206:209], v[82:85]
	v_mfma_f32_16x16x32_bf16 v[86:89], v[168:171], v[206:209], v[86:89]
	v_mfma_f32_16x16x32_bf16 v[74:77], v[160:163], v[214:217], v[74:77]
	v_mfma_f32_16x16x32_bf16 v[78:81], v[168:171], v[214:217], v[78:81]
	v_mfma_f32_16x16x32_bf16 v[66:69], v[160:163], v[222:225], v[66:69]
	v_mfma_f32_16x16x32_bf16 v[70:73], v[168:171], v[222:225], v[70:73]
	v_mfma_f32_16x16x32_bf16 v[26:29], v[172:175], v[192:195], v[26:29]
	v_mfma_f32_16x16x32_bf16 v[30:33], v[180:183], v[192:195], v[30:33]
	v_mfma_f32_16x16x32_bf16 v[18:21], v[172:175], v[200:203], v[18:21]
	v_mfma_f32_16x16x32_bf16 v[22:25], v[180:183], v[200:203], v[22:25]
	v_mfma_f32_16x16x32_bf16 v[130:133], v[172:175], v[210:213], v[130:133]
	v_mfma_f32_16x16x32_bf16 v[12:15], v[180:183], v[210:213], v[14:17]
	v_mfma_f32_16x16x32_bf16 v[2:5], v[172:175], v[218:221], v[2:5]
	v_mfma_f32_16x16x32_bf16 v[6:9], v[180:183], v[218:221], v[6:9]
	v_mfma_f32_16x16x32_bf16 v[26:29], v[176:179], v[196:199], v[26:29]
	v_mfma_f32_16x16x32_bf16 v[30:33], v[188:191], v[196:199], v[30:33]
	v_mfma_f32_16x16x32_bf16 v[18:21], v[176:179], v[206:209], v[18:21]
	v_mfma_f32_16x16x32_bf16 v[22:25], v[188:191], v[206:209], v[22:25]
	v_mfma_f32_16x16x32_bf16 v[130:133], v[176:179], v[214:217], v[130:133]
	v_mfma_f32_16x16x32_bf16 v[12:15], v[188:191], v[214:217], v[12:15]
	v_mfma_f32_16x16x32_bf16 v[2:5], v[176:179], v[222:225], v[2:5]
	v_mfma_f32_16x16x32_bf16 v[6:9], v[188:191], v[222:225], v[6:9]
	s_setprio 0
	s_barrier
	ds_read_b128 v[192:195], v154 offset:16384
	ds_read_b128 v[196:199], v154 offset:17408
	ds_read_b128 v[200:203], v154 offset:18432
	ds_read_b128 v[206:209], v154 offset:19456
	ds_read_b128 v[210:213], v154 offset:20480
	ds_read_b128 v[214:217], v154 offset:21504
	ds_read_b128 v[218:221], v154 offset:22528
	ds_read_b128 v[222:225], v154 offset:23552
	s_waitcnt vmcnt(0)
	s_waitcnt lgkmcnt(0)
	s_setprio 1
	s_barrier
	v_mfma_f32_16x16x32_bf16 v[122:125], v[156:159], v[192:195], v[122:125]
	v_mfma_f32_16x16x32_bf16 v[126:129], v[164:167], v[192:195], v[126:129]
	v_mfma_f32_16x16x32_bf16 v[114:117], v[156:159], v[200:203], v[114:117]
	v_mfma_f32_16x16x32_bf16 v[118:121], v[164:167], v[200:203], v[118:121]
	v_mfma_f32_16x16x32_bf16 v[106:109], v[156:159], v[210:213], v[106:109]
	v_mfma_f32_16x16x32_bf16 v[110:113], v[164:167], v[210:213], v[110:113]
	v_mfma_f32_16x16x32_bf16 v[98:101], v[156:159], v[218:221], v[98:101]
	v_mfma_f32_16x16x32_bf16 v[102:105], v[164:167], v[218:221], v[102:105]
	v_mfma_f32_16x16x32_bf16 v[122:125], v[160:163], v[196:199], v[122:125]
	v_mfma_f32_16x16x32_bf16 v[126:129], v[168:171], v[196:199], v[126:129]
	v_mfma_f32_16x16x32_bf16 v[114:117], v[160:163], v[206:209], v[114:117]
	v_mfma_f32_16x16x32_bf16 v[118:121], v[168:171], v[206:209], v[118:121]
	v_mfma_f32_16x16x32_bf16 v[106:109], v[160:163], v[214:217], v[106:109]
	v_mfma_f32_16x16x32_bf16 v[110:113], v[168:171], v[214:217], v[110:113]
	v_mfma_f32_16x16x32_bf16 v[98:101], v[160:163], v[222:225], v[98:101]
	v_mfma_f32_16x16x32_bf16 v[102:105], v[168:171], v[222:225], v[102:105]
	v_mfma_f32_16x16x32_bf16 v[58:61], v[172:175], v[192:195], v[58:61]
	v_mfma_f32_16x16x32_bf16 v[62:65], v[180:183], v[192:195], v[62:65]
	v_mfma_f32_16x16x32_bf16 v[50:53], v[172:175], v[200:203], v[50:53]
	v_mfma_f32_16x16x32_bf16 v[54:57], v[180:183], v[200:203], v[54:57]
	v_mfma_f32_16x16x32_bf16 v[42:45], v[172:175], v[210:213], v[42:45]
	v_mfma_f32_16x16x32_bf16 v[46:49], v[180:183], v[210:213], v[46:49]
	v_mfma_f32_16x16x32_bf16 v[38:41], v[172:175], v[218:221], v[38:41]
	v_mfma_f32_16x16x32_bf16 v[34:37], v[180:183], v[218:221], v[34:37]
	v_mfma_f32_16x16x32_bf16 v[58:61], v[176:179], v[196:199], v[58:61]
	v_mfma_f32_16x16x32_bf16 v[62:65], v[188:191], v[196:199], v[62:65]
	v_mfma_f32_16x16x32_bf16 v[50:53], v[176:179], v[206:209], v[50:53]
	v_mfma_f32_16x16x32_bf16 v[54:57], v[188:191], v[206:209], v[54:57]
	v_mfma_f32_16x16x32_bf16 v[42:45], v[176:179], v[214:217], v[42:45]
	v_mfma_f32_16x16x32_bf16 v[46:49], v[188:191], v[214:217], v[46:49]
	v_mfma_f32_16x16x32_bf16 v[38:41], v[176:179], v[222:225], v[38:41]
	v_mfma_f32_16x16x32_bf16 v[34:37], v[188:191], v[222:225], v[34:37]
	s_setprio 0
	s_barrier
	v_add_u32_e32 v16, 0x18000, v11
	v_add_u32_e32 v11, 0x1c000, v11
	ds_read_b128 v[156:159], v16
	ds_read_b128 v[160:163], v16 offset:1024
	ds_read_b128 v[164:167], v16 offset:2048
	ds_read_b128 v[168:171], v16 offset:3072
	ds_read_b128 v[172:175], v11
	ds_read_b128 v[176:179], v11 offset:1024
	ds_read_b128 v[180:183], v11 offset:2048
	ds_read_b128 v[188:191], v11 offset:3072
	ds_read_b128 v[192:195], v154 offset:32768
	ds_read_b128 v[196:199], v154 offset:33792
	ds_read_b128 v[200:203], v154 offset:34816
	ds_read_b128 v[206:209], v154 offset:35840
	ds_read_b128 v[210:213], v154 offset:36864
	ds_read_b128 v[214:217], v154 offset:37888
	ds_read_b128 v[218:221], v154 offset:38912
	ds_read_b128 v[222:225], v154 offset:39936
	s_waitcnt lgkmcnt(0)
	s_setprio 1
	s_barrier
	v_mfma_f32_16x16x32_bf16 v[90:93], v[156:159], v[192:195], v[90:93]
	v_mfma_f32_16x16x32_bf16 v[94:97], v[164:167], v[192:195], v[94:97]
	v_mfma_f32_16x16x32_bf16 v[82:85], v[156:159], v[200:203], v[82:85]
	v_mfma_f32_16x16x32_bf16 v[86:89], v[164:167], v[200:203], v[86:89]
	v_mfma_f32_16x16x32_bf16 v[74:77], v[156:159], v[210:213], v[74:77]
	v_mfma_f32_16x16x32_bf16 v[78:81], v[164:167], v[210:213], v[78:81]
	v_mfma_f32_16x16x32_bf16 v[66:69], v[156:159], v[218:221], v[66:69]
	v_mfma_f32_16x16x32_bf16 v[70:73], v[164:167], v[218:221], v[70:73]
	v_mfma_f32_16x16x32_bf16 v[90:93], v[160:163], v[196:199], v[90:93]
	v_mfma_f32_16x16x32_bf16 v[94:97], v[168:171], v[196:199], v[94:97]
	v_mfma_f32_16x16x32_bf16 v[82:85], v[160:163], v[206:209], v[82:85]
	v_mfma_f32_16x16x32_bf16 v[86:89], v[168:171], v[206:209], v[86:89]
	v_mfma_f32_16x16x32_bf16 v[74:77], v[160:163], v[214:217], v[74:77]
	v_mfma_f32_16x16x32_bf16 v[78:81], v[168:171], v[214:217], v[78:81]
	v_mfma_f32_16x16x32_bf16 v[66:69], v[160:163], v[222:225], v[66:69]
	v_mfma_f32_16x16x32_bf16 v[70:73], v[168:171], v[222:225], v[70:73]
	v_mfma_f32_16x16x32_bf16 v[26:29], v[172:175], v[192:195], v[26:29]
	v_mfma_f32_16x16x32_bf16 v[30:33], v[180:183], v[192:195], v[30:33]
	v_mfma_f32_16x16x32_bf16 v[16:19], v[172:175], v[200:203], v[18:21]
	v_mfma_f32_16x16x32_bf16 v[22:25], v[180:183], v[200:203], v[22:25]
	v_mfma_f32_16x16x32_bf16 v[130:133], v[172:175], v[210:213], v[130:133]
	v_mfma_f32_16x16x32_bf16 v[12:15], v[180:183], v[210:213], v[12:15]
	v_mfma_f32_16x16x32_bf16 v[2:5], v[172:175], v[218:221], v[2:5]
	v_mfma_f32_16x16x32_bf16 v[6:9], v[180:183], v[218:221], v[6:9]
	v_mfma_f32_16x16x32_bf16 v[26:29], v[176:179], v[196:199], v[26:29]
	v_mfma_f32_16x16x32_bf16 v[30:33], v[188:191], v[196:199], v[30:33]
	v_mfma_f32_16x16x32_bf16 v[18:21], v[176:179], v[206:209], v[16:19]
	v_mfma_f32_16x16x32_bf16 v[22:25], v[188:191], v[206:209], v[22:25]
	v_mfma_f32_16x16x32_bf16 v[130:133], v[176:179], v[214:217], v[130:133]
	v_mfma_f32_16x16x32_bf16 v[14:17], v[188:191], v[214:217], v[12:15]
	v_mfma_f32_16x16x32_bf16 v[2:5], v[176:179], v[222:225], v[2:5]
	v_mfma_f32_16x16x32_bf16 v[6:9], v[188:191], v[222:225], v[6:9]
	s_setprio 0
	s_barrier
	ds_read_b128 v[192:195], v154 offset:49152
	ds_read_b128 v[196:199], v154 offset:50176
	ds_read_b128 v[200:203], v154 offset:51200
	ds_read_b128 v[206:209], v154 offset:52224
	ds_read_b128 v[210:213], v154 offset:53248
	ds_read_b128 v[214:217], v154 offset:54272
	ds_read_b128 v[218:221], v154 offset:55296
	ds_read_b128 v[222:225], v154 offset:56320
	s_waitcnt lgkmcnt(0)
	s_setprio 1
	s_barrier
	v_mfma_f32_16x16x32_bf16 v[122:125], v[156:159], v[192:195], v[122:125]
	v_mfma_f32_16x16x32_bf16 v[126:129], v[164:167], v[192:195], v[126:129]
	v_mfma_f32_16x16x32_bf16 v[114:117], v[156:159], v[200:203], v[114:117]
	v_mfma_f32_16x16x32_bf16 v[118:121], v[164:167], v[200:203], v[118:121]
	v_mfma_f32_16x16x32_bf16 v[106:109], v[156:159], v[210:213], v[106:109]
	v_mfma_f32_16x16x32_bf16 v[110:113], v[164:167], v[210:213], v[110:113]
	v_mfma_f32_16x16x32_bf16 v[98:101], v[156:159], v[218:221], v[98:101]
	v_mfma_f32_16x16x32_bf16 v[102:105], v[164:167], v[218:221], v[102:105]
	v_mfma_f32_16x16x32_bf16 v[122:125], v[160:163], v[196:199], v[122:125]
	v_mfma_f32_16x16x32_bf16 v[126:129], v[168:171], v[196:199], v[126:129]
	v_mfma_f32_16x16x32_bf16 v[114:117], v[160:163], v[206:209], v[114:117]
	v_mfma_f32_16x16x32_bf16 v[118:121], v[168:171], v[206:209], v[118:121]
	v_mfma_f32_16x16x32_bf16 v[106:109], v[160:163], v[214:217], v[106:109]
	v_mfma_f32_16x16x32_bf16 v[110:113], v[168:171], v[214:217], v[110:113]
	v_mfma_f32_16x16x32_bf16 v[98:101], v[160:163], v[222:225], v[98:101]
	v_mfma_f32_16x16x32_bf16 v[102:105], v[168:171], v[222:225], v[102:105]
	v_mfma_f32_16x16x32_bf16 v[58:61], v[172:175], v[192:195], v[58:61]
	v_mfma_f32_16x16x32_bf16 v[62:65], v[180:183], v[192:195], v[62:65]
	v_mfma_f32_16x16x32_bf16 v[50:53], v[172:175], v[200:203], v[50:53]
	v_mfma_f32_16x16x32_bf16 v[54:57], v[180:183], v[200:203], v[54:57]
	v_mfma_f32_16x16x32_bf16 v[42:45], v[172:175], v[210:213], v[42:45]
	v_mfma_f32_16x16x32_bf16 v[46:49], v[180:183], v[210:213], v[46:49]
	v_mfma_f32_16x16x32_bf16 v[38:41], v[172:175], v[218:221], v[38:41]
	v_mfma_f32_16x16x32_bf16 v[34:37], v[180:183], v[218:221], v[34:37]
	v_mfma_f32_16x16x32_bf16 v[58:61], v[176:179], v[196:199], v[58:61]
	v_mfma_f32_16x16x32_bf16 v[62:65], v[188:191], v[196:199], v[62:65]
	v_mfma_f32_16x16x32_bf16 v[50:53], v[176:179], v[206:209], v[50:53]
	v_mfma_f32_16x16x32_bf16 v[54:57], v[188:191], v[206:209], v[54:57]
	v_mfma_f32_16x16x32_bf16 v[42:45], v[176:179], v[214:217], v[42:45]
	v_mfma_f32_16x16x32_bf16 v[46:49], v[188:191], v[214:217], v[46:49]
	v_mfma_f32_16x16x32_bf16 v[38:41], v[176:179], v[222:225], v[38:41]
	v_mfma_f32_16x16x32_bf16 v[34:37], v[188:191], v[222:225], v[34:37]
	s_setprio 0
	s_barrier
	s_andn2_b64 vcc, exec, s[28:29]
	s_cbranch_vccz .LBB0_1587
